# v39 + LayerNorm gamma/beta of the residual epilogue served from a per-wave LDS table instead of 8 global reloads per row
# speedup vs baseline: 1.0107x; 1.0012x over previous
; __device__ __forceinline__ float xsum16(float v) { const auto r = __builtin_amdgcn_permlane16_swap(__float_as_uint(v), __float_as_uint(v), false, false); return __uint_as_float(r[0]) + __uint_as_float(r[1]); }
; __device__ __forceinline__ float xsum32(float v) { const auto r = __builtin_amdgcn_permlane32_swap(__float_as_uint(v), __float_as_uint(v), false, false); return __uint_as_float(r[0]) + __uint_as_float(r[1]); }
; __device__ __forceinline__ void row_stats4(const float* st, int rowb, int fq, float (&mu)[4], float (&rs)[4]) {
;     f32x4 a[4], b[4];
; #pragma unroll
;     for (int m = 0; m < 4; ++m) { const f32x4* p = (const f32x4*)(st + (size_t)(rowb + m * 16) * 32 + fq * 8); a[m] = p[0]; b[m] = p[1]; }
; #pragma unroll
;     for (int m = 0; m < 4; ++m) { float s1 = (a[m][0] + a[m][2]) + (b[m][0] + b[m][2]), s2 = (a[m][1] + a[m][3]) + (b[m][1] + b[m][3]);
;         s1 = xsum32(xsum16(s1)); s2 = xsum32(xsum16(s2));
;         const float mm = s1 * (1.0f / 1024.0f); mu[m] = mm; rs[m] = rsqrtf(fmaxf(s2 * (1.0f / 1024.0f) - mm * mm, 0.f) + LN_EPS_); }
;     __device__ __forceinline__ void operator()(const f32x4 (&acc)[2][2][4][2], const pg8::Unit& u, int wr, int wc, int fr, int fq) const {
;     ...
;         for (int ai = 0; ai < 2; ++ai) { float mu4[4], rs4[4]; row_stats4(stp, row0 + ai * 128, fq, mu4, rs4);
; #pragma unroll
;             for (int m = 0; m < 4; ++m) { const int row = row0 + ai * 128 + m * 16; const float mu = mu4[m], rs = rs4[m];
;                 f32x4 yv[2][2], gq[2][2], bq_[2][2];
; #pragma unroll
;                 for (int bj = 0; bj < 2; ++bj)
; #pragma unroll
;                     for (int n = 0; n < 2; ++n) { yv[bj][n] = *(const f32x4*)(Yin + (size_t)row * D_ + col0 + bj * 128 + 4 * n); gq[bj][n] = *(const f32x4*)(g + col0 + bj * 128 + 4 * n); bq_[bj][n] = *(const f32x4*)(b + col0 + bj * 128 + 4 * n); }
.LBB0_372:
	s_lshl_b32 s3, s3, 8
	s_add_i32 s3, s3, s53
	v_or_b32_e32 v158, s3, v182
	v_ashrrev_i32_e32 v159, 31, v158
	v_lshlrev_b64 v[130:131], 7, v[158:159]
	v_lshl_add_u64 v[136:137], v[146:147], 0, v[130:131]
	v_or_b32_e32 v180, 16, v158
	s_nop 1
	v_bfe_u32 v153, v227, 4, 2
	v_sub_u32_e32 v152, 0, v153
	v_lshlrev_b32_e32 v152, 4, v152
	v_ashrrev_i32_e32 v153, 31, v152
	v_lshl_add_u64 v[152:153], v[136:137], 0, v[152:153]
	global_load_dwordx4 v[132:135], v[152:153], off
	global_load_dwordx4 v[166:169], v[152:153], off offset:64
	v_ashrrev_i32_e32 v181, 31, v180
	v_lshlrev_b64 v[172:173], 7, v[180:181]
	v_lshl_add_u64 v[136:137], v[146:147], 0, v[172:173]
	s_nop 1
	v_bfe_u32 v153, v227, 4, 2
	v_sub_u32_e32 v152, 0, v153
	v_lshlrev_b32_e32 v152, 4, v152
	v_ashrrev_i32_e32 v153, 31, v152
	v_lshl_add_u64 v[152:153], v[136:137], 0, v[152:153]
	global_load_dwordx4 v[174:177], v[152:153], off
	global_load_dwordx4 v[186:189], v[152:153], off offset:64
	v_or_b32_e32 v170, 32, v158
	v_ashrrev_i32_e32 v171, 31, v170
	v_lshlrev_b64 v[164:165], 7, v[170:171]
	v_lshl_add_u64 v[136:137], v[146:147], 0, v[164:165]
	s_nop 1
	v_bfe_u32 v153, v227, 4, 2
	v_sub_u32_e32 v152, 0, v153
	v_lshlrev_b32_e32 v152, 4, v152
	v_ashrrev_i32_e32 v153, 31, v152
	v_lshl_add_u64 v[152:153], v[136:137], 0, v[152:153]
	global_load_dwordx4 v[190:193], v[152:153], off
	global_load_dwordx4 v[196:199], v[152:153], off offset:64
	v_or_b32_e32 v162, 48, v158
	v_ashrrev_i32_e32 v163, 31, v162
	v_lshlrev_b64 v[160:161], 7, v[162:163]
	v_lshl_add_u64 v[204:205], v[146:147], 0, v[160:161]
	s_nop 1
	v_bfe_u32 v137, v227, 4, 2
	v_sub_u32_e32 v136, 0, v137
	v_lshlrev_b32_e32 v136, 4, v136
	v_ashrrev_i32_e32 v137, 31, v136
	v_lshl_add_u64 v[136:137], v[204:205], 0, v[136:137]
	global_load_dwordx4 v[200:203], v[136:137], off
	s_nop 0
	global_load_dwordx4 v[204:207], v[136:137], off offset:64
	s_lshl_b32 s16, s2, 8
	s_lshl_b32 s17, s2, 3
	s_or_b32 s2, s16, s54
	v_or_b32_e32 v152, s2, v183
	v_ashrrev_i32_e32 v153, 31, v152
	v_lshlrev_b64 v[136:137], 12, v[158:159]
	v_lshlrev_b64 v[152:153], 2, v[152:153]
	v_lshl_add_u64 v[178:179], s[12:13], 0, v[136:137]
	v_lshl_add_u64 v[178:179], v[178:179], 0, v[152:153]
	v_lshl_add_u64 v[154:155], s[8:9], 0, v[152:153]
	v_lshl_add_u64 v[156:157], s[10:11], 0, v[152:153]
	s_nop 1
	v_bfe_u32 v195, v227, 4, 2
	v_sub_u32_e32 v194, 0, v195
	v_lshlrev_b32_e32 v194, 4, v194
	v_ashrrev_i32_e32 v195, 31, v194
	v_lshl_add_u64 v[194:195], v[178:179], 0, v[194:195]
	global_load_dwordx4 v[208:211], v[194:195], off offset:64
	global_load_dwordx4 v[212:215], v[194:195], off
	global_load_dwordx4 v[216:219], v[154:155], off offset:16
	global_load_dwordx4 v[220:223], v[154:155], off
	global_load_dwordx4 v[234:237], v[156:157], off offset:16
	global_load_dwordx4 v[238:241], v[156:157], off
	s_mov_b32 s16, 0x3a800000
	s_mov_b32 s18, 0x3fd744fd
	s_load_dwordx16 s[60:75], s[34:35], 0x38
	s_or_b32 s24, s17, s57
	v_bitop3_b32 v194, s2, 56, v183 bitop3:0xc8
	s_ashr_i32 s40, s2, 6
	s_ashr_i32 s25, s24, 31
	s_waitcnt lgkmcnt(0)
	v_lshl_add_u64 v[136:137], s[74:75], 0, v[136:137]
	v_lshl_add_u64 v[136:137], v[136:137], 0, v[152:153]
	s_ashr_i32 s41, s40, 31
	s_nop 1
	v_lshrrev_b32_e32 v0, 4, v227
	v_lshlrev_b32_e32 v0, 7, v0
	v_add_u32_e32 v0, 0x20100, v0
	s_waitcnt vmcnt(3)
	ds_write_b128 v0, v[216:219] offset:16
	s_waitcnt vmcnt(2)
	ds_write_b128 v0, v[220:223] offset:0
	s_waitcnt vmcnt(1)
	ds_write_b128 v0, v[234:237] offset:80
	s_waitcnt vmcnt(0)
	ds_write_b128 v0, v[238:241] offset:64
	v_permlane32_swap_b32_e32 v132, v166
	v_permlane32_swap_b32_e32 v133, v167
	v_permlane32_swap_b32_e32 v134, v168
	v_permlane32_swap_b32_e32 v135, v169
	v_permlane16_swap_b32_e32 v132, v166
	v_permlane16_swap_b32_e32 v133, v167
	v_permlane16_swap_b32_e32 v134, v168
	v_permlane16_swap_b32_e32 v135, v169
	v_mov_b32_e32 v224, v132
	v_mov_b32_e32 v225, v166
	v_mov_b32_e32 v228, v134
	v_mov_b32_e32 v229, v168
	v_mov_b32_e32 v166, v133
	v_mov_b32_e32 v168, v135
	v_pk_add_f32 v[132:133], v[224:225], v[228:229]
	v_pk_add_f32 v[134:135], v[166:167], v[168:169]
	v_pk_add_f32 v[132:133], v[132:133], v[132:133] op_sel:[0,1] op_sel_hi:[1,0]
	v_pk_add_f32 v[134:135], v[134:135], v[134:135] op_sel:[0,1] op_sel_hi:[1,0]
	v_permlane32_swap_b32_e32 v174, v186
	v_permlane32_swap_b32_e32 v175, v187
	v_permlane32_swap_b32_e32 v176, v188
	v_permlane32_swap_b32_e32 v177, v189
	v_permlane16_swap_b32_e32 v174, v186
	v_permlane16_swap_b32_e32 v175, v187
	v_permlane16_swap_b32_e32 v176, v188
	v_permlane16_swap_b32_e32 v177, v189
	v_mov_b32_e32 v166, v174
	v_mov_b32_e32 v167, v186
	v_mov_b32_e32 v168, v176
	v_mov_b32_e32 v169, v188
	v_mov_b32_e32 v0, v132
	v_mov_b32_e32 v133, v134
	v_pk_add_f32 v[166:167], v[166:167], v[168:169]
	v_permlane16_swap_b32_e32 v132, v0
	v_permlane16_swap_b32_e32 v134, v133
	v_mov_b32_e32 v186, v175
	v_mov_b32_e32 v188, v177
	v_pk_add_f32 v[166:167], v[166:167], v[166:167] op_sel:[0,1] op_sel_hi:[1,0]
	v_add_f32_e32 v177, v132, v0
	v_add_f32_e32 v176, v134, v133
	v_pk_add_f32 v[168:169], v[186:187], v[188:189]
	v_mov_b32_e32 v135, v166
	v_mov_b32_e32 v187, v177
	v_mov_b32_e32 v186, v176
	v_permlane16_swap_b32_e32 v166, v135
	v_permlane32_swap_b32_e32 v177, v187
	v_permlane32_swap_b32_e32 v176, v186
	v_add_f32_e32 v133, v166, v135
	v_pk_add_f32 v[166:167], v[176:177], v[186:187]
	v_pk_add_f32 v[168:169], v[168:169], v[168:169] op_sel:[0,1] op_sel_hi:[1,0]
	v_pk_mul_f32 v[224:225], v[166:167], s[16:17] op_sel_hi:[1,0]
	v_mov_b32_e32 v159, v168
	v_fma_f32 v0, -v225, v225, v224
	v_max_f32_e32 v0, 0, v0
	v_permlane16_swap_b32_e32 v168, v159
	v_add_f32_e32 v0, 0x3727c5ac, v0
	s_mov_b32 s16, 0x800000
; __device__ __forceinline__ float xsum16(float v) { const auto r = __builtin_amdgcn_permlane16_swap(__float_as_uint(v), __float_as_uint(v), false, false); return __uint_as_float(r[0]) + __uint_as_float(r[1]); }
; __device__ __forceinline__ float xsum32(float v) { const auto r = __builtin_amdgcn_permlane32_swap(__float_as_uint(v), __float_as_uint(v), false, false); return __uint_as_float(r[0]) + __uint_as_float(r[1]); }
; __device__ __forceinline__ size_t blk_off(int r, int c, int K) { return (size_t)(r >> 8) * 256 * K + (size_t)(c >> 6) * (256 * 64) + (size_t)((r & 255) * 64 + (c & 63)); }
; __device__ __forceinline__ void row_stats4(const float* st, int rowb, int fq, float (&mu)[4], float (&rs)[4]) {
;     ...
;     for (int m = 0; m < 4; ++m) { const f32x4* p = (const f32x4*)(st + (size_t)(rowb + m * 16) * 32 + fq * 8); a[m] = p[0]; b[m] = p[1]; }
; #pragma unroll
;     for (int m = 0; m < 4; ++m) { float s1 = (a[m][0] + a[m][2]) + (b[m][0] + b[m][2]), s2 = (a[m][1] + a[m][3]) + (b[m][1] + b[m][3]);
;         s1 = xsum32(xsum16(s1)); s2 = xsum32(xsum16(s2));
;         const float mm = s1 * (1.0f / 1024.0f); mu[m] = mm; rs[m] = rsqrtf(fmaxf(s2 * (1.0f / 1024.0f) - mm * mm, 0.f) + LN_EPS_); }
;     __device__ __forceinline__ void operator()(const f32x4 (&acc)[2][2][4][2], const pg8::Unit& u, int wr, int wc, int fr, int fq) const {
;     ...
;                     for (int n = 0; n < 2; ++n) { yv[bj][n] = *(const f32x4*)(Yin + (size_t)row * D_ + col0 + bj * 128 + 4 * n); gq[bj][n] = *(const f32x4*)(g + col0 + bj * 128 + 4 * n); bq_[bj][n] = *(const f32x4*)(b + col0 + bj * 128 + 4 * n); }
;                 asm volatile("" ::: "memory");
;                 float s1 = 0.f, s2 = 0.f;
; #pragma unroll
;                 for (int bj = 0; bj < 2; ++bj) { float* yp = Y + (size_t)row * D_ + col0 + bj * 128; f32x4 v[2];
; #pragma unroll
;                     for (int n = 0; n < 2; ++n) { v[n] = (((yv[bj][n] - mu) * rs) * gq[bj][n] + bq_[bj][n]) * ALPHA_ + acc[ai][bj][m][n] * sc;
;                         *(f32x4*)(yp + 4 * n) = v[n]; s1 += (v[n][0] + v[n][1]) + (v[n][2] + v[n][3]); s2 += (v[n][0] * v[n][0] + v[n][1] * v[n][1]) + (v[n][2] * v[n][2] + v[n][3] * v[n][3]); }
;                     *(u32x4*)(Yb + blk_off(row, col0 + bj * 128, D_)) = pack8(v[0], v[1]); }
	v_add_f32_e32 v132, v168, v159
	v_mul_f32_e32 v159, 0x4b800000, v0
	v_cmp_gt_f32_e32 vcc, s16, v0
	v_permlane32_swap_b32_e32 v190, v196
	v_permlane32_swap_b32_e32 v191, v197
	v_permlane32_swap_b32_e32 v192, v198
	v_permlane32_swap_b32_e32 v193, v199
	v_permlane16_swap_b32_e32 v190, v196
	v_permlane16_swap_b32_e32 v191, v197
	v_permlane16_swap_b32_e32 v192, v198
	v_permlane16_swap_b32_e32 v193, v199
	v_mov_b32_e32 v174, v190
	v_mov_b32_e32 v175, v196
	v_cndmask_b32_e32 v0, v0, v159, vcc
	v_rsq_f32_e32 v0, v0
	v_mov_b32_e32 v166, v192
	v_mov_b32_e32 v167, v198
	v_pk_add_f32 v[166:167], v[174:175], v[166:167]
	v_mul_f32_e32 v159, 0x45800000, v0
	v_pk_add_f32 v[166:167], v[166:167], v[166:167] op_sel:[0,1] op_sel_hi:[1,0]
	v_mov_b32_e32 v196, v191
	v_mov_b32_e32 v198, v193
	v_cndmask_b32_e32 v0, v0, v159, vcc
	v_pk_add_f32 v[168:169], v[196:197], v[198:199]
	v_mov_b32_e32 v159, v166
	v_pk_add_f32 v[168:169], v[168:169], v[168:169] op_sel:[0,1] op_sel_hi:[1,0]
	s_nop 0
	v_permlane16_swap_b32_e32 v166, v159
	v_add_f32_e32 v175, v166, v159
	v_mov_b32_e32 v159, v168
	s_nop 1
	v_permlane16_swap_b32_e32 v168, v159
	s_nop 1
	v_bfe_u32 v135, v227, 4, 2
	v_sub_u32_e32 v134, 0, v135
	v_lshlrev_b32_e32 v134, 4, v134
	v_ashrrev_i32_e32 v135, 31, v134
	v_lshl_add_u64 v[134:135], v[178:179], 0, v[134:135]
	global_load_dwordx4 v[186:189], v[134:135], off offset:576
	global_load_dwordx4 v[190:193], v[134:135], off offset:512
	v_add_f32_e32 v174, v168, v159
	v_permlane32_swap_b32_e32 v200, v204
	v_permlane32_swap_b32_e32 v201, v205
	v_permlane32_swap_b32_e32 v202, v206
	v_permlane32_swap_b32_e32 v203, v207
	v_permlane16_swap_b32_e32 v200, v204
	v_permlane16_swap_b32_e32 v201, v205
	v_permlane16_swap_b32_e32 v202, v206
	v_permlane16_swap_b32_e32 v203, v207
	v_mov_b32_e32 v166, v200
	v_mov_b32_e32 v167, v204
	v_mov_b32_e32 v168, v202
	v_mov_b32_e32 v169, v206
	v_mov_b32_e32 v204, v201
	v_mov_b32_e32 v206, v203
	v_pk_add_f32 v[166:167], v[166:167], v[168:169]
	v_pk_add_f32 v[168:169], v[204:205], v[206:207]
	global_load_dwordx4 v[196:199], v[154:155], off offset:528
	global_load_dwordx4 v[200:203], v[154:155], off offset:512
	global_load_dwordx4 v[204:207], v[156:157], off offset:528
	global_load_dwordx4 v[242:245], v[156:157], off offset:512
	v_permlane32_swap_b32_e32 v212, v208
	v_permlane32_swap_b32_e32 v213, v209
	v_permlane32_swap_b32_e32 v214, v210
	v_permlane32_swap_b32_e32 v215, v211
	v_permlane16_swap_b32_e32 v212, v208
	v_permlane16_swap_b32_e32 v213, v209
	v_permlane16_swap_b32_e32 v214, v210
	v_permlane16_swap_b32_e32 v215, v211
	v_sub_f32_e32 v179, v215, v225
	v_sub_f32_e32 v178, v214, v225
	v_sub_f32_e32 v213, v213, v225
	v_sub_f32_e32 v212, v212, v225
	v_pk_mul_f32 v[212:213], v[0:1], v[212:213] op_sel_hi:[0,1]
	v_pk_mul_f32 v[178:179], v[0:1], v[178:179] op_sel_hi:[0,1]
	v_pk_fma_f32 v[178:179], v[222:223], v[178:179], v[240:241]
	v_pk_fma_f32 v[212:213], v[220:221], v[212:213], v[238:239]
	v_pk_mul_f32 v[178:179], v[178:179], s[18:19] op_sel_hi:[1,0]
	v_pk_mul_f32 v[212:213], v[212:213], s[18:19] op_sel_hi:[1,0]
	v_pk_fma_f32 v[128:129], v[128:129], 0.5, v[178:179] op_sel_hi:[1,0,1]
	v_pk_fma_f32 v[126:127], v[126:127], 0.5, v[212:213] op_sel_hi:[1,0,1]
	v_add_f32_e32 v179, v128, v129
	v_add_f32_e32 v178, v126, v127
	v_add_f32_e32 v178, v178, v179
	v_add_f32_e32 v195, 0, v178
	v_mul_f32_e32 v178, v127, v127
	v_mul_f32_e32 v179, v129, v129
	v_fmac_f32_e32 v178, v126, v126
	v_fmac_f32_e32 v179, v128, v128
	v_add_f32_e32 v212, v178, v179
	v_sub_f32_e32 v179, v211, v225
	v_sub_f32_e32 v178, v210, v225
	v_sub_f32_e32 v209, v209, v225
	v_sub_f32_e32 v208, v208, v225
	v_pk_mul_f32 v[208:209], v[0:1], v[208:209] op_sel_hi:[0,1]
	v_pk_mul_f32 v[178:179], v[0:1], v[178:179] op_sel_hi:[0,1]
	v_pk_fma_f32 v[178:179], v[218:219], v[178:179], v[236:237]
	v_pk_fma_f32 v[208:209], v[216:217], v[208:209], v[234:235]
	v_pk_mul_f32 v[178:179], v[178:179], s[18:19] op_sel_hi:[1,0]
	v_pk_mul_f32 v[208:209], v[208:209], s[18:19] op_sel_hi:[1,0]
	v_pk_add_f32 v[166:167], v[166:167], v[166:167] op_sel:[0,1] op_sel_hi:[1,0]
	v_pk_fma_f32 v[124:125], v[124:125], 0.5, v[178:179] op_sel_hi:[1,0,1]
	v_pk_fma_f32 v[122:123], v[122:123], 0.5, v[208:209] op_sel_hi:[1,0,1]
	v_mov_b32_e32 v159, v166
	v_add_f32_e32 v178, v122, v123
	v_add_f32_e32 v179, v124, v125
	v_pk_add_f32 v[168:169], v[168:169], v[168:169] op_sel:[0,1] op_sel_hi:[1,0]
	v_permlane16_swap_b32_e32 v166, v159
	v_add_f32_e32 v178, v178, v179
	v_add_f32_e32 v167, v166, v159
	v_mov_b32_e32 v159, v168
	v_add_f32_e32 v178, v195, v178
	v_mul_f32_e32 v179, v123, v123
	v_mul_f32_e32 v195, v125, v125
	v_permlane16_swap_b32_e32 v168, v159
	s_ashr_i32 s16, s3, 8
	s_nop 0
	s_nop 1
	v_bfe_u32 v135, v227, 4, 2
	v_sub_u32_e32 v134, 0, v135
	v_lshlrev_b32_e32 v134, 4, v134
	v_ashrrev_i32_e32 v135, 31, v134
	v_lshl_add_u64 v[134:135], v[136:137], 0, v[134:135]
	v_permlane16_swap_b32_e32 v126, v122
	v_permlane16_swap_b32_e32 v127, v123
	v_permlane16_swap_b32_e32 v128, v124
	v_permlane16_swap_b32_e32 v129, v125
	v_permlane32_swap_b32_e32 v126, v122
	v_permlane32_swap_b32_e32 v127, v123
	v_permlane32_swap_b32_e32 v128, v124
	v_permlane32_swap_b32_e32 v129, v125
	global_store_dwordx4 v[134:135], v[126:129], off
	global_store_dwordx4 v[134:135], v[122:125], off offset:64
	s_nop 1
	v_permlane32_swap_b32_e32 v126, v122
	v_permlane32_swap_b32_e32 v127, v123
	v_permlane32_swap_b32_e32 v128, v124
	v_permlane32_swap_b32_e32 v129, v125
	v_permlane16_swap_b32_e32 v126, v122
	v_permlane16_swap_b32_e32 v127, v123
	v_permlane16_swap_b32_e32 v128, v124
	v_permlane16_swap_b32_e32 v129, v125
	v_fmac_f32_e32 v179, v122, v122
	v_fmac_f32_e32 v195, v124, v124
	v_cvt_pk_bf16_f32 v126, v126, v127
	v_cvt_pk_bf16_f32 v127, v128, v129
	v_cvt_pk_bf16_f32 v128, v122, v123
	v_cvt_pk_bf16_f32 v129, v124, v125
	v_add_f32_e32 v166, v168, v159
	s_ashr_i32 s17, s16, 31
	v_lshlrev_b32_e32 v159, 6, v158
	s_movk_i32 s3, 0x33c0
	s_lshl_b64 s[16:17], s[16:17], 19
	v_and_or_b32 v159, v159, s3, v194
	v_readlane_b32 s2, v253, 59
	v_readlane_b32 s3, v253, 60
	s_add_u32 s16, s2, s16
	s_addc_u32 s17, s3, s17
	s_lshl_b64 s[28:29], s[40:41], 15
	s_waitcnt vmcnt(6)
; __device__ __forceinline__ float xsum16(float v) { const auto r = __builtin_amdgcn_permlane16_swap(__float_as_uint(v), __float_as_uint(v), false, false); return __uint_as_float(r[0]) + __uint_as_float(r[1]); }
; __device__ __forceinline__ float xsum32(float v) { const auto r = __builtin_amdgcn_permlane32_swap(__float_as_uint(v), __float_as_uint(v), false, false); return __uint_as_float(r[0]) + __uint_as_float(r[1]); }
; __device__ __forceinline__ size_t blk_off(int r, int c, int K) { return (size_t)(r >> 8) * 256 * K + (size_t)(c >> 6) * (256 * 64) + (size_t)((r & 255) * 64 + (c & 63)); }
; __device__ __forceinline__ u32x4 pack8(const f32x4 a, const f32x4 b) { u32x4 w; w.x = cvt_pk_bf16(a[0], a[1]); w.y = cvt_pk_bf16(a[2], a[3]); w.z = cvt_pk_bf16(b[0], b[1]); w.w = cvt_pk_bf16(b[2], b[3]); return w; }
;     __device__ __forceinline__ void operator()(const f32x4 (&acc)[2][2][4][2], const pg8::Unit& u, int wr, int wc, int fr, int fq) const {
;     ...
;                     for (int n = 0; n < 2; ++n) { yv[bj][n] = *(const f32x4*)(Yin + (size_t)row * D_ + col0 + bj * 128 + 4 * n); gq[bj][n] = *(const f32x4*)(g + col0 + bj * 128 + 4 * n); bq_[bj][n] = *(const f32x4*)(b + col0 + bj * 128 + 4 * n); }
;                 asm volatile("" ::: "memory");
;                 float s1 = 0.f, s2 = 0.f;
; #pragma unroll
;                 for (int bj = 0; bj < 2; ++bj) { float* yp = Y + (size_t)row * D_ + col0 + bj * 128; f32x4 v[2];
; #pragma unroll
;                     for (int n = 0; n < 2; ++n) { v[n] = (((yv[bj][n] - mu) * rs) * gq[bj][n] + bq_[bj][n]) * ALPHA_ + acc[ai][bj][m][n] * sc;
;                         *(f32x4*)(yp + 4 * n) = v[n]; s1 += (v[n][0] + v[n][1]) + (v[n][2] + v[n][3]); s2 += (v[n][0] * v[n][0] + v[n][1] * v[n][1]) + (v[n][2] * v[n][2] + v[n][3] * v[n][3]); }
;                     *(u32x4*)(Yb + blk_off(row, col0 + bj * 128, D_)) = pack8(v[0], v[1]); }
;                 s1 = xsum32(xsum16(s1)); s2 = xsum32(xsum16(s2));
;                 if (fq == 0) *(f32x2*)(stn + (size_t)row * 32 + (u.pn * 4 + wc) * 2) = (f32x2){s1, s2}; asm volatile("" ::: "memory"); } }
	v_permlane32_swap_b32_e32 v190, v186
	v_permlane32_swap_b32_e32 v191, v187
	v_permlane32_swap_b32_e32 v192, v188
	v_permlane32_swap_b32_e32 v193, v189
	v_permlane16_swap_b32_e32 v190, v186
	v_permlane16_swap_b32_e32 v191, v187
	v_permlane16_swap_b32_e32 v192, v188
	v_permlane16_swap_b32_e32 v193, v189
	v_sub_f32_e32 v123, v193, v225
	v_sub_f32_e32 v122, v192, v225
	v_sub_f32_e32 v125, v191, v225
	v_sub_f32_e32 v124, v190, v225
	v_pk_mul_f32 v[124:125], v[0:1], v[124:125] op_sel_hi:[0,1]
	v_pk_mul_f32 v[122:123], v[0:1], v[122:123] op_sel_hi:[0,1]
	s_add_u32 s50, s16, s28
	s_addc_u32 s51, s17, s29
	v_lshlrev_b32_e32 v159, 1, v159
	global_store_dwordx4 v159, v[126:129], s[50:51]
	s_nop 1
	v_lshrrev_b32_e32 v134, 4, v227
	v_lshlrev_b32_e32 v134, 7, v134
	v_add_u32_e32 v134, 0x20100, v134
	s_waitcnt vmcnt(6)
	ds_write_b128 v134, v[196:199] offset:48
	s_waitcnt vmcnt(5)
	ds_write_b128 v134, v[200:203] offset:32
	s_waitcnt vmcnt(4)
	ds_write_b128 v134, v[204:207] offset:112
	s_waitcnt vmcnt(3)
	ds_write_b128 v134, v[242:245] offset:96
	v_pk_fma_f32 v[122:123], v[202:203], v[122:123], v[244:245]
	v_pk_fma_f32 v[124:125], v[200:201], v[124:125], v[242:243]
	v_pk_mul_f32 v[122:123], v[122:123], s[18:19] op_sel_hi:[1,0]
	v_pk_mul_f32 v[124:125], v[124:125], s[18:19] op_sel_hi:[1,0]
	v_pk_fma_f32 v[120:121], v[120:121], 0.5, v[122:123] op_sel_hi:[1,0,1]
	v_pk_fma_f32 v[118:119], v[118:119], 0.5, v[124:125] op_sel_hi:[1,0,1]
	v_add_f32_e32 v123, v120, v121
	v_add_f32_e32 v122, v118, v119
	v_add_f32_e32 v122, v122, v123
	v_add_f32_e32 v126, v178, v122
	v_mul_f32_e32 v122, v119, v119
	v_mul_f32_e32 v123, v121, v121
	v_add_f32_e32 v179, v179, v195
	v_fmac_f32_e32 v122, v118, v118
	v_fmac_f32_e32 v123, v120, v120
	v_add_f32_e32 v179, v212, v179
	v_add_f32_e32 v122, v122, v123
	v_add_f32_e32 v127, v179, v122
	v_sub_f32_e32 v123, v189, v225
	v_sub_f32_e32 v122, v188, v225
	v_sub_f32_e32 v125, v187, v225
	v_sub_f32_e32 v124, v186, v225
	v_pk_mul_f32 v[124:125], v[0:1], v[124:125] op_sel_hi:[0,1]
	v_pk_mul_f32 v[122:123], v[0:1], v[122:123] op_sel_hi:[0,1]
	v_pk_fma_f32 v[122:123], v[198:199], v[122:123], v[206:207]
	v_pk_fma_f32 v[124:125], v[196:197], v[124:125], v[204:205]
	v_pk_mul_f32 v[122:123], v[122:123], s[18:19] op_sel_hi:[1,0]
	v_pk_mul_f32 v[124:125], v[124:125], s[18:19] op_sel_hi:[1,0]
	v_pk_fma_f32 v[116:117], v[116:117], 0.5, v[122:123] op_sel_hi:[1,0,1]
	v_pk_fma_f32 v[114:115], v[114:115], 0.5, v[124:125] op_sel_hi:[1,0,1]
	v_add_f32_e32 v122, v116, v117
	v_add_f32_e32 v0, v114, v115
	v_add_f32_e32 v0, v0, v122
	v_mul_f32_e32 v122, v115, v115
	v_mul_f32_e32 v123, v117, v117
	v_add_f32_e32 v0, v126, v0
	v_fmac_f32_e32 v122, v114, v114
	v_fmac_f32_e32 v123, v116, v116
	s_nop 0
	s_nop 1
	v_bfe_u32 v125, v227, 4, 2
	v_sub_u32_e32 v124, 0, v125
	v_lshlrev_b32_e32 v124, 4, v124
	v_ashrrev_i32_e32 v125, 31, v124
	v_lshl_add_u64 v[124:125], v[136:137], 0, v[124:125]
	v_permlane16_swap_b32_e32 v118, v114
	v_permlane16_swap_b32_e32 v119, v115
	v_permlane16_swap_b32_e32 v120, v116
	v_permlane16_swap_b32_e32 v121, v117
	v_permlane32_swap_b32_e32 v118, v114
	v_permlane32_swap_b32_e32 v119, v115
	v_permlane32_swap_b32_e32 v120, v116
	v_permlane32_swap_b32_e32 v121, v117
	global_store_dwordx4 v[124:125], v[118:121], off offset:512
	global_store_dwordx4 v[124:125], v[114:117], off offset:576
	s_nop 1
	v_permlane32_swap_b32_e32 v118, v114
	v_permlane32_swap_b32_e32 v119, v115
	v_permlane32_swap_b32_e32 v120, v116
	v_permlane32_swap_b32_e32 v121, v117
	v_permlane16_swap_b32_e32 v118, v114
	v_permlane16_swap_b32_e32 v119, v115
	v_permlane16_swap_b32_e32 v120, v116
	v_permlane16_swap_b32_e32 v121, v117
	v_add_f32_e32 v122, v122, v123
	v_cvt_pk_bf16_f32 v118, v118, v119
	v_cvt_pk_bf16_f32 v119, v120, v121
	v_cvt_pk_bf16_f32 v120, v114, v115
	v_mov_b32_e32 v114, v0
	v_add_f32_e32 v122, v127, v122
	s_nop 0
	v_permlane16_swap_b32_e32 v0, v114
	s_or_b32 s2, s40, 2
	v_add_f32_e32 v114, v0, v114
	v_mov_b32_e32 v0, v122
	s_ashr_i32 s3, s2, 31
	s_nop 0
	v_permlane16_swap_b32_e32 v122, v0
	s_lshl_b64 s[40:41], s[2:3], 15
	v_add_f32_e32 v115, v122, v0
	v_mov_b32_e32 v135, v133
	v_mov_b32_e32 v134, v132
	v_mov_b32_e32 v177, v175
	v_mov_b32_e32 v176, v174
	v_mov_b32_e32 v169, v167
	v_mov_b32_e32 v168, v166
	v_cvt_pk_bf16_f32 v121, v116, v117
	s_add_u32 s42, s16, s40
	v_mov_b32_e32 v116, v114
	v_mov_b32_e32 v117, v115
	v_permlane32_swap_b32_e32 v133, v135
	v_permlane32_swap_b32_e32 v132, v134
	v_permlane32_swap_b32_e32 v175, v177
	v_permlane32_swap_b32_e32 v174, v176
	v_permlane32_swap_b32_e32 v167, v169
	v_permlane32_swap_b32_e32 v166, v168
	s_addc_u32 s43, s17, s41
	v_permlane32_swap_b32_e32 v114, v116
	v_permlane32_swap_b32_e32 v115, v117
	global_store_dwordx4 v159, v[118:121], s[42:43]
	s_and_saveexec_b64 s[26:27], s[44:45]
	s_cbranch_execz .LBB0_374
	v_pk_add_f32 v[114:115], v[114:115], v[116:117]
	v_lshl_add_u64 v[116:117], s[30:31], 0, v[130:131]
	v_lshl_add_u64 v[116:117], s[24:25], 2, v[116:117]
	global_store_dwordx2 v[116:117], v[114:115], off
; __device__ __forceinline__ size_t blk_off(int r, int c, int K) { return (size_t)(r >> 8) * 256 * K + (size_t)(c >> 6) * (256 * 64) + (size_t)((r & 255) * 64 + (c & 63)); }
; __device__ __forceinline__ u32x4 pack8(const f32x4 a, const f32x4 b) { u32x4 w; w.x = cvt_pk_bf16(a[0], a[1]); w.y = cvt_pk_bf16(a[2], a[3]); w.z = cvt_pk_bf16(b[0], b[1]); w.w = cvt_pk_bf16(b[2], b[3]); return w; }
; __device__ __forceinline__ void row_stats4(const float* st, int rowb, int fq, float (&mu)[4], float (&rs)[4]) {
;     ...
;         const float mm = s1 * (1.0f / 1024.0f); mu[m] = mm; rs[m] = rsqrtf(fmaxf(s2 * (1.0f / 1024.0f) - mm * mm, 0.f) + LN_EPS_); }
;     __device__ __forceinline__ void operator()(const f32x4 (&acc)[2][2][4][2], const pg8::Unit& u, int wr, int wc, int fr, int fq) const {
;     ...
;             for (int m = 0; m < 4; ++m) { const int row = row0 + ai * 128 + m * 16; const float mu = mu4[m], rs = rs4[m];
;                 f32x4 yv[2][2], gq[2][2], bq_[2][2];
; #pragma unroll
;                 for (int bj = 0; bj < 2; ++bj)
; #pragma unroll
;                     for (int n = 0; n < 2; ++n) { yv[bj][n] = *(const f32x4*)(Yin + (size_t)row * D_ + col0 + bj * 128 + 4 * n); gq[bj][n] = *(const f32x4*)(g + col0 + bj * 128 + 4 * n); bq_[bj][n] = *(const f32x4*)(b + col0 + bj * 128 + 4 * n); }
;                 asm volatile("" ::: "memory");
;                 float s1 = 0.f, s2 = 0.f;
; #pragma unroll
;                 for (int bj = 0; bj < 2; ++bj) { float* yp = Y + (size_t)row * D_ + col0 + bj * 128; f32x4 v[2];
; #pragma unroll
;                     for (int n = 0; n < 2; ++n) { v[n] = (((yv[bj][n] - mu) * rs) * gq[bj][n] + bq_[bj][n]) * ALPHA_ + acc[ai][bj][m][n] * sc;
;                         *(f32x4*)(yp + 4 * n) = v[n]; s1 += (v[n][0] + v[n][1]) + (v[n][2] + v[n][3]); s2 += (v[n][0] * v[n][0] + v[n][1] * v[n][1]) + (v[n][2] * v[n][2] + v[n][3] * v[n][3]); }
;                     *(u32x4*)(Yb + blk_off(row, col0 + bj * 128, D_)) = pack8(v[0], v[1]); }
.LBB0_374:
	s_or_b64 exec, exec, s[26:27]
	v_pk_add_f32 v[114:115], v[132:133], v[134:135]
	s_mov_b32 s2, 0x3a800000
	v_pk_mul_f32 v[178:179], v[114:115], s[2:3] op_sel_hi:[1,0]
	s_mov_b32 s2, 0x800000
	v_fma_f32 v0, -v179, v179, v178
	v_max_f32_e32 v0, 0, v0
	v_add_f32_e32 v0, 0x3727c5ac, v0
	v_cmp_gt_f32_e32 vcc, s2, v0
	v_mul_f32_e32 v114, 0x4b800000, v0
	v_lshlrev_b64 v[212:213], 12, v[180:181]
	v_cndmask_b32_e32 v0, v0, v114, vcc
	v_rsq_f32_e32 v0, v0
	v_lshlrev_b32_e32 v159, 6, v180
	s_movk_i32 s2, 0x37c0
	v_mul_f32_e32 v114, 0x45800000, v0
	v_cndmask_b32_e32 v0, v0, v114, vcc
	v_lshl_add_u64 v[114:115], s[12:13], 0, v[212:213]
	v_lshl_add_u64 v[118:119], v[114:115], 0, v[152:153]
	s_nop 1
	v_bfe_u32 v117, v227, 4, 2
	v_sub_u32_e32 v116, 0, v117
	v_lshlrev_b32_e32 v116, 4, v116
	v_ashrrev_i32_e32 v117, 31, v116
	v_lshl_add_u64 v[116:117], v[118:119], 0, v[116:117]
	global_load_dwordx4 v[186:189], v[116:117], off offset:64
	global_load_dwordx4 v[190:193], v[116:117], off
	s_nop 1
	v_lshrrev_b32_e32 v178, 4, v227
	v_lshlrev_b32_e32 v178, 7, v178
	v_add_u32_e32 v178, 0x20100, v178
	ds_read_b128 v[196:199], v178 offset:16
	ds_read_b128 v[200:203], v178 offset:0
	ds_read_b128 v[204:207], v178 offset:80
	ds_read_b128 v[208:211], v178 offset:64
	s_nop 1
	v_bfe_u32 v121, v227, 4, 2
	v_sub_u32_e32 v120, 0, v121
	v_lshlrev_b32_e32 v120, 4, v120
	v_ashrrev_i32_e32 v121, 31, v120
	v_lshl_add_u64 v[120:121], v[118:119], 0, v[120:121]
	global_load_dwordx4 v[114:117], v[120:121], off offset:576
	global_load_dwordx4 v[134:137], v[120:121], off offset:512
	s_nop 0
	ds_read_b128 v[118:121], v178 offset:48
	ds_read_b128 v[126:129], v178 offset:32
	ds_read_b128 v[122:125], v178 offset:112
	ds_read_b128 v[130:133], v178 offset:96
	v_and_or_b32 v159, v159, s2, v194
	s_load_dwordx16 s[60:75], s[34:35], 0x38
	s_mov_b32 s2, 0x3fd744fd
	v_lshlrev_b32_e32 v159, 1, v159
	s_waitcnt lgkmcnt(0)
	v_lshl_add_u64 v[180:181], s[74:75], 0, v[212:213]
	v_lshl_add_u64 v[180:181], v[180:181], 0, v[152:153]
	s_waitcnt vmcnt(2)
	v_permlane32_swap_b32_e32 v190, v186
	v_permlane32_swap_b32_e32 v191, v187
	v_permlane32_swap_b32_e32 v192, v188
	v_permlane32_swap_b32_e32 v193, v189
	v_permlane16_swap_b32_e32 v190, v186
	v_permlane16_swap_b32_e32 v191, v187
	v_permlane16_swap_b32_e32 v192, v188
	v_permlane16_swap_b32_e32 v193, v189
	v_sub_f32_e32 v189, v189, v179
	v_sub_f32_e32 v193, v193, v179
	v_sub_f32_e32 v192, v192, v179
	v_sub_f32_e32 v191, v191, v179
	v_sub_f32_e32 v190, v190, v179
	v_pk_mul_f32 v[190:191], v[0:1], v[190:191] op_sel_hi:[0,1]
	v_pk_mul_f32 v[192:193], v[0:1], v[192:193] op_sel_hi:[0,1]
	v_sub_f32_e32 v188, v188, v179
	v_sub_f32_e32 v187, v187, v179
	v_sub_f32_e32 v186, v186, v179
	v_pk_fma_f32 v[192:193], v[202:203], v[192:193], v[210:211]
	v_pk_fma_f32 v[190:191], v[200:201], v[190:191], v[208:209]
	v_pk_mul_f32 v[186:187], v[0:1], v[186:187] op_sel_hi:[0,1]
	v_pk_mul_f32 v[188:189], v[0:1], v[188:189] op_sel_hi:[0,1]
	v_pk_mul_f32 v[190:191], v[190:191], s[2:3] op_sel_hi:[1,0]
	v_pk_mul_f32 v[192:193], v[192:193], s[2:3] op_sel_hi:[1,0]
	v_pk_fma_f32 v[188:189], v[198:199], v[188:189], v[206:207]
	v_pk_fma_f32 v[186:187], v[196:197], v[186:187], v[204:205]
	v_pk_fma_f32 v[112:113], v[112:113], 0.5, v[192:193] op_sel_hi:[1,0,1]
	v_pk_fma_f32 v[110:111], v[110:111], 0.5, v[190:191] op_sel_hi:[1,0,1]
	v_pk_mul_f32 v[186:187], v[186:187], s[2:3] op_sel_hi:[1,0]
	v_pk_mul_f32 v[188:189], v[188:189], s[2:3] op_sel_hi:[1,0]
	v_add_f32_e32 v178, v110, v111
	v_add_f32_e32 v190, v112, v113
	v_pk_fma_f32 v[108:109], v[108:109], 0.5, v[188:189] op_sel_hi:[1,0,1]
	v_pk_fma_f32 v[106:107], v[106:107], 0.5, v[186:187] op_sel_hi:[1,0,1]
	v_add_f32_e32 v178, v178, v190
	v_add_f32_e32 v186, v106, v107
	v_add_f32_e32 v187, v108, v109
	v_add_f32_e32 v178, 0, v178
	v_add_f32_e32 v186, v186, v187
	v_mul_f32_e32 v190, v111, v111
	v_mul_f32_e32 v191, v113, v113
	v_add_f32_e32 v178, v178, v186
	v_mul_f32_e32 v186, v107, v107
	v_mul_f32_e32 v187, v109, v109
	s_nop 0
	v_fmac_f32_e32 v190, v110, v110
	v_fmac_f32_e32 v191, v112, v112
	s_nop 1
	v_bfe_u32 v155, v227, 4, 2
	v_sub_u32_e32 v154, 0, v155
	v_lshlrev_b32_e32 v154, 4, v154
	v_ashrrev_i32_e32 v155, 31, v154
	v_lshl_add_u64 v[154:155], v[180:181], 0, v[154:155]
	v_permlane16_swap_b32_e32 v110, v106
	v_permlane16_swap_b32_e32 v111, v107
	v_permlane16_swap_b32_e32 v112, v108
	v_permlane16_swap_b32_e32 v113, v109
	v_permlane32_swap_b32_e32 v110, v106
	v_permlane32_swap_b32_e32 v111, v107
	v_permlane32_swap_b32_e32 v112, v108
	v_permlane32_swap_b32_e32 v113, v109
	global_store_dwordx4 v[154:155], v[110:113], off
	global_store_dwordx4 v[154:155], v[106:109], off offset:64
	s_nop 1
	v_permlane32_swap_b32_e32 v110, v106
	v_permlane32_swap_b32_e32 v111, v107
	v_permlane32_swap_b32_e32 v112, v108
	v_permlane32_swap_b32_e32 v113, v109
	v_permlane16_swap_b32_e32 v110, v106
	v_permlane16_swap_b32_e32 v111, v107
	v_permlane16_swap_b32_e32 v112, v108
	v_permlane16_swap_b32_e32 v113, v109
	v_fmac_f32_e32 v186, v106, v106
	v_fmac_f32_e32 v187, v108, v108
	v_cvt_pk_bf16_f32 v110, v110, v111
	v_cvt_pk_bf16_f32 v111, v112, v113
	v_cvt_pk_bf16_f32 v112, v106, v107
	v_cvt_pk_bf16_f32 v113, v108, v109
	s_waitcnt vmcnt(2)
; __device__ __forceinline__ float xsum16(float v) { const auto r = __builtin_amdgcn_permlane16_swap(__float_as_uint(v), __float_as_uint(v), false, false); return __uint_as_float(r[0]) + __uint_as_float(r[1]); }
; __device__ __forceinline__ float xsum32(float v) { const auto r = __builtin_amdgcn_permlane32_swap(__float_as_uint(v), __float_as_uint(v), false, false); return __uint_as_float(r[0]) + __uint_as_float(r[1]); }
; __device__ __forceinline__ size_t blk_off(int r, int c, int K) { return (size_t)(r >> 8) * 256 * K + (size_t)(c >> 6) * (256 * 64) + (size_t)((r & 255) * 64 + (c & 63)); }
; __device__ __forceinline__ u32x4 pack8(const f32x4 a, const f32x4 b) { u32x4 w; w.x = cvt_pk_bf16(a[0], a[1]); w.y = cvt_pk_bf16(a[2], a[3]); w.z = cvt_pk_bf16(b[0], b[1]); w.w = cvt_pk_bf16(b[2], b[3]); return w; }
;     __device__ __forceinline__ void operator()(const f32x4 (&acc)[2][2][4][2], const pg8::Unit& u, int wr, int wc, int fr, int fq) const {
;     ...
;             for (int m = 0; m < 4; ++m) { const int row = row0 + ai * 128 + m * 16; const float mu = mu4[m], rs = rs4[m];
;                 f32x4 yv[2][2], gq[2][2], bq_[2][2];
; #pragma unroll
;                 for (int bj = 0; bj < 2; ++bj)
; #pragma unroll
;                     for (int n = 0; n < 2; ++n) { yv[bj][n] = *(const f32x4*)(Yin + (size_t)row * D_ + col0 + bj * 128 + 4 * n); gq[bj][n] = *(const f32x4*)(g + col0 + bj * 128 + 4 * n); bq_[bj][n] = *(const f32x4*)(b + col0 + bj * 128 + 4 * n); }
;                 asm volatile("" ::: "memory");
;                 float s1 = 0.f, s2 = 0.f;
; #pragma unroll
;                 for (int bj = 0; bj < 2; ++bj) { float* yp = Y + (size_t)row * D_ + col0 + bj * 128; f32x4 v[2];
; #pragma unroll
;                     for (int n = 0; n < 2; ++n) { v[n] = (((yv[bj][n] - mu) * rs) * gq[bj][n] + bq_[bj][n]) * ALPHA_ + acc[ai][bj][m][n] * sc;
;                         *(f32x4*)(yp + 4 * n) = v[n]; s1 += (v[n][0] + v[n][1]) + (v[n][2] + v[n][3]); s2 += (v[n][0] * v[n][0] + v[n][1] * v[n][1]) + (v[n][2] * v[n][2] + v[n][3] * v[n][3]); }
;                     *(u32x4*)(Yb + blk_off(row, col0 + bj * 128, D_)) = pack8(v[0], v[1]); }
;                 s1 = xsum32(xsum16(s1)); s2 = xsum32(xsum16(s2));
;                 if (fq == 0) *(f32x2*)(stn + (size_t)row * 32 + (u.pn * 4 + wc) * 2) = (f32x2){s1, s2}; asm volatile("" ::: "memory"); } }
	v_permlane32_swap_b32_e32 v134, v114
	v_permlane32_swap_b32_e32 v135, v115
	v_permlane32_swap_b32_e32 v136, v116
	v_permlane32_swap_b32_e32 v137, v117
	v_permlane16_swap_b32_e32 v134, v114
	v_permlane16_swap_b32_e32 v135, v115
	v_permlane16_swap_b32_e32 v136, v116
	v_permlane16_swap_b32_e32 v137, v117
	v_sub_f32_e32 v107, v137, v179
	v_sub_f32_e32 v106, v136, v179
	v_sub_f32_e32 v109, v135, v179
	v_sub_f32_e32 v108, v134, v179
	v_pk_mul_f32 v[108:109], v[0:1], v[108:109] op_sel_hi:[0,1]
	v_pk_mul_f32 v[106:107], v[0:1], v[106:107] op_sel_hi:[0,1]
	v_pk_fma_f32 v[106:107], v[128:129], v[106:107], v[132:133]
	v_pk_fma_f32 v[108:109], v[126:127], v[108:109], v[130:131]
	v_pk_mul_f32 v[106:107], v[106:107], s[2:3] op_sel_hi:[1,0]
	v_pk_mul_f32 v[108:109], v[108:109], s[2:3] op_sel_hi:[1,0]
	v_pk_fma_f32 v[104:105], v[104:105], 0.5, v[106:107] op_sel_hi:[1,0,1]
	v_pk_fma_f32 v[102:103], v[102:103], 0.5, v[108:109] op_sel_hi:[1,0,1]
	v_add_f32_e32 v107, v104, v105
	v_add_f32_e32 v106, v102, v103
	v_add_f32_e32 v106, v106, v107
	global_store_dwordx4 v159, v[110:113], s[50:51]
	v_mul_f32_e32 v107, v105, v105
	v_add_f32_e32 v190, v190, v191
	v_add_f32_e32 v110, v178, v106
	v_mul_f32_e32 v106, v103, v103
	v_add_f32_e32 v186, v186, v187
	v_fmac_f32_e32 v106, v102, v102
	v_fmac_f32_e32 v107, v104, v104
	v_add_f32_e32 v186, v190, v186
	v_add_f32_e32 v106, v106, v107
	v_add_f32_e32 v111, v186, v106
	v_sub_f32_e32 v107, v117, v179
	v_sub_f32_e32 v106, v116, v179
	v_sub_f32_e32 v109, v115, v179
	v_sub_f32_e32 v108, v114, v179
	v_pk_mul_f32 v[108:109], v[0:1], v[108:109] op_sel_hi:[0,1]
	v_pk_mul_f32 v[106:107], v[0:1], v[106:107] op_sel_hi:[0,1]
	v_pk_fma_f32 v[106:107], v[120:121], v[106:107], v[124:125]
	v_pk_fma_f32 v[108:109], v[118:119], v[108:109], v[122:123]
	v_pk_mul_f32 v[106:107], v[106:107], s[2:3] op_sel_hi:[1,0]
	v_pk_mul_f32 v[108:109], v[108:109], s[2:3] op_sel_hi:[1,0]
	v_pk_fma_f32 v[100:101], v[100:101], 0.5, v[106:107] op_sel_hi:[1,0,1]
	v_pk_fma_f32 v[98:99], v[98:99], 0.5, v[108:109] op_sel_hi:[1,0,1]
	v_add_f32_e32 v106, v100, v101
	v_add_f32_e32 v0, v98, v99
	v_add_f32_e32 v0, v0, v106
	v_mul_f32_e32 v106, v99, v99
	v_mul_f32_e32 v107, v101, v101
	v_add_f32_e32 v0, v110, v0
	v_fmac_f32_e32 v106, v98, v98
	v_fmac_f32_e32 v107, v100, v100
	s_nop 0
	s_nop 1
	v_bfe_u32 v109, v227, 4, 2
	v_sub_u32_e32 v108, 0, v109
	v_lshlrev_b32_e32 v108, 4, v108
	v_ashrrev_i32_e32 v109, 31, v108
	v_lshl_add_u64 v[108:109], v[180:181], 0, v[108:109]
	v_permlane16_swap_b32_e32 v102, v98
	v_permlane16_swap_b32_e32 v103, v99
	v_permlane16_swap_b32_e32 v104, v100
	v_permlane16_swap_b32_e32 v105, v101
	v_permlane32_swap_b32_e32 v102, v98
	v_permlane32_swap_b32_e32 v103, v99
	v_permlane32_swap_b32_e32 v104, v100
	v_permlane32_swap_b32_e32 v105, v101
	global_store_dwordx4 v[108:109], v[102:105], off offset:512
	global_store_dwordx4 v[108:109], v[98:101], off offset:576
	s_nop 1
	v_permlane32_swap_b32_e32 v102, v98
	v_permlane32_swap_b32_e32 v103, v99
	v_permlane32_swap_b32_e32 v104, v100
	v_permlane32_swap_b32_e32 v105, v101
	v_permlane16_swap_b32_e32 v102, v98
	v_permlane16_swap_b32_e32 v103, v99
	v_permlane16_swap_b32_e32 v104, v100
	v_permlane16_swap_b32_e32 v105, v101
	v_add_f32_e32 v106, v106, v107
	v_cvt_pk_bf16_f32 v102, v102, v103
	v_cvt_pk_bf16_f32 v103, v104, v105
	v_cvt_pk_bf16_f32 v104, v98, v99
	v_mov_b32_e32 v98, v0
	v_add_f32_e32 v106, v111, v106
	s_nop 0
	v_permlane16_swap_b32_e32 v0, v98
	v_add_f32_e32 v98, v0, v98
	v_mov_b32_e32 v0, v106
	s_nop 1
	v_permlane16_swap_b32_e32 v106, v0
	v_add_f32_e32 v99, v106, v0
	v_cvt_pk_bf16_f32 v105, v100, v101
	v_mov_b32_e32 v100, v98
	v_mov_b32_e32 v101, v99
	s_nop 0
	v_permlane32_swap_b32_e32 v98, v100
	v_permlane32_swap_b32_e32 v99, v101
	global_store_dwordx4 v159, v[102:105], s[42:43]
	s_and_saveexec_b64 s[26:27], s[44:45]
	s_cbranch_execz .LBB0_376
	v_pk_add_f32 v[98:99], v[98:99], v[100:101]
	v_lshl_add_u64 v[100:101], s[30:31], 0, v[172:173]
	v_lshl_add_u64 v[100:101], s[24:25], 2, v[100:101]
	global_store_dwordx2 v[100:101], v[98:99], off
.LBB0_376:
	s_or_b64 exec, exec, s[26:27]
	v_pk_add_f32 v[98:99], v[174:175], v[176:177]
	s_mov_b32 s2, 0x3a800000
	v_pk_mul_f32 v[122:123], v[98:99], s[2:3] op_sel_hi:[1,0]
	s_mov_b32 s2, 0x800000
	v_fma_f32 v0, -v123, v123, v122
	v_max_f32_e32 v0, 0, v0
	v_add_f32_e32 v0, 0x3727c5ac, v0
	v_cmp_gt_f32_e32 vcc, s2, v0
	v_mul_f32_e32 v98, 0x4b800000, v0
	v_lshlrev_b64 v[124:125], 12, v[170:171]
	v_cndmask_b32_e32 v0, v0, v98, vcc
	v_rsq_f32_e32 v0, v0
	s_load_dwordx16 s[60:75], s[34:35], 0x38
	v_lshlrev_b32_e32 v122, 6, v170
	v_mul_f32_e32 v98, 0x45800000, v0
	v_cndmask_b32_e32 v0, v0, v98, vcc
	v_lshl_add_u64 v[98:99], s[12:13], 0, v[124:125]
	v_lshl_add_u64 v[102:103], v[98:99], 0, v[152:153]
	s_nop 1
	v_bfe_u32 v101, v227, 4, 2
	v_sub_u32_e32 v100, 0, v101
	v_lshlrev_b32_e32 v100, 4, v100
	v_ashrrev_i32_e32 v101, 31, v100
	v_lshl_add_u64 v[100:101], v[102:103], 0, v[100:101]
	global_load_dwordx4 v[126:129], v[100:101], off offset:64
	global_load_dwordx4 v[130:133], v[100:101], off
	s_nop 1
	v_lshrrev_b32_e32 v159, 4, v227
	v_lshlrev_b32_e32 v159, 7, v159
	v_add_u32_e32 v159, 0x20100, v159
	ds_read_b128 v[134:137], v159 offset:16
	ds_read_b128 v[172:175], v159 offset:0
	ds_read_b128 v[176:179], v159 offset:80
	ds_read_b128 v[186:189], v159 offset:64
	s_nop 1
	v_bfe_u32 v105, v227, 4, 2
	v_sub_u32_e32 v104, 0, v105
	v_lshlrev_b32_e32 v104, 4, v104
	v_ashrrev_i32_e32 v105, 31, v104
	v_lshl_add_u64 v[104:105], v[102:103], 0, v[104:105]
	global_load_dwordx4 v[98:101], v[104:105], off offset:576
	global_load_dwordx4 v[118:121], v[104:105], off offset:512
	s_nop 0
	ds_read_b128 v[102:105], v159 offset:48
	ds_read_b128 v[110:113], v159 offset:32
	ds_read_b128 v[106:109], v159 offset:112
	ds_read_b128 v[114:117], v159 offset:96
	s_movk_i32 s2, 0x3bc0
	v_and_or_b32 v122, v122, s2, v194
	s_mov_b32 s2, 0x3fd744fd
	s_waitcnt lgkmcnt(0)
; __device__ __forceinline__ size_t blk_off(int r, int c, int K) { return (size_t)(r >> 8) * 256 * K + (size_t)(c >> 6) * (256 * 64) + (size_t)((r & 255) * 64 + (c & 63)); }
; __device__ __forceinline__ u32x4 pack8(const f32x4 a, const f32x4 b) { u32x4 w; w.x = cvt_pk_bf16(a[0], a[1]); w.y = cvt_pk_bf16(a[2], a[3]); w.z = cvt_pk_bf16(b[0], b[1]); w.w = cvt_pk_bf16(b[2], b[3]); return w; }
;     __device__ __forceinline__ void operator()(const f32x4 (&acc)[2][2][4][2], const pg8::Unit& u, int wr, int wc, int fr, int fq) const {
;     ...
;                     for (int n = 0; n < 2; ++n) { yv[bj][n] = *(const f32x4*)(Yin + (size_t)row * D_ + col0 + bj * 128 + 4 * n); gq[bj][n] = *(const f32x4*)(g + col0 + bj * 128 + 4 * n); bq_[bj][n] = *(const f32x4*)(b + col0 + bj * 128 + 4 * n); }
;                 asm volatile("" ::: "memory");
;                 float s1 = 0.f, s2 = 0.f;
; #pragma unroll
;                 for (int bj = 0; bj < 2; ++bj) { float* yp = Y + (size_t)row * D_ + col0 + bj * 128; f32x4 v[2];
; #pragma unroll
;                     for (int n = 0; n < 2; ++n) { v[n] = (((yv[bj][n] - mu) * rs) * gq[bj][n] + bq_[bj][n]) * ALPHA_ + acc[ai][bj][m][n] * sc;
;                         *(f32x4*)(yp + 4 * n) = v[n]; s1 += (v[n][0] + v[n][1]) + (v[n][2] + v[n][3]); s2 += (v[n][0] * v[n][0] + v[n][1] * v[n][1]) + (v[n][2] * v[n][2] + v[n][3] * v[n][3]); }
;                     *(u32x4*)(Yb + blk_off(row, col0 + bj * 128, D_)) = pack8(v[0], v[1]); }
	v_lshl_add_u64 v[124:125], s[74:75], 0, v[124:125]
	v_lshl_add_u64 v[124:125], v[124:125], 0, v[152:153]
	v_lshlrev_b32_e32 v122, 1, v122
	s_waitcnt vmcnt(2)
	v_permlane32_swap_b32_e32 v130, v126
	v_permlane32_swap_b32_e32 v131, v127
	v_permlane32_swap_b32_e32 v132, v128
	v_permlane32_swap_b32_e32 v133, v129
	v_permlane16_swap_b32_e32 v130, v126
	v_permlane16_swap_b32_e32 v131, v127
	v_permlane16_swap_b32_e32 v132, v128
	v_permlane16_swap_b32_e32 v133, v129
	v_sub_f32_e32 v129, v129, v123
	v_sub_f32_e32 v133, v133, v123
	v_sub_f32_e32 v132, v132, v123
	v_sub_f32_e32 v131, v131, v123
	v_sub_f32_e32 v130, v130, v123
	v_sub_f32_e32 v128, v128, v123
	v_sub_f32_e32 v127, v127, v123
	v_sub_f32_e32 v126, v126, v123
	v_pk_mul_f32 v[130:131], v[0:1], v[130:131] op_sel_hi:[0,1]
	v_pk_mul_f32 v[132:133], v[0:1], v[132:133] op_sel_hi:[0,1]
	v_pk_mul_f32 v[126:127], v[0:1], v[126:127] op_sel_hi:[0,1]
	v_pk_mul_f32 v[128:129], v[0:1], v[128:129] op_sel_hi:[0,1]
	v_pk_fma_f32 v[132:133], v[174:175], v[132:133], v[188:189]
	v_pk_fma_f32 v[130:131], v[172:173], v[130:131], v[186:187]
	v_pk_fma_f32 v[128:129], v[136:137], v[128:129], v[178:179]
	v_pk_fma_f32 v[126:127], v[134:135], v[126:127], v[176:177]
	v_pk_mul_f32 v[130:131], v[130:131], s[2:3] op_sel_hi:[1,0]
	v_pk_mul_f32 v[132:133], v[132:133], s[2:3] op_sel_hi:[1,0]
	v_pk_mul_f32 v[126:127], v[126:127], s[2:3] op_sel_hi:[1,0]
	v_pk_mul_f32 v[128:129], v[128:129], s[2:3] op_sel_hi:[1,0]
	v_pk_fma_f32 v[96:97], v[96:97], 0.5, v[132:133] op_sel_hi:[1,0,1]
	v_pk_fma_f32 v[94:95], v[94:95], 0.5, v[130:131] op_sel_hi:[1,0,1]
	v_pk_fma_f32 v[92:93], v[92:93], 0.5, v[128:129] op_sel_hi:[1,0,1]
	v_pk_fma_f32 v[90:91], v[90:91], 0.5, v[126:127] op_sel_hi:[1,0,1]
	v_add_f32_e32 v130, v94, v95
	v_add_f32_e32 v131, v96, v97
	v_add_f32_e32 v126, v90, v91
	v_add_f32_e32 v127, v92, v93
	v_add_f32_e32 v130, v130, v131
	v_mul_f32_e32 v131, v95, v95
	v_mul_f32_e32 v132, v97, v97
	v_add_f32_e32 v126, v126, v127
	v_mul_f32_e32 v127, v91, v91
	v_mul_f32_e32 v128, v93, v93
	s_nop 0
	v_fmac_f32_e32 v131, v94, v94
	v_fmac_f32_e32 v132, v96, v96
	s_nop 1
	v_bfe_u32 v135, v227, 4, 2
	v_sub_u32_e32 v134, 0, v135
	v_lshlrev_b32_e32 v134, 4, v134
	v_ashrrev_i32_e32 v135, 31, v134
	v_lshl_add_u64 v[134:135], v[124:125], 0, v[134:135]
	v_permlane16_swap_b32_e32 v94, v90
	v_permlane16_swap_b32_e32 v95, v91
	v_permlane16_swap_b32_e32 v96, v92
	v_permlane16_swap_b32_e32 v97, v93
	v_permlane32_swap_b32_e32 v94, v90
	v_permlane32_swap_b32_e32 v95, v91
	v_permlane32_swap_b32_e32 v96, v92
	v_permlane32_swap_b32_e32 v97, v93
	global_store_dwordx4 v[134:135], v[94:97], off
	global_store_dwordx4 v[134:135], v[90:93], off offset:64
	s_nop 1
	v_permlane32_swap_b32_e32 v94, v90
	v_permlane32_swap_b32_e32 v95, v91
	v_permlane32_swap_b32_e32 v96, v92
	v_permlane32_swap_b32_e32 v97, v93
	v_permlane16_swap_b32_e32 v94, v90
	v_permlane16_swap_b32_e32 v95, v91
	v_permlane16_swap_b32_e32 v96, v92
	v_permlane16_swap_b32_e32 v97, v93
	v_fmac_f32_e32 v127, v90, v90
	v_fmac_f32_e32 v128, v92, v92
	v_cvt_pk_bf16_f32 v94, v94, v95
	v_cvt_pk_bf16_f32 v95, v96, v97
	v_cvt_pk_bf16_f32 v96, v90, v91
	v_cvt_pk_bf16_f32 v97, v92, v93
	s_waitcnt vmcnt(2)
	v_permlane32_swap_b32_e32 v118, v98
	v_permlane32_swap_b32_e32 v119, v99
	v_permlane32_swap_b32_e32 v120, v100
	v_permlane32_swap_b32_e32 v121, v101
	v_permlane16_swap_b32_e32 v118, v98
	v_permlane16_swap_b32_e32 v119, v99
	v_permlane16_swap_b32_e32 v120, v100
	v_permlane16_swap_b32_e32 v121, v101
	v_sub_f32_e32 v91, v121, v123
	v_sub_f32_e32 v90, v120, v123
	v_sub_f32_e32 v93, v119, v123
	v_sub_f32_e32 v92, v118, v123
	v_pk_mul_f32 v[92:93], v[0:1], v[92:93] op_sel_hi:[0,1]
	v_pk_mul_f32 v[90:91], v[0:1], v[90:91] op_sel_hi:[0,1]
	v_pk_fma_f32 v[90:91], v[112:113], v[90:91], v[116:117]
	v_pk_fma_f32 v[92:93], v[110:111], v[92:93], v[114:115]
	v_pk_mul_f32 v[90:91], v[90:91], s[2:3] op_sel_hi:[1,0]
	v_pk_mul_f32 v[92:93], v[92:93], s[2:3] op_sel_hi:[1,0]
	v_pk_fma_f32 v[88:89], v[88:89], 0.5, v[90:91] op_sel_hi:[1,0,1]
	v_pk_fma_f32 v[86:87], v[86:87], 0.5, v[92:93] op_sel_hi:[1,0,1]
	v_add_f32_e32 v130, 0, v130
	v_add_f32_e32 v90, v86, v87
	v_add_f32_e32 v91, v88, v89
	v_add_f32_e32 v126, v130, v126
	v_add_f32_e32 v90, v90, v91
	global_store_dwordx4 v122, v[94:97], s[50:51]
	v_mul_f32_e32 v91, v89, v89
	v_add_f32_e32 v131, v131, v132
	v_add_f32_e32 v94, v126, v90
	v_mul_f32_e32 v90, v87, v87
	v_add_f32_e32 v127, v127, v128
	v_fmac_f32_e32 v90, v86, v86
	v_fmac_f32_e32 v91, v88, v88
	v_add_f32_e32 v127, v131, v127
	v_add_f32_e32 v90, v90, v91
	v_add_f32_e32 v95, v127, v90
	v_sub_f32_e32 v91, v101, v123
	v_sub_f32_e32 v90, v100, v123
	v_sub_f32_e32 v93, v99, v123
	v_sub_f32_e32 v92, v98, v123
	v_pk_mul_f32 v[92:93], v[0:1], v[92:93] op_sel_hi:[0,1]
	v_pk_mul_f32 v[90:91], v[0:1], v[90:91] op_sel_hi:[0,1]
	v_pk_fma_f32 v[90:91], v[104:105], v[90:91], v[108:109]
	v_pk_fma_f32 v[92:93], v[102:103], v[92:93], v[106:107]
	v_pk_mul_f32 v[90:91], v[90:91], s[2:3] op_sel_hi:[1,0]
	v_pk_mul_f32 v[92:93], v[92:93], s[2:3] op_sel_hi:[1,0]
	v_pk_fma_f32 v[84:85], v[84:85], 0.5, v[90:91] op_sel_hi:[1,0,1]
	v_pk_fma_f32 v[82:83], v[82:83], 0.5, v[92:93] op_sel_hi:[1,0,1]
	v_add_f32_e32 v90, v84, v85
	v_add_f32_e32 v0, v82, v83
	v_add_f32_e32 v0, v0, v90
	v_mul_f32_e32 v90, v83, v83
	v_mul_f32_e32 v91, v85, v85
	v_add_f32_e32 v0, v94, v0
	v_fmac_f32_e32 v90, v82, v82
	v_fmac_f32_e32 v91, v84, v84
	s_nop 0
	s_nop 1
	v_bfe_u32 v93, v227, 4, 2
	v_sub_u32_e32 v92, 0, v93
	v_lshlrev_b32_e32 v92, 4, v92
	v_ashrrev_i32_e32 v93, 31, v92
	v_lshl_add_u64 v[92:93], v[124:125], 0, v[92:93]
	v_permlane16_swap_b32_e32 v86, v82
	v_permlane16_swap_b32_e32 v87, v83
	v_permlane16_swap_b32_e32 v88, v84
	v_permlane16_swap_b32_e32 v89, v85
	v_permlane32_swap_b32_e32 v86, v82
	v_permlane32_swap_b32_e32 v87, v83
	v_permlane32_swap_b32_e32 v88, v84
	v_permlane32_swap_b32_e32 v89, v85
	global_store_dwordx4 v[92:93], v[86:89], off offset:512
	global_store_dwordx4 v[92:93], v[82:85], off offset:576
	s_nop 1
	v_permlane32_swap_b32_e32 v86, v82
	v_permlane32_swap_b32_e32 v87, v83
	v_permlane32_swap_b32_e32 v88, v84
	v_permlane32_swap_b32_e32 v89, v85
	v_permlane16_swap_b32_e32 v86, v82
	v_permlane16_swap_b32_e32 v87, v83
	v_permlane16_swap_b32_e32 v88, v84
	v_permlane16_swap_b32_e32 v89, v85
	v_add_f32_e32 v90, v90, v91
	v_cvt_pk_bf16_f32 v86, v86, v87
	v_cvt_pk_bf16_f32 v87, v88, v89
	v_cvt_pk_bf16_f32 v88, v82, v83
	v_mov_b32_e32 v82, v0
	v_add_f32_e32 v90, v95, v90
	s_nop 0
	v_permlane16_swap_b32_e32 v0, v82
	v_add_f32_e32 v82, v0, v82
	v_mov_b32_e32 v0, v90
	s_nop 1
	v_permlane16_swap_b32_e32 v90, v0
	v_add_f32_e32 v83, v90, v0
	v_cvt_pk_bf16_f32 v89, v84, v85
	v_mov_b32_e32 v84, v82
	v_mov_b32_e32 v85, v83
	s_nop 0
	v_permlane32_swap_b32_e32 v82, v84
	v_permlane32_swap_b32_e32 v83, v85
	global_store_dwordx4 v122, v[86:89], s[42:43]
	s_and_saveexec_b64 s[26:27], s[44:45]
	s_cbranch_execz .LBB0_378
; __device__ __forceinline__ size_t blk_off(int r, int c, int K) { return (size_t)(r >> 8) * 256 * K + (size_t)(c >> 6) * (256 * 64) + (size_t)((r & 255) * 64 + (c & 63)); }
; __device__ __forceinline__ u32x4 pack8(const f32x4 a, const f32x4 b) { u32x4 w; w.x = cvt_pk_bf16(a[0], a[1]); w.y = cvt_pk_bf16(a[2], a[3]); w.z = cvt_pk_bf16(b[0], b[1]); w.w = cvt_pk_bf16(b[2], b[3]); return w; }
;     __device__ __forceinline__ void operator()(const f32x4 (&acc)[2][2][4][2], const pg8::Unit& u, int wr, int wc, int fr, int fq) const {
;     ...
;             for (int m = 0; m < 4; ++m) { const int row = row0 + ai * 128 + m * 16; const float mu = mu4[m], rs = rs4[m];
;                 f32x4 yv[2][2], gq[2][2], bq_[2][2];
; #pragma unroll
;                 for (int bj = 0; bj < 2; ++bj)
; #pragma unroll
;                     for (int n = 0; n < 2; ++n) { yv[bj][n] = *(const f32x4*)(Yin + (size_t)row * D_ + col0 + bj * 128 + 4 * n); gq[bj][n] = *(const f32x4*)(g + col0 + bj * 128 + 4 * n); bq_[bj][n] = *(const f32x4*)(b + col0 + bj * 128 + 4 * n); }
;                 asm volatile("" ::: "memory");
;                 float s1 = 0.f, s2 = 0.f;
; #pragma unroll
;                 for (int bj = 0; bj < 2; ++bj) { float* yp = Y + (size_t)row * D_ + col0 + bj * 128; f32x4 v[2];
; #pragma unroll
;                     for (int n = 0; n < 2; ++n) { v[n] = (((yv[bj][n] - mu) * rs) * gq[bj][n] + bq_[bj][n]) * ALPHA_ + acc[ai][bj][m][n] * sc;
;                         *(f32x4*)(yp + 4 * n) = v[n]; s1 += (v[n][0] + v[n][1]) + (v[n][2] + v[n][3]); s2 += (v[n][0] * v[n][0] + v[n][1] * v[n][1]) + (v[n][2] * v[n][2] + v[n][3] * v[n][3]); }
;                     *(u32x4*)(Yb + blk_off(row, col0 + bj * 128, D_)) = pack8(v[0], v[1]); }
	v_pk_add_f32 v[82:83], v[82:83], v[84:85]
	v_lshl_add_u64 v[84:85], s[30:31], 0, v[164:165]
	v_lshl_add_u64 v[84:85], s[24:25], 2, v[84:85]
	global_store_dwordx2 v[84:85], v[82:83], off
.LBB0_378:
	s_or_b64 exec, exec, s[26:27]
	v_pk_add_f32 v[82:83], v[166:167], v[168:169]
	s_mov_b32 s2, 0x3a800000
	v_pk_mul_f32 v[106:107], v[82:83], s[2:3] op_sel_hi:[1,0]
	s_mov_b32 s2, 0x800000
	v_fma_f32 v0, -v107, v107, v106
	v_max_f32_e32 v0, 0, v0
	v_add_f32_e32 v0, 0x3727c5ac, v0
	v_cmp_gt_f32_e32 vcc, s2, v0
	v_mul_f32_e32 v82, 0x4b800000, v0
	v_lshlrev_b64 v[108:109], 12, v[162:163]
	v_cndmask_b32_e32 v0, v0, v82, vcc
	v_rsq_f32_e32 v0, v0
	s_load_dwordx16 s[60:75], s[34:35], 0x38
	v_lshlrev_b32_e32 v106, 6, v162
	v_mul_f32_e32 v82, 0x45800000, v0
	v_cndmask_b32_e32 v0, v0, v82, vcc
	v_lshl_add_u64 v[82:83], s[12:13], 0, v[108:109]
	v_lshl_add_u64 v[86:87], v[82:83], 0, v[152:153]
	s_nop 1
	v_bfe_u32 v85, v227, 4, 2
	v_sub_u32_e32 v84, 0, v85
	v_lshlrev_b32_e32 v84, 4, v84
	v_ashrrev_i32_e32 v85, 31, v84
	v_lshl_add_u64 v[84:85], v[86:87], 0, v[84:85]
	global_load_dwordx4 v[110:113], v[84:85], off offset:64
	global_load_dwordx4 v[114:117], v[84:85], off
	s_nop 1
	v_lshrrev_b32_e32 v134, 4, v227
	v_lshlrev_b32_e32 v134, 7, v134
	v_add_u32_e32 v134, 0x20100, v134
	ds_read_b128 v[118:121], v134 offset:16
	ds_read_b128 v[122:125], v134 offset:0
	ds_read_b128 v[126:129], v134 offset:80
	ds_read_b128 v[130:133], v134 offset:64
	s_nop 1
	v_bfe_u32 v89, v227, 4, 2
	v_sub_u32_e32 v88, 0, v89
	v_lshlrev_b32_e32 v88, 4, v88
	v_ashrrev_i32_e32 v89, 31, v88
	v_lshl_add_u64 v[88:89], v[86:87], 0, v[88:89]
	global_load_dwordx4 v[82:85], v[88:89], off offset:576
	global_load_dwordx4 v[102:105], v[88:89], off offset:512
	s_nop 0
	ds_read_b128 v[86:89], v134 offset:48
	ds_read_b128 v[94:97], v134 offset:32
	ds_read_b128 v[90:93], v134 offset:112
	ds_read_b128 v[98:101], v134 offset:96
	s_movk_i32 s2, 0x3fc0
	v_and_or_b32 v106, v106, s2, v194
	s_mov_b32 s2, 0x3fd744fd
	s_waitcnt lgkmcnt(0)
	v_lshl_add_u64 v[108:109], s[74:75], 0, v[108:109]
	v_lshl_add_u64 v[108:109], v[108:109], 0, v[152:153]
	v_lshlrev_b32_e32 v106, 1, v106
	s_waitcnt vmcnt(2)
	v_permlane32_swap_b32_e32 v114, v110
	v_permlane32_swap_b32_e32 v115, v111
	v_permlane32_swap_b32_e32 v116, v112
	v_permlane32_swap_b32_e32 v117, v113
	v_permlane16_swap_b32_e32 v114, v110
	v_permlane16_swap_b32_e32 v115, v111
	v_permlane16_swap_b32_e32 v116, v112
	v_permlane16_swap_b32_e32 v117, v113
	v_sub_f32_e32 v113, v113, v107
	v_sub_f32_e32 v117, v117, v107
	v_sub_f32_e32 v116, v116, v107
	v_sub_f32_e32 v115, v115, v107
	v_sub_f32_e32 v114, v114, v107
	v_sub_f32_e32 v112, v112, v107
	v_sub_f32_e32 v111, v111, v107
	v_sub_f32_e32 v110, v110, v107
	v_pk_mul_f32 v[114:115], v[0:1], v[114:115] op_sel_hi:[0,1]
	v_pk_mul_f32 v[116:117], v[0:1], v[116:117] op_sel_hi:[0,1]
	v_pk_mul_f32 v[110:111], v[0:1], v[110:111] op_sel_hi:[0,1]
	v_pk_mul_f32 v[112:113], v[0:1], v[112:113] op_sel_hi:[0,1]
	v_pk_fma_f32 v[116:117], v[124:125], v[116:117], v[132:133]
	v_pk_fma_f32 v[114:115], v[122:123], v[114:115], v[130:131]
	v_pk_fma_f32 v[112:113], v[120:121], v[112:113], v[128:129]
	v_pk_fma_f32 v[110:111], v[118:119], v[110:111], v[126:127]
	v_pk_mul_f32 v[114:115], v[114:115], s[2:3] op_sel_hi:[1,0]
	v_pk_mul_f32 v[116:117], v[116:117], s[2:3] op_sel_hi:[1,0]
	v_pk_mul_f32 v[110:111], v[110:111], s[2:3] op_sel_hi:[1,0]
	v_pk_mul_f32 v[112:113], v[112:113], s[2:3] op_sel_hi:[1,0]
	v_pk_fma_f32 v[80:81], v[80:81], 0.5, v[116:117] op_sel_hi:[1,0,1]
	v_pk_fma_f32 v[78:79], v[78:79], 0.5, v[114:115] op_sel_hi:[1,0,1]
	v_pk_fma_f32 v[76:77], v[76:77], 0.5, v[112:113] op_sel_hi:[1,0,1]
	v_pk_fma_f32 v[74:75], v[74:75], 0.5, v[110:111] op_sel_hi:[1,0,1]
	v_add_f32_e32 v114, v78, v79
	v_add_f32_e32 v115, v80, v81
	v_add_f32_e32 v110, v74, v75
	v_add_f32_e32 v111, v76, v77
	v_add_f32_e32 v114, v114, v115
	v_mul_f32_e32 v115, v79, v79
	v_mul_f32_e32 v116, v81, v81
	v_add_f32_e32 v110, v110, v111
	v_mul_f32_e32 v111, v75, v75
	v_mul_f32_e32 v112, v77, v77
	s_nop 0
	v_fmac_f32_e32 v115, v78, v78
	v_fmac_f32_e32 v116, v80, v80
	s_nop 1
	v_bfe_u32 v119, v227, 4, 2
	v_sub_u32_e32 v118, 0, v119
	v_lshlrev_b32_e32 v118, 4, v118
	v_ashrrev_i32_e32 v119, 31, v118
	v_lshl_add_u64 v[118:119], v[108:109], 0, v[118:119]
	v_permlane16_swap_b32_e32 v78, v74
	v_permlane16_swap_b32_e32 v79, v75
	v_permlane16_swap_b32_e32 v80, v76
	v_permlane16_swap_b32_e32 v81, v77
	v_permlane32_swap_b32_e32 v78, v74
	v_permlane32_swap_b32_e32 v79, v75
	v_permlane32_swap_b32_e32 v80, v76
	v_permlane32_swap_b32_e32 v81, v77
	global_store_dwordx4 v[118:119], v[78:81], off
	global_store_dwordx4 v[118:119], v[74:77], off offset:64
	s_nop 1
	v_permlane32_swap_b32_e32 v78, v74
	v_permlane32_swap_b32_e32 v79, v75
	v_permlane32_swap_b32_e32 v80, v76
	v_permlane32_swap_b32_e32 v81, v77
	v_permlane16_swap_b32_e32 v78, v74
	v_permlane16_swap_b32_e32 v79, v75
	v_permlane16_swap_b32_e32 v80, v76
	v_permlane16_swap_b32_e32 v81, v77
	v_fmac_f32_e32 v111, v74, v74
	v_fmac_f32_e32 v112, v76, v76
	v_cvt_pk_bf16_f32 v78, v78, v79
	v_cvt_pk_bf16_f32 v79, v80, v81
	v_cvt_pk_bf16_f32 v80, v74, v75
	v_cvt_pk_bf16_f32 v81, v76, v77
	s_waitcnt vmcnt(2)
; __device__ __forceinline__ float xsum16(float v) { const auto r = __builtin_amdgcn_permlane16_swap(__float_as_uint(v), __float_as_uint(v), false, false); return __uint_as_float(r[0]) + __uint_as_float(r[1]); }
; __device__ __forceinline__ float xsum32(float v) { const auto r = __builtin_amdgcn_permlane32_swap(__float_as_uint(v), __float_as_uint(v), false, false); return __uint_as_float(r[0]) + __uint_as_float(r[1]); }
; __device__ __forceinline__ size_t blk_off(int r, int c, int K) { return (size_t)(r >> 8) * 256 * K + (size_t)(c >> 6) * (256 * 64) + (size_t)((r & 255) * 64 + (c & 63)); }
; __device__ __forceinline__ u32x4 pack8(const f32x4 a, const f32x4 b) { u32x4 w; w.x = cvt_pk_bf16(a[0], a[1]); w.y = cvt_pk_bf16(a[2], a[3]); w.z = cvt_pk_bf16(b[0], b[1]); w.w = cvt_pk_bf16(b[2], b[3]); return w; }
; __device__ __forceinline__ void row_stats4(const float* st, int rowb, int fq, float (&mu)[4], float (&rs)[4]) {
;     ...
;     for (int m = 0; m < 4; ++m) { const f32x4* p = (const f32x4*)(st + (size_t)(rowb + m * 16) * 32 + fq * 8); a[m] = p[0]; b[m] = p[1]; }
; #pragma unroll
;     for (int m = 0; m < 4; ++m) { float s1 = (a[m][0] + a[m][2]) + (b[m][0] + b[m][2]), s2 = (a[m][1] + a[m][3]) + (b[m][1] + b[m][3]);
;     __device__ __forceinline__ void operator()(const f32x4 (&acc)[2][2][4][2], const pg8::Unit& u, int wr, int wc, int fr, int fq) const {
;     ...
;                 for (int bj = 0; bj < 2; ++bj) { float* yp = Y + (size_t)row * D_ + col0 + bj * 128; f32x4 v[2];
; #pragma unroll
;                     for (int n = 0; n < 2; ++n) { v[n] = (((yv[bj][n] - mu) * rs) * gq[bj][n] + bq_[bj][n]) * ALPHA_ + acc[ai][bj][m][n] * sc;
;                         *(f32x4*)(yp + 4 * n) = v[n]; s1 += (v[n][0] + v[n][1]) + (v[n][2] + v[n][3]); s2 += (v[n][0] * v[n][0] + v[n][1] * v[n][1]) + (v[n][2] * v[n][2] + v[n][3] * v[n][3]); }
;                     *(u32x4*)(Yb + blk_off(row, col0 + bj * 128, D_)) = pack8(v[0], v[1]); }
;                 s1 = xsum32(xsum16(s1)); s2 = xsum32(xsum16(s2));
;                 if (fq == 0) *(f32x2*)(stn + (size_t)row * 32 + (u.pn * 4 + wc) * 2) = (f32x2){s1, s2}; asm volatile("" ::: "memory"); } }
	v_permlane32_swap_b32_e32 v102, v82
	v_permlane32_swap_b32_e32 v103, v83
	v_permlane32_swap_b32_e32 v104, v84
	v_permlane32_swap_b32_e32 v105, v85
	v_permlane16_swap_b32_e32 v102, v82
	v_permlane16_swap_b32_e32 v103, v83
	v_permlane16_swap_b32_e32 v104, v84
	v_permlane16_swap_b32_e32 v105, v85
	v_sub_f32_e32 v75, v105, v107
	v_sub_f32_e32 v74, v104, v107
	v_sub_f32_e32 v77, v103, v107
	v_sub_f32_e32 v76, v102, v107
	v_pk_mul_f32 v[76:77], v[0:1], v[76:77] op_sel_hi:[0,1]
	v_pk_mul_f32 v[74:75], v[0:1], v[74:75] op_sel_hi:[0,1]
	v_pk_fma_f32 v[74:75], v[96:97], v[74:75], v[100:101]
	v_pk_fma_f32 v[76:77], v[94:95], v[76:77], v[98:99]
	v_pk_mul_f32 v[74:75], v[74:75], s[2:3] op_sel_hi:[1,0]
	v_pk_mul_f32 v[76:77], v[76:77], s[2:3] op_sel_hi:[1,0]
	v_pk_fma_f32 v[72:73], v[72:73], 0.5, v[74:75] op_sel_hi:[1,0,1]
	v_pk_fma_f32 v[70:71], v[70:71], 0.5, v[76:77] op_sel_hi:[1,0,1]
	v_add_f32_e32 v114, 0, v114
	v_add_f32_e32 v74, v70, v71
	v_add_f32_e32 v75, v72, v73
	v_add_f32_e32 v110, v114, v110
	v_add_f32_e32 v74, v74, v75
	global_store_dwordx4 v106, v[78:81], s[50:51]
	v_mul_f32_e32 v75, v73, v73
	v_add_f32_e32 v115, v115, v116
	v_add_f32_e32 v78, v110, v74
	v_mul_f32_e32 v74, v71, v71
	v_add_f32_e32 v111, v111, v112
	v_fmac_f32_e32 v74, v70, v70
	v_fmac_f32_e32 v75, v72, v72
	v_add_f32_e32 v111, v115, v111
	v_add_f32_e32 v74, v74, v75
	v_add_f32_e32 v79, v111, v74
	v_sub_f32_e32 v75, v85, v107
	v_sub_f32_e32 v74, v84, v107
	v_sub_f32_e32 v77, v83, v107
	v_sub_f32_e32 v76, v82, v107
	v_pk_mul_f32 v[76:77], v[0:1], v[76:77] op_sel_hi:[0,1]
	v_pk_mul_f32 v[74:75], v[0:1], v[74:75] op_sel_hi:[0,1]
	v_pk_fma_f32 v[74:75], v[88:89], v[74:75], v[92:93]
	v_pk_fma_f32 v[76:77], v[86:87], v[76:77], v[90:91]
	v_pk_mul_f32 v[74:75], v[74:75], s[2:3] op_sel_hi:[1,0]
	v_pk_mul_f32 v[76:77], v[76:77], s[2:3] op_sel_hi:[1,0]
	v_pk_fma_f32 v[68:69], v[68:69], 0.5, v[74:75] op_sel_hi:[1,0,1]
	v_pk_fma_f32 v[66:67], v[66:67], 0.5, v[76:77] op_sel_hi:[1,0,1]
	v_add_f32_e32 v74, v68, v69
	v_add_f32_e32 v0, v66, v67
	v_add_f32_e32 v0, v0, v74
	v_mul_f32_e32 v74, v67, v67
	v_mul_f32_e32 v75, v69, v69
	v_add_f32_e32 v0, v78, v0
	v_fmac_f32_e32 v74, v66, v66
	v_fmac_f32_e32 v75, v68, v68
	s_nop 0
	s_nop 1
	v_bfe_u32 v77, v227, 4, 2
	v_sub_u32_e32 v76, 0, v77
	v_lshlrev_b32_e32 v76, 4, v76
	v_ashrrev_i32_e32 v77, 31, v76
	v_lshl_add_u64 v[76:77], v[108:109], 0, v[76:77]
	v_permlane16_swap_b32_e32 v70, v66
	v_permlane16_swap_b32_e32 v71, v67
	v_permlane16_swap_b32_e32 v72, v68
	v_permlane16_swap_b32_e32 v73, v69
	v_permlane32_swap_b32_e32 v70, v66
	v_permlane32_swap_b32_e32 v71, v67
	v_permlane32_swap_b32_e32 v72, v68
	v_permlane32_swap_b32_e32 v73, v69
	global_store_dwordx4 v[76:77], v[70:73], off offset:512
	global_store_dwordx4 v[76:77], v[66:69], off offset:576
	s_nop 1
	v_permlane32_swap_b32_e32 v70, v66
	v_permlane32_swap_b32_e32 v71, v67
	v_permlane32_swap_b32_e32 v72, v68
	v_permlane32_swap_b32_e32 v73, v69
	v_permlane16_swap_b32_e32 v70, v66
	v_permlane16_swap_b32_e32 v71, v67
	v_permlane16_swap_b32_e32 v72, v68
	v_permlane16_swap_b32_e32 v73, v69
	v_add_f32_e32 v74, v74, v75
	v_cvt_pk_bf16_f32 v70, v70, v71
	v_cvt_pk_bf16_f32 v71, v72, v73
	v_cvt_pk_bf16_f32 v72, v66, v67
	v_mov_b32_e32 v66, v0
	v_add_f32_e32 v74, v79, v74
	s_nop 0
	v_permlane16_swap_b32_e32 v0, v66
	v_add_f32_e32 v66, v0, v66
	v_mov_b32_e32 v0, v74
	s_nop 1
	v_permlane16_swap_b32_e32 v74, v0
	v_add_f32_e32 v67, v74, v0
	v_cvt_pk_bf16_f32 v73, v68, v69
	v_mov_b32_e32 v68, v66
	v_mov_b32_e32 v69, v67
	s_nop 0
	v_permlane32_swap_b32_e32 v66, v68
	v_permlane32_swap_b32_e32 v67, v69
	global_store_dwordx4 v106, v[70:73], s[42:43]
	s_and_saveexec_b64 s[26:27], s[44:45]
	s_cbranch_execz .LBB0_380
	v_pk_add_f32 v[66:67], v[66:67], v[68:69]
	v_lshl_add_u64 v[68:69], s[30:31], 0, v[160:161]
	v_lshl_add_u64 v[68:69], s[24:25], 2, v[68:69]
	global_store_dwordx2 v[68:69], v[66:67], off
.LBB0_380:
	s_or_b64 exec, exec, s[26:27]
	v_add_u32_e32 v68, 0x80, v158
	v_ashrrev_i32_e32 v69, 31, v68
	v_add_u32_e32 v94, 0x90, v158
	v_lshlrev_b64 v[66:67], 7, v[68:69]
	v_ashrrev_i32_e32 v95, 31, v94
	v_lshl_add_u64 v[74:75], v[146:147], 0, v[66:67]
	v_lshlrev_b64 v[86:87], 7, v[94:95]
	v_add_u32_e32 v76, 0xa0, v158
	s_nop 1
	v_bfe_u32 v83, v227, 4, 2
	v_sub_u32_e32 v82, 0, v83
	v_lshlrev_b32_e32 v82, 4, v82
	v_ashrrev_i32_e32 v83, 31, v82
	v_lshl_add_u64 v[82:83], v[74:75], 0, v[82:83]
	global_load_dwordx4 v[70:73], v[82:83], off
	global_load_dwordx4 v[78:81], v[82:83], off offset:64
	v_lshl_add_u64 v[74:75], v[146:147], 0, v[86:87]
	v_ashrrev_i32_e32 v77, 31, v76
	s_nop 1
	v_bfe_u32 v93, v227, 4, 2
	v_sub_u32_e32 v92, 0, v93
	v_lshlrev_b32_e32 v92, 4, v92
	v_ashrrev_i32_e32 v93, 31, v92
	v_lshl_add_u64 v[92:93], v[74:75], 0, v[92:93]
	global_load_dwordx4 v[82:85], v[92:93], off
	global_load_dwordx4 v[88:91], v[92:93], off offset:64
	v_lshlrev_b64 v[74:75], 7, v[76:77]
	v_lshl_add_u64 v[74:75], v[146:147], 0, v[74:75]
	s_nop 1
	v_bfe_u32 v93, v227, 4, 2
	v_sub_u32_e32 v92, 0, v93
	v_lshlrev_b32_e32 v92, 4, v92
	v_ashrrev_i32_e32 v93, 31, v92
	v_lshl_add_u64 v[92:93], v[74:75], 0, v[92:93]
	global_load_dwordx4 v[96:99], v[92:93], off
	global_load_dwordx4 v[100:103], v[92:93], off offset:64
	v_add_u32_e32 v74, 0xb0, v158
	v_ashrrev_i32_e32 v75, 31, v74
	v_lshlrev_b64 v[92:93], 7, v[74:75]
	v_lshl_add_u64 v[92:93], v[146:147], 0, v[92:93]
	s_nop 1
	v_bfe_u32 v113, v227, 4, 2
	v_sub_u32_e32 v112, 0, v113
	v_lshlrev_b32_e32 v112, 4, v112
	v_ashrrev_i32_e32 v113, 31, v112
	v_lshl_add_u64 v[112:113], v[92:93], 0, v[112:113]
	global_load_dwordx4 v[104:107], v[112:113], off
	global_load_dwordx4 v[108:111], v[112:113], off offset:64
	v_lshlrev_b64 v[136:137], 12, v[68:69]
	v_lshl_add_u64 v[112:113], s[12:13], 0, v[136:137]
	v_lshl_add_u64 v[92:93], v[112:113], 0, v[152:153]
	s_nop 1
	v_bfe_u32 v121, v227, 4, 2
	v_sub_u32_e32 v120, 0, v121
	v_lshlrev_b32_e32 v120, 4, v120
	v_ashrrev_i32_e32 v121, 31, v120
	v_lshl_add_u64 v[120:121], v[92:93], 0, v[120:121]
	global_load_dwordx4 v[112:115], v[120:121], off offset:64
	global_load_dwordx4 v[116:119], v[120:121], off
	s_nop 1
	v_lshrrev_b32_e32 v166, 4, v227
	v_lshlrev_b32_e32 v166, 7, v166
	v_add_u32_e32 v166, 0x20100, v166
	ds_read_b128 v[120:123], v166 offset:16
	ds_read_b128 v[124:127], v166 offset:0
	ds_read_b128 v[128:131], v166 offset:80
	ds_read_b128 v[132:135], v166 offset:64
	s_mov_b32 s2, 0x3a800000
	s_mov_b32 s16, 0x3fd744fd
	s_load_dwordx16 s[60:75], s[34:35], 0x38
	s_waitcnt vmcnt(8)
; __device__ __forceinline__ float xsum16(float v) { const auto r = __builtin_amdgcn_permlane16_swap(__float_as_uint(v), __float_as_uint(v), false, false); return __uint_as_float(r[0]) + __uint_as_float(r[1]); }
; __device__ __forceinline__ float xsum32(float v) { const auto r = __builtin_amdgcn_permlane32_swap(__float_as_uint(v), __float_as_uint(v), false, false); return __uint_as_float(r[0]) + __uint_as_float(r[1]); }
; __device__ __forceinline__ void row_stats4(const float* st, int rowb, int fq, float (&mu)[4], float (&rs)[4]) {
;     ...
;     for (int m = 0; m < 4; ++m) { const f32x4* p = (const f32x4*)(st + (size_t)(rowb + m * 16) * 32 + fq * 8); a[m] = p[0]; b[m] = p[1]; }
; #pragma unroll
;     for (int m = 0; m < 4; ++m) { float s1 = (a[m][0] + a[m][2]) + (b[m][0] + b[m][2]), s2 = (a[m][1] + a[m][3]) + (b[m][1] + b[m][3]);
;         s1 = xsum32(xsum16(s1)); s2 = xsum32(xsum16(s2));
;         const float mm = s1 * (1.0f / 1024.0f); mu[m] = mm; rs[m] = rsqrtf(fmaxf(s2 * (1.0f / 1024.0f) - mm * mm, 0.f) + LN_EPS_); }
;     __device__ __forceinline__ void operator()(const f32x4 (&acc)[2][2][4][2], const pg8::Unit& u, int wr, int wc, int fr, int fq) const {
;     ...
;                     for (int n = 0; n < 2; ++n) { yv[bj][n] = *(const f32x4*)(Yin + (size_t)row * D_ + col0 + bj * 128 + 4 * n); gq[bj][n] = *(const f32x4*)(g + col0 + bj * 128 + 4 * n); bq_[bj][n] = *(const f32x4*)(b + col0 + bj * 128 + 4 * n); }
;                 asm volatile("" ::: "memory");
;                 float s1 = 0.f, s2 = 0.f;
; #pragma unroll
;                 for (int bj = 0; bj < 2; ++bj) { float* yp = Y + (size_t)row * D_ + col0 + bj * 128; f32x4 v[2];
; #pragma unroll
;                     for (int n = 0; n < 2; ++n) { v[n] = (((yv[bj][n] - mu) * rs) * gq[bj][n] + bq_[bj][n]) * ALPHA_ + acc[ai][bj][m][n] * sc;
	v_permlane32_swap_b32_e32 v70, v78
	v_permlane32_swap_b32_e32 v71, v79
	v_permlane32_swap_b32_e32 v72, v80
	v_permlane32_swap_b32_e32 v73, v81
	v_permlane16_swap_b32_e32 v70, v78
	v_permlane16_swap_b32_e32 v71, v79
	v_permlane16_swap_b32_e32 v72, v80
	v_permlane16_swap_b32_e32 v73, v81
	v_mov_b32_e32 v158, v70
	v_mov_b32_e32 v159, v78
	v_mov_b32_e32 v160, v72
	v_mov_b32_e32 v161, v80
	v_mov_b32_e32 v78, v71
	v_mov_b32_e32 v80, v73
	s_waitcnt vmcnt(6)
	v_permlane32_swap_b32_e32 v82, v88
	v_permlane32_swap_b32_e32 v83, v89
	v_permlane32_swap_b32_e32 v84, v90
	v_permlane32_swap_b32_e32 v85, v91
	v_permlane16_swap_b32_e32 v82, v88
	v_permlane16_swap_b32_e32 v83, v89
	v_permlane16_swap_b32_e32 v84, v90
	v_permlane16_swap_b32_e32 v85, v91
	v_mov_b32_e32 v70, v82
	v_mov_b32_e32 v71, v88
	v_mov_b32_e32 v72, v84
	v_mov_b32_e32 v73, v90
	v_mov_b32_e32 v88, v83
	v_mov_b32_e32 v90, v85
	s_waitcnt vmcnt(4)
	v_permlane32_swap_b32_e32 v96, v100
	v_permlane32_swap_b32_e32 v97, v101
	v_permlane32_swap_b32_e32 v98, v102
	v_permlane32_swap_b32_e32 v99, v103
	v_permlane16_swap_b32_e32 v96, v100
	v_permlane16_swap_b32_e32 v97, v101
	v_permlane16_swap_b32_e32 v98, v102
	v_permlane16_swap_b32_e32 v99, v103
	v_mov_b32_e32 v82, v96
	v_mov_b32_e32 v83, v100
	v_mov_b32_e32 v84, v98
	v_mov_b32_e32 v85, v102
	v_mov_b32_e32 v100, v97
	v_pk_add_f32 v[96:97], v[158:159], v[160:161]
	v_pk_add_f32 v[78:79], v[78:79], v[80:81]
	v_pk_add_f32 v[80:81], v[82:83], v[84:85]
	v_pk_add_f32 v[84:85], v[96:97], v[96:97] op_sel:[0,1] op_sel_hi:[1,0]
	v_pk_add_f32 v[78:79], v[78:79], v[78:79] op_sel:[0,1] op_sel_hi:[1,0]
	v_mov_b32_e32 v0, v84
	v_mov_b32_e32 v69, v78
	s_nop 0
	v_permlane16_swap_b32_e32 v84, v0
	v_permlane16_swap_b32_e32 v78, v69
	v_add_f32_e32 v79, v84, v0
	v_add_f32_e32 v78, v78, v69
	v_mov_b32_e32 v85, v79
	v_mov_b32_e32 v84, v78
	s_nop 0
	v_permlane32_swap_b32_e32 v79, v85
	v_permlane32_swap_b32_e32 v78, v84
	v_pk_add_f32 v[78:79], v[78:79], v[84:85]
	v_mov_b32_e32 v102, v99
	v_pk_mul_f32 v[78:79], v[78:79], s[2:3] op_sel_hi:[1,0]
	s_mov_b32 s2, 0x800000
	v_fma_f32 v0, -v79, v79, v78
	v_max_f32_e32 v0, 0, v0
	v_add_f32_e32 v0, 0x3727c5ac, v0
	v_mul_f32_e32 v69, 0x4b800000, v0
	v_cmp_gt_f32_e32 vcc, s2, v0
	v_pk_add_f32 v[82:83], v[100:101], v[102:103]
	v_pk_add_f32 v[80:81], v[80:81], v[80:81] op_sel:[0,1] op_sel_hi:[1,0]
	v_cndmask_b32_e32 v0, v0, v69, vcc
	v_rsq_f32_e32 v0, v0
	v_pk_add_f32 v[82:83], v[82:83], v[82:83] op_sel:[0,1] op_sel_hi:[1,0]
	v_mov_b32_e32 v81, v80
	s_nop 1
	v_permlane16_swap_b32_e32 v80, v81
	v_mul_f32_e32 v69, 0x45800000, v0
	v_cndmask_b32_e32 v78, v0, v69, vcc
	v_mov_b32_e32 v0, v82
	s_nop 1
	v_permlane16_swap_b32_e32 v82, v0
	s_nop 1
	v_bfe_u32 v85, v227, 4, 2
	v_sub_u32_e32 v84, 0, v85
	v_lshlrev_b32_e32 v84, 4, v84
	v_ashrrev_i32_e32 v85, 31, v84
	v_lshl_add_u64 v[84:85], v[92:93], 0, v[84:85]
	global_load_dwordx4 v[96:99], v[84:85], off offset:576
	global_load_dwordx4 v[100:103], v[84:85], off offset:512
	v_pk_add_f32 v[70:71], v[70:71], v[72:73]
	v_pk_add_f32 v[72:73], v[88:89], v[90:91]
	v_add_f32_e32 v89, v80, v81
	v_add_f32_e32 v88, v82, v0
	s_waitcnt vmcnt(4)
	v_permlane32_swap_b32_e32 v104, v108
	v_permlane32_swap_b32_e32 v105, v109
	v_permlane32_swap_b32_e32 v106, v110
	v_permlane32_swap_b32_e32 v107, v111
	v_permlane16_swap_b32_e32 v104, v108
	v_permlane16_swap_b32_e32 v105, v109
	v_permlane16_swap_b32_e32 v106, v110
	v_permlane16_swap_b32_e32 v107, v111
	v_mov_b32_e32 v80, v104
	v_mov_b32_e32 v81, v108
	v_mov_b32_e32 v82, v106
	v_mov_b32_e32 v83, v110
	v_mov_b32_e32 v108, v105
	v_mov_b32_e32 v110, v107
	v_pk_add_f32 v[80:81], v[80:81], v[82:83]
	v_pk_add_f32 v[82:83], v[108:109], v[110:111]
	ds_read_b128 v[104:107], v166 offset:48
	ds_read_b128 v[108:111], v166 offset:32
	ds_read_b128 v[158:161], v166 offset:112
	ds_read_b128 v[162:165], v166 offset:96
	s_waitcnt vmcnt(2)
	v_permlane32_swap_b32_e32 v116, v112
	v_permlane32_swap_b32_e32 v117, v113
	v_permlane32_swap_b32_e32 v118, v114
	v_permlane32_swap_b32_e32 v119, v115
	v_permlane16_swap_b32_e32 v116, v112
	v_permlane16_swap_b32_e32 v117, v113
	v_permlane16_swap_b32_e32 v118, v114
	v_permlane16_swap_b32_e32 v119, v115
	v_sub_f32_e32 v93, v119, v79
	v_sub_f32_e32 v92, v118, v79
	v_sub_f32_e32 v117, v117, v79
	v_sub_f32_e32 v116, v116, v79
	v_pk_mul_f32 v[116:117], v[78:79], v[116:117] op_sel_hi:[0,1]
	v_pk_mul_f32 v[92:93], v[78:79], v[92:93] op_sel_hi:[0,1]
	s_waitcnt lgkmcnt(0)
	v_pk_fma_f32 v[92:93], v[126:127], v[92:93], v[134:135]
	v_pk_fma_f32 v[116:117], v[124:125], v[116:117], v[132:133]
	v_pk_mul_f32 v[92:93], v[92:93], s[16:17] op_sel_hi:[1,0]
	v_pk_mul_f32 v[116:117], v[116:117], s[16:17] op_sel_hi:[1,0]
	v_pk_fma_f32 v[64:65], v[64:65], 0.5, v[92:93] op_sel_hi:[1,0,1]
	v_pk_fma_f32 v[62:63], v[62:63], 0.5, v[116:117] op_sel_hi:[1,0,1]
	v_add_f32_e32 v93, v64, v65
	v_add_f32_e32 v92, v62, v63
	v_add_f32_e32 v92, v92, v93
	v_add_f32_e32 v116, 0, v92
	v_mul_f32_e32 v92, v63, v63
	v_mul_f32_e32 v93, v65, v65
	v_pk_add_f32 v[80:81], v[80:81], v[80:81] op_sel:[0,1] op_sel_hi:[1,0]
	v_fmac_f32_e32 v92, v62, v62
	v_fmac_f32_e32 v93, v64, v64
	v_mov_b32_e32 v0, v80
	v_add_f32_e32 v117, v92, v93
	v_sub_f32_e32 v93, v115, v79
	v_sub_f32_e32 v92, v114, v79
	v_sub_f32_e32 v113, v113, v79
	v_sub_f32_e32 v112, v112, v79
	v_pk_add_f32 v[82:83], v[82:83], v[82:83] op_sel:[0,1] op_sel_hi:[1,0]
	v_permlane16_swap_b32_e32 v80, v0
	v_pk_mul_f32 v[112:113], v[78:79], v[112:113] op_sel_hi:[0,1]
	v_pk_mul_f32 v[92:93], v[78:79], v[92:93] op_sel_hi:[0,1]
	v_add_f32_e32 v83, v80, v0
	v_mov_b32_e32 v0, v82
	v_pk_fma_f32 v[92:93], v[122:123], v[92:93], v[130:131]
	v_pk_fma_f32 v[112:113], v[120:121], v[112:113], v[128:129]
	v_permlane16_swap_b32_e32 v82, v0
	v_pk_mul_f32 v[112:113], v[112:113], s[16:17] op_sel_hi:[1,0]
	v_pk_mul_f32 v[92:93], v[92:93], s[16:17] op_sel_hi:[1,0]
	v_add_f32_e32 v82, v82, v0
	v_ashrrev_i32_e32 v80, 8, v68
	v_lshlrev_b32_e32 v0, 6, v68
	s_movk_i32 s2, 0x33c0
	v_pk_fma_f32 v[60:61], v[60:61], 0.5, v[92:93] op_sel_hi:[1,0,1]
	v_pk_fma_f32 v[58:59], v[58:59], 0.5, v[112:113] op_sel_hi:[1,0,1]
	v_ashrrev_i32_e32 v81, 31, v80
	v_and_or_b32 v0, v0, s2, v194
	s_waitcnt lgkmcnt(0)
; __device__ __forceinline__ float xsum16(float v) { const auto r = __builtin_amdgcn_permlane16_swap(__float_as_uint(v), __float_as_uint(v), false, false); return __uint_as_float(r[0]) + __uint_as_float(r[1]); }
; __device__ __forceinline__ float xsum32(float v) { const auto r = __builtin_amdgcn_permlane32_swap(__float_as_uint(v), __float_as_uint(v), false, false); return __uint_as_float(r[0]) + __uint_as_float(r[1]); }
; __device__ __forceinline__ size_t blk_off(int r, int c, int K) { return (size_t)(r >> 8) * 256 * K + (size_t)(c >> 6) * (256 * 64) + (size_t)((r & 255) * 64 + (c & 63)); }
; __device__ __forceinline__ u32x4 pack8(const f32x4 a, const f32x4 b) { u32x4 w; w.x = cvt_pk_bf16(a[0], a[1]); w.y = cvt_pk_bf16(a[2], a[3]); w.z = cvt_pk_bf16(b[0], b[1]); w.w = cvt_pk_bf16(b[2], b[3]); return w; }
;     __device__ __forceinline__ void operator()(const f32x4 (&acc)[2][2][4][2], const pg8::Unit& u, int wr, int wc, int fr, int fq) const {
;     ...
;                 float s1 = 0.f, s2 = 0.f;
; #pragma unroll
;                 for (int bj = 0; bj < 2; ++bj) { float* yp = Y + (size_t)row * D_ + col0 + bj * 128; f32x4 v[2];
; #pragma unroll
;                     for (int n = 0; n < 2; ++n) { v[n] = (((yv[bj][n] - mu) * rs) * gq[bj][n] + bq_[bj][n]) * ALPHA_ + acc[ai][bj][m][n] * sc;
;                         *(f32x4*)(yp + 4 * n) = v[n]; s1 += (v[n][0] + v[n][1]) + (v[n][2] + v[n][3]); s2 += (v[n][0] * v[n][0] + v[n][1] * v[n][1]) + (v[n][2] * v[n][2] + v[n][3] * v[n][3]); }
;                     *(u32x4*)(Yb + blk_off(row, col0 + bj * 128, D_)) = pack8(v[0], v[1]); }
;                 s1 = xsum32(xsum16(s1)); s2 = xsum32(xsum16(s2));
;                 if (fq == 0) *(f32x2*)(stn + (size_t)row * 32 + (u.pn * 4 + wc) * 2) = (f32x2){s1, s2}; asm volatile("" ::: "memory"); } }
	v_lshl_add_u64 v[68:69], s[74:75], 0, v[136:137]
	v_add_f32_e32 v92, v58, v59
	v_add_f32_e32 v93, v60, v61
	v_readlane_b32 s2, v253, 59
	v_lshlrev_b64 v[80:81], 19, v[80:81]
	v_lshl_add_u64 v[68:69], v[68:69], 0, v[152:153]
	v_add_f32_e32 v92, v92, v93
	v_mul_f32_e32 v93, v59, v59
	v_readlane_b32 s3, v253, 60
	s_nop 0
	s_nop 1
	v_bfe_u32 v85, v227, 4, 2
	v_sub_u32_e32 v84, 0, v85
	v_lshlrev_b32_e32 v84, 4, v84
	v_ashrrev_i32_e32 v85, 31, v84
	v_lshl_add_u64 v[84:85], v[68:69], 0, v[84:85]
	v_permlane16_swap_b32_e32 v62, v58
	v_permlane16_swap_b32_e32 v63, v59
	v_permlane16_swap_b32_e32 v64, v60
	v_permlane16_swap_b32_e32 v65, v61
	v_permlane32_swap_b32_e32 v62, v58
	v_permlane32_swap_b32_e32 v63, v59
	v_permlane32_swap_b32_e32 v64, v60
	v_permlane32_swap_b32_e32 v65, v61
	global_store_dwordx4 v[84:85], v[62:65], off
	global_store_dwordx4 v[84:85], v[58:61], off offset:64
	s_nop 1
	v_permlane32_swap_b32_e32 v62, v58
	v_permlane32_swap_b32_e32 v63, v59
	v_permlane32_swap_b32_e32 v64, v60
	v_permlane32_swap_b32_e32 v65, v61
	v_permlane16_swap_b32_e32 v62, v58
	v_permlane16_swap_b32_e32 v63, v59
	v_permlane16_swap_b32_e32 v64, v60
	v_permlane16_swap_b32_e32 v65, v61
	v_fmac_f32_e32 v93, v58, v58
	v_cvt_pk_bf16_f32 v62, v62, v63
	v_cvt_pk_bf16_f32 v63, v64, v65
	v_cvt_pk_bf16_f32 v64, v58, v59
	v_lshl_add_u64 v[58:59], s[2:3], 0, v[80:81]
	v_mul_f32_e32 v112, v61, v61
	v_lshl_add_u64 v[80:81], v[58:59], 0, s[28:29]
	v_lshlrev_b32_e32 v0, 1, v0
	v_fmac_f32_e32 v112, v60, v60
	v_cvt_pk_bf16_f32 v65, v60, v61
	v_lshl_add_u64 v[60:61], v[80:81], 0, v[0:1]
	global_store_dwordx4 v[60:61], v[62:65], off
	s_waitcnt vmcnt(3)
	v_permlane32_swap_b32_e32 v100, v96
	v_permlane32_swap_b32_e32 v101, v97
	v_permlane32_swap_b32_e32 v102, v98
	v_permlane32_swap_b32_e32 v103, v99
	v_permlane16_swap_b32_e32 v100, v96
	v_permlane16_swap_b32_e32 v101, v97
	v_permlane16_swap_b32_e32 v102, v98
	v_permlane16_swap_b32_e32 v103, v99
	v_sub_f32_e32 v61, v103, v79
	v_sub_f32_e32 v60, v102, v79
	v_sub_f32_e32 v63, v101, v79
	v_sub_f32_e32 v62, v100, v79
	v_pk_mul_f32 v[62:63], v[78:79], v[62:63] op_sel_hi:[0,1]
	v_pk_mul_f32 v[60:61], v[78:79], v[60:61] op_sel_hi:[0,1]
	v_add_f32_e32 v92, v116, v92
	v_pk_fma_f32 v[60:61], v[110:111], v[60:61], v[164:165]
	v_pk_fma_f32 v[62:63], v[108:109], v[62:63], v[162:163]
	v_pk_mul_f32 v[60:61], v[60:61], s[16:17] op_sel_hi:[1,0]
	v_pk_mul_f32 v[62:63], v[62:63], s[16:17] op_sel_hi:[1,0]
	v_pk_fma_f32 v[56:57], v[56:57], 0.5, v[60:61] op_sel_hi:[1,0,1]
	v_pk_fma_f32 v[54:55], v[54:55], 0.5, v[62:63] op_sel_hi:[1,0,1]
	v_add_f32_e32 v61, v56, v57
	v_add_f32_e32 v60, v54, v55
	v_add_f32_e32 v60, v60, v61
	v_add_f32_e32 v64, v92, v60
	v_mul_f32_e32 v60, v55, v55
	v_mul_f32_e32 v61, v57, v57
	v_add_f32_e32 v93, v93, v112
	v_fmac_f32_e32 v60, v54, v54
	v_fmac_f32_e32 v61, v56, v56
	v_add_f32_e32 v93, v117, v93
	v_add_f32_e32 v60, v60, v61
	v_add_f32_e32 v65, v93, v60
	v_sub_f32_e32 v61, v99, v79
	v_sub_f32_e32 v60, v98, v79
	v_sub_f32_e32 v63, v97, v79
	v_sub_f32_e32 v62, v96, v79
	v_pk_mul_f32 v[62:63], v[78:79], v[62:63] op_sel_hi:[0,1]
	v_pk_mul_f32 v[60:61], v[78:79], v[60:61] op_sel_hi:[0,1]
	v_pk_fma_f32 v[60:61], v[106:107], v[60:61], v[160:161]
	v_pk_fma_f32 v[62:63], v[104:105], v[62:63], v[158:159]
	v_pk_mul_f32 v[60:61], v[60:61], s[16:17] op_sel_hi:[1,0]
	v_pk_mul_f32 v[62:63], v[62:63], s[16:17] op_sel_hi:[1,0]
	v_pk_fma_f32 v[52:53], v[52:53], 0.5, v[60:61] op_sel_hi:[1,0,1]
	v_pk_fma_f32 v[50:51], v[50:51], 0.5, v[62:63] op_sel_hi:[1,0,1]
	v_add_f32_e32 v61, v52, v53
	v_add_f32_e32 v60, v50, v51
	v_add_f32_e32 v60, v60, v61
	v_mul_f32_e32 v61, v51, v51
	v_mul_f32_e32 v62, v53, v53
	v_add_f32_e32 v60, v64, v60
	v_fmac_f32_e32 v61, v50, v50
	v_fmac_f32_e32 v62, v52, v52
	v_lshl_add_u64 v[78:79], v[58:59], 0, s[40:41]
	s_nop 0
	s_nop 1
	v_bfe_u32 v85, v227, 4, 2
	v_sub_u32_e32 v84, 0, v85
	v_lshlrev_b32_e32 v84, 4, v84
	v_ashrrev_i32_e32 v85, 31, v84
	v_lshl_add_u64 v[84:85], v[68:69], 0, v[84:85]
	v_permlane16_swap_b32_e32 v54, v50
	v_permlane16_swap_b32_e32 v55, v51
	v_permlane16_swap_b32_e32 v56, v52
	v_permlane16_swap_b32_e32 v57, v53
	v_permlane32_swap_b32_e32 v54, v50
	v_permlane32_swap_b32_e32 v55, v51
	v_permlane32_swap_b32_e32 v56, v52
	v_permlane32_swap_b32_e32 v57, v53
	global_store_dwordx4 v[84:85], v[54:57], off offset:512
	global_store_dwordx4 v[84:85], v[50:53], off offset:576
	s_nop 1
	v_permlane32_swap_b32_e32 v54, v50
	v_permlane32_swap_b32_e32 v55, v51
	v_permlane32_swap_b32_e32 v56, v52
	v_permlane32_swap_b32_e32 v57, v53
	v_permlane16_swap_b32_e32 v54, v50
	v_permlane16_swap_b32_e32 v55, v51
	v_permlane16_swap_b32_e32 v56, v52
	v_permlane16_swap_b32_e32 v57, v53
	v_add_f32_e32 v61, v61, v62
	v_cvt_pk_bf16_f32 v54, v54, v55
	v_cvt_pk_bf16_f32 v55, v56, v57
	v_cvt_pk_bf16_f32 v56, v50, v51
	v_lshl_add_u64 v[50:51], v[78:79], 0, v[0:1]
	v_mov_b32_e32 v0, v60
	v_pk_add_f32 v[70:71], v[70:71], v[70:71] op_sel:[0,1] op_sel_hi:[1,0]
	v_pk_add_f32 v[72:73], v[72:73], v[72:73] op_sel:[0,1] op_sel_hi:[1,0]
	v_add_f32_e32 v61, v65, v61
	v_cvt_pk_bf16_f32 v57, v52, v53
	v_permlane16_swap_b32_e32 v60, v0
	v_mov_b32_e32 v71, v70
	v_mov_b32_e32 v73, v72
	global_store_dwordx4 v[50:51], v[54:57], off
	v_add_f32_e32 v50, v60, v0
	v_mov_b32_e32 v0, v61
	v_permlane16_swap_b32_e32 v70, v71
	v_permlane16_swap_b32_e32 v72, v73
	v_permlane16_swap_b32_e32 v61, v0
	v_add_f32_e32 v71, v70, v71
	v_add_f32_e32 v70, v72, v73
	v_add_f32_e32 v51, v61, v0
	v_mov_b32_e32 v73, v71
	v_mov_b32_e32 v72, v70
	v_mov_b32_e32 v91, v89
	v_mov_b32_e32 v90, v88
	v_mov_b32_e32 v85, v83
	v_mov_b32_e32 v84, v82
	v_mov_b32_e32 v52, v50
	v_mov_b32_e32 v53, v51
	v_permlane32_swap_b32_e32 v71, v73
	v_permlane32_swap_b32_e32 v70, v72
	v_permlane32_swap_b32_e32 v89, v91
	v_permlane32_swap_b32_e32 v88, v90
	v_permlane32_swap_b32_e32 v83, v85
	v_permlane32_swap_b32_e32 v82, v84
	v_permlane32_swap_b32_e32 v50, v52
	v_permlane32_swap_b32_e32 v51, v53
	s_and_saveexec_b64 s[26:27], s[44:45]
	s_cbranch_execz .LBB0_382
	v_pk_add_f32 v[50:51], v[50:51], v[52:53]
	v_lshl_add_u64 v[52:53], s[30:31], 0, v[66:67]
	v_lshl_add_u64 v[52:53], s[24:25], 2, v[52:53]
	global_store_dwordx2 v[52:53], v[50:51], off
; __device__ __forceinline__ size_t blk_off(int r, int c, int K) { return (size_t)(r >> 8) * 256 * K + (size_t)(c >> 6) * (256 * 64) + (size_t)((r & 255) * 64 + (c & 63)); }
; __device__ __forceinline__ u32x4 pack8(const f32x4 a, const f32x4 b) { u32x4 w; w.x = cvt_pk_bf16(a[0], a[1]); w.y = cvt_pk_bf16(a[2], a[3]); w.z = cvt_pk_bf16(b[0], b[1]); w.w = cvt_pk_bf16(b[2], b[3]); return w; }
;     __device__ __forceinline__ void operator()(const f32x4 (&acc)[2][2][4][2], const pg8::Unit& u, int wr, int wc, int fr, int fq) const {
;     ...
;             for (int m = 0; m < 4; ++m) { const int row = row0 + ai * 128 + m * 16; const float mu = mu4[m], rs = rs4[m];
;                 f32x4 yv[2][2], gq[2][2], bq_[2][2];
; #pragma unroll
;                 for (int bj = 0; bj < 2; ++bj)
; #pragma unroll
;                     for (int n = 0; n < 2; ++n) { yv[bj][n] = *(const f32x4*)(Yin + (size_t)row * D_ + col0 + bj * 128 + 4 * n); gq[bj][n] = *(const f32x4*)(g + col0 + bj * 128 + 4 * n); bq_[bj][n] = *(const f32x4*)(b + col0 + bj * 128 + 4 * n); }
;                 asm volatile("" ::: "memory");
;                 float s1 = 0.f, s2 = 0.f;
; #pragma unroll
;                 for (int bj = 0; bj < 2; ++bj) { float* yp = Y + (size_t)row * D_ + col0 + bj * 128; f32x4 v[2];
; #pragma unroll
;                     for (int n = 0; n < 2; ++n) { v[n] = (((yv[bj][n] - mu) * rs) * gq[bj][n] + bq_[bj][n]) * ALPHA_ + acc[ai][bj][m][n] * sc;
;                         *(f32x4*)(yp + 4 * n) = v[n]; s1 += (v[n][0] + v[n][1]) + (v[n][2] + v[n][3]); s2 += (v[n][0] * v[n][0] + v[n][1] * v[n][1]) + (v[n][2] * v[n][2] + v[n][3] * v[n][3]); }
;                     *(u32x4*)(Yb + blk_off(row, col0 + bj * 128, D_)) = pack8(v[0], v[1]); }
.LBB0_382:
	s_or_b64 exec, exec, s[26:27]
	v_pk_add_f32 v[50:51], v[70:71], v[72:73]
	s_mov_b32 s2, 0x3a800000
	v_pk_mul_f32 v[92:93], v[50:51], s[2:3] op_sel_hi:[1,0]
	s_mov_b32 s2, 0x800000
	v_fma_f32 v0, -v93, v93, v92
	v_max_f32_e32 v0, 0, v0
	v_add_f32_e32 v0, 0x3727c5ac, v0
	v_cmp_gt_f32_e32 vcc, s2, v0
	v_mul_f32_e32 v50, 0x4b800000, v0
	v_lshlrev_b64 v[120:121], 12, v[94:95]
	v_cndmask_b32_e32 v0, v0, v50, vcc
	v_rsq_f32_e32 v0, v0
	s_movk_i32 s2, 0x37c0
	s_load_dwordx16 s[60:75], s[34:35], 0x38
	v_mul_f32_e32 v50, 0x45800000, v0
	v_cndmask_b32_e32 v92, v0, v50, vcc
	v_lshl_add_u64 v[50:51], s[12:13], 0, v[120:121]
	v_lshl_add_u64 v[54:55], v[50:51], 0, v[152:153]
	s_nop 1
	v_bfe_u32 v53, v227, 4, 2
	v_sub_u32_e32 v52, 0, v53
	v_lshlrev_b32_e32 v52, 4, v52
	v_ashrrev_i32_e32 v53, 31, v52
	v_lshl_add_u64 v[52:53], v[54:55], 0, v[52:53]
	global_load_dwordx4 v[96:99], v[52:53], off offset:64
	global_load_dwordx4 v[100:103], v[52:53], off
	s_nop 1
	v_lshrrev_b32_e32 v0, 4, v227
	v_lshlrev_b32_e32 v0, 7, v0
	v_add_u32_e32 v0, 0x20100, v0
	ds_read_b128 v[104:107], v0 offset:16
	ds_read_b128 v[108:111], v0 offset:0
	ds_read_b128 v[112:115], v0 offset:80
	ds_read_b128 v[116:119], v0 offset:64
	s_nop 1
	v_bfe_u32 v57, v227, 4, 2
	v_sub_u32_e32 v56, 0, v57
	v_lshlrev_b32_e32 v56, 4, v56
	v_ashrrev_i32_e32 v57, 31, v56
	v_lshl_add_u64 v[56:57], v[54:55], 0, v[56:57]
	global_load_dwordx4 v[50:53], v[56:57], off offset:576
	global_load_dwordx4 v[70:73], v[56:57], off offset:512
	s_nop 0
	ds_read_b128 v[54:57], v0 offset:48
	ds_read_b128 v[62:65], v0 offset:32
	ds_read_b128 v[58:61], v0 offset:112
	ds_read_b128 v[66:69], v0 offset:96
	v_lshlrev_b32_e32 v0, 6, v94
	v_and_or_b32 v0, v0, s2, v194
	s_mov_b32 s2, 0x3fd744fd
	s_waitcnt lgkmcnt(0)
	v_lshl_add_u64 v[94:95], s[74:75], 0, v[120:121]
	v_lshlrev_b32_e32 v0, 1, v0
	v_lshl_add_u64 v[94:95], v[94:95], 0, v[152:153]
	s_waitcnt vmcnt(2)
	v_permlane32_swap_b32_e32 v100, v96
	v_permlane32_swap_b32_e32 v101, v97
	v_permlane32_swap_b32_e32 v102, v98
	v_permlane32_swap_b32_e32 v103, v99
	v_permlane16_swap_b32_e32 v100, v96
	v_permlane16_swap_b32_e32 v101, v97
	v_permlane16_swap_b32_e32 v102, v98
	v_permlane16_swap_b32_e32 v103, v99
	v_sub_f32_e32 v103, v103, v93
	v_sub_f32_e32 v102, v102, v93
	v_sub_f32_e32 v101, v101, v93
	v_sub_f32_e32 v100, v100, v93
	v_pk_mul_f32 v[100:101], v[92:93], v[100:101] op_sel_hi:[0,1]
	v_pk_mul_f32 v[102:103], v[92:93], v[102:103] op_sel_hi:[0,1]
	v_pk_fma_f32 v[102:103], v[110:111], v[102:103], v[118:119]
	v_pk_fma_f32 v[100:101], v[108:109], v[100:101], v[116:117]
	v_pk_mul_f32 v[102:103], v[102:103], s[2:3] op_sel_hi:[1,0]
	v_pk_mul_f32 v[100:101], v[100:101], s[2:3] op_sel_hi:[1,0]
	v_pk_fma_f32 v[102:103], v[48:49], 0.5, v[102:103] op_sel_hi:[1,0,1]
	v_pk_fma_f32 v[100:101], v[46:47], 0.5, v[100:101] op_sel_hi:[1,0,1]
	v_add_f32_e32 v47, v102, v103
	v_add_f32_e32 v46, v100, v101
	v_add_f32_e32 v46, v46, v47
	v_add_f32_e32 v108, 0, v46
	v_mul_f32_e32 v46, v101, v101
	v_mul_f32_e32 v47, v103, v103
	v_fmac_f32_e32 v46, v100, v100
	v_fmac_f32_e32 v47, v102, v102
	v_add_f32_e32 v109, v46, v47
	v_sub_f32_e32 v47, v99, v93
	v_sub_f32_e32 v46, v98, v93
	v_sub_f32_e32 v49, v97, v93
	v_sub_f32_e32 v48, v96, v93
	v_pk_mul_f32 v[48:49], v[92:93], v[48:49] op_sel_hi:[0,1]
	v_pk_mul_f32 v[46:47], v[92:93], v[46:47] op_sel_hi:[0,1]
	v_pk_fma_f32 v[46:47], v[106:107], v[46:47], v[114:115]
	v_pk_fma_f32 v[48:49], v[104:105], v[48:49], v[112:113]
	v_pk_mul_f32 v[46:47], v[46:47], s[2:3] op_sel_hi:[1,0]
	v_pk_mul_f32 v[48:49], v[48:49], s[2:3] op_sel_hi:[1,0]
	v_pk_fma_f32 v[98:99], v[44:45], 0.5, v[46:47] op_sel_hi:[1,0,1]
	v_pk_fma_f32 v[96:97], v[42:43], 0.5, v[48:49] op_sel_hi:[1,0,1]
	v_add_f32_e32 v43, v98, v99
	v_add_f32_e32 v42, v96, v97
	v_add_f32_e32 v42, v42, v43
	v_add_f32_e32 v47, v108, v42
	v_mul_f32_e32 v42, v97, v97
	v_mul_f32_e32 v43, v99, v99
	v_fmac_f32_e32 v42, v96, v96
	v_fmac_f32_e32 v43, v98, v98
	v_add_f32_e32 v42, v42, v43
	v_add_f32_e32 v46, v109, v42
	v_cvt_pk_bf16_f32 v42, v100, v101
	v_cvt_pk_bf16_f32 v43, v102, v103
	v_cvt_pk_bf16_f32 v44, v96, v97
	v_cvt_pk_bf16_f32 v45, v98, v99
	v_lshl_add_u64 v[48:49], v[80:81], 0, v[0:1]
	s_nop 0
	s_nop 1
	v_bfe_u32 v105, v227, 4, 2
	v_sub_u32_e32 v104, 0, v105
	v_lshlrev_b32_e32 v104, 4, v104
	v_ashrrev_i32_e32 v105, 31, v104
	v_lshl_add_u64 v[104:105], v[94:95], 0, v[104:105]
	v_permlane16_swap_b32_e32 v100, v96
	v_permlane16_swap_b32_e32 v101, v97
	v_permlane16_swap_b32_e32 v102, v98
	v_permlane16_swap_b32_e32 v103, v99
	v_permlane32_swap_b32_e32 v100, v96
	v_permlane32_swap_b32_e32 v101, v97
	v_permlane32_swap_b32_e32 v102, v98
	v_permlane32_swap_b32_e32 v103, v99
	global_store_dwordx4 v[104:105], v[100:103], off
	global_store_dwordx4 v[104:105], v[96:99], off offset:64
	s_nop 1
	v_permlane32_swap_b32_e32 v100, v96
	v_permlane32_swap_b32_e32 v101, v97
	v_permlane32_swap_b32_e32 v102, v98
	v_permlane32_swap_b32_e32 v103, v99
	v_permlane16_swap_b32_e32 v100, v96
	v_permlane16_swap_b32_e32 v101, v97
	v_permlane16_swap_b32_e32 v102, v98
	v_permlane16_swap_b32_e32 v103, v99
	global_store_dwordx4 v[48:49], v[42:45], off
	s_nop 0
	s_waitcnt vmcnt(3)
; __device__ __forceinline__ float xsum16(float v) { const auto r = __builtin_amdgcn_permlane16_swap(__float_as_uint(v), __float_as_uint(v), false, false); return __uint_as_float(r[0]) + __uint_as_float(r[1]); }
; __device__ __forceinline__ float xsum32(float v) { const auto r = __builtin_amdgcn_permlane32_swap(__float_as_uint(v), __float_as_uint(v), false, false); return __uint_as_float(r[0]) + __uint_as_float(r[1]); }
; __device__ __forceinline__ size_t blk_off(int r, int c, int K) { return (size_t)(r >> 8) * 256 * K + (size_t)(c >> 6) * (256 * 64) + (size_t)((r & 255) * 64 + (c & 63)); }
; __device__ __forceinline__ u32x4 pack8(const f32x4 a, const f32x4 b) { u32x4 w; w.x = cvt_pk_bf16(a[0], a[1]); w.y = cvt_pk_bf16(a[2], a[3]); w.z = cvt_pk_bf16(b[0], b[1]); w.w = cvt_pk_bf16(b[2], b[3]); return w; }
;     __device__ __forceinline__ void operator()(const f32x4 (&acc)[2][2][4][2], const pg8::Unit& u, int wr, int wc, int fr, int fq) const {
;     ...
;             for (int m = 0; m < 4; ++m) { const int row = row0 + ai * 128 + m * 16; const float mu = mu4[m], rs = rs4[m];
;                 f32x4 yv[2][2], gq[2][2], bq_[2][2];
; #pragma unroll
;                 for (int bj = 0; bj < 2; ++bj)
; #pragma unroll
;                     for (int n = 0; n < 2; ++n) { yv[bj][n] = *(const f32x4*)(Yin + (size_t)row * D_ + col0 + bj * 128 + 4 * n); gq[bj][n] = *(const f32x4*)(g + col0 + bj * 128 + 4 * n); bq_[bj][n] = *(const f32x4*)(b + col0 + bj * 128 + 4 * n); }
;     ...
;                 for (int bj = 0; bj < 2; ++bj) { float* yp = Y + (size_t)row * D_ + col0 + bj * 128; f32x4 v[2];
; #pragma unroll
;                     for (int n = 0; n < 2; ++n) { v[n] = (((yv[bj][n] - mu) * rs) * gq[bj][n] + bq_[bj][n]) * ALPHA_ + acc[ai][bj][m][n] * sc;
;                         *(f32x4*)(yp + 4 * n) = v[n]; s1 += (v[n][0] + v[n][1]) + (v[n][2] + v[n][3]); s2 += (v[n][0] * v[n][0] + v[n][1] * v[n][1]) + (v[n][2] * v[n][2] + v[n][3] * v[n][3]); }
;                     *(u32x4*)(Yb + blk_off(row, col0 + bj * 128, D_)) = pack8(v[0], v[1]); }
;                 s1 = xsum32(xsum16(s1)); s2 = xsum32(xsum16(s2));
;                 if (fq == 0) *(f32x2*)(stn + (size_t)row * 32 + (u.pn * 4 + wc) * 2) = (f32x2){s1, s2}; asm volatile("" ::: "memory"); } }
	v_permlane32_swap_b32_e32 v70, v50
	v_permlane32_swap_b32_e32 v71, v51
	v_permlane32_swap_b32_e32 v72, v52
	v_permlane32_swap_b32_e32 v73, v53
	v_permlane16_swap_b32_e32 v70, v50
	v_permlane16_swap_b32_e32 v71, v51
	v_permlane16_swap_b32_e32 v72, v52
	v_permlane16_swap_b32_e32 v73, v53
	v_sub_f32_e32 v43, v73, v93
	v_sub_f32_e32 v42, v72, v93
	v_sub_f32_e32 v45, v71, v93
	v_sub_f32_e32 v44, v70, v93
	v_pk_mul_f32 v[44:45], v[92:93], v[44:45] op_sel_hi:[0,1]
	v_pk_mul_f32 v[42:43], v[92:93], v[42:43] op_sel_hi:[0,1]
	v_pk_fma_f32 v[42:43], v[64:65], v[42:43], v[68:69]
	v_pk_fma_f32 v[44:45], v[62:63], v[44:45], v[66:67]
	v_pk_mul_f32 v[42:43], v[42:43], s[2:3] op_sel_hi:[1,0]
	v_pk_mul_f32 v[44:45], v[44:45], s[2:3] op_sel_hi:[1,0]
	v_pk_fma_f32 v[40:41], v[40:41], 0.5, v[42:43] op_sel_hi:[1,0,1]
	v_pk_fma_f32 v[38:39], v[38:39], 0.5, v[44:45] op_sel_hi:[1,0,1]
	v_add_f32_e32 v43, v40, v41
	v_add_f32_e32 v42, v38, v39
	v_add_f32_e32 v42, v42, v43
	v_add_f32_e32 v47, v47, v42
	v_mul_f32_e32 v42, v39, v39
	v_mul_f32_e32 v43, v41, v41
	v_fmac_f32_e32 v42, v38, v38
	v_fmac_f32_e32 v43, v40, v40
	v_add_f32_e32 v42, v42, v43
	v_add_f32_e32 v46, v46, v42
	v_sub_f32_e32 v43, v53, v93
	v_sub_f32_e32 v42, v52, v93
	v_sub_f32_e32 v45, v51, v93
	v_sub_f32_e32 v44, v50, v93
	v_pk_mul_f32 v[44:45], v[92:93], v[44:45] op_sel_hi:[0,1]
	v_pk_mul_f32 v[42:43], v[92:93], v[42:43] op_sel_hi:[0,1]
	v_pk_fma_f32 v[42:43], v[56:57], v[42:43], v[60:61]
	v_pk_fma_f32 v[44:45], v[54:55], v[44:45], v[58:59]
	v_pk_mul_f32 v[42:43], v[42:43], s[2:3] op_sel_hi:[1,0]
	v_pk_mul_f32 v[44:45], v[44:45], s[2:3] op_sel_hi:[1,0]
	v_pk_fma_f32 v[36:37], v[36:37], 0.5, v[42:43] op_sel_hi:[1,0,1]
	v_pk_fma_f32 v[34:35], v[34:35], 0.5, v[44:45] op_sel_hi:[1,0,1]
	v_add_f32_e32 v43, v36, v37
	v_add_f32_e32 v42, v34, v35
	v_add_f32_e32 v42, v42, v43
	v_mul_f32_e32 v43, v35, v35
	v_mul_f32_e32 v44, v37, v37
	v_add_f32_e32 v42, v47, v42
	v_fmac_f32_e32 v43, v34, v34
	v_fmac_f32_e32 v44, v36, v36
	s_nop 0
	s_nop 1
	v_bfe_u32 v49, v227, 4, 2
	v_sub_u32_e32 v48, 0, v49
	v_lshlrev_b32_e32 v48, 4, v48
	v_ashrrev_i32_e32 v49, 31, v48
	v_lshl_add_u64 v[48:49], v[94:95], 0, v[48:49]
	v_permlane16_swap_b32_e32 v38, v34
	v_permlane16_swap_b32_e32 v39, v35
	v_permlane16_swap_b32_e32 v40, v36
	v_permlane16_swap_b32_e32 v41, v37
	v_permlane32_swap_b32_e32 v38, v34
	v_permlane32_swap_b32_e32 v39, v35
	v_permlane32_swap_b32_e32 v40, v36
	v_permlane32_swap_b32_e32 v41, v37
	global_store_dwordx4 v[48:49], v[38:41], off offset:512
	global_store_dwordx4 v[48:49], v[34:37], off offset:576
	s_nop 1
	v_permlane32_swap_b32_e32 v38, v34
	v_permlane32_swap_b32_e32 v39, v35
	v_permlane32_swap_b32_e32 v40, v36
	v_permlane32_swap_b32_e32 v41, v37
	v_permlane16_swap_b32_e32 v38, v34
	v_permlane16_swap_b32_e32 v39, v35
	v_permlane16_swap_b32_e32 v40, v36
	v_permlane16_swap_b32_e32 v41, v37
	v_add_f32_e32 v43, v43, v44
	v_cvt_pk_bf16_f32 v38, v38, v39
	v_cvt_pk_bf16_f32 v39, v40, v41
	v_cvt_pk_bf16_f32 v40, v34, v35
	v_lshl_add_u64 v[34:35], v[78:79], 0, v[0:1]
	v_mov_b32_e32 v0, v42
	v_add_f32_e32 v43, v46, v43
	v_cvt_pk_bf16_f32 v41, v36, v37
	v_permlane16_swap_b32_e32 v42, v0
	global_store_dwordx4 v[34:35], v[38:41], off
	v_add_f32_e32 v34, v42, v0
	v_mov_b32_e32 v0, v43
	s_nop 1
	v_permlane16_swap_b32_e32 v43, v0
	v_add_f32_e32 v35, v43, v0
	v_mov_b32_e32 v36, v34
	v_mov_b32_e32 v37, v35
	s_nop 0
	v_permlane32_swap_b32_e32 v34, v36
	v_permlane32_swap_b32_e32 v35, v37
	s_and_saveexec_b64 s[26:27], s[44:45]
	s_cbranch_execz .LBB0_384
	v_pk_add_f32 v[34:35], v[34:35], v[36:37]
	v_lshl_add_u64 v[36:37], s[30:31], 0, v[86:87]
	v_lshl_add_u64 v[36:37], s[24:25], 2, v[36:37]
	global_store_dwordx2 v[36:37], v[34:35], off
.LBB0_384:
	s_or_b64 exec, exec, s[26:27]
	v_pk_add_f32 v[34:35], v[88:89], v[90:91]
	s_mov_b32 s2, 0x3a800000
	v_pk_mul_f32 v[58:59], v[34:35], s[2:3] op_sel_hi:[1,0]
	s_mov_b32 s2, 0x800000
	v_fma_f32 v0, -v59, v59, v58
	v_max_f32_e32 v0, 0, v0
	v_add_f32_e32 v0, 0x3727c5ac, v0
	v_cmp_gt_f32_e32 vcc, s2, v0
	v_mul_f32_e32 v34, 0x4b800000, v0
	v_lshlrev_b64 v[60:61], 12, v[76:77]
	v_cndmask_b32_e32 v0, v0, v34, vcc
	v_rsq_f32_e32 v0, v0
	s_movk_i32 s2, 0x3bc0
	s_load_dwordx16 s[60:75], s[34:35], 0x38
	v_mul_f32_e32 v34, 0x45800000, v0
	v_cndmask_b32_e32 v58, v0, v34, vcc
	v_lshl_add_u64 v[34:35], s[12:13], 0, v[60:61]
	v_lshl_add_u64 v[38:39], v[34:35], 0, v[152:153]
	s_nop 1
	v_bfe_u32 v37, v227, 4, 2
	v_sub_u32_e32 v36, 0, v37
	v_lshlrev_b32_e32 v36, 4, v36
	v_ashrrev_i32_e32 v37, 31, v36
	v_lshl_add_u64 v[36:37], v[38:39], 0, v[36:37]
	global_load_dwordx4 v[62:65], v[36:37], off offset:64
	global_load_dwordx4 v[66:69], v[36:37], off
	s_nop 1
	v_lshrrev_b32_e32 v0, 4, v227
	v_lshlrev_b32_e32 v0, 7, v0
	v_add_u32_e32 v0, 0x20100, v0
	ds_read_b128 v[70:73], v0 offset:16
	ds_read_b128 v[86:89], v0 offset:0
	ds_read_b128 v[90:93], v0 offset:80
	ds_read_b128 v[94:97], v0 offset:64
	s_nop 1
	v_bfe_u32 v41, v227, 4, 2
	v_sub_u32_e32 v40, 0, v41
	v_lshlrev_b32_e32 v40, 4, v40
	v_ashrrev_i32_e32 v41, 31, v40
	v_lshl_add_u64 v[40:41], v[38:39], 0, v[40:41]
	global_load_dwordx4 v[34:37], v[40:41], off offset:576
	global_load_dwordx4 v[54:57], v[40:41], off offset:512
	s_nop 0
	ds_read_b128 v[38:41], v0 offset:48
	ds_read_b128 v[46:49], v0 offset:32
	ds_read_b128 v[42:45], v0 offset:112
	ds_read_b128 v[50:53], v0 offset:96
	v_lshlrev_b32_e32 v0, 6, v76
	v_and_or_b32 v0, v0, s2, v194
	s_mov_b32 s2, 0x3fd744fd
	s_waitcnt lgkmcnt(0)
	v_lshl_add_u64 v[60:61], s[74:75], 0, v[60:61]
	v_lshlrev_b32_e32 v0, 1, v0
	v_lshl_add_u64 v[60:61], v[60:61], 0, v[152:153]
	s_waitcnt vmcnt(2)
; __device__ __forceinline__ float xsum16(float v) { const auto r = __builtin_amdgcn_permlane16_swap(__float_as_uint(v), __float_as_uint(v), false, false); return __uint_as_float(r[0]) + __uint_as_float(r[1]); }
; __device__ __forceinline__ float xsum32(float v) { const auto r = __builtin_amdgcn_permlane32_swap(__float_as_uint(v), __float_as_uint(v), false, false); return __uint_as_float(r[0]) + __uint_as_float(r[1]); }
; __device__ __forceinline__ size_t blk_off(int r, int c, int K) { return (size_t)(r >> 8) * 256 * K + (size_t)(c >> 6) * (256 * 64) + (size_t)((r & 255) * 64 + (c & 63)); }
; __device__ __forceinline__ u32x4 pack8(const f32x4 a, const f32x4 b) { u32x4 w; w.x = cvt_pk_bf16(a[0], a[1]); w.y = cvt_pk_bf16(a[2], a[3]); w.z = cvt_pk_bf16(b[0], b[1]); w.w = cvt_pk_bf16(b[2], b[3]); return w; }
;     __device__ __forceinline__ void operator()(const f32x4 (&acc)[2][2][4][2], const pg8::Unit& u, int wr, int wc, int fr, int fq) const {
;     ...
;                 for (int bj = 0; bj < 2; ++bj) { float* yp = Y + (size_t)row * D_ + col0 + bj * 128; f32x4 v[2];
; #pragma unroll
;                     for (int n = 0; n < 2; ++n) { v[n] = (((yv[bj][n] - mu) * rs) * gq[bj][n] + bq_[bj][n]) * ALPHA_ + acc[ai][bj][m][n] * sc;
;                         *(f32x4*)(yp + 4 * n) = v[n]; s1 += (v[n][0] + v[n][1]) + (v[n][2] + v[n][3]); s2 += (v[n][0] * v[n][0] + v[n][1] * v[n][1]) + (v[n][2] * v[n][2] + v[n][3] * v[n][3]); }
;                     *(u32x4*)(Yb + blk_off(row, col0 + bj * 128, D_)) = pack8(v[0], v[1]); }
;                 s1 = xsum32(xsum16(s1)); s2 = xsum32(xsum16(s2));
;                 if (fq == 0) *(f32x2*)(stn + (size_t)row * 32 + (u.pn * 4 + wc) * 2) = (f32x2){s1, s2}; asm volatile("" ::: "memory"); } }
	v_permlane32_swap_b32_e32 v66, v62
	v_permlane32_swap_b32_e32 v67, v63
	v_permlane32_swap_b32_e32 v68, v64
	v_permlane32_swap_b32_e32 v69, v65
	v_permlane16_swap_b32_e32 v66, v62
	v_permlane16_swap_b32_e32 v67, v63
	v_permlane16_swap_b32_e32 v68, v64
	v_permlane16_swap_b32_e32 v69, v65
	v_sub_f32_e32 v69, v69, v59
	v_sub_f32_e32 v68, v68, v59
	v_sub_f32_e32 v67, v67, v59
	v_sub_f32_e32 v66, v66, v59
	v_pk_mul_f32 v[66:67], v[58:59], v[66:67] op_sel_hi:[0,1]
	v_pk_mul_f32 v[68:69], v[58:59], v[68:69] op_sel_hi:[0,1]
	v_pk_fma_f32 v[68:69], v[88:89], v[68:69], v[96:97]
	v_pk_fma_f32 v[66:67], v[86:87], v[66:67], v[94:95]
	v_pk_mul_f32 v[68:69], v[68:69], s[2:3] op_sel_hi:[1,0]
	v_pk_mul_f32 v[66:67], v[66:67], s[2:3] op_sel_hi:[1,0]
	v_pk_fma_f32 v[68:69], v[32:33], 0.5, v[68:69] op_sel_hi:[1,0,1]
	v_pk_fma_f32 v[66:67], v[30:31], 0.5, v[66:67] op_sel_hi:[1,0,1]
	v_add_f32_e32 v31, v68, v69
	v_add_f32_e32 v30, v66, v67
	v_add_f32_e32 v30, v30, v31
	v_add_f32_e32 v86, 0, v30
	v_mul_f32_e32 v30, v67, v67
	v_mul_f32_e32 v31, v69, v69
	v_fmac_f32_e32 v30, v66, v66
	v_fmac_f32_e32 v31, v68, v68
	v_add_f32_e32 v87, v30, v31
	v_sub_f32_e32 v31, v65, v59
	v_sub_f32_e32 v30, v64, v59
	v_sub_f32_e32 v33, v63, v59
	v_sub_f32_e32 v32, v62, v59
	v_pk_mul_f32 v[32:33], v[58:59], v[32:33] op_sel_hi:[0,1]
	v_pk_mul_f32 v[30:31], v[58:59], v[30:31] op_sel_hi:[0,1]
	v_pk_fma_f32 v[30:31], v[72:73], v[30:31], v[92:93]
	v_pk_fma_f32 v[32:33], v[70:71], v[32:33], v[90:91]
	v_pk_mul_f32 v[30:31], v[30:31], s[2:3] op_sel_hi:[1,0]
	v_pk_mul_f32 v[32:33], v[32:33], s[2:3] op_sel_hi:[1,0]
	v_pk_fma_f32 v[64:65], v[28:29], 0.5, v[30:31] op_sel_hi:[1,0,1]
	v_pk_fma_f32 v[62:63], v[26:27], 0.5, v[32:33] op_sel_hi:[1,0,1]
	v_add_f32_e32 v27, v64, v65
	v_add_f32_e32 v26, v62, v63
	v_add_f32_e32 v26, v26, v27
	v_add_f32_e32 v31, v86, v26
	v_mul_f32_e32 v26, v63, v63
	v_mul_f32_e32 v27, v65, v65
	v_fmac_f32_e32 v26, v62, v62
	v_fmac_f32_e32 v27, v64, v64
	v_add_f32_e32 v26, v26, v27
	v_add_f32_e32 v30, v87, v26
	v_cvt_pk_bf16_f32 v26, v66, v67
	v_cvt_pk_bf16_f32 v27, v68, v69
	v_cvt_pk_bf16_f32 v28, v62, v63
	v_cvt_pk_bf16_f32 v29, v64, v65
	v_lshl_add_u64 v[32:33], v[80:81], 0, v[0:1]
	s_nop 0
	s_nop 1
	v_bfe_u32 v71, v227, 4, 2
	v_sub_u32_e32 v70, 0, v71
	v_lshlrev_b32_e32 v70, 4, v70
	v_ashrrev_i32_e32 v71, 31, v70
	v_lshl_add_u64 v[70:71], v[60:61], 0, v[70:71]
	v_permlane16_swap_b32_e32 v66, v62
	v_permlane16_swap_b32_e32 v67, v63
	v_permlane16_swap_b32_e32 v68, v64
	v_permlane16_swap_b32_e32 v69, v65
	v_permlane32_swap_b32_e32 v66, v62
	v_permlane32_swap_b32_e32 v67, v63
	v_permlane32_swap_b32_e32 v68, v64
	v_permlane32_swap_b32_e32 v69, v65
	global_store_dwordx4 v[70:71], v[66:69], off
	global_store_dwordx4 v[70:71], v[62:65], off offset:64
	s_nop 1
	v_permlane32_swap_b32_e32 v66, v62
	v_permlane32_swap_b32_e32 v67, v63
	v_permlane32_swap_b32_e32 v68, v64
	v_permlane32_swap_b32_e32 v69, v65
	v_permlane16_swap_b32_e32 v66, v62
	v_permlane16_swap_b32_e32 v67, v63
	v_permlane16_swap_b32_e32 v68, v64
	v_permlane16_swap_b32_e32 v69, v65
	global_store_dwordx4 v[32:33], v[26:29], off
	s_nop 0
	s_waitcnt vmcnt(3)
	v_permlane32_swap_b32_e32 v54, v34
	v_permlane32_swap_b32_e32 v55, v35
	v_permlane32_swap_b32_e32 v56, v36
	v_permlane32_swap_b32_e32 v57, v37
	v_permlane16_swap_b32_e32 v54, v34
	v_permlane16_swap_b32_e32 v55, v35
	v_permlane16_swap_b32_e32 v56, v36
	v_permlane16_swap_b32_e32 v57, v37
	v_sub_f32_e32 v27, v57, v59
	v_sub_f32_e32 v26, v56, v59
	v_sub_f32_e32 v29, v55, v59
	v_sub_f32_e32 v28, v54, v59
	v_pk_mul_f32 v[28:29], v[58:59], v[28:29] op_sel_hi:[0,1]
	v_pk_mul_f32 v[26:27], v[58:59], v[26:27] op_sel_hi:[0,1]
	v_pk_fma_f32 v[26:27], v[48:49], v[26:27], v[52:53]
	v_pk_fma_f32 v[28:29], v[46:47], v[28:29], v[50:51]
	v_pk_mul_f32 v[26:27], v[26:27], s[2:3] op_sel_hi:[1,0]
	v_pk_mul_f32 v[28:29], v[28:29], s[2:3] op_sel_hi:[1,0]
	v_pk_fma_f32 v[24:25], v[24:25], 0.5, v[26:27] op_sel_hi:[1,0,1]
	v_pk_fma_f32 v[22:23], v[22:23], 0.5, v[28:29] op_sel_hi:[1,0,1]
	v_add_f32_e32 v27, v24, v25
	v_add_f32_e32 v26, v22, v23
	v_add_f32_e32 v26, v26, v27
	v_add_f32_e32 v31, v31, v26
	v_mul_f32_e32 v26, v23, v23
	v_mul_f32_e32 v27, v25, v25
	v_fmac_f32_e32 v26, v22, v22
	v_fmac_f32_e32 v27, v24, v24
	v_add_f32_e32 v26, v26, v27
	v_add_f32_e32 v30, v30, v26
	v_sub_f32_e32 v27, v37, v59
	v_sub_f32_e32 v26, v36, v59
	v_sub_f32_e32 v29, v35, v59
	v_sub_f32_e32 v28, v34, v59
	v_pk_mul_f32 v[28:29], v[58:59], v[28:29] op_sel_hi:[0,1]
	v_pk_mul_f32 v[26:27], v[58:59], v[26:27] op_sel_hi:[0,1]
	v_pk_fma_f32 v[26:27], v[40:41], v[26:27], v[44:45]
	v_pk_fma_f32 v[28:29], v[38:39], v[28:29], v[42:43]
	v_pk_mul_f32 v[26:27], v[26:27], s[2:3] op_sel_hi:[1,0]
	v_pk_mul_f32 v[28:29], v[28:29], s[2:3] op_sel_hi:[1,0]
	v_pk_fma_f32 v[20:21], v[20:21], 0.5, v[26:27] op_sel_hi:[1,0,1]
	v_pk_fma_f32 v[18:19], v[18:19], 0.5, v[28:29] op_sel_hi:[1,0,1]
	v_add_f32_e32 v27, v20, v21
	v_add_f32_e32 v26, v18, v19
	v_add_f32_e32 v26, v26, v27
	v_mul_f32_e32 v27, v19, v19
	v_mul_f32_e32 v28, v21, v21
	v_add_f32_e32 v26, v31, v26
	v_fmac_f32_e32 v27, v18, v18
	v_fmac_f32_e32 v28, v20, v20
	s_nop 0
	s_nop 1
	v_bfe_u32 v33, v227, 4, 2
	v_sub_u32_e32 v32, 0, v33
	v_lshlrev_b32_e32 v32, 4, v32
	v_ashrrev_i32_e32 v33, 31, v32
	v_lshl_add_u64 v[32:33], v[60:61], 0, v[32:33]
	v_permlane16_swap_b32_e32 v22, v18
	v_permlane16_swap_b32_e32 v23, v19
	v_permlane16_swap_b32_e32 v24, v20
	v_permlane16_swap_b32_e32 v25, v21
	v_permlane32_swap_b32_e32 v22, v18
	v_permlane32_swap_b32_e32 v23, v19
	v_permlane32_swap_b32_e32 v24, v20
	v_permlane32_swap_b32_e32 v25, v21
	global_store_dwordx4 v[32:33], v[22:25], off offset:512
	global_store_dwordx4 v[32:33], v[18:21], off offset:576
	s_nop 1
	v_permlane32_swap_b32_e32 v22, v18
	v_permlane32_swap_b32_e32 v23, v19
	v_permlane32_swap_b32_e32 v24, v20
	v_permlane32_swap_b32_e32 v25, v21
	v_permlane16_swap_b32_e32 v22, v18
	v_permlane16_swap_b32_e32 v23, v19
	v_permlane16_swap_b32_e32 v24, v20
	v_permlane16_swap_b32_e32 v25, v21
	v_add_f32_e32 v27, v27, v28
	v_cvt_pk_bf16_f32 v22, v22, v23
	v_cvt_pk_bf16_f32 v23, v24, v25
	v_cvt_pk_bf16_f32 v24, v18, v19
	v_lshl_add_u64 v[18:19], v[78:79], 0, v[0:1]
	v_mov_b32_e32 v0, v26
	v_add_f32_e32 v27, v30, v27
	v_cvt_pk_bf16_f32 v25, v20, v21
	v_permlane16_swap_b32_e32 v26, v0
	global_store_dwordx4 v[18:19], v[22:25], off
	v_add_f32_e32 v18, v26, v0
	v_mov_b32_e32 v0, v27
	s_nop 1
	v_permlane16_swap_b32_e32 v27, v0
	v_add_f32_e32 v19, v27, v0
	v_mov_b32_e32 v20, v18
	v_mov_b32_e32 v21, v19
	s_nop 0
	v_permlane32_swap_b32_e32 v18, v20
	v_permlane32_swap_b32_e32 v19, v21
	s_and_saveexec_b64 s[26:27], s[44:45]
	s_cbranch_execz .LBB0_386
	v_pk_add_f32 v[18:19], v[18:19], v[20:21]
	v_lshlrev_b64 v[20:21], 7, v[76:77]
	v_lshl_add_u64 v[20:21], s[30:31], 0, v[20:21]
	v_lshl_add_u64 v[20:21], s[24:25], 2, v[20:21]
	global_store_dwordx2 v[20:21], v[18:19], off
; __device__ __forceinline__ size_t blk_off(int r, int c, int K) { return (size_t)(r >> 8) * 256 * K + (size_t)(c >> 6) * (256 * 64) + (size_t)((r & 255) * 64 + (c & 63)); }
; __device__ __forceinline__ u32x4 pack8(const f32x4 a, const f32x4 b) { u32x4 w; w.x = cvt_pk_bf16(a[0], a[1]); w.y = cvt_pk_bf16(a[2], a[3]); w.z = cvt_pk_bf16(b[0], b[1]); w.w = cvt_pk_bf16(b[2], b[3]); return w; }
;     __device__ __forceinline__ void operator()(const f32x4 (&acc)[2][2][4][2], const pg8::Unit& u, int wr, int wc, int fr, int fq) const {
;     ...
;             for (int m = 0; m < 4; ++m) { const int row = row0 + ai * 128 + m * 16; const float mu = mu4[m], rs = rs4[m];
;                 f32x4 yv[2][2], gq[2][2], bq_[2][2];
; #pragma unroll
;                 for (int bj = 0; bj < 2; ++bj)
; #pragma unroll
;                     for (int n = 0; n < 2; ++n) { yv[bj][n] = *(const f32x4*)(Yin + (size_t)row * D_ + col0 + bj * 128 + 4 * n); gq[bj][n] = *(const f32x4*)(g + col0 + bj * 128 + 4 * n); bq_[bj][n] = *(const f32x4*)(b + col0 + bj * 128 + 4 * n); }
;                 asm volatile("" ::: "memory");
;                 float s1 = 0.f, s2 = 0.f;
; #pragma unroll
;                 for (int bj = 0; bj < 2; ++bj) { float* yp = Y + (size_t)row * D_ + col0 + bj * 128; f32x4 v[2];
; #pragma unroll
;                     for (int n = 0; n < 2; ++n) { v[n] = (((yv[bj][n] - mu) * rs) * gq[bj][n] + bq_[bj][n]) * ALPHA_ + acc[ai][bj][m][n] * sc;
;                         *(f32x4*)(yp + 4 * n) = v[n]; s1 += (v[n][0] + v[n][1]) + (v[n][2] + v[n][3]); s2 += (v[n][0] * v[n][0] + v[n][1] * v[n][1]) + (v[n][2] * v[n][2] + v[n][3] * v[n][3]); }
;                     *(u32x4*)(Yb + blk_off(row, col0 + bj * 128, D_)) = pack8(v[0], v[1]); }
.LBB0_386:
	s_or_b64 exec, exec, s[26:27]
	v_lshlrev_b64 v[26:27], 12, v[74:75]
	v_lshl_add_u64 v[18:19], s[12:13], 0, v[26:27]
	v_lshl_add_u64 v[28:29], v[18:19], 0, v[152:153]
	s_nop 1
	v_bfe_u32 v21, v227, 4, 2
	v_sub_u32_e32 v20, 0, v21
	v_lshlrev_b32_e32 v20, 4, v20
	v_ashrrev_i32_e32 v21, 31, v20
	v_lshl_add_u64 v[20:21], v[28:29], 0, v[20:21]
	global_load_dwordx4 v[34:37], v[20:21], off
	global_load_dwordx4 v[38:41], v[20:21], off offset:64
	global_load_dwordx4 v[42:45], v[28:29], off offset:512
	s_nop 1
	v_lshrrev_b32_e32 v0, 4, v227
	v_lshlrev_b32_e32 v0, 7, v0
	v_add_u32_e32 v0, 0x20100, v0
	ds_read_b128 v[46:49], v0 offset:64
	ds_read_b128 v[50:53], v0 offset:0
	ds_read_b128 v[54:57], v0 offset:16
	ds_read_b128 v[58:61], v0 offset:80
	ds_read_b128 v[62:65], v0 offset:32
	ds_read_b128 v[66:69], v0 offset:96
	s_load_dwordx16 s[60:75], s[34:35], 0x38
	v_pk_add_f32 v[18:19], v[82:83], v[84:85]
	s_mov_b32 s2, 0x3a800000
	v_pk_mul_f32 v[32:33], v[18:19], s[2:3] op_sel_hi:[1,0]
	ds_read_b128 v[18:21], v0 offset:48
	ds_read_b128 v[22:25], v0 offset:112
	s_waitcnt lgkmcnt(0)
	v_lshl_add_u64 v[26:27], s[74:75], 0, v[26:27]
	v_lshl_add_u64 v[30:31], v[26:27], 0, v[152:153]
	global_load_dwordx4 v[26:29], v[28:29], off offset:528
	v_fma_f32 v32, -v33, v33, v32
	v_lshlrev_b32_e32 v0, 6, v74
	s_movk_i32 s2, 0x3fc0
	v_max_f32_e32 v32, 0, v32
	v_and_or_b32 v0, v0, s2, v194
	v_add_f32_e32 v32, 0x3727c5ac, v32
	s_mov_b32 s2, 0x800000
	v_mul_f32_e32 v70, 0x4b800000, v32
	v_cmp_gt_f32_e32 vcc, s2, v32
	s_mov_b32 s2, 0x3fd744fd
	v_lshlrev_b32_e32 v0, 1, v0
	v_cndmask_b32_e32 v32, v32, v70, vcc
	v_rsq_f32_e32 v32, v32
	v_lshl_add_u64 v[70:71], v[80:81], 0, v[0:1]
	v_mul_f32_e32 v72, 0x45800000, v32
	v_cndmask_b32_e32 v32, v32, v72, vcc
	s_waitcnt vmcnt(2)
	v_permlane32_swap_b32_e32 v34, v38
	v_permlane32_swap_b32_e32 v35, v39
	v_permlane32_swap_b32_e32 v36, v40
	v_permlane32_swap_b32_e32 v37, v41
	v_permlane16_swap_b32_e32 v34, v38
	v_permlane16_swap_b32_e32 v35, v39
	v_permlane16_swap_b32_e32 v36, v40
	v_permlane16_swap_b32_e32 v37, v41
	v_sub_f32_e32 v37, v37, v33
	v_sub_f32_e32 v36, v36, v33
	v_sub_f32_e32 v35, v35, v33
	v_sub_f32_e32 v34, v34, v33
	v_sub_f32_e32 v41, v41, v33
	v_sub_f32_e32 v40, v40, v33
	v_sub_f32_e32 v39, v39, v33
	v_sub_f32_e32 v38, v38, v33
	v_pk_mul_f32 v[34:35], v[32:33], v[34:35] op_sel_hi:[0,1]
	v_pk_mul_f32 v[36:37], v[32:33], v[36:37] op_sel_hi:[0,1]
	v_pk_mul_f32 v[38:39], v[32:33], v[38:39] op_sel_hi:[0,1]
	v_pk_mul_f32 v[40:41], v[32:33], v[40:41] op_sel_hi:[0,1]
	v_pk_fma_f32 v[36:37], v[52:53], v[36:37], v[48:49]
	v_pk_fma_f32 v[34:35], v[50:51], v[34:35], v[46:47]
	v_pk_fma_f32 v[40:41], v[56:57], v[40:41], v[60:61]
	v_pk_fma_f32 v[38:39], v[54:55], v[38:39], v[58:59]
	v_pk_mul_f32 v[34:35], v[34:35], s[2:3] op_sel_hi:[1,0]
	v_pk_mul_f32 v[36:37], v[36:37], s[2:3] op_sel_hi:[1,0]
	v_pk_mul_f32 v[38:39], v[38:39], s[2:3] op_sel_hi:[1,0]
	v_pk_mul_f32 v[40:41], v[40:41], s[2:3] op_sel_hi:[1,0]
	v_pk_fma_f32 v[16:17], v[16:17], 0.5, v[36:37] op_sel_hi:[1,0,1]
	v_pk_fma_f32 v[14:15], v[14:15], 0.5, v[34:35] op_sel_hi:[1,0,1]
	v_pk_fma_f32 v[12:13], v[12:13], 0.5, v[40:41] op_sel_hi:[1,0,1]
	v_pk_fma_f32 v[10:11], v[10:11], 0.5, v[38:39] op_sel_hi:[1,0,1]
	s_waitcnt vmcnt(1)
; __device__ __forceinline__ float xsum16(float v) { const auto r = __builtin_amdgcn_permlane16_swap(__float_as_uint(v), __float_as_uint(v), false, false); return __uint_as_float(r[0]) + __uint_as_float(r[1]); }
; __device__ __forceinline__ float xsum32(float v) { const auto r = __builtin_amdgcn_permlane32_swap(__float_as_uint(v), __float_as_uint(v), false, false); return __uint_as_float(r[0]) + __uint_as_float(r[1]); }
; __device__ __forceinline__ size_t blk_off(int r, int c, int K) { return (size_t)(r >> 8) * 256 * K + (size_t)(c >> 6) * (256 * 64) + (size_t)((r & 255) * 64 + (c & 63)); }
; __device__ __forceinline__ u32x4 pack8(const f32x4 a, const f32x4 b) { u32x4 w; w.x = cvt_pk_bf16(a[0], a[1]); w.y = cvt_pk_bf16(a[2], a[3]); w.z = cvt_pk_bf16(b[0], b[1]); w.w = cvt_pk_bf16(b[2], b[3]); return w; }
;     __device__ __forceinline__ void operator()(const f32x4 (&acc)[2][2][4][2], const pg8::Unit& u, int wr, int wc, int fr, int fq) const {
;     ...
;                 for (int bj = 0; bj < 2; ++bj) { float* yp = Y + (size_t)row * D_ + col0 + bj * 128; f32x4 v[2];
; #pragma unroll
;                     for (int n = 0; n < 2; ++n) { v[n] = (((yv[bj][n] - mu) * rs) * gq[bj][n] + bq_[bj][n]) * ALPHA_ + acc[ai][bj][m][n] * sc;
;                         *(f32x4*)(yp + 4 * n) = v[n]; s1 += (v[n][0] + v[n][1]) + (v[n][2] + v[n][3]); s2 += (v[n][0] * v[n][0] + v[n][1] * v[n][1]) + (v[n][2] * v[n][2] + v[n][3] * v[n][3]); }
;                     *(u32x4*)(Yb + blk_off(row, col0 + bj * 128, D_)) = pack8(v[0], v[1]); }
;                 s1 = xsum32(xsum16(s1)); s2 = xsum32(xsum16(s2));
;                 if (fq == 0) *(f32x2*)(stn + (size_t)row * 32 + (u.pn * 4 + wc) * 2) = (f32x2){s1, s2}; asm volatile("" ::: "memory"); } }
	v_sub_f32_e32 v45, v45, v33
	v_sub_f32_e32 v44, v44, v33
	v_sub_f32_e32 v43, v43, v33
	v_sub_f32_e32 v42, v42, v33
	v_add_f32_e32 v38, v14, v15
	v_add_f32_e32 v39, v16, v17
	v_mul_f32_e32 v40, v15, v15
	v_mul_f32_e32 v41, v17, v17
	v_mul_f32_e32 v48, v11, v11
	v_mul_f32_e32 v49, v13, v13
	v_pk_mul_f32 v[42:43], v[32:33], v[42:43] op_sel_hi:[0,1]
	v_pk_mul_f32 v[44:45], v[32:33], v[44:45] op_sel_hi:[0,1]
	global_store_dwordx4 v[30:31], v[10:13], off offset:16
	v_add_f32_e32 v46, v10, v11
	v_add_f32_e32 v47, v12, v13
	v_cvt_pk_bf16_f32 v36, v10, v11
	v_add_f32_e32 v11, v38, v39
	v_fmac_f32_e32 v40, v14, v14
	v_fmac_f32_e32 v41, v16, v16
	v_fmac_f32_e32 v48, v10, v10
	v_fmac_f32_e32 v49, v12, v12
	v_pk_fma_f32 v[44:45], v[64:65], v[44:45], v[68:69]
	v_pk_fma_f32 v[42:43], v[62:63], v[42:43], v[66:67]
	v_cvt_pk_bf16_f32 v37, v12, v13
	v_add_f32_e32 v13, v46, v47
	v_add_f32_e32 v10, 0, v11
	v_add_f32_e32 v11, v40, v41
	v_add_f32_e32 v12, v48, v49
	global_store_dwordx4 v[30:31], v[14:17], off
	v_cvt_pk_bf16_f32 v34, v14, v15
	v_cvt_pk_bf16_f32 v35, v16, v17
	v_add_f32_e32 v14, v10, v13
	v_add_f32_e32 v15, v11, v12
	v_pk_mul_f32 v[10:11], v[42:43], s[2:3] op_sel_hi:[1,0]
	v_pk_mul_f32 v[12:13], v[44:45], s[2:3] op_sel_hi:[1,0]
	v_pk_fma_f32 v[6:7], v[6:7], 0.5, v[10:11] op_sel_hi:[1,0,1]
	v_pk_fma_f32 v[8:9], v[8:9], 0.5, v[12:13] op_sel_hi:[1,0,1]
	v_add_f32_e32 v10, v6, v7
	v_add_f32_e32 v11, v8, v9
	v_add_f32_e32 v10, v10, v11
	v_add_f32_e32 v14, v14, v10
	v_mul_f32_e32 v10, v7, v7
	v_mul_f32_e32 v11, v9, v9
	v_fmac_f32_e32 v10, v6, v6
	v_fmac_f32_e32 v11, v8, v8
	v_add_f32_e32 v10, v10, v11
	v_add_f32_e32 v15, v15, v10
	s_waitcnt vmcnt(2)
	v_sub_f32_e32 v11, v29, v33
	v_sub_f32_e32 v10, v28, v33
	v_sub_f32_e32 v13, v27, v33
	v_sub_f32_e32 v12, v26, v33
	v_pk_mul_f32 v[12:13], v[32:33], v[12:13] op_sel_hi:[0,1]
	v_pk_mul_f32 v[10:11], v[32:33], v[10:11] op_sel_hi:[0,1]
	v_pk_fma_f32 v[10:11], v[20:21], v[10:11], v[24:25]
	v_pk_fma_f32 v[12:13], v[18:19], v[12:13], v[22:23]
	v_pk_mul_f32 v[10:11], v[10:11], s[2:3] op_sel_hi:[1,0]
	v_pk_mul_f32 v[12:13], v[12:13], s[2:3] op_sel_hi:[1,0]
	v_pk_fma_f32 v[4:5], v[4:5], 0.5, v[10:11] op_sel_hi:[1,0,1]
	v_pk_fma_f32 v[2:3], v[2:3], 0.5, v[12:13] op_sel_hi:[1,0,1]
	v_add_f32_e32 v11, v4, v5
	v_add_f32_e32 v10, v2, v3
	v_add_f32_e32 v10, v10, v11
	v_mul_f32_e32 v11, v3, v3
	v_mul_f32_e32 v12, v5, v5
	v_add_f32_e32 v10, v14, v10
	v_fmac_f32_e32 v11, v2, v2
	v_fmac_f32_e32 v12, v4, v4
	global_store_dwordx4 v[70:71], v[34:37], off
	s_nop 0
	s_nop 1
	v_bfe_u32 v17, v227, 4, 2
	v_sub_u32_e32 v16, 0, v17
	v_lshlrev_b32_e32 v16, 4, v16
	v_ashrrev_i32_e32 v17, 31, v16
	v_lshl_add_u64 v[16:17], v[30:31], 0, v[16:17]
	v_permlane16_swap_b32_e32 v6, v2
	v_permlane16_swap_b32_e32 v7, v3
	v_permlane16_swap_b32_e32 v8, v4
	v_permlane16_swap_b32_e32 v9, v5
	v_permlane32_swap_b32_e32 v6, v2
	v_permlane32_swap_b32_e32 v7, v3
	v_permlane32_swap_b32_e32 v8, v4
	v_permlane32_swap_b32_e32 v9, v5
	global_store_dwordx4 v[16:17], v[6:9], off offset:512
	global_store_dwordx4 v[16:17], v[2:5], off offset:576
	s_nop 1
	v_permlane32_swap_b32_e32 v6, v2
	v_permlane32_swap_b32_e32 v7, v3
	v_permlane32_swap_b32_e32 v8, v4
	v_permlane32_swap_b32_e32 v9, v5
	v_permlane16_swap_b32_e32 v6, v2
	v_permlane16_swap_b32_e32 v7, v3
	v_permlane16_swap_b32_e32 v8, v4
	v_permlane16_swap_b32_e32 v9, v5
	v_add_f32_e32 v11, v11, v12
	v_cvt_pk_bf16_f32 v6, v6, v7
	v_cvt_pk_bf16_f32 v7, v8, v9
	v_cvt_pk_bf16_f32 v8, v2, v3
	v_lshl_add_u64 v[2:3], v[78:79], 0, v[0:1]
	v_mov_b32_e32 v0, v10
	v_add_f32_e32 v11, v15, v11
	v_cvt_pk_bf16_f32 v9, v4, v5
	v_permlane16_swap_b32_e32 v10, v0
	global_store_dwordx4 v[2:3], v[6:9], off
	v_add_f32_e32 v2, v10, v0
	v_mov_b32_e32 v0, v11
	s_nop 1
	v_permlane16_swap_b32_e32 v11, v0
	v_add_f32_e32 v3, v11, v0
	v_mov_b32_e32 v4, v2
	v_mov_b32_e32 v5, v3
	s_nop 0
	v_permlane32_swap_b32_e32 v2, v4
	v_permlane32_swap_b32_e32 v3, v5
	s_and_saveexec_b64 s[26:27], s[44:45]
	s_cbranch_execz .LBB0_388
	v_pk_add_f32 v[2:3], v[2:3], v[4:5]
	v_lshlrev_b64 v[4:5], 7, v[74:75]
	v_lshl_add_u64 v[4:5], s[30:31], 0, v[4:5]
	v_lshl_add_u64 v[4:5], s[24:25], 2, v[4:5]
	global_store_dwordx2 v[4:5], v[2:3], off

; __device__ __forceinline__ float xsum16(float v) { const auto r = __builtin_amdgcn_permlane16_swap(__float_as_uint(v), __float_as_uint(v), false, false); return __uint_as_float(r[0]) + __uint_as_float(r[1]); }
; __device__ __forceinline__ float xsum32(float v) { const auto r = __builtin_amdgcn_permlane32_swap(__float_as_uint(v), __float_as_uint(v), false, false); return __uint_as_float(r[0]) + __uint_as_float(r[1]); }
; __device__ __forceinline__ void row_stats4(const float* st, int rowb, int fq, float (&mu)[4], float (&rs)[4]) {
;     f32x4 a[4], b[4];
; #pragma unroll
;     for (int m = 0; m < 4; ++m) { const f32x4* p = (const f32x4*)(st + (size_t)(rowb + m * 16) * 32 + fq * 8); a[m] = p[0]; b[m] = p[1]; }
; #pragma unroll
;     for (int m = 0; m < 4; ++m) { float s1 = (a[m][0] + a[m][2]) + (b[m][0] + b[m][2]), s2 = (a[m][1] + a[m][3]) + (b[m][1] + b[m][3]);
;         s1 = xsum32(xsum16(s1)); s2 = xsum32(xsum16(s2));
;         const float mm = s1 * (1.0f / 1024.0f); mu[m] = mm; rs[m] = rsqrtf(fmaxf(s2 * (1.0f / 1024.0f) - mm * mm, 0.f) + LN_EPS_); }
;     __device__ __forceinline__ void operator()(const f32x4 (&acc)[2][2][4][2], const pg8::Unit& u, int wr, int wc, int fr, int fq) const {
;     ...
;             for (int m = 0; m < 4; ++m) { const int row = row0 + ai * 128 + m * 16; const float mu = mu4[m], rs = rs4[m];
;                 f32x4 yv[2][2], gq[2][2], bq_[2][2];
; #pragma unroll
;                 for (int bj = 0; bj < 2; ++bj)
; #pragma unroll
;                     for (int n = 0; n < 2; ++n) { yv[bj][n] = *(const f32x4*)(Yin + (size_t)row * D_ + col0 + bj * 128 + 4 * n); gq[bj][n] = *(const f32x4*)(g + col0 + bj * 128 + 4 * n); bq_[bj][n] = *(const f32x4*)(b + col0 + bj * 128 + 4 * n); }
;                 asm volatile("" ::: "memory");
.LBB0_1535:
	s_lshl_b32 s3, s3, 8
	s_add_i32 s3, s3, s0
	v_or_b32_e32 v158, s3, v184
	v_ashrrev_i32_e32 v159, 31, v158
	v_lshlrev_b64 v[130:131], 7, v[158:159]
	v_lshl_add_u64 v[136:137], v[146:147], 0, v[130:131]
	v_or_b32_e32 v180, 16, v158
	s_nop 1
	v_bfe_u32 v153, v227, 4, 2
	v_sub_u32_e32 v152, 0, v153
	v_lshlrev_b32_e32 v152, 4, v152
	v_ashrrev_i32_e32 v153, 31, v152
	v_lshl_add_u64 v[152:153], v[136:137], 0, v[152:153]
	global_load_dwordx4 v[132:135], v[152:153], off
	global_load_dwordx4 v[166:169], v[152:153], off offset:64
	v_ashrrev_i32_e32 v181, 31, v180
	v_lshlrev_b64 v[172:173], 7, v[180:181]
	v_lshl_add_u64 v[136:137], v[146:147], 0, v[172:173]
	s_nop 1
	v_bfe_u32 v153, v227, 4, 2
	v_sub_u32_e32 v152, 0, v153
	v_lshlrev_b32_e32 v152, 4, v152
	v_ashrrev_i32_e32 v153, 31, v152
	v_lshl_add_u64 v[152:153], v[136:137], 0, v[152:153]
	global_load_dwordx4 v[174:177], v[152:153], off
	global_load_dwordx4 v[186:189], v[152:153], off offset:64
	v_or_b32_e32 v170, 32, v158
	v_ashrrev_i32_e32 v171, 31, v170
	v_lshlrev_b64 v[164:165], 7, v[170:171]
	v_lshl_add_u64 v[136:137], v[146:147], 0, v[164:165]
	s_nop 1
	v_bfe_u32 v153, v227, 4, 2
	v_sub_u32_e32 v152, 0, v153
	v_lshlrev_b32_e32 v152, 4, v152
	v_ashrrev_i32_e32 v153, 31, v152
	v_lshl_add_u64 v[152:153], v[136:137], 0, v[152:153]
	global_load_dwordx4 v[190:193], v[152:153], off
	global_load_dwordx4 v[198:201], v[152:153], off offset:64
	v_or_b32_e32 v162, 48, v158
	v_ashrrev_i32_e32 v163, 31, v162
	v_lshlrev_b64 v[160:161], 7, v[162:163]
	v_lshl_add_u64 v[182:183], v[146:147], 0, v[160:161]
	s_nop 1
	v_bfe_u32 v137, v227, 4, 2
	v_sub_u32_e32 v136, 0, v137
	v_lshlrev_b32_e32 v136, 4, v136
	v_ashrrev_i32_e32 v137, 31, v136
	v_lshl_add_u64 v[136:137], v[182:183], 0, v[136:137]
	global_load_dwordx4 v[202:205], v[136:137], off
	global_load_dwordx4 v[206:209], v[136:137], off offset:64
	s_load_dwordx16 s[64:79], s[34:35], 0x38
	s_lshl_b32 s1, s2, 8
	s_lshl_b32 s14, s2, 3
	s_or_b32 s2, s1, s57
	v_or_b32_e32 v152, s2, v185
	v_ashrrev_i32_e32 v153, 31, v152
	v_lshlrev_b64 v[136:137], 12, v[158:159]
	v_lshlrev_b64 v[178:179], 2, v[152:153]
	s_waitcnt lgkmcnt(0)
	v_lshl_add_u64 v[136:137], s[78:79], 0, v[136:137]
	v_lshl_add_u64 v[156:157], s[8:9], 0, v[178:179]
	v_lshl_add_u64 v[154:155], s[10:11], 0, v[178:179]
	v_lshl_add_u64 v[136:137], v[136:137], 0, v[178:179]
	s_or_b32 s52, s14, s61
	s_mov_b32 s14, 0x3a800000
	s_nop 1
	v_bfe_u32 v179, v227, 4, 2
	v_sub_u32_e32 v178, 0, v179
	v_lshlrev_b32_e32 v178, 4, v178
	v_ashrrev_i32_e32 v179, 31, v178
	v_lshl_add_u64 v[178:179], v[136:137], 0, v[178:179]
	global_load_dwordx4 v[210:213], v[178:179], off offset:64
	global_load_dwordx4 v[214:217], v[178:179], off
	global_load_dwordx4 v[218:221], v[156:157], off offset:16
	global_load_dwordx4 v[222:225], v[156:157], off
	global_load_dwordx4 v[234:237], v[154:155], off offset:16
	global_load_dwordx4 v[238:241], v[154:155], off
	s_mov_b32 s1, 0x800000
	s_mov_b32 s18, 0x3fd744fd
	v_bitop3_b32 v196, s2, 56, v185 bitop3:0xc8
	s_ashr_i32 s2, s2, 6
	s_ashr_i32 s53, s52, 31
	v_readlane_b32 s16, v253, 59
	v_readlane_b32 s17, v253, 60
	s_nop 1
	v_lshrrev_b32_e32 v0, 4, v227
	v_lshlrev_b32_e32 v0, 7, v0
	v_add_u32_e32 v0, 0x20100, v0
	s_waitcnt vmcnt(3)
	ds_write_b128 v0, v[218:221] offset:16
	s_waitcnt vmcnt(2)
	ds_write_b128 v0, v[222:225] offset:0
	s_waitcnt vmcnt(1)
	ds_write_b128 v0, v[234:237] offset:80
	s_waitcnt vmcnt(0)
	ds_write_b128 v0, v[238:241] offset:64
	v_permlane32_swap_b32_e32 v132, v166
	v_permlane32_swap_b32_e32 v133, v167
	v_permlane32_swap_b32_e32 v134, v168
	v_permlane32_swap_b32_e32 v135, v169
	v_permlane16_swap_b32_e32 v132, v166
	v_permlane16_swap_b32_e32 v133, v167
	v_permlane16_swap_b32_e32 v134, v168
	v_permlane16_swap_b32_e32 v135, v169
	v_mov_b32_e32 v178, v132
	v_mov_b32_e32 v179, v166
	v_mov_b32_e32 v182, v134
	v_mov_b32_e32 v183, v168
	v_mov_b32_e32 v166, v133
	v_mov_b32_e32 v168, v135
	v_pk_add_f32 v[132:133], v[178:179], v[182:183]
	v_pk_add_f32 v[134:135], v[166:167], v[168:169]
	v_pk_add_f32 v[132:133], v[132:133], v[132:133] op_sel:[0,1] op_sel_hi:[1,0]
	v_pk_add_f32 v[134:135], v[134:135], v[134:135] op_sel:[0,1] op_sel_hi:[1,0]
	v_permlane32_swap_b32_e32 v174, v186
	v_permlane32_swap_b32_e32 v175, v187
	v_permlane32_swap_b32_e32 v176, v188
	v_permlane32_swap_b32_e32 v177, v189
	v_permlane16_swap_b32_e32 v174, v186
	v_permlane16_swap_b32_e32 v175, v187
	v_permlane16_swap_b32_e32 v176, v188
	v_permlane16_swap_b32_e32 v177, v189
	v_mov_b32_e32 v166, v174
	v_mov_b32_e32 v167, v186
	v_mov_b32_e32 v168, v176
	v_mov_b32_e32 v169, v188
	v_mov_b32_e32 v0, v132
	v_mov_b32_e32 v133, v134
	v_pk_add_f32 v[166:167], v[166:167], v[168:169]
	v_permlane16_swap_b32_e32 v132, v0
	v_permlane16_swap_b32_e32 v134, v133
	v_mov_b32_e32 v188, v177
	v_pk_add_f32 v[166:167], v[166:167], v[166:167] op_sel:[0,1] op_sel_hi:[1,0]
	v_add_f32_e32 v177, v132, v0
	v_add_f32_e32 v176, v134, v133
	v_mov_b32_e32 v135, v166
	v_mov_b32_e32 v179, v177
	v_mov_b32_e32 v178, v176
	v_permlane16_swap_b32_e32 v166, v135
	v_permlane32_swap_b32_e32 v177, v179
	v_permlane32_swap_b32_e32 v176, v178
	v_mov_b32_e32 v186, v175
	v_add_f32_e32 v133, v166, v135
	v_pk_add_f32 v[166:167], v[176:177], v[178:179]
	v_pk_add_f32 v[168:169], v[186:187], v[188:189]
	v_pk_mul_f32 v[178:179], v[166:167], s[14:15] op_sel_hi:[1,0]
	v_pk_add_f32 v[168:169], v[168:169], v[168:169] op_sel:[0,1] op_sel_hi:[1,0]
	v_fma_f32 v0, -v179, v179, v178
	v_mov_b32_e32 v159, v168
	v_max_f32_e32 v0, 0, v0
	s_nop 0
	v_permlane16_swap_b32_e32 v168, v159
	v_add_f32_e32 v0, 0x3727c5ac, v0
	v_add_f32_e32 v132, v168, v159
	v_mul_f32_e32 v159, 0x4b800000, v0
; __device__ __forceinline__ float xsum16(float v) { const auto r = __builtin_amdgcn_permlane16_swap(__float_as_uint(v), __float_as_uint(v), false, false); return __uint_as_float(r[0]) + __uint_as_float(r[1]); }
; __device__ __forceinline__ float xsum32(float v) { const auto r = __builtin_amdgcn_permlane32_swap(__float_as_uint(v), __float_as_uint(v), false, false); return __uint_as_float(r[0]) + __uint_as_float(r[1]); }
; __device__ __forceinline__ size_t blk_off(int r, int c, int K) { return (size_t)(r >> 8) * 256 * K + (size_t)(c >> 6) * (256 * 64) + (size_t)((r & 255) * 64 + (c & 63)); }
; __device__ __forceinline__ void row_stats4(const float* st, int rowb, int fq, float (&mu)[4], float (&rs)[4]) {
;     ...
;     for (int m = 0; m < 4; ++m) { const f32x4* p = (const f32x4*)(st + (size_t)(rowb + m * 16) * 32 + fq * 8); a[m] = p[0]; b[m] = p[1]; }
; #pragma unroll
;     for (int m = 0; m < 4; ++m) { float s1 = (a[m][0] + a[m][2]) + (b[m][0] + b[m][2]), s2 = (a[m][1] + a[m][3]) + (b[m][1] + b[m][3]);
;         s1 = xsum32(xsum16(s1)); s2 = xsum32(xsum16(s2));
;         const float mm = s1 * (1.0f / 1024.0f); mu[m] = mm; rs[m] = rsqrtf(fmaxf(s2 * (1.0f / 1024.0f) - mm * mm, 0.f) + LN_EPS_); }
;     __device__ __forceinline__ void operator()(const f32x4 (&acc)[2][2][4][2], const pg8::Unit& u, int wr, int wc, int fr, int fq) const {
;     ...
;                     for (int n = 0; n < 2; ++n) { yv[bj][n] = *(const f32x4*)(Yin + (size_t)row * D_ + col0 + bj * 128 + 4 * n); gq[bj][n] = *(const f32x4*)(g + col0 + bj * 128 + 4 * n); bq_[bj][n] = *(const f32x4*)(b + col0 + bj * 128 + 4 * n); }
;                 asm volatile("" ::: "memory");
;                 float s1 = 0.f, s2 = 0.f;
; #pragma unroll
;                 for (int bj = 0; bj < 2; ++bj) { float* yp = Y + (size_t)row * D_ + col0 + bj * 128; f32x4 v[2];
; #pragma unroll
;                     for (int n = 0; n < 2; ++n) { v[n] = (((yv[bj][n] - mu) * rs) * gq[bj][n] + bq_[bj][n]) * ALPHA_ + acc[ai][bj][m][n] * sc;
;                         *(f32x4*)(yp + 4 * n) = v[n]; s1 += (v[n][0] + v[n][1]) + (v[n][2] + v[n][3]); s2 += (v[n][0] * v[n][0] + v[n][1] * v[n][1]) + (v[n][2] * v[n][2] + v[n][3] * v[n][3]); }
;                     *(u32x4*)(Yb + blk_off(row, col0 + bj * 128, D_)) = pack8(v[0], v[1]); }
	v_cmp_gt_f32_e32 vcc, s1, v0
	v_permlane32_swap_b32_e32 v190, v198
	v_permlane32_swap_b32_e32 v191, v199
	v_permlane32_swap_b32_e32 v192, v200
	v_permlane32_swap_b32_e32 v193, v201
	v_permlane16_swap_b32_e32 v190, v198
	v_permlane16_swap_b32_e32 v191, v199
	v_permlane16_swap_b32_e32 v192, v200
	v_permlane16_swap_b32_e32 v193, v201
	v_mov_b32_e32 v174, v190
	v_mov_b32_e32 v175, v198
	v_cndmask_b32_e32 v0, v0, v159, vcc
	v_rsq_f32_e32 v0, v0
	v_mov_b32_e32 v166, v192
	v_mov_b32_e32 v167, v200
	v_pk_add_f32 v[166:167], v[174:175], v[166:167]
	v_mul_f32_e32 v159, 0x45800000, v0
	v_pk_add_f32 v[166:167], v[166:167], v[166:167] op_sel:[0,1] op_sel_hi:[1,0]
	v_mov_b32_e32 v198, v191
	v_mov_b32_e32 v200, v193
	v_cndmask_b32_e32 v0, v0, v159, vcc
	v_pk_add_f32 v[168:169], v[198:199], v[200:201]
	v_mov_b32_e32 v159, v166
	v_pk_add_f32 v[168:169], v[168:169], v[168:169] op_sel:[0,1] op_sel_hi:[1,0]
	s_nop 0
	v_permlane16_swap_b32_e32 v166, v159
	v_add_f32_e32 v175, v166, v159
	v_mov_b32_e32 v159, v168
	s_nop 1
	v_permlane16_swap_b32_e32 v168, v159
	s_nop 1
	v_bfe_u32 v135, v227, 4, 2
	v_sub_u32_e32 v134, 0, v135
	v_lshlrev_b32_e32 v134, 4, v134
	v_ashrrev_i32_e32 v135, 31, v134
	v_lshl_add_u64 v[134:135], v[136:137], 0, v[134:135]
	global_load_dwordx4 v[186:189], v[134:135], off offset:576
	global_load_dwordx4 v[190:193], v[134:135], off offset:512
	v_add_f32_e32 v174, v168, v159
	v_permlane32_swap_b32_e32 v202, v206
	v_permlane32_swap_b32_e32 v203, v207
	v_permlane32_swap_b32_e32 v204, v208
	v_permlane32_swap_b32_e32 v205, v209
	v_permlane16_swap_b32_e32 v202, v206
	v_permlane16_swap_b32_e32 v203, v207
	v_permlane16_swap_b32_e32 v204, v208
	v_permlane16_swap_b32_e32 v205, v209
	v_mov_b32_e32 v166, v202
	v_mov_b32_e32 v167, v206
	v_mov_b32_e32 v168, v204
	v_mov_b32_e32 v169, v208
	v_mov_b32_e32 v206, v203
	v_mov_b32_e32 v208, v205
	v_pk_add_f32 v[166:167], v[166:167], v[168:169]
	v_pk_add_f32 v[168:169], v[206:207], v[208:209]
	global_load_dwordx4 v[198:201], v[156:157], off offset:528
	global_load_dwordx4 v[202:205], v[156:157], off offset:512
	global_load_dwordx4 v[206:209], v[154:155], off offset:528
	global_load_dwordx4 v[242:245], v[154:155], off offset:512
	v_permlane32_swap_b32_e32 v214, v210
	v_permlane32_swap_b32_e32 v215, v211
	v_permlane32_swap_b32_e32 v216, v212
	v_permlane32_swap_b32_e32 v217, v213
	v_permlane16_swap_b32_e32 v214, v210
	v_permlane16_swap_b32_e32 v215, v211
	v_permlane16_swap_b32_e32 v216, v212
	v_permlane16_swap_b32_e32 v217, v213
	v_sub_f32_e32 v183, v215, v179
	v_sub_f32_e32 v182, v214, v179
	v_sub_f32_e32 v215, v217, v179
	v_sub_f32_e32 v214, v216, v179
	v_pk_mul_f32 v[214:215], v[0:1], v[214:215] op_sel_hi:[0,1]
	v_pk_mul_f32 v[182:183], v[0:1], v[182:183] op_sel_hi:[0,1]
	v_pk_fma_f32 v[182:183], v[222:223], v[182:183], v[238:239]
	v_pk_fma_f32 v[214:215], v[224:225], v[214:215], v[240:241]
	v_pk_fma_f32 v[126:127], v[182:183], s[18:19], v[126:127] op_sel_hi:[1,0,1]
	v_pk_fma_f32 v[128:129], v[214:215], s[18:19], v[128:129] op_sel_hi:[1,0,1]
	v_add_f32_e32 v178, v126, v127
	v_add_f32_e32 v182, v128, v129
	v_add_f32_e32 v178, v178, v182
	v_mul_f32_e32 v182, v127, v127
	v_mul_f32_e32 v183, v129, v129
	v_fmac_f32_e32 v182, v126, v126
	v_fmac_f32_e32 v183, v128, v128
	v_add_f32_e32 v197, v182, v183
	v_sub_f32_e32 v183, v211, v179
	v_sub_f32_e32 v182, v210, v179
	v_sub_f32_e32 v211, v213, v179
	v_sub_f32_e32 v210, v212, v179
	v_pk_mul_f32 v[210:211], v[0:1], v[210:211] op_sel_hi:[0,1]
	v_pk_mul_f32 v[182:183], v[0:1], v[182:183] op_sel_hi:[0,1]
	v_pk_fma_f32 v[182:183], v[218:219], v[182:183], v[234:235]
	v_pk_fma_f32 v[210:211], v[220:221], v[210:211], v[236:237]
	v_pk_add_f32 v[166:167], v[166:167], v[166:167] op_sel:[0,1] op_sel_hi:[1,0]
	v_pk_fma_f32 v[124:125], v[210:211], s[18:19], v[124:125] op_sel_hi:[1,0,1]
	v_pk_fma_f32 v[122:123], v[182:183], s[18:19], v[122:123] op_sel_hi:[1,0,1]
	v_mov_b32_e32 v159, v166
	v_add_f32_e32 v182, v122, v123
	v_add_f32_e32 v183, v124, v125
	v_pk_add_f32 v[168:169], v[168:169], v[168:169] op_sel:[0,1] op_sel_hi:[1,0]
	v_permlane16_swap_b32_e32 v166, v159
	v_add_f32_e32 v178, 0, v178
	v_add_f32_e32 v182, v182, v183
	v_add_f32_e32 v167, v166, v159
	v_mov_b32_e32 v159, v168
	s_ashr_i32 s14, s3, 8
	v_add_f32_e32 v178, v178, v182
	v_mul_f32_e32 v182, v123, v123
	v_mul_f32_e32 v183, v125, v125
	v_permlane16_swap_b32_e32 v168, v159
	s_ashr_i32 s15, s14, 31
	s_nop 0
	s_nop 1
	v_bfe_u32 v135, v227, 4, 2
	v_sub_u32_e32 v134, 0, v135
	v_lshlrev_b32_e32 v134, 4, v134
	v_ashrrev_i32_e32 v135, 31, v134
	v_lshl_add_u64 v[134:135], v[136:137], 0, v[134:135]
	v_permlane16_swap_b32_e32 v126, v122
	v_permlane16_swap_b32_e32 v127, v123
	v_permlane16_swap_b32_e32 v128, v124
	v_permlane16_swap_b32_e32 v129, v125
	v_permlane32_swap_b32_e32 v126, v122
	v_permlane32_swap_b32_e32 v127, v123
	v_permlane32_swap_b32_e32 v128, v124
	v_permlane32_swap_b32_e32 v129, v125
	global_store_dwordx4 v[134:135], v[126:129], off
	global_store_dwordx4 v[134:135], v[122:125], off offset:64
	s_nop 1
	v_permlane32_swap_b32_e32 v126, v122
	v_permlane32_swap_b32_e32 v127, v123
	v_permlane32_swap_b32_e32 v128, v124
	v_permlane32_swap_b32_e32 v129, v125
	v_permlane16_swap_b32_e32 v126, v122
	v_permlane16_swap_b32_e32 v127, v123
	v_permlane16_swap_b32_e32 v128, v124
	v_permlane16_swap_b32_e32 v129, v125
	v_fmac_f32_e32 v182, v122, v122
	v_fmac_f32_e32 v183, v124, v124
	v_cvt_pk_bf16_f32 v126, v126, v127
	v_cvt_pk_bf16_f32 v127, v128, v129
	v_cvt_pk_bf16_f32 v128, v122, v123
	v_cvt_pk_bf16_f32 v129, v124, v125
	v_add_f32_e32 v166, v168, v159
	s_lshl_b64 s[14:15], s[14:15], 19
	v_lshlrev_b32_e32 v159, 6, v158
	s_movk_i32 s1, 0x33c0
	s_ashr_i32 s3, s2, 31
	v_and_or_b32 v159, v159, s1, v196
	s_add_u32 s1, s16, s14
	s_addc_u32 s14, s17, s15
	s_lshl_b64 s[24:25], s[2:3], 15
	s_add_u32 s42, s1, s24
	s_addc_u32 s43, s14, s25
	v_lshlrev_b32_e32 v159, 1, v159
	global_store_dwordx4 v159, v[126:129], s[42:43]
	v_add_f32_e32 v182, v182, v183
	s_waitcnt vmcnt(7)
; __device__ __forceinline__ float xsum16(float v) { const auto r = __builtin_amdgcn_permlane16_swap(__float_as_uint(v), __float_as_uint(v), false, false); return __uint_as_float(r[0]) + __uint_as_float(r[1]); }
; __device__ __forceinline__ float xsum32(float v) { const auto r = __builtin_amdgcn_permlane32_swap(__float_as_uint(v), __float_as_uint(v), false, false); return __uint_as_float(r[0]) + __uint_as_float(r[1]); }
; __device__ __forceinline__ size_t blk_off(int r, int c, int K) { return (size_t)(r >> 8) * 256 * K + (size_t)(c >> 6) * (256 * 64) + (size_t)((r & 255) * 64 + (c & 63)); }
; __device__ __forceinline__ u32x4 pack8(const f32x4 a, const f32x4 b) { u32x4 w; w.x = cvt_pk_bf16(a[0], a[1]); w.y = cvt_pk_bf16(a[2], a[3]); w.z = cvt_pk_bf16(b[0], b[1]); w.w = cvt_pk_bf16(b[2], b[3]); return w; }
;     __device__ __forceinline__ void operator()(const f32x4 (&acc)[2][2][4][2], const pg8::Unit& u, int wr, int wc, int fr, int fq) const {
;     ...
;                 for (int bj = 0; bj < 2; ++bj) { float* yp = Y + (size_t)row * D_ + col0 + bj * 128; f32x4 v[2];
; #pragma unroll
;                     for (int n = 0; n < 2; ++n) { v[n] = (((yv[bj][n] - mu) * rs) * gq[bj][n] + bq_[bj][n]) * ALPHA_ + acc[ai][bj][m][n] * sc;
;                         *(f32x4*)(yp + 4 * n) = v[n]; s1 += (v[n][0] + v[n][1]) + (v[n][2] + v[n][3]); s2 += (v[n][0] * v[n][0] + v[n][1] * v[n][1]) + (v[n][2] * v[n][2] + v[n][3] * v[n][3]); }
;                     *(u32x4*)(Yb + blk_off(row, col0 + bj * 128, D_)) = pack8(v[0], v[1]); }
;                 s1 = xsum32(xsum16(s1)); s2 = xsum32(xsum16(s2));
;                 if (fq == 0) *(f32x2*)(stn + (size_t)row * 32 + (u.pn * 4 + wc) * 2) = (f32x2){s1, s2}; asm volatile("" ::: "memory"); } }
	v_permlane32_swap_b32_e32 v190, v186
	v_permlane32_swap_b32_e32 v191, v187
	v_permlane32_swap_b32_e32 v192, v188
	v_permlane32_swap_b32_e32 v193, v189
	v_permlane16_swap_b32_e32 v190, v186
	v_permlane16_swap_b32_e32 v191, v187
	v_permlane16_swap_b32_e32 v192, v188
	v_permlane16_swap_b32_e32 v193, v189
	v_sub_f32_e32 v123, v191, v179
	v_sub_f32_e32 v122, v190, v179
	v_sub_f32_e32 v125, v193, v179
	v_sub_f32_e32 v124, v192, v179
	v_pk_mul_f32 v[124:125], v[0:1], v[124:125] op_sel_hi:[0,1]
	v_pk_mul_f32 v[122:123], v[0:1], v[122:123] op_sel_hi:[0,1]
	v_add_f32_e32 v182, v197, v182
	s_or_b32 s2, s2, 2
	s_ashr_i32 s3, s2, 31
	s_lshl_b64 s[28:29], s[2:3], 15
	s_nop 1
	v_lshrrev_b32_e32 v126, 4, v227
	v_lshlrev_b32_e32 v126, 7, v126
	v_add_u32_e32 v126, 0x20100, v126
	s_waitcnt vmcnt(6)
	ds_write_b128 v126, v[198:201] offset:48
	s_waitcnt vmcnt(5)
	ds_write_b128 v126, v[202:205] offset:32
	s_waitcnt vmcnt(4)
	ds_write_b128 v126, v[206:209] offset:112
	s_waitcnt vmcnt(3)
	ds_write_b128 v126, v[242:245] offset:96
	v_pk_fma_f32 v[122:123], v[202:203], v[122:123], v[242:243]
	v_pk_fma_f32 v[124:125], v[204:205], v[124:125], v[244:245]
	v_pk_fma_f32 v[118:119], v[122:123], s[18:19], v[118:119] op_sel_hi:[1,0,1]
	v_pk_fma_f32 v[120:121], v[124:125], s[18:19], v[120:121] op_sel_hi:[1,0,1]
	v_add_f32_e32 v122, v118, v119
	v_add_f32_e32 v123, v120, v121
	v_add_f32_e32 v122, v122, v123
	v_add_f32_e32 v126, v178, v122
	v_mul_f32_e32 v122, v119, v119
	v_mul_f32_e32 v123, v121, v121
	v_fmac_f32_e32 v122, v118, v118
	v_fmac_f32_e32 v123, v120, v120
	v_add_f32_e32 v122, v122, v123
	v_add_f32_e32 v127, v182, v122
	v_sub_f32_e32 v123, v187, v179
	v_sub_f32_e32 v122, v186, v179
	v_sub_f32_e32 v125, v189, v179
	v_sub_f32_e32 v124, v188, v179
	v_pk_mul_f32 v[124:125], v[0:1], v[124:125] op_sel_hi:[0,1]
	v_pk_mul_f32 v[122:123], v[0:1], v[122:123] op_sel_hi:[0,1]
	v_pk_fma_f32 v[122:123], v[198:199], v[122:123], v[206:207]
	v_pk_fma_f32 v[124:125], v[200:201], v[124:125], v[208:209]
	v_pk_fma_f32 v[114:115], v[122:123], s[18:19], v[114:115] op_sel_hi:[1,0,1]
	v_pk_fma_f32 v[116:117], v[124:125], s[18:19], v[116:117] op_sel_hi:[1,0,1]
	v_add_f32_e32 v0, v114, v115
	v_add_f32_e32 v122, v116, v117
	v_add_f32_e32 v0, v0, v122
	v_mul_f32_e32 v122, v115, v115
	v_mul_f32_e32 v123, v117, v117
	v_add_f32_e32 v0, v126, v0
	v_fmac_f32_e32 v122, v114, v114
	v_fmac_f32_e32 v123, v116, v116
	s_nop 0
	s_nop 1
	v_bfe_u32 v125, v227, 4, 2
	v_sub_u32_e32 v124, 0, v125
	v_lshlrev_b32_e32 v124, 4, v124
	v_ashrrev_i32_e32 v125, 31, v124
	v_lshl_add_u64 v[124:125], v[136:137], 0, v[124:125]
	v_permlane16_swap_b32_e32 v118, v114
	v_permlane16_swap_b32_e32 v119, v115
	v_permlane16_swap_b32_e32 v120, v116
	v_permlane16_swap_b32_e32 v121, v117
	v_permlane32_swap_b32_e32 v118, v114
	v_permlane32_swap_b32_e32 v119, v115
	v_permlane32_swap_b32_e32 v120, v116
	v_permlane32_swap_b32_e32 v121, v117
	global_store_dwordx4 v[124:125], v[118:121], off offset:512
	global_store_dwordx4 v[124:125], v[114:117], off offset:576
	s_nop 1
	v_permlane32_swap_b32_e32 v118, v114
	v_permlane32_swap_b32_e32 v119, v115
	v_permlane32_swap_b32_e32 v120, v116
	v_permlane32_swap_b32_e32 v121, v117
	v_permlane16_swap_b32_e32 v118, v114
	v_permlane16_swap_b32_e32 v119, v115
	v_permlane16_swap_b32_e32 v120, v116
	v_permlane16_swap_b32_e32 v121, v117
	v_add_f32_e32 v122, v122, v123
	v_cvt_pk_bf16_f32 v118, v118, v119
	v_cvt_pk_bf16_f32 v119, v120, v121
	v_cvt_pk_bf16_f32 v120, v114, v115
	v_mov_b32_e32 v114, v0
	v_add_f32_e32 v122, v127, v122
	s_nop 0
	v_permlane16_swap_b32_e32 v0, v114
	v_add_f32_e32 v114, v0, v114
	v_mov_b32_e32 v0, v122
	s_nop 1
	v_permlane16_swap_b32_e32 v122, v0
	v_add_f32_e32 v115, v122, v0
	v_mov_b32_e32 v135, v133
	v_mov_b32_e32 v134, v132
	v_mov_b32_e32 v177, v175
	v_mov_b32_e32 v176, v174
	v_mov_b32_e32 v169, v167
	v_mov_b32_e32 v168, v166
	v_cvt_pk_bf16_f32 v121, v116, v117
	s_add_u32 s40, s1, s28
	v_mov_b32_e32 v116, v114
	v_mov_b32_e32 v117, v115
	v_permlane32_swap_b32_e32 v133, v135
	v_permlane32_swap_b32_e32 v132, v134
	v_permlane32_swap_b32_e32 v175, v177
	v_permlane32_swap_b32_e32 v174, v176
	v_permlane32_swap_b32_e32 v167, v169
	v_permlane32_swap_b32_e32 v166, v168
	s_addc_u32 s41, s14, s29
	v_permlane32_swap_b32_e32 v114, v116
	v_permlane32_swap_b32_e32 v115, v117
	global_store_dwordx4 v159, v[118:121], s[40:41]
	s_and_saveexec_b64 s[26:27], s[44:45]
	s_cbranch_execz .LBB0_1537
	v_pk_add_f32 v[114:115], v[114:115], v[116:117]
	v_lshl_add_u64 v[116:117], s[6:7], 0, v[130:131]
	v_lshl_add_u64 v[116:117], s[52:53], 2, v[116:117]
	global_store_dwordx2 v[116:117], v[114:115], off
;     __device__ __forceinline__ void operator()(const f32x4 (&acc)[2][2][4][2], const pg8::Unit& u, int wr, int wc, int fr, int fq) const {
;     ...
;             for (int m = 0; m < 4; ++m) { const int row = row0 + ai * 128 + m * 16; const float mu = mu4[m], rs = rs4[m];
;                 f32x4 yv[2][2], gq[2][2], bq_[2][2];
; #pragma unroll
;                 for (int bj = 0; bj < 2; ++bj)
; #pragma unroll
;                     for (int n = 0; n < 2; ++n) { yv[bj][n] = *(const f32x4*)(Yin + (size_t)row * D_ + col0 + bj * 128 + 4 * n); gq[bj][n] = *(const f32x4*)(g + col0 + bj * 128 + 4 * n); bq_[bj][n] = *(const f32x4*)(b + col0 + bj * 128 + 4 * n); }
;                 asm volatile("" ::: "memory");
;                 float s1 = 0.f, s2 = 0.f;
; #pragma unroll
;                 for (int bj = 0; bj < 2; ++bj) { float* yp = Y + (size_t)row * D_ + col0 + bj * 128; f32x4 v[2];
; #pragma unroll
;                     for (int n = 0; n < 2; ++n) { v[n] = (((yv[bj][n] - mu) * rs) * gq[bj][n] + bq_[bj][n]) * ALPHA_ + acc[ai][bj][m][n] * sc;
.LBB0_1537:
	s_or_b64 exec, exec, s[26:27]
	v_pk_add_f32 v[114:115], v[132:133], v[134:135]
	s_mov_b32 s2, 0x3a800000
	v_pk_mul_f32 v[178:179], v[114:115], s[2:3] op_sel_hi:[1,0]
	s_mov_b32 s1, 0x800000
	v_fma_f32 v0, -v179, v179, v178
	v_max_f32_e32 v0, 0, v0
	v_add_f32_e32 v0, 0x3727c5ac, v0
	v_cmp_gt_f32_e32 vcc, s1, v0
	v_mul_f32_e32 v114, 0x4b800000, v0
	s_load_dwordx16 s[64:79], s[34:35], 0x38
	v_cndmask_b32_e32 v0, v0, v114, vcc
	v_rsq_f32_e32 v0, v0
	v_lshlrev_b32_e32 v159, 6, v180
	s_mov_b32 s2, 0x3fd744fd
	v_mul_f32_e32 v114, 0x45800000, v0
	v_cndmask_b32_e32 v0, v0, v114, vcc
	v_lshlrev_b64 v[114:115], 12, v[180:181]
	s_waitcnt lgkmcnt(0)
	v_lshl_add_u64 v[114:115], s[78:79], 0, v[114:115]
	v_lshl_add_u64 v[182:183], v[152:153], 2, v[114:115]
	s_nop 1
	v_bfe_u32 v117, v227, 4, 2
	v_sub_u32_e32 v116, 0, v117
	v_lshlrev_b32_e32 v116, 4, v116
	v_ashrrev_i32_e32 v117, 31, v116
	v_lshl_add_u64 v[116:117], v[182:183], 0, v[116:117]
	global_load_dwordx4 v[186:189], v[116:117], off offset:64
	global_load_dwordx4 v[190:193], v[116:117], off
	s_nop 1
	v_lshrrev_b32_e32 v178, 4, v227
	v_lshlrev_b32_e32 v178, 7, v178
	v_add_u32_e32 v178, 0x20100, v178
	ds_read_b128 v[198:201], v178 offset:16
	ds_read_b128 v[202:205], v178 offset:0
	ds_read_b128 v[206:209], v178 offset:80
	ds_read_b128 v[210:213], v178 offset:64
	s_nop 1
	v_bfe_u32 v119, v227, 4, 2
	v_sub_u32_e32 v118, 0, v119
	v_lshlrev_b32_e32 v118, 4, v118
	v_ashrrev_i32_e32 v119, 31, v118
	v_lshl_add_u64 v[118:119], v[182:183], 0, v[118:119]
	global_load_dwordx4 v[114:117], v[118:119], off offset:576
	global_load_dwordx4 v[134:137], v[118:119], off offset:512
	ds_read_b128 v[118:121], v178 offset:48
	ds_read_b128 v[126:129], v178 offset:32
	ds_read_b128 v[122:125], v178 offset:112
	ds_read_b128 v[130:133], v178 offset:96
	s_movk_i32 s1, 0x37c0
	v_and_or_b32 v159, v159, s1, v196
	v_lshlrev_b32_e32 v159, 1, v159
	s_waitcnt vmcnt(2)
	v_permlane32_swap_b32_e32 v190, v186
	v_permlane32_swap_b32_e32 v191, v187
	v_permlane32_swap_b32_e32 v192, v188
	v_permlane32_swap_b32_e32 v193, v189
	v_permlane16_swap_b32_e32 v190, v186
	v_permlane16_swap_b32_e32 v191, v187
	v_permlane16_swap_b32_e32 v192, v188
	v_permlane16_swap_b32_e32 v193, v189
	v_sub_f32_e32 v181, v191, v179
	v_sub_f32_e32 v180, v190, v179
	v_sub_f32_e32 v191, v193, v179
	v_sub_f32_e32 v190, v192, v179
	v_pk_mul_f32 v[190:191], v[0:1], v[190:191] op_sel_hi:[0,1]
	v_pk_mul_f32 v[180:181], v[0:1], v[180:181] op_sel_hi:[0,1]
	s_waitcnt lgkmcnt(0)
	v_pk_fma_f32 v[180:181], v[202:203], v[180:181], v[210:211]
	v_pk_fma_f32 v[190:191], v[204:205], v[190:191], v[212:213]
	v_pk_fma_f32 v[110:111], v[180:181], s[2:3], v[110:111] op_sel_hi:[1,0,1]
	v_pk_fma_f32 v[112:113], v[190:191], s[2:3], v[112:113] op_sel_hi:[1,0,1]
	v_add_f32_e32 v178, v110, v111
	v_add_f32_e32 v180, v112, v113
	v_add_f32_e32 v178, v178, v180
	v_mul_f32_e32 v180, v111, v111
	v_mul_f32_e32 v181, v113, v113
	v_fmac_f32_e32 v180, v110, v110
	v_fmac_f32_e32 v181, v112, v112
	v_add_f32_e32 v190, v180, v181
	v_sub_f32_e32 v181, v187, v179
	v_sub_f32_e32 v180, v186, v179
	v_sub_f32_e32 v187, v189, v179
	v_sub_f32_e32 v186, v188, v179
	v_pk_mul_f32 v[186:187], v[0:1], v[186:187] op_sel_hi:[0,1]
	v_pk_mul_f32 v[180:181], v[0:1], v[180:181] op_sel_hi:[0,1]
	v_pk_fma_f32 v[180:181], v[198:199], v[180:181], v[206:207]
	v_pk_fma_f32 v[186:187], v[200:201], v[186:187], v[208:209]
	v_pk_fma_f32 v[106:107], v[180:181], s[2:3], v[106:107] op_sel_hi:[1,0,1]
	v_pk_fma_f32 v[108:109], v[186:187], s[2:3], v[108:109] op_sel_hi:[1,0,1]
	v_add_f32_e32 v180, v106, v107
	v_add_f32_e32 v181, v108, v109
	v_add_f32_e32 v178, 0, v178
	v_add_f32_e32 v180, v180, v181
	v_add_f32_e32 v178, v178, v180
	v_mul_f32_e32 v180, v107, v107
	v_mul_f32_e32 v181, v109, v109
	s_nop 0
	s_nop 1
	v_bfe_u32 v155, v227, 4, 2
	v_sub_u32_e32 v154, 0, v155
	v_lshlrev_b32_e32 v154, 4, v154
	v_ashrrev_i32_e32 v155, 31, v154
	v_lshl_add_u64 v[154:155], v[182:183], 0, v[154:155]
	v_permlane16_swap_b32_e32 v110, v106
	v_permlane16_swap_b32_e32 v111, v107
	v_permlane16_swap_b32_e32 v112, v108
	v_permlane16_swap_b32_e32 v113, v109
	v_permlane32_swap_b32_e32 v110, v106
	v_permlane32_swap_b32_e32 v111, v107
	v_permlane32_swap_b32_e32 v112, v108
	v_permlane32_swap_b32_e32 v113, v109
	global_store_dwordx4 v[154:155], v[110:113], off
	global_store_dwordx4 v[154:155], v[106:109], off offset:64
	s_nop 1
	v_permlane32_swap_b32_e32 v110, v106
	v_permlane32_swap_b32_e32 v111, v107
	v_permlane32_swap_b32_e32 v112, v108
	v_permlane32_swap_b32_e32 v113, v109
	v_permlane16_swap_b32_e32 v110, v106
	v_permlane16_swap_b32_e32 v111, v107
	v_permlane16_swap_b32_e32 v112, v108
	v_permlane16_swap_b32_e32 v113, v109
	v_fmac_f32_e32 v180, v106, v106
	v_fmac_f32_e32 v181, v108, v108
	v_cvt_pk_bf16_f32 v110, v110, v111
	v_cvt_pk_bf16_f32 v111, v112, v113
	v_cvt_pk_bf16_f32 v112, v106, v107
	v_cvt_pk_bf16_f32 v113, v108, v109
	s_waitcnt vmcnt(2)
; __device__ __forceinline__ float xsum16(float v) { const auto r = __builtin_amdgcn_permlane16_swap(__float_as_uint(v), __float_as_uint(v), false, false); return __uint_as_float(r[0]) + __uint_as_float(r[1]); }
; __device__ __forceinline__ float xsum32(float v) { const auto r = __builtin_amdgcn_permlane32_swap(__float_as_uint(v), __float_as_uint(v), false, false); return __uint_as_float(r[0]) + __uint_as_float(r[1]); }
; __device__ __forceinline__ size_t blk_off(int r, int c, int K) { return (size_t)(r >> 8) * 256 * K + (size_t)(c >> 6) * (256 * 64) + (size_t)((r & 255) * 64 + (c & 63)); }
; __device__ __forceinline__ u32x4 pack8(const f32x4 a, const f32x4 b) { u32x4 w; w.x = cvt_pk_bf16(a[0], a[1]); w.y = cvt_pk_bf16(a[2], a[3]); w.z = cvt_pk_bf16(b[0], b[1]); w.w = cvt_pk_bf16(b[2], b[3]); return w; }
;     __device__ __forceinline__ void operator()(const f32x4 (&acc)[2][2][4][2], const pg8::Unit& u, int wr, int wc, int fr, int fq) const {
;     ...
;             for (int m = 0; m < 4; ++m) { const int row = row0 + ai * 128 + m * 16; const float mu = mu4[m], rs = rs4[m];
;                 f32x4 yv[2][2], gq[2][2], bq_[2][2];
; #pragma unroll
;                 for (int bj = 0; bj < 2; ++bj)
; #pragma unroll
;                     for (int n = 0; n < 2; ++n) { yv[bj][n] = *(const f32x4*)(Yin + (size_t)row * D_ + col0 + bj * 128 + 4 * n); gq[bj][n] = *(const f32x4*)(g + col0 + bj * 128 + 4 * n); bq_[bj][n] = *(const f32x4*)(b + col0 + bj * 128 + 4 * n); }
;     ...
;                 for (int bj = 0; bj < 2; ++bj) { float* yp = Y + (size_t)row * D_ + col0 + bj * 128; f32x4 v[2];
; #pragma unroll
;                     for (int n = 0; n < 2; ++n) { v[n] = (((yv[bj][n] - mu) * rs) * gq[bj][n] + bq_[bj][n]) * ALPHA_ + acc[ai][bj][m][n] * sc;
;                         *(f32x4*)(yp + 4 * n) = v[n]; s1 += (v[n][0] + v[n][1]) + (v[n][2] + v[n][3]); s2 += (v[n][0] * v[n][0] + v[n][1] * v[n][1]) + (v[n][2] * v[n][2] + v[n][3] * v[n][3]); }
;                     *(u32x4*)(Yb + blk_off(row, col0 + bj * 128, D_)) = pack8(v[0], v[1]); }
;                 s1 = xsum32(xsum16(s1)); s2 = xsum32(xsum16(s2));
;                 if (fq == 0) *(f32x2*)(stn + (size_t)row * 32 + (u.pn * 4 + wc) * 2) = (f32x2){s1, s2}; asm volatile("" ::: "memory"); } }
	v_permlane32_swap_b32_e32 v134, v114
	v_permlane32_swap_b32_e32 v135, v115
	v_permlane32_swap_b32_e32 v136, v116
	v_permlane32_swap_b32_e32 v137, v117
	v_permlane16_swap_b32_e32 v134, v114
	v_permlane16_swap_b32_e32 v135, v115
	v_permlane16_swap_b32_e32 v136, v116
	v_permlane16_swap_b32_e32 v137, v117
	v_sub_f32_e32 v107, v135, v179
	v_sub_f32_e32 v106, v134, v179
	v_sub_f32_e32 v109, v137, v179
	v_sub_f32_e32 v108, v136, v179
	v_pk_mul_f32 v[108:109], v[0:1], v[108:109] op_sel_hi:[0,1]
	v_pk_mul_f32 v[106:107], v[0:1], v[106:107] op_sel_hi:[0,1]
	v_pk_fma_f32 v[106:107], v[126:127], v[106:107], v[130:131]
	v_pk_fma_f32 v[108:109], v[128:129], v[108:109], v[132:133]
	v_pk_fma_f32 v[102:103], v[106:107], s[2:3], v[102:103] op_sel_hi:[1,0,1]
	v_pk_fma_f32 v[104:105], v[108:109], s[2:3], v[104:105] op_sel_hi:[1,0,1]
	v_add_f32_e32 v106, v102, v103
	v_add_f32_e32 v107, v104, v105
	v_add_f32_e32 v106, v106, v107
	global_store_dwordx4 v159, v[110:113], s[42:43]
	v_mul_f32_e32 v107, v105, v105
	v_add_f32_e32 v180, v180, v181
	v_add_f32_e32 v110, v178, v106
	v_mul_f32_e32 v106, v103, v103
	v_fmac_f32_e32 v106, v102, v102
	v_fmac_f32_e32 v107, v104, v104
	v_add_f32_e32 v180, v190, v180
	v_add_f32_e32 v106, v106, v107
	v_add_f32_e32 v111, v180, v106
	v_sub_f32_e32 v107, v115, v179
	v_sub_f32_e32 v106, v114, v179
	v_sub_f32_e32 v109, v117, v179
	v_sub_f32_e32 v108, v116, v179
	v_pk_mul_f32 v[108:109], v[0:1], v[108:109] op_sel_hi:[0,1]
	v_pk_mul_f32 v[106:107], v[0:1], v[106:107] op_sel_hi:[0,1]
	v_pk_fma_f32 v[106:107], v[118:119], v[106:107], v[122:123]
	v_pk_fma_f32 v[108:109], v[120:121], v[108:109], v[124:125]
	v_pk_fma_f32 v[98:99], v[106:107], s[2:3], v[98:99] op_sel_hi:[1,0,1]
	v_pk_fma_f32 v[100:101], v[108:109], s[2:3], v[100:101] op_sel_hi:[1,0,1]
	v_add_f32_e32 v0, v98, v99
	v_add_f32_e32 v106, v100, v101
	v_add_f32_e32 v0, v0, v106
	v_mul_f32_e32 v106, v99, v99
	v_mul_f32_e32 v107, v101, v101
	v_add_f32_e32 v0, v110, v0
	v_fmac_f32_e32 v106, v98, v98
	v_fmac_f32_e32 v107, v100, v100
	s_nop 0
	s_nop 1
	v_bfe_u32 v109, v227, 4, 2
	v_sub_u32_e32 v108, 0, v109
	v_lshlrev_b32_e32 v108, 4, v108
	v_ashrrev_i32_e32 v109, 31, v108
	v_lshl_add_u64 v[108:109], v[182:183], 0, v[108:109]
	v_permlane16_swap_b32_e32 v102, v98
	v_permlane16_swap_b32_e32 v103, v99
	v_permlane16_swap_b32_e32 v104, v100
	v_permlane16_swap_b32_e32 v105, v101
	v_permlane32_swap_b32_e32 v102, v98
	v_permlane32_swap_b32_e32 v103, v99
	v_permlane32_swap_b32_e32 v104, v100
	v_permlane32_swap_b32_e32 v105, v101
	global_store_dwordx4 v[108:109], v[102:105], off offset:512
	global_store_dwordx4 v[108:109], v[98:101], off offset:576
	s_nop 1
	v_permlane32_swap_b32_e32 v102, v98
	v_permlane32_swap_b32_e32 v103, v99
	v_permlane32_swap_b32_e32 v104, v100
	v_permlane32_swap_b32_e32 v105, v101
	v_permlane16_swap_b32_e32 v102, v98
	v_permlane16_swap_b32_e32 v103, v99
	v_permlane16_swap_b32_e32 v104, v100
	v_permlane16_swap_b32_e32 v105, v101
	v_add_f32_e32 v106, v106, v107
	v_cvt_pk_bf16_f32 v102, v102, v103
	v_cvt_pk_bf16_f32 v103, v104, v105
	v_cvt_pk_bf16_f32 v104, v98, v99
	v_mov_b32_e32 v98, v0
	v_add_f32_e32 v106, v111, v106
	s_nop 0
	v_permlane16_swap_b32_e32 v0, v98
	v_add_f32_e32 v98, v0, v98
	v_mov_b32_e32 v0, v106
	s_nop 1
	v_permlane16_swap_b32_e32 v106, v0
	v_add_f32_e32 v99, v106, v0
	v_cvt_pk_bf16_f32 v105, v100, v101
	v_mov_b32_e32 v100, v98
	v_mov_b32_e32 v101, v99
	s_nop 0
	v_permlane32_swap_b32_e32 v98, v100
	v_permlane32_swap_b32_e32 v99, v101
	global_store_dwordx4 v159, v[102:105], s[40:41]
	s_and_saveexec_b64 s[26:27], s[44:45]
	s_cbranch_execz .LBB0_1539
	v_pk_add_f32 v[98:99], v[98:99], v[100:101]
	v_lshl_add_u64 v[100:101], s[6:7], 0, v[172:173]
	v_lshl_add_u64 v[100:101], s[52:53], 2, v[100:101]
	global_store_dwordx2 v[100:101], v[98:99], off
.LBB0_1539:
	s_or_b64 exec, exec, s[26:27]
	v_pk_add_f32 v[98:99], v[174:175], v[176:177]
	s_mov_b32 s2, 0x3a800000
	v_pk_mul_f32 v[122:123], v[98:99], s[2:3] op_sel_hi:[1,0]
	s_mov_b32 s1, 0x800000
	v_fma_f32 v0, -v123, v123, v122
	v_max_f32_e32 v0, 0, v0
	v_add_f32_e32 v0, 0x3727c5ac, v0
	v_cmp_gt_f32_e32 vcc, s1, v0
	v_mul_f32_e32 v98, 0x4b800000, v0
	s_load_dwordx16 s[64:79], s[34:35], 0x38
	v_cndmask_b32_e32 v0, v0, v98, vcc
	v_rsq_f32_e32 v0, v0
	s_mov_b32 s2, 0x3fd744fd
	v_lshlrev_b32_e32 v122, 6, v170
	v_mul_f32_e32 v98, 0x45800000, v0
	v_cndmask_b32_e32 v0, v0, v98, vcc
	v_lshlrev_b64 v[98:99], 12, v[170:171]
	s_waitcnt lgkmcnt(0)
	v_lshl_add_u64 v[98:99], s[78:79], 0, v[98:99]
	v_lshl_add_u64 v[124:125], v[152:153], 2, v[98:99]
	s_nop 1
	v_bfe_u32 v101, v227, 4, 2
	v_sub_u32_e32 v100, 0, v101
	v_lshlrev_b32_e32 v100, 4, v100
	v_ashrrev_i32_e32 v101, 31, v100
	v_lshl_add_u64 v[100:101], v[124:125], 0, v[100:101]
	global_load_dwordx4 v[126:129], v[100:101], off offset:64
	global_load_dwordx4 v[130:133], v[100:101], off
	s_nop 1
	v_lshrrev_b32_e32 v159, 4, v227
	v_lshlrev_b32_e32 v159, 7, v159
	v_add_u32_e32 v159, 0x20100, v159
	ds_read_b128 v[134:137], v159 offset:16
	ds_read_b128 v[172:175], v159 offset:0
	ds_read_b128 v[176:179], v159 offset:80
	ds_read_b128 v[180:183], v159 offset:64
	s_nop 1
	v_bfe_u32 v103, v227, 4, 2
	v_sub_u32_e32 v102, 0, v103
	v_lshlrev_b32_e32 v102, 4, v102
	v_ashrrev_i32_e32 v103, 31, v102
	v_lshl_add_u64 v[102:103], v[124:125], 0, v[102:103]
	global_load_dwordx4 v[98:101], v[102:103], off offset:576
	global_load_dwordx4 v[118:121], v[102:103], off offset:512
	ds_read_b128 v[102:105], v159 offset:48
	ds_read_b128 v[110:113], v159 offset:32
	ds_read_b128 v[106:109], v159 offset:112
	ds_read_b128 v[114:117], v159 offset:96
	s_movk_i32 s1, 0x3bc0
	v_and_or_b32 v122, v122, s1, v196
	v_lshlrev_b32_e32 v122, 1, v122
	s_waitcnt vmcnt(2)
; __device__ __forceinline__ size_t blk_off(int r, int c, int K) { return (size_t)(r >> 8) * 256 * K + (size_t)(c >> 6) * (256 * 64) + (size_t)((r & 255) * 64 + (c & 63)); }
; __device__ __forceinline__ u32x4 pack8(const f32x4 a, const f32x4 b) { u32x4 w; w.x = cvt_pk_bf16(a[0], a[1]); w.y = cvt_pk_bf16(a[2], a[3]); w.z = cvt_pk_bf16(b[0], b[1]); w.w = cvt_pk_bf16(b[2], b[3]); return w; }
;     __device__ __forceinline__ void operator()(const f32x4 (&acc)[2][2][4][2], const pg8::Unit& u, int wr, int wc, int fr, int fq) const {
;     ...
;                 for (int bj = 0; bj < 2; ++bj) { float* yp = Y + (size_t)row * D_ + col0 + bj * 128; f32x4 v[2];
; #pragma unroll
;                     for (int n = 0; n < 2; ++n) { v[n] = (((yv[bj][n] - mu) * rs) * gq[bj][n] + bq_[bj][n]) * ALPHA_ + acc[ai][bj][m][n] * sc;
;                         *(f32x4*)(yp + 4 * n) = v[n]; s1 += (v[n][0] + v[n][1]) + (v[n][2] + v[n][3]); s2 += (v[n][0] * v[n][0] + v[n][1] * v[n][1]) + (v[n][2] * v[n][2] + v[n][3] * v[n][3]); }
;                     *(u32x4*)(Yb + blk_off(row, col0 + bj * 128, D_)) = pack8(v[0], v[1]); }
	v_permlane32_swap_b32_e32 v130, v126
	v_permlane32_swap_b32_e32 v131, v127
	v_permlane32_swap_b32_e32 v132, v128
	v_permlane32_swap_b32_e32 v133, v129
	v_permlane16_swap_b32_e32 v130, v126
	v_permlane16_swap_b32_e32 v131, v127
	v_permlane16_swap_b32_e32 v132, v128
	v_permlane16_swap_b32_e32 v133, v129
	v_sub_f32_e32 v127, v127, v123
	v_sub_f32_e32 v131, v131, v123
	v_sub_f32_e32 v130, v130, v123
	v_sub_f32_e32 v133, v133, v123
	v_sub_f32_e32 v132, v132, v123
	v_sub_f32_e32 v126, v126, v123
	v_sub_f32_e32 v129, v129, v123
	v_sub_f32_e32 v128, v128, v123
	v_pk_mul_f32 v[132:133], v[0:1], v[132:133] op_sel_hi:[0,1]
	v_pk_mul_f32 v[130:131], v[0:1], v[130:131] op_sel_hi:[0,1]
	v_pk_mul_f32 v[128:129], v[0:1], v[128:129] op_sel_hi:[0,1]
	v_pk_mul_f32 v[126:127], v[0:1], v[126:127] op_sel_hi:[0,1]
	s_waitcnt lgkmcnt(0)
	v_pk_fma_f32 v[130:131], v[172:173], v[130:131], v[180:181]
	v_pk_fma_f32 v[132:133], v[174:175], v[132:133], v[182:183]
	v_pk_fma_f32 v[126:127], v[134:135], v[126:127], v[176:177]
	v_pk_fma_f32 v[128:129], v[136:137], v[128:129], v[178:179]
	v_pk_fma_f32 v[96:97], v[132:133], s[2:3], v[96:97] op_sel_hi:[1,0,1]
	v_pk_fma_f32 v[94:95], v[130:131], s[2:3], v[94:95] op_sel_hi:[1,0,1]
	v_pk_fma_f32 v[92:93], v[128:129], s[2:3], v[92:93] op_sel_hi:[1,0,1]
	v_pk_fma_f32 v[90:91], v[126:127], s[2:3], v[90:91] op_sel_hi:[1,0,1]
	v_add_f32_e32 v130, v94, v95
	v_add_f32_e32 v131, v96, v97
	v_add_f32_e32 v126, v90, v91
	v_add_f32_e32 v127, v92, v93
	v_add_f32_e32 v130, v130, v131
	v_mul_f32_e32 v131, v95, v95
	v_mul_f32_e32 v132, v97, v97
	v_add_f32_e32 v126, v126, v127
	v_mul_f32_e32 v127, v91, v91
	v_mul_f32_e32 v128, v93, v93
	s_nop 0
	v_fmac_f32_e32 v131, v94, v94
	v_fmac_f32_e32 v132, v96, v96
	s_nop 1
	v_bfe_u32 v135, v227, 4, 2
	v_sub_u32_e32 v134, 0, v135
	v_lshlrev_b32_e32 v134, 4, v134
	v_ashrrev_i32_e32 v135, 31, v134
	v_lshl_add_u64 v[134:135], v[124:125], 0, v[134:135]
	v_permlane16_swap_b32_e32 v94, v90
	v_permlane16_swap_b32_e32 v95, v91
	v_permlane16_swap_b32_e32 v96, v92
	v_permlane16_swap_b32_e32 v97, v93
	v_permlane32_swap_b32_e32 v94, v90
	v_permlane32_swap_b32_e32 v95, v91
	v_permlane32_swap_b32_e32 v96, v92
	v_permlane32_swap_b32_e32 v97, v93
	global_store_dwordx4 v[134:135], v[94:97], off
	global_store_dwordx4 v[134:135], v[90:93], off offset:64
	s_nop 1
	v_permlane32_swap_b32_e32 v94, v90
	v_permlane32_swap_b32_e32 v95, v91
	v_permlane32_swap_b32_e32 v96, v92
	v_permlane32_swap_b32_e32 v97, v93
	v_permlane16_swap_b32_e32 v94, v90
	v_permlane16_swap_b32_e32 v95, v91
	v_permlane16_swap_b32_e32 v96, v92
	v_permlane16_swap_b32_e32 v97, v93
	v_fmac_f32_e32 v127, v90, v90
	v_fmac_f32_e32 v128, v92, v92
	v_cvt_pk_bf16_f32 v94, v94, v95
	v_cvt_pk_bf16_f32 v95, v96, v97
	v_cvt_pk_bf16_f32 v96, v90, v91
	v_cvt_pk_bf16_f32 v97, v92, v93
	s_waitcnt vmcnt(2)
	v_permlane32_swap_b32_e32 v118, v98
	v_permlane32_swap_b32_e32 v119, v99
	v_permlane32_swap_b32_e32 v120, v100
	v_permlane32_swap_b32_e32 v121, v101
	v_permlane16_swap_b32_e32 v118, v98
	v_permlane16_swap_b32_e32 v119, v99
	v_permlane16_swap_b32_e32 v120, v100
	v_permlane16_swap_b32_e32 v121, v101
	v_sub_f32_e32 v91, v119, v123
	v_sub_f32_e32 v90, v118, v123
	v_sub_f32_e32 v93, v121, v123
	v_sub_f32_e32 v92, v120, v123
	v_pk_mul_f32 v[92:93], v[0:1], v[92:93] op_sel_hi:[0,1]
	v_pk_mul_f32 v[90:91], v[0:1], v[90:91] op_sel_hi:[0,1]
	v_pk_fma_f32 v[90:91], v[110:111], v[90:91], v[114:115]
	v_pk_fma_f32 v[92:93], v[112:113], v[92:93], v[116:117]
	v_pk_fma_f32 v[86:87], v[90:91], s[2:3], v[86:87] op_sel_hi:[1,0,1]
	v_pk_fma_f32 v[88:89], v[92:93], s[2:3], v[88:89] op_sel_hi:[1,0,1]
	v_add_f32_e32 v130, 0, v130
	v_add_f32_e32 v90, v86, v87
	v_add_f32_e32 v91, v88, v89
	v_add_f32_e32 v126, v130, v126
	v_add_f32_e32 v90, v90, v91
	global_store_dwordx4 v122, v[94:97], s[42:43]
	v_mul_f32_e32 v91, v89, v89
	v_add_f32_e32 v131, v131, v132
	v_add_f32_e32 v94, v126, v90
	v_mul_f32_e32 v90, v87, v87
	v_add_f32_e32 v127, v127, v128
	v_fmac_f32_e32 v90, v86, v86
	v_fmac_f32_e32 v91, v88, v88
	v_add_f32_e32 v127, v131, v127
	v_add_f32_e32 v90, v90, v91
	v_add_f32_e32 v95, v127, v90
	v_sub_f32_e32 v91, v99, v123
	v_sub_f32_e32 v90, v98, v123
	v_sub_f32_e32 v93, v101, v123
	v_sub_f32_e32 v92, v100, v123
	v_pk_mul_f32 v[92:93], v[0:1], v[92:93] op_sel_hi:[0,1]
	v_pk_mul_f32 v[90:91], v[0:1], v[90:91] op_sel_hi:[0,1]
	v_pk_fma_f32 v[90:91], v[102:103], v[90:91], v[106:107]
	v_pk_fma_f32 v[92:93], v[104:105], v[92:93], v[108:109]
	v_pk_fma_f32 v[82:83], v[90:91], s[2:3], v[82:83] op_sel_hi:[1,0,1]
	v_pk_fma_f32 v[84:85], v[92:93], s[2:3], v[84:85] op_sel_hi:[1,0,1]
	v_add_f32_e32 v0, v82, v83
	v_add_f32_e32 v90, v84, v85
	v_add_f32_e32 v0, v0, v90
	v_mul_f32_e32 v90, v83, v83
	v_mul_f32_e32 v91, v85, v85
	v_add_f32_e32 v0, v94, v0
	v_fmac_f32_e32 v90, v82, v82
	v_fmac_f32_e32 v91, v84, v84
	s_nop 0
	s_nop 1
	v_bfe_u32 v93, v227, 4, 2
	v_sub_u32_e32 v92, 0, v93
	v_lshlrev_b32_e32 v92, 4, v92
	v_ashrrev_i32_e32 v93, 31, v92
	v_lshl_add_u64 v[92:93], v[124:125], 0, v[92:93]
	v_permlane16_swap_b32_e32 v86, v82
	v_permlane16_swap_b32_e32 v87, v83
	v_permlane16_swap_b32_e32 v88, v84
	v_permlane16_swap_b32_e32 v89, v85
	v_permlane32_swap_b32_e32 v86, v82
	v_permlane32_swap_b32_e32 v87, v83
	v_permlane32_swap_b32_e32 v88, v84
	v_permlane32_swap_b32_e32 v89, v85
	global_store_dwordx4 v[92:93], v[86:89], off offset:512
	global_store_dwordx4 v[92:93], v[82:85], off offset:576
	s_nop 1
	v_permlane32_swap_b32_e32 v86, v82
	v_permlane32_swap_b32_e32 v87, v83
	v_permlane32_swap_b32_e32 v88, v84
	v_permlane32_swap_b32_e32 v89, v85
	v_permlane16_swap_b32_e32 v86, v82
	v_permlane16_swap_b32_e32 v87, v83
	v_permlane16_swap_b32_e32 v88, v84
	v_permlane16_swap_b32_e32 v89, v85
	v_add_f32_e32 v90, v90, v91
	v_cvt_pk_bf16_f32 v86, v86, v87
	v_cvt_pk_bf16_f32 v87, v88, v89
	v_cvt_pk_bf16_f32 v88, v82, v83
	v_mov_b32_e32 v82, v0
	v_add_f32_e32 v90, v95, v90
	s_nop 0
	v_permlane16_swap_b32_e32 v0, v82
	v_add_f32_e32 v82, v0, v82
	v_mov_b32_e32 v0, v90
	s_nop 1
	v_permlane16_swap_b32_e32 v90, v0
	v_add_f32_e32 v83, v90, v0
	v_cvt_pk_bf16_f32 v89, v84, v85
	v_mov_b32_e32 v84, v82
	v_mov_b32_e32 v85, v83
	s_nop 0
	v_permlane32_swap_b32_e32 v82, v84
	v_permlane32_swap_b32_e32 v83, v85
	global_store_dwordx4 v122, v[86:89], s[40:41]
	s_and_saveexec_b64 s[26:27], s[44:45]
	s_cbranch_execz .LBB0_1541
	v_pk_add_f32 v[82:83], v[82:83], v[84:85]
	v_lshl_add_u64 v[84:85], s[6:7], 0, v[164:165]
	v_lshl_add_u64 v[84:85], s[52:53], 2, v[84:85]
	global_store_dwordx2 v[84:85], v[82:83], off
;     __device__ __forceinline__ void operator()(const f32x4 (&acc)[2][2][4][2], const pg8::Unit& u, int wr, int wc, int fr, int fq) const {
;     ...
;             for (int m = 0; m < 4; ++m) { const int row = row0 + ai * 128 + m * 16; const float mu = mu4[m], rs = rs4[m];
;                 f32x4 yv[2][2], gq[2][2], bq_[2][2];
; #pragma unroll
;                 for (int bj = 0; bj < 2; ++bj)
; #pragma unroll
;                     for (int n = 0; n < 2; ++n) { yv[bj][n] = *(const f32x4*)(Yin + (size_t)row * D_ + col0 + bj * 128 + 4 * n); gq[bj][n] = *(const f32x4*)(g + col0 + bj * 128 + 4 * n); bq_[bj][n] = *(const f32x4*)(b + col0 + bj * 128 + 4 * n); }
;                 asm volatile("" ::: "memory");
;                 float s1 = 0.f, s2 = 0.f;
; #pragma unroll
;                 for (int bj = 0; bj < 2; ++bj) { float* yp = Y + (size_t)row * D_ + col0 + bj * 128; f32x4 v[2];
; #pragma unroll
;                     for (int n = 0; n < 2; ++n) { v[n] = (((yv[bj][n] - mu) * rs) * gq[bj][n] + bq_[bj][n]) * ALPHA_ + acc[ai][bj][m][n] * sc;
.LBB0_1541:
	s_or_b64 exec, exec, s[26:27]
	v_pk_add_f32 v[82:83], v[166:167], v[168:169]
	s_mov_b32 s2, 0x3a800000
	v_pk_mul_f32 v[106:107], v[82:83], s[2:3] op_sel_hi:[1,0]
	s_mov_b32 s1, 0x800000
	v_fma_f32 v0, -v107, v107, v106
	v_max_f32_e32 v0, 0, v0
	v_add_f32_e32 v0, 0x3727c5ac, v0
	v_cmp_gt_f32_e32 vcc, s1, v0
	v_mul_f32_e32 v82, 0x4b800000, v0
	s_load_dwordx16 s[64:79], s[34:35], 0x38
	v_cndmask_b32_e32 v0, v0, v82, vcc
	v_rsq_f32_e32 v0, v0
	s_mov_b32 s2, 0x3fd744fd
	v_lshlrev_b32_e32 v106, 6, v162
	v_mul_f32_e32 v82, 0x45800000, v0
	v_cndmask_b32_e32 v0, v0, v82, vcc
	v_lshlrev_b64 v[82:83], 12, v[162:163]
	s_waitcnt lgkmcnt(0)
	v_lshl_add_u64 v[82:83], s[78:79], 0, v[82:83]
	v_lshl_add_u64 v[108:109], v[152:153], 2, v[82:83]
	s_nop 1
	v_bfe_u32 v85, v227, 4, 2
	v_sub_u32_e32 v84, 0, v85
	v_lshlrev_b32_e32 v84, 4, v84
	v_ashrrev_i32_e32 v85, 31, v84
	v_lshl_add_u64 v[84:85], v[108:109], 0, v[84:85]
	global_load_dwordx4 v[110:113], v[84:85], off offset:64
	global_load_dwordx4 v[114:117], v[84:85], off
	s_nop 1
	v_lshrrev_b32_e32 v134, 4, v227
	v_lshlrev_b32_e32 v134, 7, v134
	v_add_u32_e32 v134, 0x20100, v134
	ds_read_b128 v[118:121], v134 offset:16
	ds_read_b128 v[122:125], v134 offset:0
	ds_read_b128 v[126:129], v134 offset:80
	ds_read_b128 v[130:133], v134 offset:64
	s_nop 1
	v_bfe_u32 v87, v227, 4, 2
	v_sub_u32_e32 v86, 0, v87
	v_lshlrev_b32_e32 v86, 4, v86
	v_ashrrev_i32_e32 v87, 31, v86
	v_lshl_add_u64 v[86:87], v[108:109], 0, v[86:87]
	global_load_dwordx4 v[82:85], v[86:87], off offset:576
	global_load_dwordx4 v[102:105], v[86:87], off offset:512
	ds_read_b128 v[86:89], v134 offset:48
	ds_read_b128 v[94:97], v134 offset:32
	ds_read_b128 v[90:93], v134 offset:112
	ds_read_b128 v[98:101], v134 offset:96
	s_movk_i32 s1, 0x3fc0
	v_and_or_b32 v106, v106, s1, v196
	v_lshlrev_b32_e32 v106, 1, v106
	s_waitcnt vmcnt(2)
	v_permlane32_swap_b32_e32 v114, v110
	v_permlane32_swap_b32_e32 v115, v111
	v_permlane32_swap_b32_e32 v116, v112
	v_permlane32_swap_b32_e32 v117, v113
	v_permlane16_swap_b32_e32 v114, v110
	v_permlane16_swap_b32_e32 v115, v111
	v_permlane16_swap_b32_e32 v116, v112
	v_permlane16_swap_b32_e32 v117, v113
	v_sub_f32_e32 v111, v111, v107
	v_sub_f32_e32 v115, v115, v107
	v_sub_f32_e32 v114, v114, v107
	v_sub_f32_e32 v117, v117, v107
	v_sub_f32_e32 v116, v116, v107
	v_sub_f32_e32 v110, v110, v107
	v_sub_f32_e32 v113, v113, v107
	v_sub_f32_e32 v112, v112, v107
	v_pk_mul_f32 v[116:117], v[0:1], v[116:117] op_sel_hi:[0,1]
	v_pk_mul_f32 v[114:115], v[0:1], v[114:115] op_sel_hi:[0,1]
	v_pk_mul_f32 v[112:113], v[0:1], v[112:113] op_sel_hi:[0,1]
	v_pk_mul_f32 v[110:111], v[0:1], v[110:111] op_sel_hi:[0,1]
	s_waitcnt lgkmcnt(0)
	v_pk_fma_f32 v[114:115], v[122:123], v[114:115], v[130:131]
	v_pk_fma_f32 v[116:117], v[124:125], v[116:117], v[132:133]
	v_pk_fma_f32 v[110:111], v[118:119], v[110:111], v[126:127]
	v_pk_fma_f32 v[112:113], v[120:121], v[112:113], v[128:129]
	v_pk_fma_f32 v[80:81], v[116:117], s[2:3], v[80:81] op_sel_hi:[1,0,1]
	v_pk_fma_f32 v[78:79], v[114:115], s[2:3], v[78:79] op_sel_hi:[1,0,1]
	v_pk_fma_f32 v[76:77], v[112:113], s[2:3], v[76:77] op_sel_hi:[1,0,1]
	v_pk_fma_f32 v[74:75], v[110:111], s[2:3], v[74:75] op_sel_hi:[1,0,1]
	v_add_f32_e32 v114, v78, v79
	v_add_f32_e32 v115, v80, v81
	v_add_f32_e32 v110, v74, v75
	v_add_f32_e32 v111, v76, v77
	v_add_f32_e32 v114, v114, v115
	v_mul_f32_e32 v115, v79, v79
	v_mul_f32_e32 v116, v81, v81
	v_add_f32_e32 v110, v110, v111
	v_mul_f32_e32 v111, v75, v75
	v_mul_f32_e32 v112, v77, v77
	s_nop 0
	v_fmac_f32_e32 v115, v78, v78
	v_fmac_f32_e32 v116, v80, v80
	s_nop 1
	v_bfe_u32 v119, v227, 4, 2
	v_sub_u32_e32 v118, 0, v119
	v_lshlrev_b32_e32 v118, 4, v118
	v_ashrrev_i32_e32 v119, 31, v118
	v_lshl_add_u64 v[118:119], v[108:109], 0, v[118:119]
	v_permlane16_swap_b32_e32 v78, v74
	v_permlane16_swap_b32_e32 v79, v75
	v_permlane16_swap_b32_e32 v80, v76
	v_permlane16_swap_b32_e32 v81, v77
	v_permlane32_swap_b32_e32 v78, v74
	v_permlane32_swap_b32_e32 v79, v75
	v_permlane32_swap_b32_e32 v80, v76
	v_permlane32_swap_b32_e32 v81, v77
	global_store_dwordx4 v[118:119], v[78:81], off
	global_store_dwordx4 v[118:119], v[74:77], off offset:64
	s_nop 1
	v_permlane32_swap_b32_e32 v78, v74
	v_permlane32_swap_b32_e32 v79, v75
	v_permlane32_swap_b32_e32 v80, v76
	v_permlane32_swap_b32_e32 v81, v77
	v_permlane16_swap_b32_e32 v78, v74
	v_permlane16_swap_b32_e32 v79, v75
	v_permlane16_swap_b32_e32 v80, v76
	v_permlane16_swap_b32_e32 v81, v77
	v_fmac_f32_e32 v111, v74, v74
	v_fmac_f32_e32 v112, v76, v76
	v_cvt_pk_bf16_f32 v78, v78, v79
	v_cvt_pk_bf16_f32 v79, v80, v81
	v_cvt_pk_bf16_f32 v80, v74, v75
	v_cvt_pk_bf16_f32 v81, v76, v77
	s_waitcnt vmcnt(2)
; __device__ __forceinline__ float xsum16(float v) { const auto r = __builtin_amdgcn_permlane16_swap(__float_as_uint(v), __float_as_uint(v), false, false); return __uint_as_float(r[0]) + __uint_as_float(r[1]); }
; __device__ __forceinline__ float xsum32(float v) { const auto r = __builtin_amdgcn_permlane32_swap(__float_as_uint(v), __float_as_uint(v), false, false); return __uint_as_float(r[0]) + __uint_as_float(r[1]); }
; __device__ __forceinline__ size_t blk_off(int r, int c, int K) { return (size_t)(r >> 8) * 256 * K + (size_t)(c >> 6) * (256 * 64) + (size_t)((r & 255) * 64 + (c & 63)); }
; __device__ __forceinline__ u32x4 pack8(const f32x4 a, const f32x4 b) { u32x4 w; w.x = cvt_pk_bf16(a[0], a[1]); w.y = cvt_pk_bf16(a[2], a[3]); w.z = cvt_pk_bf16(b[0], b[1]); w.w = cvt_pk_bf16(b[2], b[3]); return w; }
; __device__ __forceinline__ void row_stats4(const float* st, int rowb, int fq, float (&mu)[4], float (&rs)[4]) {
;     ...
;     for (int m = 0; m < 4; ++m) { const f32x4* p = (const f32x4*)(st + (size_t)(rowb + m * 16) * 32 + fq * 8); a[m] = p[0]; b[m] = p[1]; }
; #pragma unroll
;     for (int m = 0; m < 4; ++m) { float s1 = (a[m][0] + a[m][2]) + (b[m][0] + b[m][2]), s2 = (a[m][1] + a[m][3]) + (b[m][1] + b[m][3]);
;     __device__ __forceinline__ void operator()(const f32x4 (&acc)[2][2][4][2], const pg8::Unit& u, int wr, int wc, int fr, int fq) const {
;     ...
;                     for (int n = 0; n < 2; ++n) { v[n] = (((yv[bj][n] - mu) * rs) * gq[bj][n] + bq_[bj][n]) * ALPHA_ + acc[ai][bj][m][n] * sc;
;                         *(f32x4*)(yp + 4 * n) = v[n]; s1 += (v[n][0] + v[n][1]) + (v[n][2] + v[n][3]); s2 += (v[n][0] * v[n][0] + v[n][1] * v[n][1]) + (v[n][2] * v[n][2] + v[n][3] * v[n][3]); }
;                     *(u32x4*)(Yb + blk_off(row, col0 + bj * 128, D_)) = pack8(v[0], v[1]); }
;                 s1 = xsum32(xsum16(s1)); s2 = xsum32(xsum16(s2));
;                 if (fq == 0) *(f32x2*)(stn + (size_t)row * 32 + (u.pn * 4 + wc) * 2) = (f32x2){s1, s2}; asm volatile("" ::: "memory"); } }
	v_permlane32_swap_b32_e32 v102, v82
	v_permlane32_swap_b32_e32 v103, v83
	v_permlane32_swap_b32_e32 v104, v84
	v_permlane32_swap_b32_e32 v105, v85
	v_permlane16_swap_b32_e32 v102, v82
	v_permlane16_swap_b32_e32 v103, v83
	v_permlane16_swap_b32_e32 v104, v84
	v_permlane16_swap_b32_e32 v105, v85
	v_sub_f32_e32 v75, v103, v107
	v_sub_f32_e32 v74, v102, v107
	v_sub_f32_e32 v77, v105, v107
	v_sub_f32_e32 v76, v104, v107
	v_pk_mul_f32 v[76:77], v[0:1], v[76:77] op_sel_hi:[0,1]
	v_pk_mul_f32 v[74:75], v[0:1], v[74:75] op_sel_hi:[0,1]
	v_pk_fma_f32 v[74:75], v[94:95], v[74:75], v[98:99]
	v_pk_fma_f32 v[76:77], v[96:97], v[76:77], v[100:101]
	v_pk_fma_f32 v[70:71], v[74:75], s[2:3], v[70:71] op_sel_hi:[1,0,1]
	v_pk_fma_f32 v[72:73], v[76:77], s[2:3], v[72:73] op_sel_hi:[1,0,1]
	v_add_f32_e32 v114, 0, v114
	v_add_f32_e32 v74, v70, v71
	v_add_f32_e32 v75, v72, v73
	v_add_f32_e32 v110, v114, v110
	v_add_f32_e32 v74, v74, v75
	global_store_dwordx4 v106, v[78:81], s[42:43]
	v_mul_f32_e32 v75, v73, v73
	v_add_f32_e32 v115, v115, v116
	v_add_f32_e32 v78, v110, v74
	v_mul_f32_e32 v74, v71, v71
	v_add_f32_e32 v111, v111, v112
	v_fmac_f32_e32 v74, v70, v70
	v_fmac_f32_e32 v75, v72, v72
	v_add_f32_e32 v111, v115, v111
	v_add_f32_e32 v74, v74, v75
	v_add_f32_e32 v79, v111, v74
	v_sub_f32_e32 v75, v83, v107
	v_sub_f32_e32 v74, v82, v107
	v_sub_f32_e32 v77, v85, v107
	v_sub_f32_e32 v76, v84, v107
	v_pk_mul_f32 v[76:77], v[0:1], v[76:77] op_sel_hi:[0,1]
	v_pk_mul_f32 v[74:75], v[0:1], v[74:75] op_sel_hi:[0,1]
	v_pk_fma_f32 v[74:75], v[86:87], v[74:75], v[90:91]
	v_pk_fma_f32 v[76:77], v[88:89], v[76:77], v[92:93]
	v_pk_fma_f32 v[66:67], v[74:75], s[2:3], v[66:67] op_sel_hi:[1,0,1]
	v_pk_fma_f32 v[68:69], v[76:77], s[2:3], v[68:69] op_sel_hi:[1,0,1]
	v_add_f32_e32 v0, v66, v67
	v_add_f32_e32 v74, v68, v69
	v_add_f32_e32 v0, v0, v74
	v_mul_f32_e32 v74, v67, v67
	v_mul_f32_e32 v75, v69, v69
	v_add_f32_e32 v0, v78, v0
	v_fmac_f32_e32 v74, v66, v66
	v_fmac_f32_e32 v75, v68, v68
	s_nop 0
	s_nop 1
	v_bfe_u32 v77, v227, 4, 2
	v_sub_u32_e32 v76, 0, v77
	v_lshlrev_b32_e32 v76, 4, v76
	v_ashrrev_i32_e32 v77, 31, v76
	v_lshl_add_u64 v[76:77], v[108:109], 0, v[76:77]
	v_permlane16_swap_b32_e32 v70, v66
	v_permlane16_swap_b32_e32 v71, v67
	v_permlane16_swap_b32_e32 v72, v68
	v_permlane16_swap_b32_e32 v73, v69
	v_permlane32_swap_b32_e32 v70, v66
	v_permlane32_swap_b32_e32 v71, v67
	v_permlane32_swap_b32_e32 v72, v68
	v_permlane32_swap_b32_e32 v73, v69
	global_store_dwordx4 v[76:77], v[70:73], off offset:512
	global_store_dwordx4 v[76:77], v[66:69], off offset:576
	s_nop 1
	v_permlane32_swap_b32_e32 v70, v66
	v_permlane32_swap_b32_e32 v71, v67
	v_permlane32_swap_b32_e32 v72, v68
	v_permlane32_swap_b32_e32 v73, v69
	v_permlane16_swap_b32_e32 v70, v66
	v_permlane16_swap_b32_e32 v71, v67
	v_permlane16_swap_b32_e32 v72, v68
	v_permlane16_swap_b32_e32 v73, v69
	v_add_f32_e32 v74, v74, v75
	v_cvt_pk_bf16_f32 v70, v70, v71
	v_cvt_pk_bf16_f32 v71, v72, v73
	v_cvt_pk_bf16_f32 v72, v66, v67
	v_mov_b32_e32 v66, v0
	v_add_f32_e32 v74, v79, v74
	s_nop 0
	v_permlane16_swap_b32_e32 v0, v66
	v_add_f32_e32 v66, v0, v66
	v_mov_b32_e32 v0, v74
	s_nop 1
	v_permlane16_swap_b32_e32 v74, v0
	v_add_f32_e32 v67, v74, v0
	v_cvt_pk_bf16_f32 v73, v68, v69
	v_mov_b32_e32 v68, v66
	v_mov_b32_e32 v69, v67
	s_nop 0
	v_permlane32_swap_b32_e32 v66, v68
	v_permlane32_swap_b32_e32 v67, v69
	global_store_dwordx4 v106, v[70:73], s[40:41]
	s_and_saveexec_b64 s[26:27], s[44:45]
	s_cbranch_execz .LBB0_1543
	v_pk_add_f32 v[66:67], v[66:67], v[68:69]
	v_lshl_add_u64 v[68:69], s[6:7], 0, v[160:161]
	v_lshl_add_u64 v[68:69], s[52:53], 2, v[68:69]
	global_store_dwordx2 v[68:69], v[66:67], off
.LBB0_1543:
	s_or_b64 exec, exec, s[26:27]
	v_add_u32_e32 v118, 0x80, v158
	v_ashrrev_i32_e32 v119, 31, v118
	v_lshlrev_b64 v[110:111], 7, v[118:119]
	v_lshl_add_u64 v[70:71], v[146:147], 0, v[110:111]
	s_nop 1
	v_bfe_u32 v75, v227, 4, 2
	v_sub_u32_e32 v74, 0, v75
	v_lshlrev_b32_e32 v74, 4, v74
	v_ashrrev_i32_e32 v75, 31, v74
	v_lshl_add_u64 v[74:75], v[70:71], 0, v[74:75]
	global_load_dwordx4 v[66:69], v[74:75], off
	s_nop 0
	global_load_dwordx4 v[70:73], v[74:75], off offset:64
	v_add_u32_e32 v108, 0x90, v158
	v_ashrrev_i32_e32 v109, 31, v108
	v_lshlrev_b64 v[102:103], 7, v[108:109]
	v_lshl_add_u64 v[78:79], v[146:147], 0, v[102:103]
	s_nop 1
	v_bfe_u32 v83, v227, 4, 2
	v_sub_u32_e32 v82, 0, v83
	v_lshlrev_b32_e32 v82, 4, v82
	v_ashrrev_i32_e32 v83, 31, v82
	v_lshl_add_u64 v[82:83], v[78:79], 0, v[82:83]
	global_load_dwordx4 v[74:77], v[82:83], off
	s_nop 0
	global_load_dwordx4 v[78:81], v[82:83], off offset:64
	v_add_u32_e32 v96, 0xa0, v158
	v_ashrrev_i32_e32 v97, 31, v96
	v_lshlrev_b64 v[82:83], 7, v[96:97]
	v_lshl_add_u64 v[86:87], v[146:147], 0, v[82:83]
	s_nop 1
	v_bfe_u32 v91, v227, 4, 2
	v_sub_u32_e32 v90, 0, v91
	v_lshlrev_b32_e32 v90, 4, v90
	v_ashrrev_i32_e32 v91, 31, v90
	v_lshl_add_u64 v[90:91], v[86:87], 0, v[90:91]
	global_load_dwordx4 v[82:85], v[90:91], off
	s_nop 0
	global_load_dwordx4 v[86:89], v[90:91], off offset:64
	v_add_u32_e32 v94, 0xb0, v158
	v_ashrrev_i32_e32 v95, 31, v94
	v_lshlrev_b64 v[90:91], 7, v[94:95]
	v_lshl_add_u64 v[98:99], v[146:147], 0, v[90:91]
	s_nop 1
	v_bfe_u32 v105, v227, 4, 2
	v_sub_u32_e32 v104, 0, v105
	v_lshlrev_b32_e32 v104, 4, v104
	v_ashrrev_i32_e32 v105, 31, v104
	v_lshl_add_u64 v[104:105], v[98:99], 0, v[104:105]
	global_load_dwordx4 v[90:93], v[104:105], off
	s_nop 0
	global_load_dwordx4 v[98:101], v[104:105], off offset:64
	s_mov_b32 s2, 0x3a800000
	s_mov_b32 s1, 0x800000
	s_load_dwordx16 s[64:79], s[34:35], 0x38
	s_mov_b32 s14, 0x3fd744fd
	s_waitcnt vmcnt(6)
; __device__ __forceinline__ float xsum16(float v) { const auto r = __builtin_amdgcn_permlane16_swap(__float_as_uint(v), __float_as_uint(v), false, false); return __uint_as_float(r[0]) + __uint_as_float(r[1]); }
; __device__ __forceinline__ float xsum32(float v) { const auto r = __builtin_amdgcn_permlane32_swap(__float_as_uint(v), __float_as_uint(v), false, false); return __uint_as_float(r[0]) + __uint_as_float(r[1]); }
; __device__ __forceinline__ void row_stats4(const float* st, int rowb, int fq, float (&mu)[4], float (&rs)[4]) {
;     ...
;     for (int m = 0; m < 4; ++m) { const f32x4* p = (const f32x4*)(st + (size_t)(rowb + m * 16) * 32 + fq * 8); a[m] = p[0]; b[m] = p[1]; }
; #pragma unroll
;     for (int m = 0; m < 4; ++m) { float s1 = (a[m][0] + a[m][2]) + (b[m][0] + b[m][2]), s2 = (a[m][1] + a[m][3]) + (b[m][1] + b[m][3]);
;         s1 = xsum32(xsum16(s1)); s2 = xsum32(xsum16(s2));
;         const float mm = s1 * (1.0f / 1024.0f); mu[m] = mm; rs[m] = rsqrtf(fmaxf(s2 * (1.0f / 1024.0f) - mm * mm, 0.f) + LN_EPS_); }
;     __device__ __forceinline__ void operator()(const f32x4 (&acc)[2][2][4][2], const pg8::Unit& u, int wr, int wc, int fr, int fq) const {
;     ...
;                     for (int n = 0; n < 2; ++n) { yv[bj][n] = *(const f32x4*)(Yin + (size_t)row * D_ + col0 + bj * 128 + 4 * n); gq[bj][n] = *(const f32x4*)(g + col0 + bj * 128 + 4 * n); bq_[bj][n] = *(const f32x4*)(b + col0 + bj * 128 + 4 * n); }
;                 asm volatile("" ::: "memory");
	v_permlane32_swap_b32_e32 v66, v70
	v_permlane32_swap_b32_e32 v67, v71
	v_permlane32_swap_b32_e32 v68, v72
	v_permlane32_swap_b32_e32 v69, v73
	v_permlane16_swap_b32_e32 v66, v70
	v_permlane16_swap_b32_e32 v67, v71
	v_permlane16_swap_b32_e32 v68, v72
	v_permlane16_swap_b32_e32 v69, v73
	v_mov_b32_e32 v104, v66
	v_mov_b32_e32 v105, v70
	v_mov_b32_e32 v106, v68
	v_mov_b32_e32 v107, v72
	v_pk_add_f32 v[104:105], v[104:105], v[106:107]
	v_mov_b32_e32 v70, v67
	v_pk_add_f32 v[104:105], v[104:105], v[104:105] op_sel:[0,1] op_sel_hi:[1,0]
	v_mov_b32_e32 v72, v69
	v_pk_add_f32 v[66:67], v[70:71], v[72:73]
	v_mov_b32_e32 v0, v104
	v_pk_add_f32 v[66:67], v[66:67], v[66:67] op_sel:[0,1] op_sel_hi:[1,0]
	s_nop 0
	v_permlane16_swap_b32_e32 v104, v0
	v_add_f32_e32 v67, v104, v0
	v_mov_b32_e32 v0, v66
	s_nop 1
	v_permlane16_swap_b32_e32 v66, v0
	v_add_f32_e32 v66, v66, v0
	v_mov_b32_e32 v69, v67
	v_mov_b32_e32 v68, v66
	s_nop 0
	v_permlane32_swap_b32_e32 v67, v69
	v_permlane32_swap_b32_e32 v66, v68
	v_pk_add_f32 v[66:67], v[66:67], v[68:69]
	s_waitcnt vmcnt(4)
	v_permlane32_swap_b32_e32 v74, v78
	v_permlane32_swap_b32_e32 v75, v79
	v_permlane32_swap_b32_e32 v76, v80
	v_permlane32_swap_b32_e32 v77, v81
	v_permlane16_swap_b32_e32 v74, v78
	v_permlane16_swap_b32_e32 v75, v79
	v_permlane16_swap_b32_e32 v76, v80
	v_permlane16_swap_b32_e32 v77, v81
	v_mov_b32_e32 v68, v76
	v_pk_mul_f32 v[116:117], v[66:67], s[2:3] op_sel_hi:[1,0]
	v_mov_b32_e32 v67, v78
	v_fma_f32 v0, -v117, v117, v116
	v_max_f32_e32 v0, 0, v0
	v_add_f32_e32 v0, 0x3727c5ac, v0
	v_cmp_gt_f32_e32 vcc, s1, v0
	v_mul_f32_e32 v66, 0x4b800000, v0
	v_mov_b32_e32 v69, v80
	v_cndmask_b32_e32 v0, v0, v66, vcc
	v_rsq_f32_e32 v0, v0
	v_mov_b32_e32 v78, v75
	v_mov_b32_e32 v80, v77
	v_readlane_b32 s2, v253, 59
	v_mul_f32_e32 v66, 0x45800000, v0
	v_cndmask_b32_e32 v116, v0, v66, vcc
	v_mov_b32_e32 v66, v74
	v_pk_add_f32 v[66:67], v[66:67], v[68:69]
	v_pk_add_f32 v[68:69], v[78:79], v[80:81]
	v_pk_add_f32 v[66:67], v[66:67], v[66:67] op_sel:[0,1] op_sel_hi:[1,0]
	v_pk_add_f32 v[68:69], v[68:69], v[68:69] op_sel:[0,1] op_sel_hi:[1,0]
	v_mov_b32_e32 v0, v66
	s_nop 1
	v_permlane16_swap_b32_e32 v66, v0
	v_add_f32_e32 v113, v66, v0
	v_mov_b32_e32 v0, v68
	s_nop 1
	v_permlane16_swap_b32_e32 v68, v0
	v_add_f32_e32 v112, v68, v0
	s_waitcnt vmcnt(2)
	v_permlane32_swap_b32_e32 v82, v86
	v_permlane32_swap_b32_e32 v83, v87
	v_permlane32_swap_b32_e32 v84, v88
	v_permlane32_swap_b32_e32 v85, v89
	v_permlane16_swap_b32_e32 v82, v86
	v_permlane16_swap_b32_e32 v83, v87
	v_permlane16_swap_b32_e32 v84, v88
	v_permlane16_swap_b32_e32 v85, v89
	v_mov_b32_e32 v66, v82
	v_mov_b32_e32 v67, v86
	v_mov_b32_e32 v68, v84
	v_mov_b32_e32 v69, v88
	v_pk_add_f32 v[66:67], v[66:67], v[68:69]
	v_mov_b32_e32 v86, v83
	v_pk_add_f32 v[66:67], v[66:67], v[66:67] op_sel:[0,1] op_sel_hi:[1,0]
	v_mov_b32_e32 v88, v85
	v_pk_add_f32 v[68:69], v[86:87], v[88:89]
	v_mov_b32_e32 v0, v66
	v_pk_add_f32 v[68:69], v[68:69], v[68:69] op_sel:[0,1] op_sel_hi:[1,0]
	s_nop 0
	v_permlane16_swap_b32_e32 v66, v0
	v_add_f32_e32 v105, v66, v0
	v_mov_b32_e32 v0, v68
	s_nop 1
	v_permlane16_swap_b32_e32 v68, v0
	v_add_f32_e32 v104, v68, v0
	s_waitcnt vmcnt(0)
	v_permlane32_swap_b32_e32 v90, v98
	v_permlane32_swap_b32_e32 v91, v99
	v_permlane32_swap_b32_e32 v92, v100
	v_permlane32_swap_b32_e32 v93, v101
	v_permlane16_swap_b32_e32 v90, v98
	v_permlane16_swap_b32_e32 v91, v99
	v_permlane16_swap_b32_e32 v92, v100
	v_permlane16_swap_b32_e32 v93, v101
	v_mov_b32_e32 v66, v90
	v_mov_b32_e32 v67, v98
	v_mov_b32_e32 v68, v92
	v_mov_b32_e32 v69, v100
	v_pk_add_f32 v[66:67], v[66:67], v[68:69]
	v_mov_b32_e32 v98, v91
	v_pk_add_f32 v[66:67], v[66:67], v[66:67] op_sel:[0,1] op_sel_hi:[1,0]
	v_mov_b32_e32 v100, v93
	v_mov_b32_e32 v0, v66
	s_nop 1
	v_permlane16_swap_b32_e32 v66, v0
	v_pk_add_f32 v[68:69], v[98:99], v[100:101]
	v_add_f32_e32 v99, v66, v0
	v_ashrrev_i32_e32 v66, 8, v118
	v_ashrrev_i32_e32 v67, 31, v66
	v_pk_add_f32 v[68:69], v[68:69], v[68:69] op_sel:[0,1] op_sel_hi:[1,0]
	v_lshlrev_b64 v[120:121], 19, v[66:67]
	v_lshlrev_b64 v[66:67], 12, v[118:119]
	v_mov_b32_e32 v0, v68
	s_waitcnt lgkmcnt(0)
	v_lshl_add_u64 v[66:67], s[78:79], 0, v[66:67]
	v_permlane16_swap_b32_e32 v68, v0
	v_lshl_add_u64 v[122:123], v[152:153], 2, v[66:67]
	v_add_f32_e32 v98, v68, v0
	s_nop 1
	v_bfe_u32 v71, v227, 4, 2
	v_sub_u32_e32 v70, 0, v71
	v_lshlrev_b32_e32 v70, 4, v70
	v_ashrrev_i32_e32 v71, 31, v70
	v_lshl_add_u64 v[70:71], v[122:123], 0, v[70:71]
	global_load_dwordx4 v[74:77], v[70:71], off offset:64
	global_load_dwordx4 v[86:89], v[70:71], off
	s_nop 1
	v_lshrrev_b32_e32 v0, 4, v227
	v_lshlrev_b32_e32 v0, 7, v0
	v_add_u32_e32 v0, 0x20100, v0
	ds_read_b128 v[66:69], v0 offset:16
	ds_read_b128 v[78:81], v0 offset:0
	ds_read_b128 v[70:73], v0 offset:80
	ds_read_b128 v[82:85], v0 offset:64
	s_nop 1
	v_bfe_u32 v101, v227, 4, 2
	v_sub_u32_e32 v100, 0, v101
	v_lshlrev_b32_e32 v100, 4, v100
	v_ashrrev_i32_e32 v101, 31, v100
	v_lshl_add_u64 v[100:101], v[122:123], 0, v[100:101]
	global_load_dwordx4 v[90:93], v[100:101], off offset:576
	global_load_dwordx4 v[124:127], v[100:101], off offset:512
	ds_read_b128 v[128:131], v0 offset:48
	ds_read_b128 v[132:135], v0 offset:32
	ds_read_b128 v[158:161], v0 offset:112
	ds_read_b128 v[162:165], v0 offset:96
	v_lshlrev_b32_e32 v0, 6, v118
	s_movk_i32 s1, 0x33c0
	v_readlane_b32 s3, v253, 60
	v_and_or_b32 v0, v0, s1, v196
	v_lshlrev_b32_e32 v0, 1, v0
	v_mov_b32_e32 v115, v113
	v_mov_b32_e32 v114, v112
	v_mov_b32_e32 v107, v105
	v_mov_b32_e32 v106, v104
	v_mov_b32_e32 v101, v99
	v_mov_b32_e32 v100, v98
	v_permlane32_swap_b32_e32 v113, v115
	v_permlane32_swap_b32_e32 v112, v114
	v_permlane32_swap_b32_e32 v105, v107
	v_permlane32_swap_b32_e32 v104, v106
	v_permlane32_swap_b32_e32 v99, v101
	v_permlane32_swap_b32_e32 v98, v100
	s_waitcnt vmcnt(2)
; __device__ __forceinline__ float xsum16(float v) { const auto r = __builtin_amdgcn_permlane16_swap(__float_as_uint(v), __float_as_uint(v), false, false); return __uint_as_float(r[0]) + __uint_as_float(r[1]); }
; __device__ __forceinline__ float xsum32(float v) { const auto r = __builtin_amdgcn_permlane32_swap(__float_as_uint(v), __float_as_uint(v), false, false); return __uint_as_float(r[0]) + __uint_as_float(r[1]); }
; __device__ __forceinline__ size_t blk_off(int r, int c, int K) { return (size_t)(r >> 8) * 256 * K + (size_t)(c >> 6) * (256 * 64) + (size_t)((r & 255) * 64 + (c & 63)); }
;     __device__ __forceinline__ void operator()(const f32x4 (&acc)[2][2][4][2], const pg8::Unit& u, int wr, int wc, int fr, int fq) const {
;     ...
;         for (int ai = 0; ai < 2; ++ai) { float mu4[4], rs4[4]; row_stats4(stp, row0 + ai * 128, fq, mu4, rs4);
; #pragma unroll
;             for (int m = 0; m < 4; ++m) { const int row = row0 + ai * 128 + m * 16; const float mu = mu4[m], rs = rs4[m];
;                 f32x4 yv[2][2], gq[2][2], bq_[2][2];
; #pragma unroll
;                 for (int bj = 0; bj < 2; ++bj)
; #pragma unroll
;                     for (int n = 0; n < 2; ++n) { yv[bj][n] = *(const f32x4*)(Yin + (size_t)row * D_ + col0 + bj * 128 + 4 * n); gq[bj][n] = *(const f32x4*)(g + col0 + bj * 128 + 4 * n); bq_[bj][n] = *(const f32x4*)(b + col0 + bj * 128 + 4 * n); }
;                 asm volatile("" ::: "memory");
;                 float s1 = 0.f, s2 = 0.f;
; #pragma unroll
;                 for (int bj = 0; bj < 2; ++bj) { float* yp = Y + (size_t)row * D_ + col0 + bj * 128; f32x4 v[2];
; #pragma unroll
;                     for (int n = 0; n < 2; ++n) { v[n] = (((yv[bj][n] - mu) * rs) * gq[bj][n] + bq_[bj][n]) * ALPHA_ + acc[ai][bj][m][n] * sc;
;                         *(f32x4*)(yp + 4 * n) = v[n]; s1 += (v[n][0] + v[n][1]) + (v[n][2] + v[n][3]); s2 += (v[n][0] * v[n][0] + v[n][1] * v[n][1]) + (v[n][2] * v[n][2] + v[n][3] * v[n][3]); }
;                     *(u32x4*)(Yb + blk_off(row, col0 + bj * 128, D_)) = pack8(v[0], v[1]); }
;                 s1 = xsum32(xsum16(s1)); s2 = xsum32(xsum16(s2));
;                 if (fq == 0) *(f32x2*)(stn + (size_t)row * 32 + (u.pn * 4 + wc) * 2) = (f32x2){s1, s2}; asm volatile("" ::: "memory"); } }
	v_permlane32_swap_b32_e32 v86, v74
	v_permlane32_swap_b32_e32 v87, v75
	v_permlane32_swap_b32_e32 v88, v76
	v_permlane32_swap_b32_e32 v89, v77
	v_permlane16_swap_b32_e32 v86, v74
	v_permlane16_swap_b32_e32 v87, v75
	v_permlane16_swap_b32_e32 v88, v76
	v_permlane16_swap_b32_e32 v89, v77
	v_sub_f32_e32 v75, v75, v117
	v_sub_f32_e32 v87, v87, v117
	v_sub_f32_e32 v86, v86, v117
	v_sub_f32_e32 v89, v89, v117
	v_sub_f32_e32 v88, v88, v117
	v_sub_f32_e32 v74, v74, v117
	v_sub_f32_e32 v77, v77, v117
	v_sub_f32_e32 v76, v76, v117
	v_pk_mul_f32 v[88:89], v[116:117], v[88:89] op_sel_hi:[0,1]
	v_pk_mul_f32 v[86:87], v[116:117], v[86:87] op_sel_hi:[0,1]
	v_pk_mul_f32 v[76:77], v[116:117], v[76:77] op_sel_hi:[0,1]
	v_pk_mul_f32 v[74:75], v[116:117], v[74:75] op_sel_hi:[0,1]
	s_waitcnt lgkmcnt(0)
	v_pk_fma_f32 v[78:79], v[78:79], v[86:87], v[82:83]
	v_pk_fma_f32 v[80:81], v[80:81], v[88:89], v[84:85]
	v_pk_fma_f32 v[66:67], v[66:67], v[74:75], v[70:71]
	v_pk_fma_f32 v[68:69], v[68:69], v[76:77], v[72:73]
	v_pk_fma_f32 v[64:65], v[80:81], s[14:15], v[64:65] op_sel_hi:[1,0,1]
	v_pk_fma_f32 v[62:63], v[78:79], s[14:15], v[62:63] op_sel_hi:[1,0,1]
	v_pk_fma_f32 v[60:61], v[68:69], s[14:15], v[60:61] op_sel_hi:[1,0,1]
	v_pk_fma_f32 v[58:59], v[66:67], s[14:15], v[58:59] op_sel_hi:[1,0,1]
	v_add_f32_e32 v78, v62, v63
	v_add_f32_e32 v79, v64, v65
	v_add_f32_e32 v66, v58, v59
	v_add_f32_e32 v67, v60, v61
	v_add_f32_e32 v78, v78, v79
	v_mul_f32_e32 v79, v63, v63
	v_mul_f32_e32 v80, v65, v65
	v_add_f32_e32 v66, v66, v67
	v_mul_f32_e32 v67, v59, v59
	s_nop 0
	v_fmac_f32_e32 v79, v62, v62
	v_fmac_f32_e32 v80, v64, v64
	s_nop 1
	v_bfe_u32 v69, v227, 4, 2
	v_sub_u32_e32 v68, 0, v69
	v_lshlrev_b32_e32 v68, 4, v68
	v_ashrrev_i32_e32 v69, 31, v68
	v_lshl_add_u64 v[68:69], v[122:123], 0, v[68:69]
	v_permlane16_swap_b32_e32 v62, v58
	v_permlane16_swap_b32_e32 v63, v59
	v_permlane16_swap_b32_e32 v64, v60
	v_permlane16_swap_b32_e32 v65, v61
	v_permlane32_swap_b32_e32 v62, v58
	v_permlane32_swap_b32_e32 v63, v59
	v_permlane32_swap_b32_e32 v64, v60
	v_permlane32_swap_b32_e32 v65, v61
	global_store_dwordx4 v[68:69], v[62:65], off
	global_store_dwordx4 v[68:69], v[58:61], off offset:64
	s_nop 1
	v_permlane32_swap_b32_e32 v62, v58
	v_permlane32_swap_b32_e32 v63, v59
	v_permlane32_swap_b32_e32 v64, v60
	v_permlane32_swap_b32_e32 v65, v61
	v_permlane16_swap_b32_e32 v62, v58
	v_permlane16_swap_b32_e32 v63, v59
	v_permlane16_swap_b32_e32 v64, v60
	v_permlane16_swap_b32_e32 v65, v61
	v_fmac_f32_e32 v67, v58, v58
	v_cvt_pk_bf16_f32 v62, v62, v63
	v_cvt_pk_bf16_f32 v63, v64, v65
	v_cvt_pk_bf16_f32 v64, v58, v59
	v_lshl_add_u64 v[58:59], s[2:3], 0, v[120:121]
	v_mul_f32_e32 v68, v61, v61
	v_lshl_add_u64 v[76:77], v[58:59], 0, s[24:25]
	v_fmac_f32_e32 v68, v60, v60
	v_cvt_pk_bf16_f32 v65, v60, v61
	v_lshl_add_u64 v[60:61], v[76:77], 0, v[0:1]
	global_store_dwordx4 v[60:61], v[62:65], off
	s_waitcnt vmcnt(3)
	v_permlane32_swap_b32_e32 v124, v90
	v_permlane32_swap_b32_e32 v125, v91
	v_permlane32_swap_b32_e32 v126, v92
	v_permlane32_swap_b32_e32 v127, v93
	v_permlane16_swap_b32_e32 v124, v90
	v_permlane16_swap_b32_e32 v125, v91
	v_permlane16_swap_b32_e32 v126, v92
	v_permlane16_swap_b32_e32 v127, v93
	v_sub_f32_e32 v61, v125, v117
	v_sub_f32_e32 v60, v124, v117
	v_sub_f32_e32 v63, v127, v117
	v_sub_f32_e32 v62, v126, v117
	v_pk_mul_f32 v[62:63], v[116:117], v[62:63] op_sel_hi:[0,1]
	v_pk_mul_f32 v[60:61], v[116:117], v[60:61] op_sel_hi:[0,1]
	v_pk_fma_f32 v[60:61], v[132:133], v[60:61], v[162:163]
	v_pk_fma_f32 v[62:63], v[134:135], v[62:63], v[164:165]
	v_pk_fma_f32 v[54:55], v[60:61], s[14:15], v[54:55] op_sel_hi:[1,0,1]
	v_pk_fma_f32 v[56:57], v[62:63], s[14:15], v[56:57] op_sel_hi:[1,0,1]
	v_add_f32_e32 v78, 0, v78
	v_add_f32_e32 v60, v54, v55
	v_add_f32_e32 v61, v56, v57
	v_add_f32_e32 v66, v78, v66
	v_add_f32_e32 v60, v60, v61
	v_add_f32_e32 v64, v66, v60
	v_mul_f32_e32 v60, v55, v55
	v_mul_f32_e32 v61, v57, v57
	v_add_f32_e32 v79, v79, v80
	v_add_f32_e32 v67, v67, v68
	v_fmac_f32_e32 v60, v54, v54
	v_fmac_f32_e32 v61, v56, v56
	v_add_f32_e32 v67, v79, v67
	v_add_f32_e32 v60, v60, v61
	v_add_f32_e32 v65, v67, v60
	v_sub_f32_e32 v61, v91, v117
	v_sub_f32_e32 v60, v90, v117
	v_sub_f32_e32 v63, v93, v117
	v_sub_f32_e32 v62, v92, v117
	v_pk_mul_f32 v[62:63], v[116:117], v[62:63] op_sel_hi:[0,1]
	v_pk_mul_f32 v[60:61], v[116:117], v[60:61] op_sel_hi:[0,1]
	v_pk_fma_f32 v[60:61], v[128:129], v[60:61], v[158:159]
	v_pk_fma_f32 v[62:63], v[130:131], v[62:63], v[160:161]
	v_pk_fma_f32 v[50:51], v[60:61], s[14:15], v[50:51] op_sel_hi:[1,0,1]
	v_pk_fma_f32 v[52:53], v[62:63], s[14:15], v[52:53] op_sel_hi:[1,0,1]
	v_add_f32_e32 v60, v50, v51
	v_add_f32_e32 v61, v52, v53
	v_add_f32_e32 v60, v60, v61
	v_mul_f32_e32 v61, v51, v51
	v_mul_f32_e32 v62, v53, v53
	v_add_f32_e32 v60, v64, v60
	v_fmac_f32_e32 v61, v50, v50
	v_fmac_f32_e32 v62, v52, v52
	v_lshl_add_u64 v[74:75], v[58:59], 0, s[28:29]
	s_nop 0
	s_nop 1
	v_bfe_u32 v67, v227, 4, 2
	v_sub_u32_e32 v66, 0, v67
	v_lshlrev_b32_e32 v66, 4, v66
	v_ashrrev_i32_e32 v67, 31, v66
	v_lshl_add_u64 v[66:67], v[122:123], 0, v[66:67]
	v_permlane16_swap_b32_e32 v54, v50
	v_permlane16_swap_b32_e32 v55, v51
	v_permlane16_swap_b32_e32 v56, v52
	v_permlane16_swap_b32_e32 v57, v53
	v_permlane32_swap_b32_e32 v54, v50
	v_permlane32_swap_b32_e32 v55, v51
	v_permlane32_swap_b32_e32 v56, v52
	v_permlane32_swap_b32_e32 v57, v53
	global_store_dwordx4 v[66:67], v[54:57], off offset:512
	global_store_dwordx4 v[66:67], v[50:53], off offset:576
	s_nop 1
	v_permlane32_swap_b32_e32 v54, v50
	v_permlane32_swap_b32_e32 v55, v51
	v_permlane32_swap_b32_e32 v56, v52
	v_permlane32_swap_b32_e32 v57, v53
	v_permlane16_swap_b32_e32 v54, v50
	v_permlane16_swap_b32_e32 v55, v51
	v_permlane16_swap_b32_e32 v56, v52
	v_permlane16_swap_b32_e32 v57, v53
	v_add_f32_e32 v61, v61, v62
	v_cvt_pk_bf16_f32 v54, v54, v55
	v_cvt_pk_bf16_f32 v55, v56, v57
	v_cvt_pk_bf16_f32 v56, v50, v51
	v_lshl_add_u64 v[50:51], v[74:75], 0, v[0:1]
	v_mov_b32_e32 v0, v60
	v_add_f32_e32 v61, v65, v61
	v_cvt_pk_bf16_f32 v57, v52, v53
	v_permlane16_swap_b32_e32 v60, v0
	global_store_dwordx4 v[50:51], v[54:57], off
	v_add_f32_e32 v50, v60, v0
	v_mov_b32_e32 v0, v61
	s_nop 1
	v_permlane16_swap_b32_e32 v61, v0
	v_add_f32_e32 v51, v61, v0
	v_mov_b32_e32 v52, v50
	v_mov_b32_e32 v53, v51
	s_nop 0
	v_permlane32_swap_b32_e32 v50, v52
	v_permlane32_swap_b32_e32 v51, v53
	s_and_saveexec_b64 s[24:25], s[44:45]
	s_cbranch_execz .LBB0_1545
	v_pk_add_f32 v[50:51], v[50:51], v[52:53]
	v_lshl_add_u64 v[52:53], s[6:7], 0, v[110:111]
	v_lshl_add_u64 v[52:53], s[52:53], 2, v[52:53]
	global_store_dwordx2 v[52:53], v[50:51], off
; __device__ __forceinline__ float xsum16(float v) { const auto r = __builtin_amdgcn_permlane16_swap(__float_as_uint(v), __float_as_uint(v), false, false); return __uint_as_float(r[0]) + __uint_as_float(r[1]); }
; __device__ __forceinline__ float xsum32(float v) { const auto r = __builtin_amdgcn_permlane32_swap(__float_as_uint(v), __float_as_uint(v), false, false); return __uint_as_float(r[0]) + __uint_as_float(r[1]); }
; __device__ __forceinline__ size_t blk_off(int r, int c, int K) { return (size_t)(r >> 8) * 256 * K + (size_t)(c >> 6) * (256 * 64) + (size_t)((r & 255) * 64 + (c & 63)); }
; __device__ __forceinline__ void row_stats4(const float* st, int rowb, int fq, float (&mu)[4], float (&rs)[4]) {
;     ...
;     for (int m = 0; m < 4; ++m) { float s1 = (a[m][0] + a[m][2]) + (b[m][0] + b[m][2]), s2 = (a[m][1] + a[m][3]) + (b[m][1] + b[m][3]);
;         s1 = xsum32(xsum16(s1)); s2 = xsum32(xsum16(s2));
;         const float mm = s1 * (1.0f / 1024.0f); mu[m] = mm; rs[m] = rsqrtf(fmaxf(s2 * (1.0f / 1024.0f) - mm * mm, 0.f) + LN_EPS_); }
;     __device__ __forceinline__ void operator()(const f32x4 (&acc)[2][2][4][2], const pg8::Unit& u, int wr, int wc, int fr, int fq) const {
;     ...
;             for (int m = 0; m < 4; ++m) { const int row = row0 + ai * 128 + m * 16; const float mu = mu4[m], rs = rs4[m];
;                 f32x4 yv[2][2], gq[2][2], bq_[2][2];
; #pragma unroll
;                 for (int bj = 0; bj < 2; ++bj)
; #pragma unroll
;                     for (int n = 0; n < 2; ++n) { yv[bj][n] = *(const f32x4*)(Yin + (size_t)row * D_ + col0 + bj * 128 + 4 * n); gq[bj][n] = *(const f32x4*)(g + col0 + bj * 128 + 4 * n); bq_[bj][n] = *(const f32x4*)(b + col0 + bj * 128 + 4 * n); }
;                 asm volatile("" ::: "memory");
;                 float s1 = 0.f, s2 = 0.f;
; #pragma unroll
;                 for (int bj = 0; bj < 2; ++bj) { float* yp = Y + (size_t)row * D_ + col0 + bj * 128; f32x4 v[2];
; #pragma unroll
;                     for (int n = 0; n < 2; ++n) { v[n] = (((yv[bj][n] - mu) * rs) * gq[bj][n] + bq_[bj][n]) * ALPHA_ + acc[ai][bj][m][n] * sc;
;                         *(f32x4*)(yp + 4 * n) = v[n]; s1 += (v[n][0] + v[n][1]) + (v[n][2] + v[n][3]); s2 += (v[n][0] * v[n][0] + v[n][1] * v[n][1]) + (v[n][2] * v[n][2] + v[n][3] * v[n][3]); }
;                     *(u32x4*)(Yb + blk_off(row, col0 + bj * 128, D_)) = pack8(v[0], v[1]); }
.LBB0_1545:
	s_or_b64 exec, exec, s[24:25]
	v_pk_add_f32 v[50:51], v[112:113], v[114:115]
	s_mov_b32 s2, 0x3a800000
	v_pk_mul_f32 v[78:79], v[50:51], s[2:3] op_sel_hi:[1,0]
	s_mov_b32 s1, 0x800000
	v_fma_f32 v0, -v79, v79, v78
	v_max_f32_e32 v0, 0, v0
	v_add_f32_e32 v0, 0x3727c5ac, v0
	v_cmp_gt_f32_e32 vcc, s1, v0
	v_mul_f32_e32 v50, 0x4b800000, v0
	s_load_dwordx16 s[64:79], s[34:35], 0x38
	v_cndmask_b32_e32 v0, v0, v50, vcc
	v_rsq_f32_e32 v0, v0
	s_mov_b32 s2, 0x3fd744fd
	s_movk_i32 s1, 0x37c0
	v_mul_f32_e32 v50, 0x45800000, v0
	v_cndmask_b32_e32 v78, v0, v50, vcc
	v_lshlrev_b64 v[50:51], 12, v[108:109]
	s_waitcnt lgkmcnt(0)
	v_lshl_add_u64 v[50:51], s[78:79], 0, v[50:51]
	v_lshl_add_u64 v[80:81], v[152:153], 2, v[50:51]
	s_nop 1
	v_bfe_u32 v53, v227, 4, 2
	v_sub_u32_e32 v52, 0, v53
	v_lshlrev_b32_e32 v52, 4, v52
	v_ashrrev_i32_e32 v53, 31, v52
	v_lshl_add_u64 v[52:53], v[80:81], 0, v[52:53]
	global_load_dwordx4 v[82:85], v[52:53], off offset:64
	global_load_dwordx4 v[86:89], v[52:53], off
	s_nop 1
	v_lshrrev_b32_e32 v0, 4, v227
	v_lshlrev_b32_e32 v0, 7, v0
	v_add_u32_e32 v0, 0x20100, v0
	ds_read_b128 v[90:93], v0 offset:16
	ds_read_b128 v[110:113], v0 offset:0
	ds_read_b128 v[114:117], v0 offset:80
	ds_read_b128 v[118:121], v0 offset:64
	s_nop 1
	v_bfe_u32 v55, v227, 4, 2
	v_sub_u32_e32 v54, 0, v55
	v_lshlrev_b32_e32 v54, 4, v54
	v_ashrrev_i32_e32 v55, 31, v54
	v_lshl_add_u64 v[54:55], v[80:81], 0, v[54:55]
	global_load_dwordx4 v[50:53], v[54:55], off offset:576
	global_load_dwordx4 v[70:73], v[54:55], off offset:512
	ds_read_b128 v[54:57], v0 offset:48
	ds_read_b128 v[62:65], v0 offset:32
	ds_read_b128 v[58:61], v0 offset:112
	ds_read_b128 v[66:69], v0 offset:96
	v_lshlrev_b32_e32 v0, 6, v108
	v_and_or_b32 v0, v0, s1, v196
	v_lshlrev_b32_e32 v0, 1, v0
	s_waitcnt vmcnt(2)
	v_permlane32_swap_b32_e32 v86, v82
	v_permlane32_swap_b32_e32 v87, v83
	v_permlane32_swap_b32_e32 v88, v84
	v_permlane32_swap_b32_e32 v89, v85
	v_permlane16_swap_b32_e32 v86, v82
	v_permlane16_swap_b32_e32 v87, v83
	v_permlane16_swap_b32_e32 v88, v84
	v_permlane16_swap_b32_e32 v89, v85
	v_sub_f32_e32 v87, v87, v79
	v_sub_f32_e32 v86, v86, v79
	v_sub_f32_e32 v89, v89, v79
	v_sub_f32_e32 v88, v88, v79
	v_pk_mul_f32 v[88:89], v[78:79], v[88:89] op_sel_hi:[0,1]
	v_pk_mul_f32 v[86:87], v[78:79], v[86:87] op_sel_hi:[0,1]
	s_waitcnt lgkmcnt(0)
	v_pk_fma_f32 v[86:87], v[110:111], v[86:87], v[118:119]
	v_pk_fma_f32 v[88:89], v[112:113], v[88:89], v[120:121]
	v_pk_fma_f32 v[86:87], v[86:87], s[2:3], v[46:47] op_sel_hi:[1,0,1]
	v_pk_fma_f32 v[88:89], v[88:89], s[2:3], v[48:49] op_sel_hi:[1,0,1]
	v_add_f32_e32 v46, v86, v87
	v_add_f32_e32 v47, v88, v89
	v_add_f32_e32 v46, v46, v47
	v_add_f32_e32 v108, 0, v46
	v_mul_f32_e32 v46, v87, v87
	v_mul_f32_e32 v47, v89, v89
	v_fmac_f32_e32 v46, v86, v86
	v_fmac_f32_e32 v47, v88, v88
	v_add_f32_e32 v109, v46, v47
	v_sub_f32_e32 v47, v83, v79
	v_sub_f32_e32 v46, v82, v79
	v_sub_f32_e32 v49, v85, v79
	v_sub_f32_e32 v48, v84, v79
	v_pk_mul_f32 v[48:49], v[78:79], v[48:49] op_sel_hi:[0,1]
	v_pk_mul_f32 v[46:47], v[78:79], v[46:47] op_sel_hi:[0,1]
	v_pk_fma_f32 v[46:47], v[90:91], v[46:47], v[114:115]
	v_pk_fma_f32 v[48:49], v[92:93], v[48:49], v[116:117]
	v_pk_fma_f32 v[82:83], v[46:47], s[2:3], v[42:43] op_sel_hi:[1,0,1]
	v_pk_fma_f32 v[84:85], v[48:49], s[2:3], v[44:45] op_sel_hi:[1,0,1]
	v_add_f32_e32 v42, v82, v83
	v_add_f32_e32 v43, v84, v85
	v_add_f32_e32 v42, v42, v43
	v_add_f32_e32 v47, v108, v42
	v_mul_f32_e32 v42, v83, v83
	v_mul_f32_e32 v43, v85, v85
	v_fmac_f32_e32 v42, v82, v82
	v_fmac_f32_e32 v43, v84, v84
	v_add_f32_e32 v42, v42, v43
	v_add_f32_e32 v46, v109, v42
	v_cvt_pk_bf16_f32 v42, v86, v87
	v_cvt_pk_bf16_f32 v43, v88, v89
	v_cvt_pk_bf16_f32 v44, v82, v83
	v_cvt_pk_bf16_f32 v45, v84, v85
	v_lshl_add_u64 v[48:49], v[76:77], 0, v[0:1]
	s_nop 0
	s_nop 1
	v_bfe_u32 v91, v227, 4, 2
	v_sub_u32_e32 v90, 0, v91
	v_lshlrev_b32_e32 v90, 4, v90
	v_ashrrev_i32_e32 v91, 31, v90
	v_lshl_add_u64 v[90:91], v[80:81], 0, v[90:91]
	v_permlane16_swap_b32_e32 v86, v82
	v_permlane16_swap_b32_e32 v87, v83
	v_permlane16_swap_b32_e32 v88, v84
	v_permlane16_swap_b32_e32 v89, v85
	v_permlane32_swap_b32_e32 v86, v82
	v_permlane32_swap_b32_e32 v87, v83
	v_permlane32_swap_b32_e32 v88, v84
	v_permlane32_swap_b32_e32 v89, v85
	global_store_dwordx4 v[90:91], v[86:89], off
	global_store_dwordx4 v[90:91], v[82:85], off offset:64
	s_nop 1
	v_permlane32_swap_b32_e32 v86, v82
	v_permlane32_swap_b32_e32 v87, v83
	v_permlane32_swap_b32_e32 v88, v84
	v_permlane32_swap_b32_e32 v89, v85
	v_permlane16_swap_b32_e32 v86, v82
	v_permlane16_swap_b32_e32 v87, v83
	v_permlane16_swap_b32_e32 v88, v84
	v_permlane16_swap_b32_e32 v89, v85
	global_store_dwordx4 v[48:49], v[42:45], off
	s_nop 0
	s_waitcnt vmcnt(3)
; __device__ __forceinline__ float xsum16(float v) { const auto r = __builtin_amdgcn_permlane16_swap(__float_as_uint(v), __float_as_uint(v), false, false); return __uint_as_float(r[0]) + __uint_as_float(r[1]); }
; __device__ __forceinline__ float xsum32(float v) { const auto r = __builtin_amdgcn_permlane32_swap(__float_as_uint(v), __float_as_uint(v), false, false); return __uint_as_float(r[0]) + __uint_as_float(r[1]); }
; __device__ __forceinline__ size_t blk_off(int r, int c, int K) { return (size_t)(r >> 8) * 256 * K + (size_t)(c >> 6) * (256 * 64) + (size_t)((r & 255) * 64 + (c & 63)); }
; __device__ __forceinline__ u32x4 pack8(const f32x4 a, const f32x4 b) { u32x4 w; w.x = cvt_pk_bf16(a[0], a[1]); w.y = cvt_pk_bf16(a[2], a[3]); w.z = cvt_pk_bf16(b[0], b[1]); w.w = cvt_pk_bf16(b[2], b[3]); return w; }
;     __device__ __forceinline__ void operator()(const f32x4 (&acc)[2][2][4][2], const pg8::Unit& u, int wr, int wc, int fr, int fq) const {
;     ...
;             for (int m = 0; m < 4; ++m) { const int row = row0 + ai * 128 + m * 16; const float mu = mu4[m], rs = rs4[m];
;                 f32x4 yv[2][2], gq[2][2], bq_[2][2];
; #pragma unroll
;                 for (int bj = 0; bj < 2; ++bj)
; #pragma unroll
;                     for (int n = 0; n < 2; ++n) { yv[bj][n] = *(const f32x4*)(Yin + (size_t)row * D_ + col0 + bj * 128 + 4 * n); gq[bj][n] = *(const f32x4*)(g + col0 + bj * 128 + 4 * n); bq_[bj][n] = *(const f32x4*)(b + col0 + bj * 128 + 4 * n); }
;                 asm volatile("" ::: "memory");
;                 float s1 = 0.f, s2 = 0.f;
; #pragma unroll
;                 for (int bj = 0; bj < 2; ++bj) { float* yp = Y + (size_t)row * D_ + col0 + bj * 128; f32x4 v[2];
; #pragma unroll
;                     for (int n = 0; n < 2; ++n) { v[n] = (((yv[bj][n] - mu) * rs) * gq[bj][n] + bq_[bj][n]) * ALPHA_ + acc[ai][bj][m][n] * sc;
;                         *(f32x4*)(yp + 4 * n) = v[n]; s1 += (v[n][0] + v[n][1]) + (v[n][2] + v[n][3]); s2 += (v[n][0] * v[n][0] + v[n][1] * v[n][1]) + (v[n][2] * v[n][2] + v[n][3] * v[n][3]); }
;                     *(u32x4*)(Yb + blk_off(row, col0 + bj * 128, D_)) = pack8(v[0], v[1]); }
;                 s1 = xsum32(xsum16(s1)); s2 = xsum32(xsum16(s2));
;                 if (fq == 0) *(f32x2*)(stn + (size_t)row * 32 + (u.pn * 4 + wc) * 2) = (f32x2){s1, s2}; asm volatile("" ::: "memory"); } }
	v_permlane32_swap_b32_e32 v70, v50
	v_permlane32_swap_b32_e32 v71, v51
	v_permlane32_swap_b32_e32 v72, v52
	v_permlane32_swap_b32_e32 v73, v53
	v_permlane16_swap_b32_e32 v70, v50
	v_permlane16_swap_b32_e32 v71, v51
	v_permlane16_swap_b32_e32 v72, v52
	v_permlane16_swap_b32_e32 v73, v53
	v_sub_f32_e32 v43, v71, v79
	v_sub_f32_e32 v42, v70, v79
	v_sub_f32_e32 v45, v73, v79
	v_sub_f32_e32 v44, v72, v79
	v_pk_mul_f32 v[44:45], v[78:79], v[44:45] op_sel_hi:[0,1]
	v_pk_mul_f32 v[42:43], v[78:79], v[42:43] op_sel_hi:[0,1]
	v_pk_fma_f32 v[42:43], v[62:63], v[42:43], v[66:67]
	v_pk_fma_f32 v[44:45], v[64:65], v[44:45], v[68:69]
	v_pk_fma_f32 v[38:39], v[42:43], s[2:3], v[38:39] op_sel_hi:[1,0,1]
	v_pk_fma_f32 v[40:41], v[44:45], s[2:3], v[40:41] op_sel_hi:[1,0,1]
	v_add_f32_e32 v42, v38, v39
	v_add_f32_e32 v43, v40, v41
	v_add_f32_e32 v42, v42, v43
	v_add_f32_e32 v47, v47, v42
	v_mul_f32_e32 v42, v39, v39
	v_mul_f32_e32 v43, v41, v41
	v_fmac_f32_e32 v42, v38, v38
	v_fmac_f32_e32 v43, v40, v40
	v_add_f32_e32 v42, v42, v43
	v_add_f32_e32 v46, v46, v42
	v_sub_f32_e32 v43, v51, v79
	v_sub_f32_e32 v42, v50, v79
	v_sub_f32_e32 v45, v53, v79
	v_sub_f32_e32 v44, v52, v79
	v_pk_mul_f32 v[44:45], v[78:79], v[44:45] op_sel_hi:[0,1]
	v_pk_mul_f32 v[42:43], v[78:79], v[42:43] op_sel_hi:[0,1]
	v_pk_fma_f32 v[42:43], v[54:55], v[42:43], v[58:59]
	v_pk_fma_f32 v[44:45], v[56:57], v[44:45], v[60:61]
	v_pk_fma_f32 v[34:35], v[42:43], s[2:3], v[34:35] op_sel_hi:[1,0,1]
	v_pk_fma_f32 v[36:37], v[44:45], s[2:3], v[36:37] op_sel_hi:[1,0,1]
	v_add_f32_e32 v42, v34, v35
	v_add_f32_e32 v43, v36, v37
	v_add_f32_e32 v42, v42, v43
	v_mul_f32_e32 v43, v35, v35
	v_mul_f32_e32 v44, v37, v37
	v_add_f32_e32 v42, v47, v42
	v_fmac_f32_e32 v43, v34, v34
	v_fmac_f32_e32 v44, v36, v36
	s_nop 0
	s_nop 1
	v_bfe_u32 v49, v227, 4, 2
	v_sub_u32_e32 v48, 0, v49
	v_lshlrev_b32_e32 v48, 4, v48
	v_ashrrev_i32_e32 v49, 31, v48
	v_lshl_add_u64 v[48:49], v[80:81], 0, v[48:49]
	v_permlane16_swap_b32_e32 v38, v34
	v_permlane16_swap_b32_e32 v39, v35
	v_permlane16_swap_b32_e32 v40, v36
	v_permlane16_swap_b32_e32 v41, v37
	v_permlane32_swap_b32_e32 v38, v34
	v_permlane32_swap_b32_e32 v39, v35
	v_permlane32_swap_b32_e32 v40, v36
	v_permlane32_swap_b32_e32 v41, v37
	global_store_dwordx4 v[48:49], v[38:41], off offset:512
	global_store_dwordx4 v[48:49], v[34:37], off offset:576
	s_nop 1
	v_permlane32_swap_b32_e32 v38, v34
	v_permlane32_swap_b32_e32 v39, v35
	v_permlane32_swap_b32_e32 v40, v36
	v_permlane32_swap_b32_e32 v41, v37
	v_permlane16_swap_b32_e32 v38, v34
	v_permlane16_swap_b32_e32 v39, v35
	v_permlane16_swap_b32_e32 v40, v36
	v_permlane16_swap_b32_e32 v41, v37
	v_add_f32_e32 v43, v43, v44
	v_cvt_pk_bf16_f32 v38, v38, v39
	v_cvt_pk_bf16_f32 v39, v40, v41
	v_cvt_pk_bf16_f32 v40, v34, v35
	v_lshl_add_u64 v[34:35], v[74:75], 0, v[0:1]
	v_mov_b32_e32 v0, v42
	v_add_f32_e32 v43, v46, v43
	v_cvt_pk_bf16_f32 v41, v36, v37
	v_permlane16_swap_b32_e32 v42, v0
	global_store_dwordx4 v[34:35], v[38:41], off
	v_add_f32_e32 v34, v42, v0
	v_mov_b32_e32 v0, v43
	s_nop 1
	v_permlane16_swap_b32_e32 v43, v0
	v_add_f32_e32 v35, v43, v0
	v_mov_b32_e32 v36, v34
	v_mov_b32_e32 v37, v35
	s_nop 0
	v_permlane32_swap_b32_e32 v34, v36
	v_permlane32_swap_b32_e32 v35, v37
	s_and_saveexec_b64 s[24:25], s[44:45]
	s_cbranch_execz .LBB0_1547
	v_pk_add_f32 v[34:35], v[34:35], v[36:37]
	v_lshl_add_u64 v[36:37], s[6:7], 0, v[102:103]
	v_lshl_add_u64 v[36:37], s[52:53], 2, v[36:37]
	global_store_dwordx2 v[36:37], v[34:35], off
.LBB0_1547:
	s_or_b64 exec, exec, s[24:25]
	v_pk_add_f32 v[34:35], v[104:105], v[106:107]
	s_mov_b32 s2, 0x3a800000
	v_pk_mul_f32 v[58:59], v[34:35], s[2:3] op_sel_hi:[1,0]
	s_mov_b32 s1, 0x800000
	v_fma_f32 v0, -v59, v59, v58
	v_max_f32_e32 v0, 0, v0
	v_add_f32_e32 v0, 0x3727c5ac, v0
	v_cmp_gt_f32_e32 vcc, s1, v0
	v_mul_f32_e32 v34, 0x4b800000, v0
	s_load_dwordx16 s[64:79], s[34:35], 0x38
	v_cndmask_b32_e32 v0, v0, v34, vcc
	v_rsq_f32_e32 v0, v0
	s_mov_b32 s2, 0x3fd744fd
	s_movk_i32 s1, 0x3bc0
	v_mul_f32_e32 v34, 0x45800000, v0
	v_cndmask_b32_e32 v58, v0, v34, vcc
	v_lshlrev_b64 v[34:35], 12, v[96:97]
	s_waitcnt lgkmcnt(0)
	v_lshl_add_u64 v[34:35], s[78:79], 0, v[34:35]
	v_lshl_add_u64 v[60:61], v[152:153], 2, v[34:35]
	s_nop 1
	v_bfe_u32 v37, v227, 4, 2
	v_sub_u32_e32 v36, 0, v37
	v_lshlrev_b32_e32 v36, 4, v36
	v_ashrrev_i32_e32 v37, 31, v36
	v_lshl_add_u64 v[36:37], v[60:61], 0, v[36:37]
	global_load_dwordx4 v[62:65], v[36:37], off offset:64
	global_load_dwordx4 v[66:69], v[36:37], off
	s_nop 1
	v_lshrrev_b32_e32 v0, 4, v227
	v_lshlrev_b32_e32 v0, 7, v0
	v_add_u32_e32 v0, 0x20100, v0
	ds_read_b128 v[70:73], v0 offset:16
	ds_read_b128 v[78:81], v0 offset:0
	ds_read_b128 v[82:85], v0 offset:80
	ds_read_b128 v[86:89], v0 offset:64
	s_nop 1
	v_bfe_u32 v39, v227, 4, 2
	v_sub_u32_e32 v38, 0, v39
	v_lshlrev_b32_e32 v38, 4, v38
	v_ashrrev_i32_e32 v39, 31, v38
	v_lshl_add_u64 v[38:39], v[60:61], 0, v[38:39]
	global_load_dwordx4 v[34:37], v[38:39], off offset:576
	global_load_dwordx4 v[54:57], v[38:39], off offset:512
	ds_read_b128 v[38:41], v0 offset:48
	ds_read_b128 v[46:49], v0 offset:32
	ds_read_b128 v[42:45], v0 offset:112
	ds_read_b128 v[50:53], v0 offset:96
	v_lshlrev_b32_e32 v0, 6, v96
	v_and_or_b32 v0, v0, s1, v196
	v_lshlrev_b32_e32 v0, 1, v0
	s_waitcnt vmcnt(2)
	v_permlane32_swap_b32_e32 v66, v62
	v_permlane32_swap_b32_e32 v67, v63
	v_permlane32_swap_b32_e32 v68, v64
	v_permlane32_swap_b32_e32 v69, v65
	v_permlane16_swap_b32_e32 v66, v62
	v_permlane16_swap_b32_e32 v67, v63
	v_permlane16_swap_b32_e32 v68, v64
	v_permlane16_swap_b32_e32 v69, v65
	v_sub_f32_e32 v67, v67, v59
	v_sub_f32_e32 v66, v66, v59
	v_sub_f32_e32 v69, v69, v59
	v_sub_f32_e32 v68, v68, v59
	v_pk_mul_f32 v[68:69], v[58:59], v[68:69] op_sel_hi:[0,1]
	v_pk_mul_f32 v[66:67], v[58:59], v[66:67] op_sel_hi:[0,1]
	s_waitcnt lgkmcnt(0)
; __device__ __forceinline__ float xsum16(float v) { const auto r = __builtin_amdgcn_permlane16_swap(__float_as_uint(v), __float_as_uint(v), false, false); return __uint_as_float(r[0]) + __uint_as_float(r[1]); }
; __device__ __forceinline__ float xsum32(float v) { const auto r = __builtin_amdgcn_permlane32_swap(__float_as_uint(v), __float_as_uint(v), false, false); return __uint_as_float(r[0]) + __uint_as_float(r[1]); }
; __device__ __forceinline__ size_t blk_off(int r, int c, int K) { return (size_t)(r >> 8) * 256 * K + (size_t)(c >> 6) * (256 * 64) + (size_t)((r & 255) * 64 + (c & 63)); }
; __device__ __forceinline__ u32x4 pack8(const f32x4 a, const f32x4 b) { u32x4 w; w.x = cvt_pk_bf16(a[0], a[1]); w.y = cvt_pk_bf16(a[2], a[3]); w.z = cvt_pk_bf16(b[0], b[1]); w.w = cvt_pk_bf16(b[2], b[3]); return w; }
;     __device__ __forceinline__ void operator()(const f32x4 (&acc)[2][2][4][2], const pg8::Unit& u, int wr, int wc, int fr, int fq) const {
;     ...
;                 for (int bj = 0; bj < 2; ++bj) { float* yp = Y + (size_t)row * D_ + col0 + bj * 128; f32x4 v[2];
; #pragma unroll
;                     for (int n = 0; n < 2; ++n) { v[n] = (((yv[bj][n] - mu) * rs) * gq[bj][n] + bq_[bj][n]) * ALPHA_ + acc[ai][bj][m][n] * sc;
;                         *(f32x4*)(yp + 4 * n) = v[n]; s1 += (v[n][0] + v[n][1]) + (v[n][2] + v[n][3]); s2 += (v[n][0] * v[n][0] + v[n][1] * v[n][1]) + (v[n][2] * v[n][2] + v[n][3] * v[n][3]); }
;                     *(u32x4*)(Yb + blk_off(row, col0 + bj * 128, D_)) = pack8(v[0], v[1]); }
;                 s1 = xsum32(xsum16(s1)); s2 = xsum32(xsum16(s2));
;                 if (fq == 0) *(f32x2*)(stn + (size_t)row * 32 + (u.pn * 4 + wc) * 2) = (f32x2){s1, s2}; asm volatile("" ::: "memory"); } }
	v_pk_fma_f32 v[66:67], v[78:79], v[66:67], v[86:87]
	v_pk_fma_f32 v[68:69], v[80:81], v[68:69], v[88:89]
	v_pk_fma_f32 v[66:67], v[66:67], s[2:3], v[30:31] op_sel_hi:[1,0,1]
	v_pk_fma_f32 v[68:69], v[68:69], s[2:3], v[32:33] op_sel_hi:[1,0,1]
	v_add_f32_e32 v30, v66, v67
	v_add_f32_e32 v31, v68, v69
	v_add_f32_e32 v30, v30, v31
	v_add_f32_e32 v78, 0, v30
	v_mul_f32_e32 v30, v67, v67
	v_mul_f32_e32 v31, v69, v69
	v_fmac_f32_e32 v30, v66, v66
	v_fmac_f32_e32 v31, v68, v68
	v_add_f32_e32 v79, v30, v31
	v_sub_f32_e32 v31, v63, v59
	v_sub_f32_e32 v30, v62, v59
	v_sub_f32_e32 v33, v65, v59
	v_sub_f32_e32 v32, v64, v59
	v_pk_mul_f32 v[32:33], v[58:59], v[32:33] op_sel_hi:[0,1]
	v_pk_mul_f32 v[30:31], v[58:59], v[30:31] op_sel_hi:[0,1]
	v_pk_fma_f32 v[30:31], v[70:71], v[30:31], v[82:83]
	v_pk_fma_f32 v[32:33], v[72:73], v[32:33], v[84:85]
	v_pk_fma_f32 v[62:63], v[30:31], s[2:3], v[26:27] op_sel_hi:[1,0,1]
	v_pk_fma_f32 v[64:65], v[32:33], s[2:3], v[28:29] op_sel_hi:[1,0,1]
	v_add_f32_e32 v26, v62, v63
	v_add_f32_e32 v27, v64, v65
	v_add_f32_e32 v26, v26, v27
	v_add_f32_e32 v31, v78, v26
	v_mul_f32_e32 v26, v63, v63
	v_mul_f32_e32 v27, v65, v65
	v_fmac_f32_e32 v26, v62, v62
	v_fmac_f32_e32 v27, v64, v64
	v_add_f32_e32 v26, v26, v27
	v_add_f32_e32 v30, v79, v26
	v_cvt_pk_bf16_f32 v26, v66, v67
	v_cvt_pk_bf16_f32 v27, v68, v69
	v_cvt_pk_bf16_f32 v28, v62, v63
	v_cvt_pk_bf16_f32 v29, v64, v65
	v_lshl_add_u64 v[32:33], v[76:77], 0, v[0:1]
	s_nop 0
	s_nop 1
	v_bfe_u32 v71, v227, 4, 2
	v_sub_u32_e32 v70, 0, v71
	v_lshlrev_b32_e32 v70, 4, v70
	v_ashrrev_i32_e32 v71, 31, v70
	v_lshl_add_u64 v[70:71], v[60:61], 0, v[70:71]
	v_permlane16_swap_b32_e32 v66, v62
	v_permlane16_swap_b32_e32 v67, v63
	v_permlane16_swap_b32_e32 v68, v64
	v_permlane16_swap_b32_e32 v69, v65
	v_permlane32_swap_b32_e32 v66, v62
	v_permlane32_swap_b32_e32 v67, v63
	v_permlane32_swap_b32_e32 v68, v64
	v_permlane32_swap_b32_e32 v69, v65
	global_store_dwordx4 v[70:71], v[66:69], off
	global_store_dwordx4 v[70:71], v[62:65], off offset:64
	s_nop 1
	v_permlane32_swap_b32_e32 v66, v62
	v_permlane32_swap_b32_e32 v67, v63
	v_permlane32_swap_b32_e32 v68, v64
	v_permlane32_swap_b32_e32 v69, v65
	v_permlane16_swap_b32_e32 v66, v62
	v_permlane16_swap_b32_e32 v67, v63
	v_permlane16_swap_b32_e32 v68, v64
	v_permlane16_swap_b32_e32 v69, v65
	global_store_dwordx4 v[32:33], v[26:29], off
	s_nop 0
	s_waitcnt vmcnt(3)
	v_permlane32_swap_b32_e32 v54, v34
	v_permlane32_swap_b32_e32 v55, v35
	v_permlane32_swap_b32_e32 v56, v36
	v_permlane32_swap_b32_e32 v57, v37
	v_permlane16_swap_b32_e32 v54, v34
	v_permlane16_swap_b32_e32 v55, v35
	v_permlane16_swap_b32_e32 v56, v36
	v_permlane16_swap_b32_e32 v57, v37
	v_sub_f32_e32 v27, v55, v59
	v_sub_f32_e32 v26, v54, v59
	v_sub_f32_e32 v29, v57, v59
	v_sub_f32_e32 v28, v56, v59
	v_pk_mul_f32 v[28:29], v[58:59], v[28:29] op_sel_hi:[0,1]
	v_pk_mul_f32 v[26:27], v[58:59], v[26:27] op_sel_hi:[0,1]
	v_pk_fma_f32 v[26:27], v[46:47], v[26:27], v[50:51]
	v_pk_fma_f32 v[28:29], v[48:49], v[28:29], v[52:53]
	v_pk_fma_f32 v[22:23], v[26:27], s[2:3], v[22:23] op_sel_hi:[1,0,1]
	v_pk_fma_f32 v[24:25], v[28:29], s[2:3], v[24:25] op_sel_hi:[1,0,1]
	v_add_f32_e32 v26, v22, v23
	v_add_f32_e32 v27, v24, v25
	v_add_f32_e32 v26, v26, v27
	v_add_f32_e32 v31, v31, v26
	v_mul_f32_e32 v26, v23, v23
	v_mul_f32_e32 v27, v25, v25
	v_fmac_f32_e32 v26, v22, v22
	v_fmac_f32_e32 v27, v24, v24
	v_add_f32_e32 v26, v26, v27
	v_add_f32_e32 v30, v30, v26
	v_sub_f32_e32 v27, v35, v59
	v_sub_f32_e32 v26, v34, v59
	v_sub_f32_e32 v29, v37, v59
	v_sub_f32_e32 v28, v36, v59
	v_pk_mul_f32 v[28:29], v[58:59], v[28:29] op_sel_hi:[0,1]
	v_pk_mul_f32 v[26:27], v[58:59], v[26:27] op_sel_hi:[0,1]
	v_pk_fma_f32 v[26:27], v[38:39], v[26:27], v[42:43]
	v_pk_fma_f32 v[28:29], v[40:41], v[28:29], v[44:45]
	v_pk_fma_f32 v[18:19], v[26:27], s[2:3], v[18:19] op_sel_hi:[1,0,1]
	v_pk_fma_f32 v[20:21], v[28:29], s[2:3], v[20:21] op_sel_hi:[1,0,1]
	v_add_f32_e32 v26, v18, v19
	v_add_f32_e32 v27, v20, v21
	v_add_f32_e32 v26, v26, v27
	v_mul_f32_e32 v27, v19, v19
	v_mul_f32_e32 v28, v21, v21
	v_add_f32_e32 v26, v31, v26
	v_fmac_f32_e32 v27, v18, v18
	v_fmac_f32_e32 v28, v20, v20
	s_nop 0
	s_nop 1
	v_bfe_u32 v33, v227, 4, 2
	v_sub_u32_e32 v32, 0, v33
	v_lshlrev_b32_e32 v32, 4, v32
	v_ashrrev_i32_e32 v33, 31, v32
	v_lshl_add_u64 v[32:33], v[60:61], 0, v[32:33]
	v_permlane16_swap_b32_e32 v22, v18
	v_permlane16_swap_b32_e32 v23, v19
	v_permlane16_swap_b32_e32 v24, v20
	v_permlane16_swap_b32_e32 v25, v21
	v_permlane32_swap_b32_e32 v22, v18
	v_permlane32_swap_b32_e32 v23, v19
	v_permlane32_swap_b32_e32 v24, v20
	v_permlane32_swap_b32_e32 v25, v21
	global_store_dwordx4 v[32:33], v[22:25], off offset:512
	global_store_dwordx4 v[32:33], v[18:21], off offset:576
	s_nop 1
	v_permlane32_swap_b32_e32 v22, v18
	v_permlane32_swap_b32_e32 v23, v19
	v_permlane32_swap_b32_e32 v24, v20
	v_permlane32_swap_b32_e32 v25, v21
	v_permlane16_swap_b32_e32 v22, v18
	v_permlane16_swap_b32_e32 v23, v19
	v_permlane16_swap_b32_e32 v24, v20
	v_permlane16_swap_b32_e32 v25, v21
	v_add_f32_e32 v27, v27, v28
	v_cvt_pk_bf16_f32 v22, v22, v23
	v_cvt_pk_bf16_f32 v23, v24, v25
	v_cvt_pk_bf16_f32 v24, v18, v19
	v_lshl_add_u64 v[18:19], v[74:75], 0, v[0:1]
	v_mov_b32_e32 v0, v26
	v_add_f32_e32 v27, v30, v27
	v_cvt_pk_bf16_f32 v25, v20, v21
	v_permlane16_swap_b32_e32 v26, v0
	global_store_dwordx4 v[18:19], v[22:25], off
	v_add_f32_e32 v18, v26, v0
	v_mov_b32_e32 v0, v27
	s_nop 1
	v_permlane16_swap_b32_e32 v27, v0
	v_add_f32_e32 v19, v27, v0
	v_mov_b32_e32 v20, v18
	v_mov_b32_e32 v21, v19
	s_nop 0
	v_permlane32_swap_b32_e32 v18, v20
	v_permlane32_swap_b32_e32 v19, v21
	s_and_saveexec_b64 s[24:25], s[44:45]
	s_cbranch_execz .LBB0_1549
	v_pk_add_f32 v[18:19], v[18:19], v[20:21]
	v_lshlrev_b64 v[20:21], 7, v[96:97]
	v_lshl_add_u64 v[20:21], s[6:7], 0, v[20:21]
	v_lshl_add_u64 v[20:21], s[52:53], 2, v[20:21]
	global_store_dwordx2 v[20:21], v[18:19], off
; __device__ __forceinline__ float xsum16(float v) { const auto r = __builtin_amdgcn_permlane16_swap(__float_as_uint(v), __float_as_uint(v), false, false); return __uint_as_float(r[0]) + __uint_as_float(r[1]); }
; __device__ __forceinline__ float xsum32(float v) { const auto r = __builtin_amdgcn_permlane32_swap(__float_as_uint(v), __float_as_uint(v), false, false); return __uint_as_float(r[0]) + __uint_as_float(r[1]); }
; __device__ __forceinline__ size_t blk_off(int r, int c, int K) { return (size_t)(r >> 8) * 256 * K + (size_t)(c >> 6) * (256 * 64) + (size_t)((r & 255) * 64 + (c & 63)); }
; __device__ __forceinline__ void row_stats4(const float* st, int rowb, int fq, float (&mu)[4], float (&rs)[4]) {
;     ...
;     for (int m = 0; m < 4; ++m) { float s1 = (a[m][0] + a[m][2]) + (b[m][0] + b[m][2]), s2 = (a[m][1] + a[m][3]) + (b[m][1] + b[m][3]);
;         s1 = xsum32(xsum16(s1)); s2 = xsum32(xsum16(s2));
;         const float mm = s1 * (1.0f / 1024.0f); mu[m] = mm; rs[m] = rsqrtf(fmaxf(s2 * (1.0f / 1024.0f) - mm * mm, 0.f) + LN_EPS_); }
;     __device__ __forceinline__ void operator()(const f32x4 (&acc)[2][2][4][2], const pg8::Unit& u, int wr, int wc, int fr, int fq) const {
;     ...
;             for (int m = 0; m < 4; ++m) { const int row = row0 + ai * 128 + m * 16; const float mu = mu4[m], rs = rs4[m];
;                 f32x4 yv[2][2], gq[2][2], bq_[2][2];
; #pragma unroll
;                 for (int bj = 0; bj < 2; ++bj)
; #pragma unroll
;                     for (int n = 0; n < 2; ++n) { yv[bj][n] = *(const f32x4*)(Yin + (size_t)row * D_ + col0 + bj * 128 + 4 * n); gq[bj][n] = *(const f32x4*)(g + col0 + bj * 128 + 4 * n); bq_[bj][n] = *(const f32x4*)(b + col0 + bj * 128 + 4 * n); }
;                 asm volatile("" ::: "memory");
;                 float s1 = 0.f, s2 = 0.f;
; #pragma unroll
;                 for (int bj = 0; bj < 2; ++bj) { float* yp = Y + (size_t)row * D_ + col0 + bj * 128; f32x4 v[2];
; #pragma unroll
;                     for (int n = 0; n < 2; ++n) { v[n] = (((yv[bj][n] - mu) * rs) * gq[bj][n] + bq_[bj][n]) * ALPHA_ + acc[ai][bj][m][n] * sc;
;                         *(f32x4*)(yp + 4 * n) = v[n]; s1 += (v[n][0] + v[n][1]) + (v[n][2] + v[n][3]); s2 += (v[n][0] * v[n][0] + v[n][1] * v[n][1]) + (v[n][2] * v[n][2] + v[n][3] * v[n][3]); }
;                     *(u32x4*)(Yb + blk_off(row, col0 + bj * 128, D_)) = pack8(v[0], v[1]); }
.LBB0_1549:
	s_or_b64 exec, exec, s[24:25]
	v_pk_add_f32 v[18:19], v[98:99], v[100:101]
	s_mov_b32 s2, 0x3a800000
	v_pk_mul_f32 v[42:43], v[18:19], s[2:3] op_sel_hi:[1,0]
	s_mov_b32 s1, 0x800000
	v_fma_f32 v0, -v43, v43, v42
	v_max_f32_e32 v0, 0, v0
	v_add_f32_e32 v0, 0x3727c5ac, v0
	v_cmp_gt_f32_e32 vcc, s1, v0
	v_mul_f32_e32 v18, 0x4b800000, v0
	s_load_dwordx16 s[64:79], s[34:35], 0x38
	v_cndmask_b32_e32 v0, v0, v18, vcc
	v_rsq_f32_e32 v0, v0
	s_mov_b32 s2, 0x3fd744fd
	s_movk_i32 s1, 0x3fc0
	v_mul_f32_e32 v18, 0x45800000, v0
	v_cndmask_b32_e32 v42, v0, v18, vcc
	v_lshlrev_b64 v[18:19], 12, v[94:95]
	s_waitcnt lgkmcnt(0)
	v_lshl_add_u64 v[18:19], s[78:79], 0, v[18:19]
	v_lshl_add_u64 v[44:45], v[152:153], 2, v[18:19]
	s_nop 1
	v_bfe_u32 v21, v227, 4, 2
	v_sub_u32_e32 v20, 0, v21
	v_lshlrev_b32_e32 v20, 4, v20
	v_ashrrev_i32_e32 v21, 31, v20
	v_lshl_add_u64 v[20:21], v[44:45], 0, v[20:21]
	global_load_dwordx4 v[46:49], v[20:21], off offset:64
	global_load_dwordx4 v[50:53], v[20:21], off
	s_nop 1
	v_lshrrev_b32_e32 v0, 4, v227
	v_lshlrev_b32_e32 v0, 7, v0
	v_add_u32_e32 v0, 0x20100, v0
	ds_read_b128 v[54:57], v0 offset:16
	ds_read_b128 v[58:61], v0 offset:0
	ds_read_b128 v[62:65], v0 offset:80
	ds_read_b128 v[66:69], v0 offset:64
	s_nop 1
	v_bfe_u32 v23, v227, 4, 2
	v_sub_u32_e32 v22, 0, v23
	v_lshlrev_b32_e32 v22, 4, v22
	v_ashrrev_i32_e32 v23, 31, v22
	v_lshl_add_u64 v[22:23], v[44:45], 0, v[22:23]
	global_load_dwordx4 v[18:21], v[22:23], off offset:576
	global_load_dwordx4 v[38:41], v[22:23], off offset:512
	ds_read_b128 v[22:25], v0 offset:48
	ds_read_b128 v[30:33], v0 offset:32
	ds_read_b128 v[26:29], v0 offset:112
	ds_read_b128 v[34:37], v0 offset:96
	v_lshlrev_b32_e32 v0, 6, v94
	v_and_or_b32 v0, v0, s1, v196
	v_lshlrev_b32_e32 v0, 1, v0
	s_waitcnt vmcnt(2)
	v_permlane32_swap_b32_e32 v50, v46
	v_permlane32_swap_b32_e32 v51, v47
	v_permlane32_swap_b32_e32 v52, v48
	v_permlane32_swap_b32_e32 v53, v49
	v_permlane16_swap_b32_e32 v50, v46
	v_permlane16_swap_b32_e32 v51, v47
	v_permlane16_swap_b32_e32 v52, v48
	v_permlane16_swap_b32_e32 v53, v49
	v_sub_f32_e32 v51, v51, v43
	v_sub_f32_e32 v50, v50, v43
	v_sub_f32_e32 v53, v53, v43
	v_sub_f32_e32 v52, v52, v43
	v_pk_mul_f32 v[52:53], v[42:43], v[52:53] op_sel_hi:[0,1]
	v_pk_mul_f32 v[50:51], v[42:43], v[50:51] op_sel_hi:[0,1]
	s_waitcnt lgkmcnt(0)
	v_pk_fma_f32 v[50:51], v[58:59], v[50:51], v[66:67]
	v_pk_fma_f32 v[52:53], v[60:61], v[52:53], v[68:69]
	v_pk_fma_f32 v[50:51], v[50:51], s[2:3], v[14:15] op_sel_hi:[1,0,1]
	v_pk_fma_f32 v[52:53], v[52:53], s[2:3], v[16:17] op_sel_hi:[1,0,1]
	v_add_f32_e32 v14, v50, v51
	v_add_f32_e32 v15, v52, v53
	v_add_f32_e32 v14, v14, v15
	v_add_f32_e32 v58, 0, v14
	v_mul_f32_e32 v14, v51, v51
	v_mul_f32_e32 v15, v53, v53
	v_fmac_f32_e32 v14, v50, v50
	v_fmac_f32_e32 v15, v52, v52
	v_add_f32_e32 v59, v14, v15
	v_sub_f32_e32 v15, v47, v43
	v_sub_f32_e32 v14, v46, v43
	v_sub_f32_e32 v17, v49, v43
	v_sub_f32_e32 v16, v48, v43
	v_pk_mul_f32 v[16:17], v[42:43], v[16:17] op_sel_hi:[0,1]
	v_pk_mul_f32 v[14:15], v[42:43], v[14:15] op_sel_hi:[0,1]
	v_pk_fma_f32 v[14:15], v[54:55], v[14:15], v[62:63]
	v_pk_fma_f32 v[16:17], v[56:57], v[16:17], v[64:65]
	v_pk_fma_f32 v[46:47], v[14:15], s[2:3], v[10:11] op_sel_hi:[1,0,1]
	v_pk_fma_f32 v[48:49], v[16:17], s[2:3], v[12:13] op_sel_hi:[1,0,1]
	v_add_f32_e32 v10, v46, v47
	v_add_f32_e32 v11, v48, v49
	v_add_f32_e32 v10, v10, v11
	v_add_f32_e32 v15, v58, v10
	v_mul_f32_e32 v10, v47, v47
	v_mul_f32_e32 v11, v49, v49
	v_fmac_f32_e32 v10, v46, v46
	v_fmac_f32_e32 v11, v48, v48
	v_add_f32_e32 v10, v10, v11
	v_add_f32_e32 v14, v59, v10
	v_cvt_pk_bf16_f32 v10, v50, v51
	v_cvt_pk_bf16_f32 v11, v52, v53
	v_cvt_pk_bf16_f32 v12, v46, v47
	v_cvt_pk_bf16_f32 v13, v48, v49
	v_lshl_add_u64 v[16:17], v[76:77], 0, v[0:1]
	s_nop 0
	s_nop 1
	v_bfe_u32 v55, v227, 4, 2
	v_sub_u32_e32 v54, 0, v55
	v_lshlrev_b32_e32 v54, 4, v54
	v_ashrrev_i32_e32 v55, 31, v54
	v_lshl_add_u64 v[54:55], v[44:45], 0, v[54:55]
	v_permlane16_swap_b32_e32 v50, v46
	v_permlane16_swap_b32_e32 v51, v47
	v_permlane16_swap_b32_e32 v52, v48
	v_permlane16_swap_b32_e32 v53, v49
	v_permlane32_swap_b32_e32 v50, v46
	v_permlane32_swap_b32_e32 v51, v47
	v_permlane32_swap_b32_e32 v52, v48
	v_permlane32_swap_b32_e32 v53, v49
	global_store_dwordx4 v[54:55], v[50:53], off
	global_store_dwordx4 v[54:55], v[46:49], off offset:64
	s_nop 1
	v_permlane32_swap_b32_e32 v50, v46
	v_permlane32_swap_b32_e32 v51, v47
	v_permlane32_swap_b32_e32 v52, v48
	v_permlane32_swap_b32_e32 v53, v49
	v_permlane16_swap_b32_e32 v50, v46
	v_permlane16_swap_b32_e32 v51, v47
	v_permlane16_swap_b32_e32 v52, v48
	v_permlane16_swap_b32_e32 v53, v49
	global_store_dwordx4 v[16:17], v[10:13], off
	s_nop 0
	s_waitcnt vmcnt(3)
; __device__ __forceinline__ float xsum16(float v) { const auto r = __builtin_amdgcn_permlane16_swap(__float_as_uint(v), __float_as_uint(v), false, false); return __uint_as_float(r[0]) + __uint_as_float(r[1]); }
; __device__ __forceinline__ float xsum32(float v) { const auto r = __builtin_amdgcn_permlane32_swap(__float_as_uint(v), __float_as_uint(v), false, false); return __uint_as_float(r[0]) + __uint_as_float(r[1]); }
; __device__ __forceinline__ size_t blk_off(int r, int c, int K) { return (size_t)(r >> 8) * 256 * K + (size_t)(c >> 6) * (256 * 64) + (size_t)((r & 255) * 64 + (c & 63)); }
; __device__ __forceinline__ u32x4 pack8(const f32x4 a, const f32x4 b) { u32x4 w; w.x = cvt_pk_bf16(a[0], a[1]); w.y = cvt_pk_bf16(a[2], a[3]); w.z = cvt_pk_bf16(b[0], b[1]); w.w = cvt_pk_bf16(b[2], b[3]); return w; }
;     __device__ __forceinline__ void operator()(const f32x4 (&acc)[2][2][4][2], const pg8::Unit& u, int wr, int wc, int fr, int fq) const {
;     ...
;                 for (int bj = 0; bj < 2; ++bj) { float* yp = Y + (size_t)row * D_ + col0 + bj * 128; f32x4 v[2];
; #pragma unroll
;                     for (int n = 0; n < 2; ++n) { v[n] = (((yv[bj][n] - mu) * rs) * gq[bj][n] + bq_[bj][n]) * ALPHA_ + acc[ai][bj][m][n] * sc;
;                         *(f32x4*)(yp + 4 * n) = v[n]; s1 += (v[n][0] + v[n][1]) + (v[n][2] + v[n][3]); s2 += (v[n][0] * v[n][0] + v[n][1] * v[n][1]) + (v[n][2] * v[n][2] + v[n][3] * v[n][3]); }
;                     *(u32x4*)(Yb + blk_off(row, col0 + bj * 128, D_)) = pack8(v[0], v[1]); }
;                 s1 = xsum32(xsum16(s1)); s2 = xsum32(xsum16(s2));
;                 if (fq == 0) *(f32x2*)(stn + (size_t)row * 32 + (u.pn * 4 + wc) * 2) = (f32x2){s1, s2}; asm volatile("" ::: "memory"); } }
	v_permlane32_swap_b32_e32 v38, v18
	v_permlane32_swap_b32_e32 v39, v19
	v_permlane32_swap_b32_e32 v40, v20
	v_permlane32_swap_b32_e32 v41, v21
	v_permlane16_swap_b32_e32 v38, v18
	v_permlane16_swap_b32_e32 v39, v19
	v_permlane16_swap_b32_e32 v40, v20
	v_permlane16_swap_b32_e32 v41, v21
	v_sub_f32_e32 v11, v39, v43
	v_sub_f32_e32 v10, v38, v43
	v_sub_f32_e32 v13, v41, v43
	v_sub_f32_e32 v12, v40, v43
	v_pk_mul_f32 v[12:13], v[42:43], v[12:13] op_sel_hi:[0,1]
	v_pk_mul_f32 v[10:11], v[42:43], v[10:11] op_sel_hi:[0,1]
	v_pk_fma_f32 v[10:11], v[30:31], v[10:11], v[34:35]
	v_pk_fma_f32 v[12:13], v[32:33], v[12:13], v[36:37]
	v_pk_fma_f32 v[6:7], v[10:11], s[2:3], v[6:7] op_sel_hi:[1,0,1]
	v_pk_fma_f32 v[8:9], v[12:13], s[2:3], v[8:9] op_sel_hi:[1,0,1]
	v_add_f32_e32 v10, v6, v7
	v_add_f32_e32 v11, v8, v9
	v_add_f32_e32 v10, v10, v11
	v_add_f32_e32 v15, v15, v10
	v_mul_f32_e32 v10, v7, v7
	v_mul_f32_e32 v11, v9, v9
	v_fmac_f32_e32 v10, v6, v6
	v_fmac_f32_e32 v11, v8, v8
	v_add_f32_e32 v10, v10, v11
	v_add_f32_e32 v14, v14, v10
	v_sub_f32_e32 v11, v19, v43
	v_sub_f32_e32 v10, v18, v43
	v_sub_f32_e32 v13, v21, v43
	v_sub_f32_e32 v12, v20, v43
	v_pk_mul_f32 v[12:13], v[42:43], v[12:13] op_sel_hi:[0,1]
	v_pk_mul_f32 v[10:11], v[42:43], v[10:11] op_sel_hi:[0,1]
	v_pk_fma_f32 v[10:11], v[22:23], v[10:11], v[26:27]
	v_pk_fma_f32 v[12:13], v[24:25], v[12:13], v[28:29]
	v_pk_fma_f32 v[2:3], v[10:11], s[2:3], v[2:3] op_sel_hi:[1,0,1]
	v_pk_fma_f32 v[4:5], v[12:13], s[2:3], v[4:5] op_sel_hi:[1,0,1]
	v_add_f32_e32 v10, v2, v3
	v_add_f32_e32 v11, v4, v5
	v_add_f32_e32 v10, v10, v11
	v_mul_f32_e32 v11, v3, v3
	v_mul_f32_e32 v12, v5, v5
	v_add_f32_e32 v10, v15, v10
	v_fmac_f32_e32 v11, v2, v2
	v_fmac_f32_e32 v12, v4, v4
	s_nop 0
	s_nop 1
	v_bfe_u32 v17, v227, 4, 2
	v_sub_u32_e32 v16, 0, v17
	v_lshlrev_b32_e32 v16, 4, v16
	v_ashrrev_i32_e32 v17, 31, v16
	v_lshl_add_u64 v[16:17], v[44:45], 0, v[16:17]
	v_permlane16_swap_b32_e32 v6, v2
	v_permlane16_swap_b32_e32 v7, v3
	v_permlane16_swap_b32_e32 v8, v4
	v_permlane16_swap_b32_e32 v9, v5
	v_permlane32_swap_b32_e32 v6, v2
	v_permlane32_swap_b32_e32 v7, v3
	v_permlane32_swap_b32_e32 v8, v4
	v_permlane32_swap_b32_e32 v9, v5
	global_store_dwordx4 v[16:17], v[6:9], off offset:512
	global_store_dwordx4 v[16:17], v[2:5], off offset:576
	s_nop 1
	v_permlane32_swap_b32_e32 v6, v2
	v_permlane32_swap_b32_e32 v7, v3
	v_permlane32_swap_b32_e32 v8, v4
	v_permlane32_swap_b32_e32 v9, v5
	v_permlane16_swap_b32_e32 v6, v2
	v_permlane16_swap_b32_e32 v7, v3
	v_permlane16_swap_b32_e32 v8, v4
	v_permlane16_swap_b32_e32 v9, v5
	v_add_f32_e32 v11, v11, v12
	v_cvt_pk_bf16_f32 v6, v6, v7
	v_cvt_pk_bf16_f32 v7, v8, v9
	v_cvt_pk_bf16_f32 v8, v2, v3
	v_lshl_add_u64 v[2:3], v[74:75], 0, v[0:1]
	v_mov_b32_e32 v0, v10
	v_add_f32_e32 v11, v14, v11
	v_cvt_pk_bf16_f32 v9, v4, v5
	v_permlane16_swap_b32_e32 v10, v0
	global_store_dwordx4 v[2:3], v[6:9], off
	v_add_f32_e32 v2, v10, v0
	v_mov_b32_e32 v0, v11
	s_nop 1
	v_permlane16_swap_b32_e32 v11, v0
	v_add_f32_e32 v3, v11, v0
	v_mov_b32_e32 v4, v2
	v_mov_b32_e32 v5, v3
	s_nop 0
	v_permlane32_swap_b32_e32 v2, v4
	v_permlane32_swap_b32_e32 v3, v5
	s_and_saveexec_b64 s[24:25], s[44:45]
	s_cbranch_execz .LBB0_1551
	v_pk_add_f32 v[2:3], v[2:3], v[4:5]
	v_lshlrev_b64 v[4:5], 7, v[94:95]
	v_lshl_add_u64 v[4:5], s[6:7], 0, v[4:5]
	v_lshl_add_u64 v[4:5], s[52:53], 2, v[4:5]
	global_store_dwordx2 v[4:5], v[2:3], off

; __device__ __forceinline__ float xsum16(float v) { const auto r = __builtin_amdgcn_permlane16_swap(__float_as_uint(v), __float_as_uint(v), false, false); return __uint_as_float(r[0]) + __uint_as_float(r[1]); }
; __device__ __forceinline__ float xsum32(float v) { const auto r = __builtin_amdgcn_permlane32_swap(__float_as_uint(v), __float_as_uint(v), false, false); return __uint_as_float(r[0]) + __uint_as_float(r[1]); }
; __device__ __forceinline__ void row_stats4(const float* st, int rowb, int fq, float (&mu)[4], float (&rs)[4]) {
;     f32x4 a[4], b[4];
; #pragma unroll
;     for (int m = 0; m < 4; ++m) { const f32x4* p = (const f32x4*)(st + (size_t)(rowb + m * 16) * 32 + fq * 8); a[m] = p[0]; b[m] = p[1]; }
; #pragma unroll
;     for (int m = 0; m < 4; ++m) { float s1 = (a[m][0] + a[m][2]) + (b[m][0] + b[m][2]), s2 = (a[m][1] + a[m][3]) + (b[m][1] + b[m][3]);
;         s1 = xsum32(xsum16(s1)); s2 = xsum32(xsum16(s2));
;         const float mm = s1 * (1.0f / 1024.0f); mu[m] = mm; rs[m] = rsqrtf(fmaxf(s2 * (1.0f / 1024.0f) - mm * mm, 0.f) + LN_EPS_); }
;     __device__ __forceinline__ void operator()(const f32x4 (&acc)[2][2][4][2], const pg8::Unit& u, int wr, int wc, int fr, int fq) const {
;     ...
;         for (int ai = 0; ai < 2; ++ai) { float mu4[4], rs4[4]; row_stats4(stp, row0 + ai * 128, fq, mu4, rs4);
; #pragma unroll
;             for (int m = 0; m < 4; ++m) { const int row = row0 + ai * 128 + m * 16; const float mu = mu4[m], rs = rs4[m];
;                 f32x4 yv[2][2], gq[2][2], bq_[2][2];
; #pragma unroll
;                 for (int bj = 0; bj < 2; ++bj)
; #pragma unroll
;                     for (int n = 0; n < 2; ++n) { yv[bj][n] = *(const f32x4*)(Yin + (size_t)row * D_ + col0 + bj * 128 + 4 * n); gq[bj][n] = *(const f32x4*)(g + col0 + bj * 128 + 4 * n); bq_[bj][n] = *(const f32x4*)(b + col0 + bj * 128 + 4 * n); }
;                 asm volatile("" ::: "memory");
.LBB0_1703:
	s_lshl_b32 s3, s3, 8
	s_add_i32 s3, s3, s0
	v_or_b32_e32 v158, s3, v184
	v_ashrrev_i32_e32 v159, 31, v158
	v_lshlrev_b64 v[130:131], 7, v[158:159]
	v_lshl_add_u64 v[136:137], v[146:147], 0, v[130:131]
	v_or_b32_e32 v182, 16, v158
	s_nop 1
	v_bfe_u32 v153, v227, 4, 2
	v_sub_u32_e32 v152, 0, v153
	v_lshlrev_b32_e32 v152, 4, v152
	v_ashrrev_i32_e32 v153, 31, v152
	v_lshl_add_u64 v[152:153], v[136:137], 0, v[152:153]
	global_load_dwordx4 v[132:135], v[152:153], off
	global_load_dwordx4 v[166:169], v[152:153], off offset:64
	v_ashrrev_i32_e32 v183, 31, v182
	v_lshlrev_b64 v[172:173], 7, v[182:183]
	v_lshl_add_u64 v[136:137], v[146:147], 0, v[172:173]
	s_nop 1
	v_bfe_u32 v153, v227, 4, 2
	v_sub_u32_e32 v152, 0, v153
	v_lshlrev_b32_e32 v152, 4, v152
	v_ashrrev_i32_e32 v153, 31, v152
	v_lshl_add_u64 v[152:153], v[136:137], 0, v[152:153]
	global_load_dwordx4 v[174:177], v[152:153], off
	global_load_dwordx4 v[178:181], v[152:153], off offset:64
	v_or_b32_e32 v170, 32, v158
	v_ashrrev_i32_e32 v171, 31, v170
	v_lshlrev_b64 v[164:165], 7, v[170:171]
	v_lshl_add_u64 v[136:137], v[146:147], 0, v[164:165]
	s_nop 1
	v_bfe_u32 v153, v227, 4, 2
	v_sub_u32_e32 v152, 0, v153
	v_lshlrev_b32_e32 v152, 4, v152
	v_ashrrev_i32_e32 v153, 31, v152
	v_lshl_add_u64 v[152:153], v[136:137], 0, v[152:153]
	global_load_dwordx4 v[186:189], v[152:153], off
	global_load_dwordx4 v[190:193], v[152:153], off offset:64
	s_load_dwordx16 s[60:75], s[34:35], 0x38
	s_lshl_b32 s1, s2, 8
	s_lshl_b32 s16, s2, 3
	s_or_b32 s2, s1, s53
	v_or_b32_e32 v162, 48, v158
	v_or_b32_e32 v152, s2, v185
	v_ashrrev_i32_e32 v163, 31, v162
	v_ashrrev_i32_e32 v153, 31, v152
	v_lshlrev_b64 v[136:137], 12, v[158:159]
	v_lshlrev_b64 v[160:161], 7, v[162:163]
	v_lshlrev_b64 v[198:199], 2, v[152:153]
	s_waitcnt lgkmcnt(0)
	v_lshl_add_u64 v[136:137], s[74:75], 0, v[136:137]
	v_lshl_add_u64 v[202:203], v[146:147], 0, v[160:161]
	v_lshl_add_u64 v[156:157], s[10:11], 0, v[198:199]
	v_lshl_add_u64 v[154:155], s[12:13], 0, v[198:199]
	v_lshl_add_u64 v[136:137], v[136:137], 0, v[198:199]
	s_nop 1
	v_bfe_u32 v197, v227, 4, 2
	v_sub_u32_e32 v196, 0, v197
	v_lshlrev_b32_e32 v196, 4, v196
	v_ashrrev_i32_e32 v197, 31, v196
	v_lshl_add_u64 v[196:197], v[202:203], 0, v[196:197]
	global_load_dwordx4 v[198:201], v[196:197], off
	s_nop 0
	global_load_dwordx4 v[202:205], v[196:197], off offset:64
	s_or_b32 s38, s16, s15
	s_mov_b32 s16, 0x3a800000
	s_mov_b32 s1, 0x800000
	s_nop 1
	v_bfe_u32 v197, v227, 4, 2
	v_sub_u32_e32 v196, 0, v197
	v_lshlrev_b32_e32 v196, 4, v196
	v_ashrrev_i32_e32 v197, 31, v196
	v_lshl_add_u64 v[196:197], v[136:137], 0, v[196:197]
	global_load_dwordx4 v[206:209], v[196:197], off offset:64
	global_load_dwordx4 v[210:213], v[196:197], off
	global_load_dwordx4 v[214:217], v[156:157], off offset:16
	global_load_dwordx4 v[218:221], v[156:157], off
	global_load_dwordx4 v[222:225], v[154:155], off offset:16
	global_load_dwordx4 v[234:237], v[154:155], off
	s_mov_b32 s18, 0x3fd744fd
	s_ashr_i32 s44, s2, 6
	v_bitop3_b32 v196, s2, 56, v185 bitop3:0xc8
	s_ashr_i32 s39, s38, 31
	s_ashr_i32 s45, s44, 31
	s_nop 1
	v_lshrrev_b32_e32 v0, 4, v227
	v_lshlrev_b32_e32 v0, 7, v0
	v_add_u32_e32 v0, 0x20100, v0
	s_waitcnt vmcnt(3)
	ds_write_b128 v0, v[214:217] offset:16
	s_waitcnt vmcnt(2)
	ds_write_b128 v0, v[218:221] offset:0
	s_waitcnt vmcnt(1)
	ds_write_b128 v0, v[222:225] offset:80
	s_waitcnt vmcnt(0)
	ds_write_b128 v0, v[234:237] offset:64
	v_permlane32_swap_b32_e32 v132, v166
	v_permlane32_swap_b32_e32 v133, v167
	v_permlane32_swap_b32_e32 v134, v168
	v_permlane32_swap_b32_e32 v135, v169
	v_permlane16_swap_b32_e32 v132, v166
	v_permlane16_swap_b32_e32 v133, v167
	v_permlane16_swap_b32_e32 v134, v168
	v_permlane16_swap_b32_e32 v135, v169
	v_mov_b32_e32 v228, v132
	v_mov_b32_e32 v229, v166
	v_mov_b32_e32 v238, v134
	v_mov_b32_e32 v239, v168
	v_mov_b32_e32 v166, v133
	v_mov_b32_e32 v168, v135
	v_pk_add_f32 v[132:133], v[228:229], v[238:239]
	v_pk_add_f32 v[134:135], v[166:167], v[168:169]
	v_pk_add_f32 v[132:133], v[132:133], v[132:133] op_sel:[0,1] op_sel_hi:[1,0]
	v_pk_add_f32 v[134:135], v[134:135], v[134:135] op_sel:[0,1] op_sel_hi:[1,0]
	v_permlane32_swap_b32_e32 v174, v178
	v_permlane32_swap_b32_e32 v175, v179
	v_permlane32_swap_b32_e32 v176, v180
	v_permlane32_swap_b32_e32 v177, v181
	v_permlane16_swap_b32_e32 v174, v178
	v_permlane16_swap_b32_e32 v175, v179
	v_permlane16_swap_b32_e32 v176, v180
	v_permlane16_swap_b32_e32 v177, v181
	v_mov_b32_e32 v166, v174
	v_mov_b32_e32 v167, v178
	v_mov_b32_e32 v168, v176
	v_mov_b32_e32 v169, v180
	v_mov_b32_e32 v0, v132
	v_mov_b32_e32 v133, v134
	v_pk_add_f32 v[166:167], v[166:167], v[168:169]
	v_permlane16_swap_b32_e32 v132, v0
	v_permlane16_swap_b32_e32 v134, v133
	v_mov_b32_e32 v178, v175
	v_mov_b32_e32 v180, v177
	v_pk_add_f32 v[166:167], v[166:167], v[166:167] op_sel:[0,1] op_sel_hi:[1,0]
	v_add_f32_e32 v177, v132, v0
	v_add_f32_e32 v176, v134, v133
	v_pk_add_f32 v[168:169], v[178:179], v[180:181]
	v_mov_b32_e32 v135, v166
	v_mov_b32_e32 v179, v177
	v_mov_b32_e32 v178, v176
	v_permlane16_swap_b32_e32 v166, v135
	v_permlane32_swap_b32_e32 v177, v179
	v_permlane32_swap_b32_e32 v176, v178
	v_add_f32_e32 v133, v166, v135
	v_pk_add_f32 v[166:167], v[176:177], v[178:179]
	v_pk_add_f32 v[168:169], v[168:169], v[168:169] op_sel:[0,1] op_sel_hi:[1,0]
	v_pk_mul_f32 v[228:229], v[166:167], s[16:17] op_sel_hi:[1,0]
	v_mov_b32_e32 v159, v168
	v_fma_f32 v0, -v229, v229, v228
	v_max_f32_e32 v0, 0, v0
	v_permlane16_swap_b32_e32 v168, v159
	v_add_f32_e32 v0, 0x3727c5ac, v0
	v_add_f32_e32 v132, v168, v159
	v_mul_f32_e32 v159, 0x4b800000, v0
	v_cmp_gt_f32_e32 vcc, s1, v0
; __device__ __forceinline__ float xsum16(float v) { const auto r = __builtin_amdgcn_permlane16_swap(__float_as_uint(v), __float_as_uint(v), false, false); return __uint_as_float(r[0]) + __uint_as_float(r[1]); }
; __device__ __forceinline__ float xsum32(float v) { const auto r = __builtin_amdgcn_permlane32_swap(__float_as_uint(v), __float_as_uint(v), false, false); return __uint_as_float(r[0]) + __uint_as_float(r[1]); }
; __device__ __forceinline__ size_t blk_off(int r, int c, int K) { return (size_t)(r >> 8) * 256 * K + (size_t)(c >> 6) * (256 * 64) + (size_t)((r & 255) * 64 + (c & 63)); }
; __device__ __forceinline__ void row_stats4(const float* st, int rowb, int fq, float (&mu)[4], float (&rs)[4]) {
;     ...
;     for (int m = 0; m < 4; ++m) { float s1 = (a[m][0] + a[m][2]) + (b[m][0] + b[m][2]), s2 = (a[m][1] + a[m][3]) + (b[m][1] + b[m][3]);
;         s1 = xsum32(xsum16(s1)); s2 = xsum32(xsum16(s2));
;         const float mm = s1 * (1.0f / 1024.0f); mu[m] = mm; rs[m] = rsqrtf(fmaxf(s2 * (1.0f / 1024.0f) - mm * mm, 0.f) + LN_EPS_); }
;     __device__ __forceinline__ void operator()(const f32x4 (&acc)[2][2][4][2], const pg8::Unit& u, int wr, int wc, int fr, int fq) const {
;     ...
;             for (int m = 0; m < 4; ++m) { const int row = row0 + ai * 128 + m * 16; const float mu = mu4[m], rs = rs4[m];
;                 f32x4 yv[2][2], gq[2][2], bq_[2][2];
; #pragma unroll
;                 for (int bj = 0; bj < 2; ++bj)
; #pragma unroll
;                     for (int n = 0; n < 2; ++n) { yv[bj][n] = *(const f32x4*)(Yin + (size_t)row * D_ + col0 + bj * 128 + 4 * n); gq[bj][n] = *(const f32x4*)(g + col0 + bj * 128 + 4 * n); bq_[bj][n] = *(const f32x4*)(b + col0 + bj * 128 + 4 * n); }
;                 asm volatile("" ::: "memory");
;                 float s1 = 0.f, s2 = 0.f;
; #pragma unroll
;                 for (int bj = 0; bj < 2; ++bj) { float* yp = Y + (size_t)row * D_ + col0 + bj * 128; f32x4 v[2];
; #pragma unroll
;                     for (int n = 0; n < 2; ++n) { v[n] = (((yv[bj][n] - mu) * rs) * gq[bj][n] + bq_[bj][n]) * ALPHA_ + acc[ai][bj][m][n] * sc;
;                         *(f32x4*)(yp + 4 * n) = v[n]; s1 += (v[n][0] + v[n][1]) + (v[n][2] + v[n][3]); s2 += (v[n][0] * v[n][0] + v[n][1] * v[n][1]) + (v[n][2] * v[n][2] + v[n][3] * v[n][3]); }
;                     *(u32x4*)(Yb + blk_off(row, col0 + bj * 128, D_)) = pack8(v[0], v[1]); }
	v_permlane32_swap_b32_e32 v186, v190
	v_permlane32_swap_b32_e32 v187, v191
	v_permlane32_swap_b32_e32 v188, v192
	v_permlane32_swap_b32_e32 v189, v193
	v_permlane16_swap_b32_e32 v186, v190
	v_permlane16_swap_b32_e32 v187, v191
	v_permlane16_swap_b32_e32 v188, v192
	v_permlane16_swap_b32_e32 v189, v193
	v_mov_b32_e32 v174, v186
	v_mov_b32_e32 v175, v190
	v_cndmask_b32_e32 v0, v0, v159, vcc
	v_rsq_f32_e32 v0, v0
	v_mov_b32_e32 v166, v188
	v_mov_b32_e32 v167, v192
	v_pk_add_f32 v[166:167], v[174:175], v[166:167]
	v_mul_f32_e32 v159, 0x45800000, v0
	v_pk_add_f32 v[166:167], v[166:167], v[166:167] op_sel:[0,1] op_sel_hi:[1,0]
	v_mov_b32_e32 v190, v187
	v_mov_b32_e32 v192, v189
	v_cndmask_b32_e32 v0, v0, v159, vcc
	v_pk_add_f32 v[168:169], v[190:191], v[192:193]
	v_mov_b32_e32 v159, v166
	v_pk_add_f32 v[168:169], v[168:169], v[168:169] op_sel:[0,1] op_sel_hi:[1,0]
	s_nop 0
	v_permlane16_swap_b32_e32 v166, v159
	v_add_f32_e32 v175, v166, v159
	v_mov_b32_e32 v159, v168
	s_nop 1
	v_permlane16_swap_b32_e32 v168, v159
	s_nop 1
	v_bfe_u32 v135, v227, 4, 2
	v_sub_u32_e32 v134, 0, v135
	v_lshlrev_b32_e32 v134, 4, v134
	v_ashrrev_i32_e32 v135, 31, v134
	v_lshl_add_u64 v[134:135], v[136:137], 0, v[134:135]
	global_load_dwordx4 v[178:181], v[134:135], off offset:576
	global_load_dwordx4 v[186:189], v[134:135], off offset:512
	v_add_f32_e32 v174, v168, v159
	v_permlane32_swap_b32_e32 v198, v202
	v_permlane32_swap_b32_e32 v199, v203
	v_permlane32_swap_b32_e32 v200, v204
	v_permlane32_swap_b32_e32 v201, v205
	v_permlane16_swap_b32_e32 v198, v202
	v_permlane16_swap_b32_e32 v199, v203
	v_permlane16_swap_b32_e32 v200, v204
	v_permlane16_swap_b32_e32 v201, v205
	v_mov_b32_e32 v166, v198
	v_mov_b32_e32 v167, v202
	v_mov_b32_e32 v168, v200
	v_mov_b32_e32 v169, v204
	v_mov_b32_e32 v202, v199
	v_mov_b32_e32 v204, v201
	v_pk_add_f32 v[166:167], v[166:167], v[168:169]
	v_pk_add_f32 v[168:169], v[202:203], v[204:205]
	global_load_dwordx4 v[190:193], v[156:157], off offset:528
	global_load_dwordx4 v[198:201], v[156:157], off offset:512
	global_load_dwordx4 v[202:205], v[154:155], off offset:528
	global_load_dwordx4 v[238:241], v[154:155], off offset:512
	v_permlane32_swap_b32_e32 v210, v206
	v_permlane32_swap_b32_e32 v211, v207
	v_permlane32_swap_b32_e32 v212, v208
	v_permlane32_swap_b32_e32 v213, v209
	v_permlane16_swap_b32_e32 v210, v206
	v_permlane16_swap_b32_e32 v211, v207
	v_permlane16_swap_b32_e32 v212, v208
	v_permlane16_swap_b32_e32 v213, v209
	v_sub_f32_e32 v213, v213, v229
	v_sub_f32_e32 v212, v212, v229
	v_sub_f32_e32 v211, v211, v229
	v_sub_f32_e32 v210, v210, v229
	v_pk_mul_f32 v[210:211], v[0:1], v[210:211] op_sel_hi:[0,1]
	v_pk_mul_f32 v[212:213], v[0:1], v[212:213] op_sel_hi:[0,1]
	v_sub_f32_e32 v209, v209, v229
	v_sub_f32_e32 v208, v208, v229
	v_sub_f32_e32 v207, v207, v229
	v_sub_f32_e32 v206, v206, v229
	v_pk_fma_f32 v[212:213], v[220:221], v[212:213], v[236:237]
	v_pk_fma_f32 v[210:211], v[218:219], v[210:211], v[234:235]
	v_pk_mul_f32 v[206:207], v[0:1], v[206:207] op_sel_hi:[0,1]
	v_pk_mul_f32 v[208:209], v[0:1], v[208:209] op_sel_hi:[0,1]
	v_pk_mul_f32 v[210:211], v[210:211], s[18:19] op_sel_hi:[1,0]
	v_pk_mul_f32 v[212:213], v[212:213], s[18:19] op_sel_hi:[1,0]
	v_pk_fma_f32 v[208:209], v[216:217], v[208:209], v[224:225]
	v_pk_fma_f32 v[206:207], v[214:215], v[206:207], v[222:223]
	v_pk_fma_f32 v[128:129], v[128:129], 0.5, v[212:213] op_sel_hi:[1,0,1]
	v_pk_fma_f32 v[126:127], v[126:127], 0.5, v[210:211] op_sel_hi:[1,0,1]
	v_pk_mul_f32 v[206:207], v[206:207], s[18:19] op_sel_hi:[1,0]
	v_pk_mul_f32 v[208:209], v[208:209], s[18:19] op_sel_hi:[1,0]
	v_add_f32_e32 v197, v126, v127
	v_add_f32_e32 v210, v128, v129
	v_pk_fma_f32 v[124:125], v[124:125], 0.5, v[208:209] op_sel_hi:[1,0,1]
	v_pk_fma_f32 v[122:123], v[122:123], 0.5, v[206:207] op_sel_hi:[1,0,1]
	v_pk_add_f32 v[166:167], v[166:167], v[166:167] op_sel:[0,1] op_sel_hi:[1,0]
	v_add_f32_e32 v197, v197, v210
	v_add_f32_e32 v206, v122, v123
	v_add_f32_e32 v207, v124, v125
	v_mov_b32_e32 v159, v166
	v_add_f32_e32 v197, 0, v197
	v_add_f32_e32 v206, v206, v207
	v_pk_add_f32 v[168:169], v[168:169], v[168:169] op_sel:[0,1] op_sel_hi:[1,0]
	v_permlane16_swap_b32_e32 v166, v159
	v_mul_f32_e32 v210, v127, v127
	v_mul_f32_e32 v211, v129, v129
	v_add_f32_e32 v197, v197, v206
	v_mul_f32_e32 v206, v123, v123
	v_mul_f32_e32 v207, v125, v125
	v_add_f32_e32 v167, v166, v159
	v_mov_b32_e32 v159, v168
	s_ashr_i32 s16, s3, 8
	s_nop 0
	v_fmac_f32_e32 v210, v126, v126
	v_fmac_f32_e32 v211, v128, v128
	s_nop 1
	v_bfe_u32 v135, v227, 4, 2
	v_sub_u32_e32 v134, 0, v135
	v_lshlrev_b32_e32 v134, 4, v134
	v_ashrrev_i32_e32 v135, 31, v134
	v_lshl_add_u64 v[134:135], v[136:137], 0, v[134:135]
	v_permlane16_swap_b32_e32 v126, v122
	v_permlane16_swap_b32_e32 v127, v123
	v_permlane16_swap_b32_e32 v128, v124
	v_permlane16_swap_b32_e32 v129, v125
	v_permlane32_swap_b32_e32 v126, v122
	v_permlane32_swap_b32_e32 v127, v123
	v_permlane32_swap_b32_e32 v128, v124
	v_permlane32_swap_b32_e32 v129, v125
	global_store_dwordx4 v[134:135], v[126:129], off
	global_store_dwordx4 v[134:135], v[122:125], off offset:64
	s_nop 1
	v_permlane32_swap_b32_e32 v126, v122
	v_permlane32_swap_b32_e32 v127, v123
	v_permlane32_swap_b32_e32 v128, v124
	v_permlane32_swap_b32_e32 v129, v125
	v_permlane16_swap_b32_e32 v126, v122
	v_permlane16_swap_b32_e32 v127, v123
	v_permlane16_swap_b32_e32 v128, v124
	v_permlane16_swap_b32_e32 v129, v125
	v_fmac_f32_e32 v206, v122, v122
	v_fmac_f32_e32 v207, v124, v124
	v_cvt_pk_bf16_f32 v126, v126, v127
	v_cvt_pk_bf16_f32 v127, v128, v129
	v_cvt_pk_bf16_f32 v128, v122, v123
	v_cvt_pk_bf16_f32 v129, v124, v125
	v_permlane16_swap_b32_e32 v168, v159
	s_ashr_i32 s17, s16, 31
	v_add_f32_e32 v166, v168, v159
	s_lshl_b64 s[16:17], s[16:17], 19
	v_lshlrev_b32_e32 v159, 6, v158
	s_movk_i32 s1, 0x33c0
	v_readlane_b32 s2, v253, 59
	v_and_or_b32 v159, v159, s1, v196
	v_readlane_b32 s3, v253, 60
	s_add_u32 s1, s2, s16
	s_addc_u32 s16, s3, s17
	s_lshl_b64 s[24:25], s[44:45], 15
	s_add_u32 s48, s1, s24
	s_waitcnt vmcnt(6)
; __device__ __forceinline__ float xsum16(float v) { const auto r = __builtin_amdgcn_permlane16_swap(__float_as_uint(v), __float_as_uint(v), false, false); return __uint_as_float(r[0]) + __uint_as_float(r[1]); }
; __device__ __forceinline__ float xsum32(float v) { const auto r = __builtin_amdgcn_permlane32_swap(__float_as_uint(v), __float_as_uint(v), false, false); return __uint_as_float(r[0]) + __uint_as_float(r[1]); }
; __device__ __forceinline__ size_t blk_off(int r, int c, int K) { return (size_t)(r >> 8) * 256 * K + (size_t)(c >> 6) * (256 * 64) + (size_t)((r & 255) * 64 + (c & 63)); }
; __device__ __forceinline__ u32x4 pack8(const f32x4 a, const f32x4 b) { u32x4 w; w.x = cvt_pk_bf16(a[0], a[1]); w.y = cvt_pk_bf16(a[2], a[3]); w.z = cvt_pk_bf16(b[0], b[1]); w.w = cvt_pk_bf16(b[2], b[3]); return w; }
;     __device__ __forceinline__ void operator()(const f32x4 (&acc)[2][2][4][2], const pg8::Unit& u, int wr, int wc, int fr, int fq) const {
;     ...
;                     for (int n = 0; n < 2; ++n) { yv[bj][n] = *(const f32x4*)(Yin + (size_t)row * D_ + col0 + bj * 128 + 4 * n); gq[bj][n] = *(const f32x4*)(g + col0 + bj * 128 + 4 * n); bq_[bj][n] = *(const f32x4*)(b + col0 + bj * 128 + 4 * n); }
;                 asm volatile("" ::: "memory");
;                 float s1 = 0.f, s2 = 0.f;
; #pragma unroll
;                 for (int bj = 0; bj < 2; ++bj) { float* yp = Y + (size_t)row * D_ + col0 + bj * 128; f32x4 v[2];
; #pragma unroll
;                     for (int n = 0; n < 2; ++n) { v[n] = (((yv[bj][n] - mu) * rs) * gq[bj][n] + bq_[bj][n]) * ALPHA_ + acc[ai][bj][m][n] * sc;
;                         *(f32x4*)(yp + 4 * n) = v[n]; s1 += (v[n][0] + v[n][1]) + (v[n][2] + v[n][3]); s2 += (v[n][0] * v[n][0] + v[n][1] * v[n][1]) + (v[n][2] * v[n][2] + v[n][3] * v[n][3]); }
;                     *(u32x4*)(Yb + blk_off(row, col0 + bj * 128, D_)) = pack8(v[0], v[1]); }
;                 s1 = xsum32(xsum16(s1)); s2 = xsum32(xsum16(s2));
;                 if (fq == 0) *(f32x2*)(stn + (size_t)row * 32 + (u.pn * 4 + wc) * 2) = (f32x2){s1, s2}; asm volatile("" ::: "memory"); } }
	v_permlane32_swap_b32_e32 v186, v178
	v_permlane32_swap_b32_e32 v187, v179
	v_permlane32_swap_b32_e32 v188, v180
	v_permlane32_swap_b32_e32 v189, v181
	v_permlane16_swap_b32_e32 v186, v178
	v_permlane16_swap_b32_e32 v187, v179
	v_permlane16_swap_b32_e32 v188, v180
	v_permlane16_swap_b32_e32 v189, v181
	v_sub_f32_e32 v123, v189, v229
	v_sub_f32_e32 v122, v188, v229
	v_sub_f32_e32 v125, v187, v229
	v_sub_f32_e32 v124, v186, v229
	v_pk_mul_f32 v[124:125], v[0:1], v[124:125] op_sel_hi:[0,1]
	v_pk_mul_f32 v[122:123], v[0:1], v[122:123] op_sel_hi:[0,1]
	s_addc_u32 s49, s16, s25
	v_lshlrev_b32_e32 v159, 1, v159
	global_store_dwordx4 v159, v[126:129], s[48:49]
	v_add_f32_e32 v210, v210, v211
	s_nop 1
	v_lshrrev_b32_e32 v134, 4, v227
	v_lshlrev_b32_e32 v134, 7, v134
	v_add_u32_e32 v134, 0x20100, v134
	s_waitcnt vmcnt(6)
	ds_write_b128 v134, v[190:193] offset:48
	s_waitcnt vmcnt(5)
	ds_write_b128 v134, v[198:201] offset:32
	s_waitcnt vmcnt(4)
	ds_write_b128 v134, v[202:205] offset:112
	s_waitcnt vmcnt(3)
	ds_write_b128 v134, v[238:241] offset:96
	v_pk_fma_f32 v[122:123], v[200:201], v[122:123], v[240:241]
	v_pk_fma_f32 v[124:125], v[198:199], v[124:125], v[238:239]
	v_pk_mul_f32 v[122:123], v[122:123], s[18:19] op_sel_hi:[1,0]
	v_pk_mul_f32 v[124:125], v[124:125], s[18:19] op_sel_hi:[1,0]
	v_pk_fma_f32 v[120:121], v[120:121], 0.5, v[122:123] op_sel_hi:[1,0,1]
	v_pk_fma_f32 v[118:119], v[118:119], 0.5, v[124:125] op_sel_hi:[1,0,1]
	v_add_f32_e32 v123, v120, v121
	v_add_f32_e32 v122, v118, v119
	v_add_f32_e32 v122, v122, v123
	v_add_f32_e32 v126, v197, v122
	v_mul_f32_e32 v122, v119, v119
	v_mul_f32_e32 v123, v121, v121
	v_add_f32_e32 v206, v206, v207
	v_fmac_f32_e32 v122, v118, v118
	v_fmac_f32_e32 v123, v120, v120
	v_add_f32_e32 v206, v210, v206
	v_add_f32_e32 v122, v122, v123
	v_add_f32_e32 v127, v206, v122
	v_sub_f32_e32 v123, v181, v229
	v_sub_f32_e32 v122, v180, v229
	v_sub_f32_e32 v125, v179, v229
	v_sub_f32_e32 v124, v178, v229
	v_pk_mul_f32 v[124:125], v[0:1], v[124:125] op_sel_hi:[0,1]
	v_pk_mul_f32 v[122:123], v[0:1], v[122:123] op_sel_hi:[0,1]
	v_pk_fma_f32 v[122:123], v[192:193], v[122:123], v[204:205]
	v_pk_fma_f32 v[124:125], v[190:191], v[124:125], v[202:203]
	v_pk_mul_f32 v[122:123], v[122:123], s[18:19] op_sel_hi:[1,0]
	v_pk_mul_f32 v[124:125], v[124:125], s[18:19] op_sel_hi:[1,0]
	v_pk_fma_f32 v[116:117], v[116:117], 0.5, v[122:123] op_sel_hi:[1,0,1]
	v_pk_fma_f32 v[114:115], v[114:115], 0.5, v[124:125] op_sel_hi:[1,0,1]
	v_add_f32_e32 v122, v116, v117
	v_add_f32_e32 v0, v114, v115
	v_add_f32_e32 v0, v0, v122
	v_mul_f32_e32 v122, v115, v115
	v_mul_f32_e32 v123, v117, v117
	v_add_f32_e32 v0, v126, v0
	v_fmac_f32_e32 v122, v114, v114
	v_fmac_f32_e32 v123, v116, v116
	s_nop 0
	s_nop 1
	v_bfe_u32 v125, v227, 4, 2
	v_sub_u32_e32 v124, 0, v125
	v_lshlrev_b32_e32 v124, 4, v124
	v_ashrrev_i32_e32 v125, 31, v124
	v_lshl_add_u64 v[124:125], v[136:137], 0, v[124:125]
	v_permlane16_swap_b32_e32 v118, v114
	v_permlane16_swap_b32_e32 v119, v115
	v_permlane16_swap_b32_e32 v120, v116
	v_permlane16_swap_b32_e32 v121, v117
	v_permlane32_swap_b32_e32 v118, v114
	v_permlane32_swap_b32_e32 v119, v115
	v_permlane32_swap_b32_e32 v120, v116
	v_permlane32_swap_b32_e32 v121, v117
	global_store_dwordx4 v[124:125], v[118:121], off offset:512
	global_store_dwordx4 v[124:125], v[114:117], off offset:576
	s_nop 1
	v_permlane32_swap_b32_e32 v118, v114
	v_permlane32_swap_b32_e32 v119, v115
	v_permlane32_swap_b32_e32 v120, v116
	v_permlane32_swap_b32_e32 v121, v117
	v_permlane16_swap_b32_e32 v118, v114
	v_permlane16_swap_b32_e32 v119, v115
	v_permlane16_swap_b32_e32 v120, v116
	v_permlane16_swap_b32_e32 v121, v117
	v_add_f32_e32 v122, v122, v123
	v_cvt_pk_bf16_f32 v118, v118, v119
	v_cvt_pk_bf16_f32 v119, v120, v121
	v_cvt_pk_bf16_f32 v120, v114, v115
	v_mov_b32_e32 v114, v0
	v_add_f32_e32 v122, v127, v122
	s_nop 0
	v_permlane16_swap_b32_e32 v0, v114
	s_or_b32 s2, s44, 2
	v_add_f32_e32 v114, v0, v114
	v_mov_b32_e32 v0, v122
	s_ashr_i32 s3, s2, 31
	s_nop 0
	v_permlane16_swap_b32_e32 v122, v0
	s_lshl_b64 s[44:45], s[2:3], 15
	v_add_f32_e32 v115, v122, v0
	v_mov_b32_e32 v135, v133
	v_mov_b32_e32 v134, v132
	v_mov_b32_e32 v177, v175
	v_mov_b32_e32 v176, v174
	v_mov_b32_e32 v169, v167
	v_mov_b32_e32 v168, v166
	v_cvt_pk_bf16_f32 v121, v116, v117
	s_add_u32 s46, s1, s44
	v_mov_b32_e32 v116, v114
	v_mov_b32_e32 v117, v115
	v_permlane32_swap_b32_e32 v133, v135
	v_permlane32_swap_b32_e32 v132, v134
	v_permlane32_swap_b32_e32 v175, v177
	v_permlane32_swap_b32_e32 v174, v176
	v_permlane32_swap_b32_e32 v167, v169
	v_permlane32_swap_b32_e32 v166, v168
	s_addc_u32 s47, s16, s45
	v_permlane32_swap_b32_e32 v114, v116
	v_permlane32_swap_b32_e32 v115, v117
	global_store_dwordx4 v159, v[118:121], s[46:47]
	s_and_saveexec_b64 s[26:27], s[40:41]
	s_cbranch_execz .LBB0_1705
	v_pk_add_f32 v[114:115], v[114:115], v[116:117]
	v_lshl_add_u64 v[116:117], s[8:9], 0, v[130:131]
	v_lshl_add_u64 v[116:117], s[38:39], 2, v[116:117]
	global_store_dwordx2 v[116:117], v[114:115], off
; __device__ __forceinline__ float xsum16(float v) { const auto r = __builtin_amdgcn_permlane16_swap(__float_as_uint(v), __float_as_uint(v), false, false); return __uint_as_float(r[0]) + __uint_as_float(r[1]); }
; __device__ __forceinline__ float xsum32(float v) { const auto r = __builtin_amdgcn_permlane32_swap(__float_as_uint(v), __float_as_uint(v), false, false); return __uint_as_float(r[0]) + __uint_as_float(r[1]); }
; __device__ __forceinline__ size_t blk_off(int r, int c, int K) { return (size_t)(r >> 8) * 256 * K + (size_t)(c >> 6) * (256 * 64) + (size_t)((r & 255) * 64 + (c & 63)); }
; __device__ __forceinline__ void row_stats4(const float* st, int rowb, int fq, float (&mu)[4], float (&rs)[4]) {
;     ...
;     for (int m = 0; m < 4; ++m) { float s1 = (a[m][0] + a[m][2]) + (b[m][0] + b[m][2]), s2 = (a[m][1] + a[m][3]) + (b[m][1] + b[m][3]);
;         s1 = xsum32(xsum16(s1)); s2 = xsum32(xsum16(s2));
;         const float mm = s1 * (1.0f / 1024.0f); mu[m] = mm; rs[m] = rsqrtf(fmaxf(s2 * (1.0f / 1024.0f) - mm * mm, 0.f) + LN_EPS_); }
;     __device__ __forceinline__ void operator()(const f32x4 (&acc)[2][2][4][2], const pg8::Unit& u, int wr, int wc, int fr, int fq) const {
;     ...
;             for (int m = 0; m < 4; ++m) { const int row = row0 + ai * 128 + m * 16; const float mu = mu4[m], rs = rs4[m];
;                 f32x4 yv[2][2], gq[2][2], bq_[2][2];
; #pragma unroll
;                 for (int bj = 0; bj < 2; ++bj)
; #pragma unroll
;                     for (int n = 0; n < 2; ++n) { yv[bj][n] = *(const f32x4*)(Yin + (size_t)row * D_ + col0 + bj * 128 + 4 * n); gq[bj][n] = *(const f32x4*)(g + col0 + bj * 128 + 4 * n); bq_[bj][n] = *(const f32x4*)(b + col0 + bj * 128 + 4 * n); }
;                 asm volatile("" ::: "memory");
;                 float s1 = 0.f, s2 = 0.f;
; #pragma unroll
;                 for (int bj = 0; bj < 2; ++bj) { float* yp = Y + (size_t)row * D_ + col0 + bj * 128; f32x4 v[2];
; #pragma unroll
;                     for (int n = 0; n < 2; ++n) { v[n] = (((yv[bj][n] - mu) * rs) * gq[bj][n] + bq_[bj][n]) * ALPHA_ + acc[ai][bj][m][n] * sc;
;                         *(f32x4*)(yp + 4 * n) = v[n]; s1 += (v[n][0] + v[n][1]) + (v[n][2] + v[n][3]); s2 += (v[n][0] * v[n][0] + v[n][1] * v[n][1]) + (v[n][2] * v[n][2] + v[n][3] * v[n][3]); }
;                     *(u32x4*)(Yb + blk_off(row, col0 + bj * 128, D_)) = pack8(v[0], v[1]); }
.LBB0_1705:
	s_or_b64 exec, exec, s[26:27]
	v_pk_add_f32 v[114:115], v[132:133], v[134:135]
	s_mov_b32 s2, 0x3a800000
	v_pk_mul_f32 v[178:179], v[114:115], s[2:3] op_sel_hi:[1,0]
	s_mov_b32 s1, 0x800000
	v_fma_f32 v0, -v179, v179, v178
	v_max_f32_e32 v0, 0, v0
	v_add_f32_e32 v0, 0x3727c5ac, v0
	v_cmp_gt_f32_e32 vcc, s1, v0
	v_mul_f32_e32 v114, 0x4b800000, v0
	s_load_dwordx16 s[60:75], s[34:35], 0x38
	v_cndmask_b32_e32 v0, v0, v114, vcc
	v_rsq_f32_e32 v0, v0
	v_lshlrev_b32_e32 v159, 6, v182
	s_mov_b32 s2, 0x3fd744fd
	v_mul_f32_e32 v114, 0x45800000, v0
	v_cndmask_b32_e32 v0, v0, v114, vcc
	v_lshlrev_b64 v[114:115], 12, v[182:183]
	s_waitcnt lgkmcnt(0)
	v_lshl_add_u64 v[114:115], s[74:75], 0, v[114:115]
	v_lshl_add_u64 v[180:181], v[152:153], 2, v[114:115]
	s_nop 1
	v_bfe_u32 v117, v227, 4, 2
	v_sub_u32_e32 v116, 0, v117
	v_lshlrev_b32_e32 v116, 4, v116
	v_ashrrev_i32_e32 v117, 31, v116
	v_lshl_add_u64 v[116:117], v[180:181], 0, v[116:117]
	global_load_dwordx4 v[186:189], v[116:117], off offset:64
	global_load_dwordx4 v[190:193], v[116:117], off
	s_nop 1
	v_lshrrev_b32_e32 v178, 4, v227
	v_lshlrev_b32_e32 v178, 7, v178
	v_add_u32_e32 v178, 0x20100, v178
	ds_read_b128 v[198:201], v178 offset:16
	ds_read_b128 v[202:205], v178 offset:0
	ds_read_b128 v[206:209], v178 offset:80
	ds_read_b128 v[210:213], v178 offset:64
	s_nop 1
	v_bfe_u32 v119, v227, 4, 2
	v_sub_u32_e32 v118, 0, v119
	v_lshlrev_b32_e32 v118, 4, v118
	v_ashrrev_i32_e32 v119, 31, v118
	v_lshl_add_u64 v[118:119], v[180:181], 0, v[118:119]
	global_load_dwordx4 v[114:117], v[118:119], off offset:576
	global_load_dwordx4 v[134:137], v[118:119], off offset:512
	ds_read_b128 v[118:121], v178 offset:48
	ds_read_b128 v[126:129], v178 offset:32
	ds_read_b128 v[122:125], v178 offset:112
	ds_read_b128 v[130:133], v178 offset:96
	s_movk_i32 s1, 0x37c0
	v_and_or_b32 v159, v159, s1, v196
	v_lshlrev_b32_e32 v159, 1, v159
	s_waitcnt vmcnt(2)
	v_permlane32_swap_b32_e32 v190, v186
	v_permlane32_swap_b32_e32 v191, v187
	v_permlane32_swap_b32_e32 v192, v188
	v_permlane32_swap_b32_e32 v193, v189
	v_permlane16_swap_b32_e32 v190, v186
	v_permlane16_swap_b32_e32 v191, v187
	v_permlane16_swap_b32_e32 v192, v188
	v_permlane16_swap_b32_e32 v193, v189
	v_sub_f32_e32 v187, v187, v179
	v_sub_f32_e32 v183, v193, v179
	v_sub_f32_e32 v182, v192, v179
	v_sub_f32_e32 v191, v191, v179
	v_sub_f32_e32 v190, v190, v179
	v_pk_mul_f32 v[190:191], v[0:1], v[190:191] op_sel_hi:[0,1]
	v_pk_mul_f32 v[182:183], v[0:1], v[182:183] op_sel_hi:[0,1]
	s_waitcnt lgkmcnt(0)
	v_pk_fma_f32 v[182:183], v[204:205], v[182:183], v[212:213]
	v_pk_fma_f32 v[190:191], v[202:203], v[190:191], v[210:211]
	v_pk_mul_f32 v[182:183], v[182:183], s[2:3] op_sel_hi:[1,0]
	v_pk_mul_f32 v[190:191], v[190:191], s[2:3] op_sel_hi:[1,0]
	v_pk_fma_f32 v[112:113], v[112:113], 0.5, v[182:183] op_sel_hi:[1,0,1]
	v_pk_fma_f32 v[110:111], v[110:111], 0.5, v[190:191] op_sel_hi:[1,0,1]
	v_add_f32_e32 v182, v112, v113
	v_add_f32_e32 v178, v110, v111
	v_add_f32_e32 v178, v178, v182
	v_mul_f32_e32 v182, v111, v111
	v_mul_f32_e32 v183, v113, v113
	v_fmac_f32_e32 v182, v110, v110
	v_fmac_f32_e32 v183, v112, v112
	v_add_f32_e32 v190, v182, v183
	v_sub_f32_e32 v183, v189, v179
	v_sub_f32_e32 v182, v188, v179
	v_sub_f32_e32 v186, v186, v179
	v_pk_mul_f32 v[186:187], v[0:1], v[186:187] op_sel_hi:[0,1]
	v_pk_mul_f32 v[182:183], v[0:1], v[182:183] op_sel_hi:[0,1]
	v_pk_fma_f32 v[182:183], v[200:201], v[182:183], v[208:209]
	v_pk_fma_f32 v[186:187], v[198:199], v[186:187], v[206:207]
	v_pk_mul_f32 v[182:183], v[182:183], s[2:3] op_sel_hi:[1,0]
	v_pk_mul_f32 v[186:187], v[186:187], s[2:3] op_sel_hi:[1,0]
	v_pk_fma_f32 v[108:109], v[108:109], 0.5, v[182:183] op_sel_hi:[1,0,1]
	v_pk_fma_f32 v[106:107], v[106:107], 0.5, v[186:187] op_sel_hi:[1,0,1]
	v_add_f32_e32 v183, v108, v109
	v_add_f32_e32 v182, v106, v107
	v_add_f32_e32 v178, 0, v178
	v_add_f32_e32 v182, v182, v183
	v_add_f32_e32 v178, v178, v182
	v_mul_f32_e32 v182, v107, v107
	v_mul_f32_e32 v183, v109, v109
	s_nop 0
	s_nop 1
	v_bfe_u32 v155, v227, 4, 2
	v_sub_u32_e32 v154, 0, v155
	v_lshlrev_b32_e32 v154, 4, v154
	v_ashrrev_i32_e32 v155, 31, v154
	v_lshl_add_u64 v[154:155], v[180:181], 0, v[154:155]
	v_permlane16_swap_b32_e32 v110, v106
	v_permlane16_swap_b32_e32 v111, v107
	v_permlane16_swap_b32_e32 v112, v108
	v_permlane16_swap_b32_e32 v113, v109
	v_permlane32_swap_b32_e32 v110, v106
	v_permlane32_swap_b32_e32 v111, v107
	v_permlane32_swap_b32_e32 v112, v108
	v_permlane32_swap_b32_e32 v113, v109
	global_store_dwordx4 v[154:155], v[110:113], off
	global_store_dwordx4 v[154:155], v[106:109], off offset:64
	s_nop 1
	v_permlane32_swap_b32_e32 v110, v106
	v_permlane32_swap_b32_e32 v111, v107
	v_permlane32_swap_b32_e32 v112, v108
	v_permlane32_swap_b32_e32 v113, v109
	v_permlane16_swap_b32_e32 v110, v106
	v_permlane16_swap_b32_e32 v111, v107
	v_permlane16_swap_b32_e32 v112, v108
	v_permlane16_swap_b32_e32 v113, v109
	v_fmac_f32_e32 v182, v106, v106
	v_fmac_f32_e32 v183, v108, v108
	v_cvt_pk_bf16_f32 v110, v110, v111
	v_cvt_pk_bf16_f32 v111, v112, v113
	v_cvt_pk_bf16_f32 v112, v106, v107
	v_cvt_pk_bf16_f32 v113, v108, v109
	s_waitcnt vmcnt(2)
; __device__ __forceinline__ float xsum16(float v) { const auto r = __builtin_amdgcn_permlane16_swap(__float_as_uint(v), __float_as_uint(v), false, false); return __uint_as_float(r[0]) + __uint_as_float(r[1]); }
; __device__ __forceinline__ float xsum32(float v) { const auto r = __builtin_amdgcn_permlane32_swap(__float_as_uint(v), __float_as_uint(v), false, false); return __uint_as_float(r[0]) + __uint_as_float(r[1]); }
; __device__ __forceinline__ size_t blk_off(int r, int c, int K) { return (size_t)(r >> 8) * 256 * K + (size_t)(c >> 6) * (256 * 64) + (size_t)((r & 255) * 64 + (c & 63)); }
; __device__ __forceinline__ u32x4 pack8(const f32x4 a, const f32x4 b) { u32x4 w; w.x = cvt_pk_bf16(a[0], a[1]); w.y = cvt_pk_bf16(a[2], a[3]); w.z = cvt_pk_bf16(b[0], b[1]); w.w = cvt_pk_bf16(b[2], b[3]); return w; }
;     __device__ __forceinline__ void operator()(const f32x4 (&acc)[2][2][4][2], const pg8::Unit& u, int wr, int wc, int fr, int fq) const {
;     ...
;             for (int m = 0; m < 4; ++m) { const int row = row0 + ai * 128 + m * 16; const float mu = mu4[m], rs = rs4[m];
;                 f32x4 yv[2][2], gq[2][2], bq_[2][2];
; #pragma unroll
;                 for (int bj = 0; bj < 2; ++bj)
; #pragma unroll
;                     for (int n = 0; n < 2; ++n) { yv[bj][n] = *(const f32x4*)(Yin + (size_t)row * D_ + col0 + bj * 128 + 4 * n); gq[bj][n] = *(const f32x4*)(g + col0 + bj * 128 + 4 * n); bq_[bj][n] = *(const f32x4*)(b + col0 + bj * 128 + 4 * n); }
;                 asm volatile("" ::: "memory");
;                 float s1 = 0.f, s2 = 0.f;
; #pragma unroll
;                 for (int bj = 0; bj < 2; ++bj) { float* yp = Y + (size_t)row * D_ + col0 + bj * 128; f32x4 v[2];
; #pragma unroll
;                     for (int n = 0; n < 2; ++n) { v[n] = (((yv[bj][n] - mu) * rs) * gq[bj][n] + bq_[bj][n]) * ALPHA_ + acc[ai][bj][m][n] * sc;
;                         *(f32x4*)(yp + 4 * n) = v[n]; s1 += (v[n][0] + v[n][1]) + (v[n][2] + v[n][3]); s2 += (v[n][0] * v[n][0] + v[n][1] * v[n][1]) + (v[n][2] * v[n][2] + v[n][3] * v[n][3]); }
;                     *(u32x4*)(Yb + blk_off(row, col0 + bj * 128, D_)) = pack8(v[0], v[1]); }
;                 s1 = xsum32(xsum16(s1)); s2 = xsum32(xsum16(s2));
;                 if (fq == 0) *(f32x2*)(stn + (size_t)row * 32 + (u.pn * 4 + wc) * 2) = (f32x2){s1, s2}; asm volatile("" ::: "memory"); } }
	v_permlane32_swap_b32_e32 v134, v114
	v_permlane32_swap_b32_e32 v135, v115
	v_permlane32_swap_b32_e32 v136, v116
	v_permlane32_swap_b32_e32 v137, v117
	v_permlane16_swap_b32_e32 v134, v114
	v_permlane16_swap_b32_e32 v135, v115
	v_permlane16_swap_b32_e32 v136, v116
	v_permlane16_swap_b32_e32 v137, v117
	v_sub_f32_e32 v107, v137, v179
	v_sub_f32_e32 v106, v136, v179
	v_sub_f32_e32 v109, v135, v179
	v_sub_f32_e32 v108, v134, v179
	v_pk_mul_f32 v[108:109], v[0:1], v[108:109] op_sel_hi:[0,1]
	v_pk_mul_f32 v[106:107], v[0:1], v[106:107] op_sel_hi:[0,1]
	v_pk_fma_f32 v[106:107], v[128:129], v[106:107], v[132:133]
	v_pk_fma_f32 v[108:109], v[126:127], v[108:109], v[130:131]
	v_pk_mul_f32 v[106:107], v[106:107], s[2:3] op_sel_hi:[1,0]
	v_pk_mul_f32 v[108:109], v[108:109], s[2:3] op_sel_hi:[1,0]
	v_pk_fma_f32 v[104:105], v[104:105], 0.5, v[106:107] op_sel_hi:[1,0,1]
	v_pk_fma_f32 v[102:103], v[102:103], 0.5, v[108:109] op_sel_hi:[1,0,1]
	v_add_f32_e32 v107, v104, v105
	v_add_f32_e32 v106, v102, v103
	v_add_f32_e32 v106, v106, v107
	global_store_dwordx4 v159, v[110:113], s[48:49]
	v_mul_f32_e32 v107, v105, v105
	v_add_f32_e32 v182, v182, v183
	v_add_f32_e32 v110, v178, v106
	v_mul_f32_e32 v106, v103, v103
	v_fmac_f32_e32 v106, v102, v102
	v_fmac_f32_e32 v107, v104, v104
	v_add_f32_e32 v182, v190, v182
	v_add_f32_e32 v106, v106, v107
	v_add_f32_e32 v111, v182, v106
	v_sub_f32_e32 v107, v117, v179
	v_sub_f32_e32 v106, v116, v179
	v_sub_f32_e32 v109, v115, v179
	v_sub_f32_e32 v108, v114, v179
	v_pk_mul_f32 v[108:109], v[0:1], v[108:109] op_sel_hi:[0,1]
	v_pk_mul_f32 v[106:107], v[0:1], v[106:107] op_sel_hi:[0,1]
	v_pk_fma_f32 v[106:107], v[120:121], v[106:107], v[124:125]
	v_pk_fma_f32 v[108:109], v[118:119], v[108:109], v[122:123]
	v_pk_mul_f32 v[106:107], v[106:107], s[2:3] op_sel_hi:[1,0]
	v_pk_mul_f32 v[108:109], v[108:109], s[2:3] op_sel_hi:[1,0]
	v_pk_fma_f32 v[100:101], v[100:101], 0.5, v[106:107] op_sel_hi:[1,0,1]
	v_pk_fma_f32 v[98:99], v[98:99], 0.5, v[108:109] op_sel_hi:[1,0,1]
	v_add_f32_e32 v106, v100, v101
	v_add_f32_e32 v0, v98, v99
	v_add_f32_e32 v0, v0, v106
	v_mul_f32_e32 v106, v99, v99
	v_mul_f32_e32 v107, v101, v101
	v_add_f32_e32 v0, v110, v0
	v_fmac_f32_e32 v106, v98, v98
	v_fmac_f32_e32 v107, v100, v100
	s_nop 0
	s_nop 1
	v_bfe_u32 v109, v227, 4, 2
	v_sub_u32_e32 v108, 0, v109
	v_lshlrev_b32_e32 v108, 4, v108
	v_ashrrev_i32_e32 v109, 31, v108
	v_lshl_add_u64 v[108:109], v[180:181], 0, v[108:109]
	v_permlane16_swap_b32_e32 v102, v98
	v_permlane16_swap_b32_e32 v103, v99
	v_permlane16_swap_b32_e32 v104, v100
	v_permlane16_swap_b32_e32 v105, v101
	v_permlane32_swap_b32_e32 v102, v98
	v_permlane32_swap_b32_e32 v103, v99
	v_permlane32_swap_b32_e32 v104, v100
	v_permlane32_swap_b32_e32 v105, v101
	global_store_dwordx4 v[108:109], v[102:105], off offset:512
	global_store_dwordx4 v[108:109], v[98:101], off offset:576
	s_nop 1
	v_permlane32_swap_b32_e32 v102, v98
	v_permlane32_swap_b32_e32 v103, v99
	v_permlane32_swap_b32_e32 v104, v100
	v_permlane32_swap_b32_e32 v105, v101
	v_permlane16_swap_b32_e32 v102, v98
	v_permlane16_swap_b32_e32 v103, v99
	v_permlane16_swap_b32_e32 v104, v100
	v_permlane16_swap_b32_e32 v105, v101
	v_add_f32_e32 v106, v106, v107
	v_cvt_pk_bf16_f32 v102, v102, v103
	v_cvt_pk_bf16_f32 v103, v104, v105
	v_cvt_pk_bf16_f32 v104, v98, v99
	v_mov_b32_e32 v98, v0
	v_add_f32_e32 v106, v111, v106
	s_nop 0
	v_permlane16_swap_b32_e32 v0, v98
	v_add_f32_e32 v98, v0, v98
	v_mov_b32_e32 v0, v106
	s_nop 1
	v_permlane16_swap_b32_e32 v106, v0
	v_add_f32_e32 v99, v106, v0
	v_cvt_pk_bf16_f32 v105, v100, v101
	v_mov_b32_e32 v100, v98
	v_mov_b32_e32 v101, v99
	s_nop 0
	v_permlane32_swap_b32_e32 v98, v100
	v_permlane32_swap_b32_e32 v99, v101
	global_store_dwordx4 v159, v[102:105], s[46:47]
	s_and_saveexec_b64 s[26:27], s[40:41]
	s_cbranch_execz .LBB0_1707
	v_pk_add_f32 v[98:99], v[98:99], v[100:101]
	v_lshl_add_u64 v[100:101], s[8:9], 0, v[172:173]
	v_lshl_add_u64 v[100:101], s[38:39], 2, v[100:101]
	global_store_dwordx2 v[100:101], v[98:99], off
.LBB0_1707:
	s_or_b64 exec, exec, s[26:27]
	v_pk_add_f32 v[98:99], v[174:175], v[176:177]
	s_mov_b32 s2, 0x3a800000
	v_pk_mul_f32 v[122:123], v[98:99], s[2:3] op_sel_hi:[1,0]
	s_mov_b32 s1, 0x800000
	v_fma_f32 v0, -v123, v123, v122
	v_max_f32_e32 v0, 0, v0
	v_add_f32_e32 v0, 0x3727c5ac, v0
	v_cmp_gt_f32_e32 vcc, s1, v0
	v_mul_f32_e32 v98, 0x4b800000, v0
	s_load_dwordx16 s[60:75], s[34:35], 0x38
	v_cndmask_b32_e32 v0, v0, v98, vcc
	v_rsq_f32_e32 v0, v0
	s_mov_b32 s2, 0x3fd744fd
	v_lshlrev_b32_e32 v122, 6, v170
	v_mul_f32_e32 v98, 0x45800000, v0
	v_cndmask_b32_e32 v0, v0, v98, vcc
	v_lshlrev_b64 v[98:99], 12, v[170:171]
	s_waitcnt lgkmcnt(0)
	v_lshl_add_u64 v[98:99], s[74:75], 0, v[98:99]
	v_lshl_add_u64 v[124:125], v[152:153], 2, v[98:99]
	s_nop 1
	v_bfe_u32 v101, v227, 4, 2
	v_sub_u32_e32 v100, 0, v101
	v_lshlrev_b32_e32 v100, 4, v100
	v_ashrrev_i32_e32 v101, 31, v100
	v_lshl_add_u64 v[100:101], v[124:125], 0, v[100:101]
	global_load_dwordx4 v[126:129], v[100:101], off offset:64
	global_load_dwordx4 v[130:133], v[100:101], off
	s_nop 1
	v_lshrrev_b32_e32 v159, 4, v227
	v_lshlrev_b32_e32 v159, 7, v159
	v_add_u32_e32 v159, 0x20100, v159
	ds_read_b128 v[134:137], v159 offset:16
	ds_read_b128 v[172:175], v159 offset:0
	ds_read_b128 v[176:179], v159 offset:80
	ds_read_b128 v[180:183], v159 offset:64
	s_nop 1
	v_bfe_u32 v103, v227, 4, 2
	v_sub_u32_e32 v102, 0, v103
	v_lshlrev_b32_e32 v102, 4, v102
	v_ashrrev_i32_e32 v103, 31, v102
	v_lshl_add_u64 v[102:103], v[124:125], 0, v[102:103]
	global_load_dwordx4 v[98:101], v[102:103], off offset:576
	global_load_dwordx4 v[118:121], v[102:103], off offset:512
	ds_read_b128 v[102:105], v159 offset:48
	ds_read_b128 v[110:113], v159 offset:32
	ds_read_b128 v[106:109], v159 offset:112
	ds_read_b128 v[114:117], v159 offset:96
	s_movk_i32 s1, 0x3bc0
	v_and_or_b32 v122, v122, s1, v196
	v_lshlrev_b32_e32 v122, 1, v122
	s_waitcnt vmcnt(2)
; __device__ __forceinline__ float xsum16(float v) { const auto r = __builtin_amdgcn_permlane16_swap(__float_as_uint(v), __float_as_uint(v), false, false); return __uint_as_float(r[0]) + __uint_as_float(r[1]); }
; __device__ __forceinline__ float xsum32(float v) { const auto r = __builtin_amdgcn_permlane32_swap(__float_as_uint(v), __float_as_uint(v), false, false); return __uint_as_float(r[0]) + __uint_as_float(r[1]); }
; __device__ __forceinline__ size_t blk_off(int r, int c, int K) { return (size_t)(r >> 8) * 256 * K + (size_t)(c >> 6) * (256 * 64) + (size_t)((r & 255) * 64 + (c & 63)); }
; __device__ __forceinline__ u32x4 pack8(const f32x4 a, const f32x4 b) { u32x4 w; w.x = cvt_pk_bf16(a[0], a[1]); w.y = cvt_pk_bf16(a[2], a[3]); w.z = cvt_pk_bf16(b[0], b[1]); w.w = cvt_pk_bf16(b[2], b[3]); return w; }
;     __device__ __forceinline__ void operator()(const f32x4 (&acc)[2][2][4][2], const pg8::Unit& u, int wr, int wc, int fr, int fq) const {
;     ...
;                     for (int n = 0; n < 2; ++n) { yv[bj][n] = *(const f32x4*)(Yin + (size_t)row * D_ + col0 + bj * 128 + 4 * n); gq[bj][n] = *(const f32x4*)(g + col0 + bj * 128 + 4 * n); bq_[bj][n] = *(const f32x4*)(b + col0 + bj * 128 + 4 * n); }
;                 asm volatile("" ::: "memory");
;                 float s1 = 0.f, s2 = 0.f;
; #pragma unroll
;                 for (int bj = 0; bj < 2; ++bj) { float* yp = Y + (size_t)row * D_ + col0 + bj * 128; f32x4 v[2];
; #pragma unroll
;                     for (int n = 0; n < 2; ++n) { v[n] = (((yv[bj][n] - mu) * rs) * gq[bj][n] + bq_[bj][n]) * ALPHA_ + acc[ai][bj][m][n] * sc;
;                         *(f32x4*)(yp + 4 * n) = v[n]; s1 += (v[n][0] + v[n][1]) + (v[n][2] + v[n][3]); s2 += (v[n][0] * v[n][0] + v[n][1] * v[n][1]) + (v[n][2] * v[n][2] + v[n][3] * v[n][3]); }
;                     *(u32x4*)(Yb + blk_off(row, col0 + bj * 128, D_)) = pack8(v[0], v[1]); }
;                 s1 = xsum32(xsum16(s1)); s2 = xsum32(xsum16(s2));
;                 if (fq == 0) *(f32x2*)(stn + (size_t)row * 32 + (u.pn * 4 + wc) * 2) = (f32x2){s1, s2}; asm volatile("" ::: "memory"); } }
	v_permlane32_swap_b32_e32 v130, v126
	v_permlane32_swap_b32_e32 v131, v127
	v_permlane32_swap_b32_e32 v132, v128
	v_permlane32_swap_b32_e32 v133, v129
	v_permlane16_swap_b32_e32 v130, v126
	v_permlane16_swap_b32_e32 v131, v127
	v_permlane16_swap_b32_e32 v132, v128
	v_permlane16_swap_b32_e32 v133, v129
	v_sub_f32_e32 v129, v129, v123
	v_sub_f32_e32 v133, v133, v123
	v_sub_f32_e32 v132, v132, v123
	v_sub_f32_e32 v131, v131, v123
	v_sub_f32_e32 v130, v130, v123
	v_sub_f32_e32 v128, v128, v123
	v_sub_f32_e32 v127, v127, v123
	v_sub_f32_e32 v126, v126, v123
	v_pk_mul_f32 v[130:131], v[0:1], v[130:131] op_sel_hi:[0,1]
	v_pk_mul_f32 v[132:133], v[0:1], v[132:133] op_sel_hi:[0,1]
	v_pk_mul_f32 v[126:127], v[0:1], v[126:127] op_sel_hi:[0,1]
	v_pk_mul_f32 v[128:129], v[0:1], v[128:129] op_sel_hi:[0,1]
	s_waitcnt lgkmcnt(0)
	v_pk_fma_f32 v[132:133], v[174:175], v[132:133], v[182:183]
	v_pk_fma_f32 v[130:131], v[172:173], v[130:131], v[180:181]
	v_pk_fma_f32 v[128:129], v[136:137], v[128:129], v[178:179]
	v_pk_fma_f32 v[126:127], v[134:135], v[126:127], v[176:177]
	v_pk_mul_f32 v[130:131], v[130:131], s[2:3] op_sel_hi:[1,0]
	v_pk_mul_f32 v[132:133], v[132:133], s[2:3] op_sel_hi:[1,0]
	v_pk_mul_f32 v[126:127], v[126:127], s[2:3] op_sel_hi:[1,0]
	v_pk_mul_f32 v[128:129], v[128:129], s[2:3] op_sel_hi:[1,0]
	v_pk_fma_f32 v[96:97], v[96:97], 0.5, v[132:133] op_sel_hi:[1,0,1]
	v_pk_fma_f32 v[94:95], v[94:95], 0.5, v[130:131] op_sel_hi:[1,0,1]
	v_pk_fma_f32 v[92:93], v[92:93], 0.5, v[128:129] op_sel_hi:[1,0,1]
	v_pk_fma_f32 v[90:91], v[90:91], 0.5, v[126:127] op_sel_hi:[1,0,1]
	v_add_f32_e32 v130, v94, v95
	v_add_f32_e32 v131, v96, v97
	v_add_f32_e32 v126, v90, v91
	v_add_f32_e32 v127, v92, v93
	v_add_f32_e32 v130, v130, v131
	v_mul_f32_e32 v131, v95, v95
	v_mul_f32_e32 v132, v97, v97
	v_add_f32_e32 v126, v126, v127
	v_mul_f32_e32 v127, v91, v91
	v_mul_f32_e32 v128, v93, v93
	s_nop 0
	v_fmac_f32_e32 v131, v94, v94
	v_fmac_f32_e32 v132, v96, v96
	s_nop 1
	v_bfe_u32 v135, v227, 4, 2
	v_sub_u32_e32 v134, 0, v135
	v_lshlrev_b32_e32 v134, 4, v134
	v_ashrrev_i32_e32 v135, 31, v134
	v_lshl_add_u64 v[134:135], v[124:125], 0, v[134:135]
	v_permlane16_swap_b32_e32 v94, v90
	v_permlane16_swap_b32_e32 v95, v91
	v_permlane16_swap_b32_e32 v96, v92
	v_permlane16_swap_b32_e32 v97, v93
	v_permlane32_swap_b32_e32 v94, v90
	v_permlane32_swap_b32_e32 v95, v91
	v_permlane32_swap_b32_e32 v96, v92
	v_permlane32_swap_b32_e32 v97, v93
	global_store_dwordx4 v[134:135], v[94:97], off
	global_store_dwordx4 v[134:135], v[90:93], off offset:64
	s_nop 1
	v_permlane32_swap_b32_e32 v94, v90
	v_permlane32_swap_b32_e32 v95, v91
	v_permlane32_swap_b32_e32 v96, v92
	v_permlane32_swap_b32_e32 v97, v93
	v_permlane16_swap_b32_e32 v94, v90
	v_permlane16_swap_b32_e32 v95, v91
	v_permlane16_swap_b32_e32 v96, v92
	v_permlane16_swap_b32_e32 v97, v93
	v_fmac_f32_e32 v127, v90, v90
	v_fmac_f32_e32 v128, v92, v92
	v_cvt_pk_bf16_f32 v94, v94, v95
	v_cvt_pk_bf16_f32 v95, v96, v97
	v_cvt_pk_bf16_f32 v96, v90, v91
	v_cvt_pk_bf16_f32 v97, v92, v93
	s_waitcnt vmcnt(2)
	v_permlane32_swap_b32_e32 v118, v98
	v_permlane32_swap_b32_e32 v119, v99
	v_permlane32_swap_b32_e32 v120, v100
	v_permlane32_swap_b32_e32 v121, v101
	v_permlane16_swap_b32_e32 v118, v98
	v_permlane16_swap_b32_e32 v119, v99
	v_permlane16_swap_b32_e32 v120, v100
	v_permlane16_swap_b32_e32 v121, v101
	v_sub_f32_e32 v91, v121, v123
	v_sub_f32_e32 v90, v120, v123
	v_sub_f32_e32 v93, v119, v123
	v_sub_f32_e32 v92, v118, v123
	v_pk_mul_f32 v[92:93], v[0:1], v[92:93] op_sel_hi:[0,1]
	v_pk_mul_f32 v[90:91], v[0:1], v[90:91] op_sel_hi:[0,1]
	v_pk_fma_f32 v[90:91], v[112:113], v[90:91], v[116:117]
	v_pk_fma_f32 v[92:93], v[110:111], v[92:93], v[114:115]
	v_pk_mul_f32 v[90:91], v[90:91], s[2:3] op_sel_hi:[1,0]
	v_pk_mul_f32 v[92:93], v[92:93], s[2:3] op_sel_hi:[1,0]
	v_pk_fma_f32 v[88:89], v[88:89], 0.5, v[90:91] op_sel_hi:[1,0,1]
	v_pk_fma_f32 v[86:87], v[86:87], 0.5, v[92:93] op_sel_hi:[1,0,1]
	v_add_f32_e32 v130, 0, v130
	v_add_f32_e32 v90, v86, v87
	v_add_f32_e32 v91, v88, v89
	v_add_f32_e32 v126, v130, v126
	v_add_f32_e32 v90, v90, v91
	global_store_dwordx4 v122, v[94:97], s[48:49]
	v_mul_f32_e32 v91, v89, v89
	v_add_f32_e32 v131, v131, v132
	v_add_f32_e32 v94, v126, v90
	v_mul_f32_e32 v90, v87, v87
	v_add_f32_e32 v127, v127, v128
	v_fmac_f32_e32 v90, v86, v86
	v_fmac_f32_e32 v91, v88, v88
	v_add_f32_e32 v127, v131, v127
	v_add_f32_e32 v90, v90, v91
	v_add_f32_e32 v95, v127, v90
	v_sub_f32_e32 v91, v101, v123
	v_sub_f32_e32 v90, v100, v123
	v_sub_f32_e32 v93, v99, v123
	v_sub_f32_e32 v92, v98, v123
	v_pk_mul_f32 v[92:93], v[0:1], v[92:93] op_sel_hi:[0,1]
	v_pk_mul_f32 v[90:91], v[0:1], v[90:91] op_sel_hi:[0,1]
	v_pk_fma_f32 v[90:91], v[104:105], v[90:91], v[108:109]
	v_pk_fma_f32 v[92:93], v[102:103], v[92:93], v[106:107]
	v_pk_mul_f32 v[90:91], v[90:91], s[2:3] op_sel_hi:[1,0]
	v_pk_mul_f32 v[92:93], v[92:93], s[2:3] op_sel_hi:[1,0]
	v_pk_fma_f32 v[84:85], v[84:85], 0.5, v[90:91] op_sel_hi:[1,0,1]
	v_pk_fma_f32 v[82:83], v[82:83], 0.5, v[92:93] op_sel_hi:[1,0,1]
	v_add_f32_e32 v90, v84, v85
	v_add_f32_e32 v0, v82, v83
	v_add_f32_e32 v0, v0, v90
	v_mul_f32_e32 v90, v83, v83
	v_mul_f32_e32 v91, v85, v85
	v_add_f32_e32 v0, v94, v0
	v_fmac_f32_e32 v90, v82, v82
	v_fmac_f32_e32 v91, v84, v84
	s_nop 0
	s_nop 1
	v_bfe_u32 v93, v227, 4, 2
	v_sub_u32_e32 v92, 0, v93
	v_lshlrev_b32_e32 v92, 4, v92
	v_ashrrev_i32_e32 v93, 31, v92
	v_lshl_add_u64 v[92:93], v[124:125], 0, v[92:93]
	v_permlane16_swap_b32_e32 v86, v82
	v_permlane16_swap_b32_e32 v87, v83
	v_permlane16_swap_b32_e32 v88, v84
	v_permlane16_swap_b32_e32 v89, v85
	v_permlane32_swap_b32_e32 v86, v82
	v_permlane32_swap_b32_e32 v87, v83
	v_permlane32_swap_b32_e32 v88, v84
	v_permlane32_swap_b32_e32 v89, v85
	global_store_dwordx4 v[92:93], v[86:89], off offset:512
	global_store_dwordx4 v[92:93], v[82:85], off offset:576
	s_nop 1
	v_permlane32_swap_b32_e32 v86, v82
	v_permlane32_swap_b32_e32 v87, v83
	v_permlane32_swap_b32_e32 v88, v84
	v_permlane32_swap_b32_e32 v89, v85
	v_permlane16_swap_b32_e32 v86, v82
	v_permlane16_swap_b32_e32 v87, v83
	v_permlane16_swap_b32_e32 v88, v84
	v_permlane16_swap_b32_e32 v89, v85
	v_add_f32_e32 v90, v90, v91
	v_cvt_pk_bf16_f32 v86, v86, v87
	v_cvt_pk_bf16_f32 v87, v88, v89
	v_cvt_pk_bf16_f32 v88, v82, v83
	v_mov_b32_e32 v82, v0
	v_add_f32_e32 v90, v95, v90
	s_nop 0
	v_permlane16_swap_b32_e32 v0, v82
	v_add_f32_e32 v82, v0, v82
	v_mov_b32_e32 v0, v90
	s_nop 1
	v_permlane16_swap_b32_e32 v90, v0
	v_add_f32_e32 v83, v90, v0
	v_cvt_pk_bf16_f32 v89, v84, v85
	v_mov_b32_e32 v84, v82
	v_mov_b32_e32 v85, v83
	s_nop 0
	v_permlane32_swap_b32_e32 v82, v84
	v_permlane32_swap_b32_e32 v83, v85
	global_store_dwordx4 v122, v[86:89], s[46:47]
	s_and_saveexec_b64 s[26:27], s[40:41]
	s_cbranch_execz .LBB0_1709
	v_pk_add_f32 v[82:83], v[82:83], v[84:85]
	v_lshl_add_u64 v[84:85], s[8:9], 0, v[164:165]
	v_lshl_add_u64 v[84:85], s[38:39], 2, v[84:85]
	global_store_dwordx2 v[84:85], v[82:83], off
; __device__ __forceinline__ float xsum16(float v) { const auto r = __builtin_amdgcn_permlane16_swap(__float_as_uint(v), __float_as_uint(v), false, false); return __uint_as_float(r[0]) + __uint_as_float(r[1]); }
; __device__ __forceinline__ float xsum32(float v) { const auto r = __builtin_amdgcn_permlane32_swap(__float_as_uint(v), __float_as_uint(v), false, false); return __uint_as_float(r[0]) + __uint_as_float(r[1]); }
; __device__ __forceinline__ size_t blk_off(int r, int c, int K) { return (size_t)(r >> 8) * 256 * K + (size_t)(c >> 6) * (256 * 64) + (size_t)((r & 255) * 64 + (c & 63)); }
; __device__ __forceinline__ void row_stats4(const float* st, int rowb, int fq, float (&mu)[4], float (&rs)[4]) {
;     ...
;     for (int m = 0; m < 4; ++m) { float s1 = (a[m][0] + a[m][2]) + (b[m][0] + b[m][2]), s2 = (a[m][1] + a[m][3]) + (b[m][1] + b[m][3]);
;         s1 = xsum32(xsum16(s1)); s2 = xsum32(xsum16(s2));
;         const float mm = s1 * (1.0f / 1024.0f); mu[m] = mm; rs[m] = rsqrtf(fmaxf(s2 * (1.0f / 1024.0f) - mm * mm, 0.f) + LN_EPS_); }
;     __device__ __forceinline__ void operator()(const f32x4 (&acc)[2][2][4][2], const pg8::Unit& u, int wr, int wc, int fr, int fq) const {
;     ...
;             for (int m = 0; m < 4; ++m) { const int row = row0 + ai * 128 + m * 16; const float mu = mu4[m], rs = rs4[m];
;                 f32x4 yv[2][2], gq[2][2], bq_[2][2];
; #pragma unroll
;                 for (int bj = 0; bj < 2; ++bj)
; #pragma unroll
;                     for (int n = 0; n < 2; ++n) { yv[bj][n] = *(const f32x4*)(Yin + (size_t)row * D_ + col0 + bj * 128 + 4 * n); gq[bj][n] = *(const f32x4*)(g + col0 + bj * 128 + 4 * n); bq_[bj][n] = *(const f32x4*)(b + col0 + bj * 128 + 4 * n); }
;                 asm volatile("" ::: "memory");
;                 float s1 = 0.f, s2 = 0.f;
; #pragma unroll
;                 for (int bj = 0; bj < 2; ++bj) { float* yp = Y + (size_t)row * D_ + col0 + bj * 128; f32x4 v[2];
; #pragma unroll
;                     for (int n = 0; n < 2; ++n) { v[n] = (((yv[bj][n] - mu) * rs) * gq[bj][n] + bq_[bj][n]) * ALPHA_ + acc[ai][bj][m][n] * sc;
;                         *(f32x4*)(yp + 4 * n) = v[n]; s1 += (v[n][0] + v[n][1]) + (v[n][2] + v[n][3]); s2 += (v[n][0] * v[n][0] + v[n][1] * v[n][1]) + (v[n][2] * v[n][2] + v[n][3] * v[n][3]); }
;                     *(u32x4*)(Yb + blk_off(row, col0 + bj * 128, D_)) = pack8(v[0], v[1]); }
.LBB0_1709:
	s_or_b64 exec, exec, s[26:27]
	v_pk_add_f32 v[82:83], v[166:167], v[168:169]
	s_mov_b32 s2, 0x3a800000
	v_pk_mul_f32 v[106:107], v[82:83], s[2:3] op_sel_hi:[1,0]
	s_mov_b32 s1, 0x800000
	v_fma_f32 v0, -v107, v107, v106
	v_max_f32_e32 v0, 0, v0
	v_add_f32_e32 v0, 0x3727c5ac, v0
	v_cmp_gt_f32_e32 vcc, s1, v0
	v_mul_f32_e32 v82, 0x4b800000, v0
	s_load_dwordx16 s[60:75], s[34:35], 0x38
	v_cndmask_b32_e32 v0, v0, v82, vcc
	v_rsq_f32_e32 v0, v0
	s_mov_b32 s2, 0x3fd744fd
	v_lshlrev_b32_e32 v106, 6, v162
	v_mul_f32_e32 v82, 0x45800000, v0
	v_cndmask_b32_e32 v0, v0, v82, vcc
	v_lshlrev_b64 v[82:83], 12, v[162:163]
	s_waitcnt lgkmcnt(0)
	v_lshl_add_u64 v[82:83], s[74:75], 0, v[82:83]
	v_lshl_add_u64 v[108:109], v[152:153], 2, v[82:83]
	s_nop 1
	v_bfe_u32 v85, v227, 4, 2
	v_sub_u32_e32 v84, 0, v85
	v_lshlrev_b32_e32 v84, 4, v84
	v_ashrrev_i32_e32 v85, 31, v84
	v_lshl_add_u64 v[84:85], v[108:109], 0, v[84:85]
	global_load_dwordx4 v[110:113], v[84:85], off offset:64
	global_load_dwordx4 v[114:117], v[84:85], off
	s_nop 1
	v_lshrrev_b32_e32 v134, 4, v227
	v_lshlrev_b32_e32 v134, 7, v134
	v_add_u32_e32 v134, 0x20100, v134
	ds_read_b128 v[118:121], v134 offset:16
	ds_read_b128 v[122:125], v134 offset:0
	ds_read_b128 v[126:129], v134 offset:80
	ds_read_b128 v[130:133], v134 offset:64
	s_nop 1
	v_bfe_u32 v87, v227, 4, 2
	v_sub_u32_e32 v86, 0, v87
	v_lshlrev_b32_e32 v86, 4, v86
	v_ashrrev_i32_e32 v87, 31, v86
	v_lshl_add_u64 v[86:87], v[108:109], 0, v[86:87]
	global_load_dwordx4 v[82:85], v[86:87], off offset:576
	global_load_dwordx4 v[102:105], v[86:87], off offset:512
	ds_read_b128 v[86:89], v134 offset:48
	ds_read_b128 v[94:97], v134 offset:32
	ds_read_b128 v[90:93], v134 offset:112
	ds_read_b128 v[98:101], v134 offset:96
	s_movk_i32 s1, 0x3fc0
	v_and_or_b32 v106, v106, s1, v196
	v_lshlrev_b32_e32 v106, 1, v106
	s_waitcnt vmcnt(2)
	v_permlane32_swap_b32_e32 v114, v110
	v_permlane32_swap_b32_e32 v115, v111
	v_permlane32_swap_b32_e32 v116, v112
	v_permlane32_swap_b32_e32 v117, v113
	v_permlane16_swap_b32_e32 v114, v110
	v_permlane16_swap_b32_e32 v115, v111
	v_permlane16_swap_b32_e32 v116, v112
	v_permlane16_swap_b32_e32 v117, v113
	v_sub_f32_e32 v113, v113, v107
	v_sub_f32_e32 v117, v117, v107
	v_sub_f32_e32 v116, v116, v107
	v_sub_f32_e32 v115, v115, v107
	v_sub_f32_e32 v114, v114, v107
	v_sub_f32_e32 v112, v112, v107
	v_sub_f32_e32 v111, v111, v107
	v_sub_f32_e32 v110, v110, v107
	v_pk_mul_f32 v[114:115], v[0:1], v[114:115] op_sel_hi:[0,1]
	v_pk_mul_f32 v[116:117], v[0:1], v[116:117] op_sel_hi:[0,1]
	v_pk_mul_f32 v[110:111], v[0:1], v[110:111] op_sel_hi:[0,1]
	v_pk_mul_f32 v[112:113], v[0:1], v[112:113] op_sel_hi:[0,1]
	s_waitcnt lgkmcnt(0)
	v_pk_fma_f32 v[116:117], v[124:125], v[116:117], v[132:133]
	v_pk_fma_f32 v[114:115], v[122:123], v[114:115], v[130:131]
	v_pk_fma_f32 v[112:113], v[120:121], v[112:113], v[128:129]
	v_pk_fma_f32 v[110:111], v[118:119], v[110:111], v[126:127]
	v_pk_mul_f32 v[114:115], v[114:115], s[2:3] op_sel_hi:[1,0]
	v_pk_mul_f32 v[116:117], v[116:117], s[2:3] op_sel_hi:[1,0]
	v_pk_mul_f32 v[110:111], v[110:111], s[2:3] op_sel_hi:[1,0]
	v_pk_mul_f32 v[112:113], v[112:113], s[2:3] op_sel_hi:[1,0]
	v_pk_fma_f32 v[80:81], v[80:81], 0.5, v[116:117] op_sel_hi:[1,0,1]
	v_pk_fma_f32 v[78:79], v[78:79], 0.5, v[114:115] op_sel_hi:[1,0,1]
	v_pk_fma_f32 v[76:77], v[76:77], 0.5, v[112:113] op_sel_hi:[1,0,1]
	v_pk_fma_f32 v[74:75], v[74:75], 0.5, v[110:111] op_sel_hi:[1,0,1]
	v_add_f32_e32 v114, v78, v79
	v_add_f32_e32 v115, v80, v81
	v_add_f32_e32 v110, v74, v75
	v_add_f32_e32 v111, v76, v77
	v_add_f32_e32 v114, v114, v115
	v_mul_f32_e32 v115, v79, v79
	v_mul_f32_e32 v116, v81, v81
	v_add_f32_e32 v110, v110, v111
	v_mul_f32_e32 v111, v75, v75
	v_mul_f32_e32 v112, v77, v77
	s_nop 0
	v_fmac_f32_e32 v115, v78, v78
	v_fmac_f32_e32 v116, v80, v80
	s_nop 1
	v_bfe_u32 v119, v227, 4, 2
	v_sub_u32_e32 v118, 0, v119
	v_lshlrev_b32_e32 v118, 4, v118
	v_ashrrev_i32_e32 v119, 31, v118
	v_lshl_add_u64 v[118:119], v[108:109], 0, v[118:119]
	v_permlane16_swap_b32_e32 v78, v74
	v_permlane16_swap_b32_e32 v79, v75
	v_permlane16_swap_b32_e32 v80, v76
	v_permlane16_swap_b32_e32 v81, v77
	v_permlane32_swap_b32_e32 v78, v74
	v_permlane32_swap_b32_e32 v79, v75
	v_permlane32_swap_b32_e32 v80, v76
	v_permlane32_swap_b32_e32 v81, v77
	global_store_dwordx4 v[118:119], v[78:81], off
	global_store_dwordx4 v[118:119], v[74:77], off offset:64
	s_nop 1
	v_permlane32_swap_b32_e32 v78, v74
	v_permlane32_swap_b32_e32 v79, v75
	v_permlane32_swap_b32_e32 v80, v76
	v_permlane32_swap_b32_e32 v81, v77
	v_permlane16_swap_b32_e32 v78, v74
	v_permlane16_swap_b32_e32 v79, v75
	v_permlane16_swap_b32_e32 v80, v76
	v_permlane16_swap_b32_e32 v81, v77
	v_fmac_f32_e32 v111, v74, v74
	v_fmac_f32_e32 v112, v76, v76
	v_cvt_pk_bf16_f32 v78, v78, v79
	v_cvt_pk_bf16_f32 v79, v80, v81
	v_cvt_pk_bf16_f32 v80, v74, v75
	v_cvt_pk_bf16_f32 v81, v76, v77
	s_waitcnt vmcnt(2)
; __device__ __forceinline__ float xsum16(float v) { const auto r = __builtin_amdgcn_permlane16_swap(__float_as_uint(v), __float_as_uint(v), false, false); return __uint_as_float(r[0]) + __uint_as_float(r[1]); }
; __device__ __forceinline__ float xsum32(float v) { const auto r = __builtin_amdgcn_permlane32_swap(__float_as_uint(v), __float_as_uint(v), false, false); return __uint_as_float(r[0]) + __uint_as_float(r[1]); }
; __device__ __forceinline__ void row_stats4(const float* st, int rowb, int fq, float (&mu)[4], float (&rs)[4]) {
;     f32x4 a[4], b[4];
; #pragma unroll
;     for (int m = 0; m < 4; ++m) { const f32x4* p = (const f32x4*)(st + (size_t)(rowb + m * 16) * 32 + fq * 8); a[m] = p[0]; b[m] = p[1]; }
;     __device__ __forceinline__ void operator()(const f32x4 (&acc)[2][2][4][2], const pg8::Unit& u, int wr, int wc, int fr, int fq) const {
;     ...
;             for (int m = 0; m < 4; ++m) { const int row = row0 + ai * 128 + m * 16; const float mu = mu4[m], rs = rs4[m];
;                 f32x4 yv[2][2], gq[2][2], bq_[2][2];
; #pragma unroll
;                 for (int bj = 0; bj < 2; ++bj)
; #pragma unroll
;                     for (int n = 0; n < 2; ++n) { yv[bj][n] = *(const f32x4*)(Yin + (size_t)row * D_ + col0 + bj * 128 + 4 * n); gq[bj][n] = *(const f32x4*)(g + col0 + bj * 128 + 4 * n); bq_[bj][n] = *(const f32x4*)(b + col0 + bj * 128 + 4 * n); }
;                 asm volatile("" ::: "memory");
;                 float s1 = 0.f, s2 = 0.f;
; #pragma unroll
;                 for (int bj = 0; bj < 2; ++bj) { float* yp = Y + (size_t)row * D_ + col0 + bj * 128; f32x4 v[2];
; #pragma unroll
;                     for (int n = 0; n < 2; ++n) { v[n] = (((yv[bj][n] - mu) * rs) * gq[bj][n] + bq_[bj][n]) * ALPHA_ + acc[ai][bj][m][n] * sc;
;                         *(f32x4*)(yp + 4 * n) = v[n]; s1 += (v[n][0] + v[n][1]) + (v[n][2] + v[n][3]); s2 += (v[n][0] * v[n][0] + v[n][1] * v[n][1]) + (v[n][2] * v[n][2] + v[n][3] * v[n][3]); }
;                     *(u32x4*)(Yb + blk_off(row, col0 + bj * 128, D_)) = pack8(v[0], v[1]); }
;                 s1 = xsum32(xsum16(s1)); s2 = xsum32(xsum16(s2));
;                 if (fq == 0) *(f32x2*)(stn + (size_t)row * 32 + (u.pn * 4 + wc) * 2) = (f32x2){s1, s2}; asm volatile("" ::: "memory"); } }
	v_permlane32_swap_b32_e32 v102, v82
	v_permlane32_swap_b32_e32 v103, v83
	v_permlane32_swap_b32_e32 v104, v84
	v_permlane32_swap_b32_e32 v105, v85
	v_permlane16_swap_b32_e32 v102, v82
	v_permlane16_swap_b32_e32 v103, v83
	v_permlane16_swap_b32_e32 v104, v84
	v_permlane16_swap_b32_e32 v105, v85
	v_sub_f32_e32 v75, v105, v107
	v_sub_f32_e32 v74, v104, v107
	v_sub_f32_e32 v77, v103, v107
	v_sub_f32_e32 v76, v102, v107
	v_pk_mul_f32 v[76:77], v[0:1], v[76:77] op_sel_hi:[0,1]
	v_pk_mul_f32 v[74:75], v[0:1], v[74:75] op_sel_hi:[0,1]
	v_pk_fma_f32 v[74:75], v[96:97], v[74:75], v[100:101]
	v_pk_fma_f32 v[76:77], v[94:95], v[76:77], v[98:99]
	v_pk_mul_f32 v[74:75], v[74:75], s[2:3] op_sel_hi:[1,0]
	v_pk_mul_f32 v[76:77], v[76:77], s[2:3] op_sel_hi:[1,0]
	v_pk_fma_f32 v[72:73], v[72:73], 0.5, v[74:75] op_sel_hi:[1,0,1]
	v_pk_fma_f32 v[70:71], v[70:71], 0.5, v[76:77] op_sel_hi:[1,0,1]
	v_add_f32_e32 v114, 0, v114
	v_add_f32_e32 v74, v70, v71
	v_add_f32_e32 v75, v72, v73
	v_add_f32_e32 v110, v114, v110
	v_add_f32_e32 v74, v74, v75
	global_store_dwordx4 v106, v[78:81], s[48:49]
	v_mul_f32_e32 v75, v73, v73
	v_add_f32_e32 v115, v115, v116
	v_add_f32_e32 v78, v110, v74
	v_mul_f32_e32 v74, v71, v71
	v_add_f32_e32 v111, v111, v112
	v_fmac_f32_e32 v74, v70, v70
	v_fmac_f32_e32 v75, v72, v72
	v_add_f32_e32 v111, v115, v111
	v_add_f32_e32 v74, v74, v75
	v_add_f32_e32 v79, v111, v74
	v_sub_f32_e32 v75, v85, v107
	v_sub_f32_e32 v74, v84, v107
	v_sub_f32_e32 v77, v83, v107
	v_sub_f32_e32 v76, v82, v107
	v_pk_mul_f32 v[76:77], v[0:1], v[76:77] op_sel_hi:[0,1]
	v_pk_mul_f32 v[74:75], v[0:1], v[74:75] op_sel_hi:[0,1]
	v_pk_fma_f32 v[74:75], v[88:89], v[74:75], v[92:93]
	v_pk_fma_f32 v[76:77], v[86:87], v[76:77], v[90:91]
	v_pk_mul_f32 v[74:75], v[74:75], s[2:3] op_sel_hi:[1,0]
	v_pk_mul_f32 v[76:77], v[76:77], s[2:3] op_sel_hi:[1,0]
	v_pk_fma_f32 v[68:69], v[68:69], 0.5, v[74:75] op_sel_hi:[1,0,1]
	v_pk_fma_f32 v[66:67], v[66:67], 0.5, v[76:77] op_sel_hi:[1,0,1]
	v_add_f32_e32 v74, v68, v69
	v_add_f32_e32 v0, v66, v67
	v_add_f32_e32 v0, v0, v74
	v_mul_f32_e32 v74, v67, v67
	v_mul_f32_e32 v75, v69, v69
	v_add_f32_e32 v0, v78, v0
	v_fmac_f32_e32 v74, v66, v66
	v_fmac_f32_e32 v75, v68, v68
	s_nop 0
	s_nop 1
	v_bfe_u32 v77, v227, 4, 2
	v_sub_u32_e32 v76, 0, v77
	v_lshlrev_b32_e32 v76, 4, v76
	v_ashrrev_i32_e32 v77, 31, v76
	v_lshl_add_u64 v[76:77], v[108:109], 0, v[76:77]
	v_permlane16_swap_b32_e32 v70, v66
	v_permlane16_swap_b32_e32 v71, v67
	v_permlane16_swap_b32_e32 v72, v68
	v_permlane16_swap_b32_e32 v73, v69
	v_permlane32_swap_b32_e32 v70, v66
	v_permlane32_swap_b32_e32 v71, v67
	v_permlane32_swap_b32_e32 v72, v68
	v_permlane32_swap_b32_e32 v73, v69
	global_store_dwordx4 v[76:77], v[70:73], off offset:512
	global_store_dwordx4 v[76:77], v[66:69], off offset:576
	s_nop 1
	v_permlane32_swap_b32_e32 v70, v66
	v_permlane32_swap_b32_e32 v71, v67
	v_permlane32_swap_b32_e32 v72, v68
	v_permlane32_swap_b32_e32 v73, v69
	v_permlane16_swap_b32_e32 v70, v66
	v_permlane16_swap_b32_e32 v71, v67
	v_permlane16_swap_b32_e32 v72, v68
	v_permlane16_swap_b32_e32 v73, v69
	v_add_f32_e32 v74, v74, v75
	v_cvt_pk_bf16_f32 v70, v70, v71
	v_cvt_pk_bf16_f32 v71, v72, v73
	v_cvt_pk_bf16_f32 v72, v66, v67
	v_mov_b32_e32 v66, v0
	v_add_f32_e32 v74, v79, v74
	s_nop 0
	v_permlane16_swap_b32_e32 v0, v66
	v_add_f32_e32 v66, v0, v66
	v_mov_b32_e32 v0, v74
	s_nop 1
	v_permlane16_swap_b32_e32 v74, v0
	v_add_f32_e32 v67, v74, v0
	v_cvt_pk_bf16_f32 v73, v68, v69
	v_mov_b32_e32 v68, v66
	v_mov_b32_e32 v69, v67
	s_nop 0
	v_permlane32_swap_b32_e32 v66, v68
	v_permlane32_swap_b32_e32 v67, v69
	global_store_dwordx4 v106, v[70:73], s[46:47]
	s_and_saveexec_b64 s[26:27], s[40:41]
	s_cbranch_execz .LBB0_1711
	v_pk_add_f32 v[66:67], v[66:67], v[68:69]
	v_lshl_add_u64 v[68:69], s[8:9], 0, v[160:161]
	v_lshl_add_u64 v[68:69], s[38:39], 2, v[68:69]
	global_store_dwordx2 v[68:69], v[66:67], off
.LBB0_1711:
	s_or_b64 exec, exec, s[26:27]
	v_add_u32_e32 v68, 0x80, v158
	v_ashrrev_i32_e32 v69, 31, v68
	v_lshlrev_b64 v[66:67], 7, v[68:69]
	v_lshl_add_u64 v[74:75], v[146:147], 0, v[66:67]
	v_add_u32_e32 v96, 0x90, v158
	s_nop 1
	v_bfe_u32 v77, v227, 4, 2
	v_sub_u32_e32 v76, 0, v77
	v_lshlrev_b32_e32 v76, 4, v76
	v_ashrrev_i32_e32 v77, 31, v76
	v_lshl_add_u64 v[76:77], v[74:75], 0, v[76:77]
	global_load_dwordx4 v[70:73], v[76:77], off
	global_load_dwordx4 v[82:85], v[76:77], off offset:64
	v_ashrrev_i32_e32 v97, 31, v96
	v_lshlrev_b64 v[86:87], 7, v[96:97]
	v_add_u32_e32 v80, 0xa0, v158
	v_lshl_add_u64 v[74:75], v[146:147], 0, v[86:87]
	v_ashrrev_i32_e32 v81, 31, v80
	s_nop 1
	v_bfe_u32 v77, v227, 4, 2
	v_sub_u32_e32 v76, 0, v77
	v_lshlrev_b32_e32 v76, 4, v76
	v_ashrrev_i32_e32 v77, 31, v76
	v_lshl_add_u64 v[76:77], v[74:75], 0, v[76:77]
	global_load_dwordx4 v[88:91], v[76:77], off
	global_load_dwordx4 v[92:95], v[76:77], off offset:64
	v_lshlrev_b64 v[74:75], 7, v[80:81]
	v_lshl_add_u64 v[74:75], v[146:147], 0, v[74:75]
	s_nop 1
	v_bfe_u32 v77, v227, 4, 2
	v_sub_u32_e32 v76, 0, v77
	v_lshlrev_b32_e32 v76, 4, v76
	v_ashrrev_i32_e32 v77, 31, v76
	v_lshl_add_u64 v[76:77], v[74:75], 0, v[76:77]
	global_load_dwordx4 v[98:101], v[76:77], off
	global_load_dwordx4 v[102:105], v[76:77], off offset:64
	v_add_u32_e32 v74, 0xb0, v158
	v_ashrrev_i32_e32 v75, 31, v74
	v_lshlrev_b64 v[76:77], 7, v[74:75]
	v_lshl_add_u64 v[76:77], v[146:147], 0, v[76:77]
	s_nop 1
	v_bfe_u32 v79, v227, 4, 2
	v_sub_u32_e32 v78, 0, v79
	v_lshlrev_b32_e32 v78, 4, v78
	v_ashrrev_i32_e32 v79, 31, v78
	v_lshl_add_u64 v[78:79], v[76:77], 0, v[78:79]
	global_load_dwordx4 v[106:109], v[78:79], off
	global_load_dwordx4 v[110:113], v[78:79], off offset:64
	s_load_dwordx16 s[60:75], s[34:35], 0x38
	v_lshlrev_b64 v[78:79], 12, v[68:69]
	s_mov_b32 s2, 0x3a800000
	s_mov_b32 s1, 0x800000
	s_waitcnt lgkmcnt(0)
; __device__ __forceinline__ float xsum16(float v) { const auto r = __builtin_amdgcn_permlane16_swap(__float_as_uint(v), __float_as_uint(v), false, false); return __uint_as_float(r[0]) + __uint_as_float(r[1]); }
; __device__ __forceinline__ float xsum32(float v) { const auto r = __builtin_amdgcn_permlane32_swap(__float_as_uint(v), __float_as_uint(v), false, false); return __uint_as_float(r[0]) + __uint_as_float(r[1]); }
; __device__ __forceinline__ void row_stats4(const float* st, int rowb, int fq, float (&mu)[4], float (&rs)[4]) {
;     ...
;     for (int m = 0; m < 4; ++m) { const f32x4* p = (const f32x4*)(st + (size_t)(rowb + m * 16) * 32 + fq * 8); a[m] = p[0]; b[m] = p[1]; }
; #pragma unroll
;     for (int m = 0; m < 4; ++m) { float s1 = (a[m][0] + a[m][2]) + (b[m][0] + b[m][2]), s2 = (a[m][1] + a[m][3]) + (b[m][1] + b[m][3]);
;         s1 = xsum32(xsum16(s1)); s2 = xsum32(xsum16(s2));
;         const float mm = s1 * (1.0f / 1024.0f); mu[m] = mm; rs[m] = rsqrtf(fmaxf(s2 * (1.0f / 1024.0f) - mm * mm, 0.f) + LN_EPS_); }
;     __device__ __forceinline__ void operator()(const f32x4 (&acc)[2][2][4][2], const pg8::Unit& u, int wr, int wc, int fr, int fq) const {
;     ...
;             for (int m = 0; m < 4; ++m) { const int row = row0 + ai * 128 + m * 16; const float mu = mu4[m], rs = rs4[m];
;                 f32x4 yv[2][2], gq[2][2], bq_[2][2];
; #pragma unroll
;                 for (int bj = 0; bj < 2; ++bj)
; #pragma unroll
;                     for (int n = 0; n < 2; ++n) { yv[bj][n] = *(const f32x4*)(Yin + (size_t)row * D_ + col0 + bj * 128 + 4 * n); gq[bj][n] = *(const f32x4*)(g + col0 + bj * 128 + 4 * n); bq_[bj][n] = *(const f32x4*)(b + col0 + bj * 128 + 4 * n); }
;                 asm volatile("" ::: "memory");
;                 float s1 = 0.f, s2 = 0.f;
; #pragma unroll
;                 for (int bj = 0; bj < 2; ++bj) { float* yp = Y + (size_t)row * D_ + col0 + bj * 128; f32x4 v[2];
; #pragma unroll
;                     for (int n = 0; n < 2; ++n) { v[n] = (((yv[bj][n] - mu) * rs) * gq[bj][n] + bq_[bj][n]) * ALPHA_ + acc[ai][bj][m][n] * sc;
;                         *(f32x4*)(yp + 4 * n) = v[n]; s1 += (v[n][0] + v[n][1]) + (v[n][2] + v[n][3]); s2 += (v[n][0] * v[n][0] + v[n][1] * v[n][1]) + (v[n][2] * v[n][2] + v[n][3] * v[n][3]); }
;                     *(u32x4*)(Yb + blk_off(row, col0 + bj * 128, D_)) = pack8(v[0], v[1]); }
	v_lshl_add_u64 v[78:79], s[74:75], 0, v[78:79]
	v_lshl_add_u64 v[76:77], v[152:153], 2, v[78:79]
	s_nop 1
	v_bfe_u32 v123, v227, 4, 2
	v_sub_u32_e32 v122, 0, v123
	v_lshlrev_b32_e32 v122, 4, v122
	v_ashrrev_i32_e32 v123, 31, v122
	v_lshl_add_u64 v[122:123], v[76:77], 0, v[122:123]
	global_load_dwordx4 v[114:117], v[122:123], off offset:64
	global_load_dwordx4 v[118:121], v[122:123], off
	s_nop 1
	v_lshrrev_b32_e32 v164, 4, v227
	v_lshlrev_b32_e32 v164, 7, v164
	v_add_u32_e32 v164, 0x20100, v164
	ds_read_b128 v[122:125], v164 offset:16
	ds_read_b128 v[126:129], v164 offset:0
	ds_read_b128 v[130:133], v164 offset:80
	ds_read_b128 v[134:137], v164 offset:64
	s_mov_b32 s16, 0x3fd744fd
	s_waitcnt vmcnt(8)
	v_permlane32_swap_b32_e32 v70, v82
	v_permlane32_swap_b32_e32 v71, v83
	v_permlane32_swap_b32_e32 v72, v84
	v_permlane32_swap_b32_e32 v73, v85
	v_permlane16_swap_b32_e32 v70, v82
	v_permlane16_swap_b32_e32 v71, v83
	v_permlane16_swap_b32_e32 v72, v84
	v_permlane16_swap_b32_e32 v73, v85
	v_mov_b32_e32 v78, v70
	v_mov_b32_e32 v79, v82
	v_mov_b32_e32 v158, v72
	v_mov_b32_e32 v159, v84
	v_mov_b32_e32 v82, v71
	v_mov_b32_e32 v84, v73
	v_pk_add_f32 v[78:79], v[78:79], v[158:159]
	v_pk_add_f32 v[82:83], v[82:83], v[84:85]
	v_pk_add_f32 v[78:79], v[78:79], v[78:79] op_sel:[0,1] op_sel_hi:[1,0]
	v_pk_add_f32 v[82:83], v[82:83], v[82:83] op_sel:[0,1] op_sel_hi:[1,0]
	v_mov_b32_e32 v0, v78
	v_mov_b32_e32 v69, v82
	s_nop 0
	v_permlane16_swap_b32_e32 v78, v0
	v_permlane16_swap_b32_e32 v82, v69
	v_add_f32_e32 v79, v78, v0
	v_add_f32_e32 v78, v82, v69
	v_mov_b32_e32 v83, v79
	v_mov_b32_e32 v82, v78
	s_waitcnt vmcnt(6)
	v_permlane32_swap_b32_e32 v88, v92
	v_permlane32_swap_b32_e32 v89, v93
	v_permlane32_swap_b32_e32 v90, v94
	v_permlane32_swap_b32_e32 v91, v95
	v_permlane16_swap_b32_e32 v88, v92
	v_permlane16_swap_b32_e32 v89, v93
	v_permlane16_swap_b32_e32 v90, v94
	v_permlane16_swap_b32_e32 v91, v95
	v_mov_b32_e32 v70, v88
	v_mov_b32_e32 v71, v92
	v_mov_b32_e32 v72, v90
	v_mov_b32_e32 v73, v94
	v_mov_b32_e32 v92, v89
	v_mov_b32_e32 v94, v91
	v_permlane32_swap_b32_e32 v79, v83
	v_permlane32_swap_b32_e32 v78, v82
	s_waitcnt vmcnt(4)
	v_permlane32_swap_b32_e32 v98, v102
	v_permlane32_swap_b32_e32 v99, v103
	v_permlane32_swap_b32_e32 v100, v104
	v_permlane32_swap_b32_e32 v101, v105
	v_permlane16_swap_b32_e32 v98, v102
	v_permlane16_swap_b32_e32 v99, v103
	v_permlane16_swap_b32_e32 v100, v104
	v_permlane16_swap_b32_e32 v101, v105
	v_mov_b32_e32 v88, v98
	v_mov_b32_e32 v89, v102
	v_mov_b32_e32 v90, v100
	v_mov_b32_e32 v91, v104
	v_mov_b32_e32 v102, v99
	v_mov_b32_e32 v104, v101
	v_pk_add_f32 v[70:71], v[70:71], v[72:73]
	v_pk_add_f32 v[72:73], v[92:93], v[94:95]
	v_pk_add_f32 v[78:79], v[78:79], v[82:83]
	s_nop 1
	v_bfe_u32 v85, v227, 4, 2
	v_sub_u32_e32 v84, 0, v85
	v_lshlrev_b32_e32 v84, 4, v84
	v_ashrrev_i32_e32 v85, 31, v84
	v_lshl_add_u64 v[84:85], v[76:77], 0, v[84:85]
	global_load_dwordx4 v[92:95], v[84:85], off offset:576
	global_load_dwordx4 v[98:101], v[84:85], off offset:512
	v_pk_mul_f32 v[162:163], v[78:79], s[2:3] op_sel_hi:[1,0]
	s_waitcnt vmcnt(4)
	v_permlane32_swap_b32_e32 v106, v110
	v_permlane32_swap_b32_e32 v107, v111
	v_permlane32_swap_b32_e32 v108, v112
	v_permlane32_swap_b32_e32 v109, v113
	v_permlane16_swap_b32_e32 v106, v110
	v_permlane16_swap_b32_e32 v107, v111
	v_permlane16_swap_b32_e32 v108, v112
	v_permlane16_swap_b32_e32 v109, v113
	v_mov_b32_e32 v78, v106
	v_mov_b32_e32 v79, v110
	v_mov_b32_e32 v82, v108
	v_mov_b32_e32 v83, v112
	v_mov_b32_e32 v110, v107
	v_mov_b32_e32 v112, v109
	v_pk_add_f32 v[84:85], v[88:89], v[90:91]
	v_pk_add_f32 v[88:89], v[102:103], v[104:105]
	v_pk_add_f32 v[78:79], v[78:79], v[82:83]
	v_pk_add_f32 v[82:83], v[110:111], v[112:113]
	ds_read_b128 v[102:105], v164 offset:48
	ds_read_b128 v[106:109], v164 offset:32
	ds_read_b128 v[110:113], v164 offset:112
	ds_read_b128 v[158:161], v164 offset:96
	v_fma_f32 v0, -v163, v163, v162
	v_max_f32_e32 v0, 0, v0
	v_add_f32_e32 v0, 0x3727c5ac, v0
	v_mul_f32_e32 v69, 0x4b800000, v0
	v_cmp_gt_f32_e32 vcc, s1, v0
	v_pk_add_f32 v[88:89], v[88:89], v[88:89] op_sel:[0,1] op_sel_hi:[1,0]
	v_pk_add_f32 v[78:79], v[78:79], v[78:79] op_sel:[0,1] op_sel_hi:[1,0]
	v_cndmask_b32_e32 v0, v0, v69, vcc
	v_rsq_f32_e32 v0, v0
	v_pk_add_f32 v[82:83], v[82:83], v[82:83] op_sel:[0,1] op_sel_hi:[1,0]
	s_waitcnt vmcnt(2)
	v_permlane32_swap_b32_e32 v118, v114
	v_permlane32_swap_b32_e32 v119, v115
	v_permlane32_swap_b32_e32 v120, v116
	v_permlane32_swap_b32_e32 v121, v117
	v_permlane16_swap_b32_e32 v118, v114
	v_permlane16_swap_b32_e32 v119, v115
	v_permlane16_swap_b32_e32 v120, v116
	v_permlane16_swap_b32_e32 v121, v117
	v_sub_f32_e32 v119, v119, v163
	v_sub_f32_e32 v118, v118, v163
	v_mul_f32_e32 v69, 0x45800000, v0
	v_cndmask_b32_e32 v162, v0, v69, vcc
	v_mov_b32_e32 v0, v88
	s_nop 1
	v_permlane16_swap_b32_e32 v88, v0
	v_add_f32_e32 v88, v88, v0
	v_mov_b32_e32 v0, v78
	s_nop 1
	v_permlane16_swap_b32_e32 v78, v0
	v_add_f32_e32 v83, v78, v0
	v_mov_b32_e32 v0, v82
	s_nop 1
	v_permlane16_swap_b32_e32 v82, v0
	v_add_f32_e32 v82, v82, v0
	v_ashrrev_i32_e32 v78, 8, v68
	v_lshlrev_b32_e32 v0, 6, v68
	v_sub_f32_e32 v69, v121, v163
	v_sub_f32_e32 v68, v120, v163
	v_pk_mul_f32 v[118:119], v[162:163], v[118:119] op_sel_hi:[0,1]
	v_pk_mul_f32 v[68:69], v[162:163], v[68:69] op_sel_hi:[0,1]
	s_waitcnt lgkmcnt(0)
; __device__ __forceinline__ float xsum16(float v) { const auto r = __builtin_amdgcn_permlane16_swap(__float_as_uint(v), __float_as_uint(v), false, false); return __uint_as_float(r[0]) + __uint_as_float(r[1]); }
; __device__ __forceinline__ float xsum32(float v) { const auto r = __builtin_amdgcn_permlane32_swap(__float_as_uint(v), __float_as_uint(v), false, false); return __uint_as_float(r[0]) + __uint_as_float(r[1]); }
; __device__ __forceinline__ size_t blk_off(int r, int c, int K) { return (size_t)(r >> 8) * 256 * K + (size_t)(c >> 6) * (256 * 64) + (size_t)((r & 255) * 64 + (c & 63)); }
; __device__ __forceinline__ u32x4 pack8(const f32x4 a, const f32x4 b) { u32x4 w; w.x = cvt_pk_bf16(a[0], a[1]); w.y = cvt_pk_bf16(a[2], a[3]); w.z = cvt_pk_bf16(b[0], b[1]); w.w = cvt_pk_bf16(b[2], b[3]); return w; }
;     __device__ __forceinline__ void operator()(const f32x4 (&acc)[2][2][4][2], const pg8::Unit& u, int wr, int wc, int fr, int fq) const {
;     ...
;                     for (int n = 0; n < 2; ++n) { yv[bj][n] = *(const f32x4*)(Yin + (size_t)row * D_ + col0 + bj * 128 + 4 * n); gq[bj][n] = *(const f32x4*)(g + col0 + bj * 128 + 4 * n); bq_[bj][n] = *(const f32x4*)(b + col0 + bj * 128 + 4 * n); }
;                 asm volatile("" ::: "memory");
;                 float s1 = 0.f, s2 = 0.f;
; #pragma unroll
;                 for (int bj = 0; bj < 2; ++bj) { float* yp = Y + (size_t)row * D_ + col0 + bj * 128; f32x4 v[2];
; #pragma unroll
;                     for (int n = 0; n < 2; ++n) { v[n] = (((yv[bj][n] - mu) * rs) * gq[bj][n] + bq_[bj][n]) * ALPHA_ + acc[ai][bj][m][n] * sc;
;                         *(f32x4*)(yp + 4 * n) = v[n]; s1 += (v[n][0] + v[n][1]) + (v[n][2] + v[n][3]); s2 += (v[n][0] * v[n][0] + v[n][1] * v[n][1]) + (v[n][2] * v[n][2] + v[n][3] * v[n][3]); }
;                     *(u32x4*)(Yb + blk_off(row, col0 + bj * 128, D_)) = pack8(v[0], v[1]); }
;                 s1 = xsum32(xsum16(s1)); s2 = xsum32(xsum16(s2));
;                 if (fq == 0) *(f32x2*)(stn + (size_t)row * 32 + (u.pn * 4 + wc) * 2) = (f32x2){s1, s2}; asm volatile("" ::: "memory"); } }
	v_pk_fma_f32 v[68:69], v[128:129], v[68:69], v[136:137]
	v_pk_fma_f32 v[118:119], v[126:127], v[118:119], v[134:135]
	v_pk_mul_f32 v[68:69], v[68:69], s[16:17] op_sel_hi:[1,0]
	v_pk_mul_f32 v[118:119], v[118:119], s[16:17] op_sel_hi:[1,0]
	v_pk_fma_f32 v[64:65], v[64:65], 0.5, v[68:69] op_sel_hi:[1,0,1]
	v_pk_fma_f32 v[62:63], v[62:63], 0.5, v[118:119] op_sel_hi:[1,0,1]
	v_add_f32_e32 v69, v64, v65
	v_add_f32_e32 v68, v62, v63
	v_add_f32_e32 v68, v68, v69
	v_add_f32_e32 v118, 0, v68
	v_mul_f32_e32 v68, v63, v63
	v_mul_f32_e32 v69, v65, v65
	v_fmac_f32_e32 v68, v62, v62
	v_fmac_f32_e32 v69, v64, v64
	v_add_f32_e32 v119, v68, v69
	v_sub_f32_e32 v69, v117, v163
	v_sub_f32_e32 v68, v116, v163
	v_sub_f32_e32 v115, v115, v163
	v_sub_f32_e32 v114, v114, v163
	v_pk_mul_f32 v[114:115], v[162:163], v[114:115] op_sel_hi:[0,1]
	v_pk_mul_f32 v[68:69], v[162:163], v[68:69] op_sel_hi:[0,1]
	v_pk_fma_f32 v[68:69], v[124:125], v[68:69], v[132:133]
	v_pk_fma_f32 v[114:115], v[122:123], v[114:115], v[130:131]
	v_pk_mul_f32 v[68:69], v[68:69], s[16:17] op_sel_hi:[1,0]
	v_pk_mul_f32 v[114:115], v[114:115], s[16:17] op_sel_hi:[1,0]
	v_pk_fma_f32 v[60:61], v[60:61], 0.5, v[68:69] op_sel_hi:[1,0,1]
	v_pk_fma_f32 v[58:59], v[58:59], 0.5, v[114:115] op_sel_hi:[1,0,1]
	v_ashrrev_i32_e32 v79, 31, v78
	v_add_f32_e32 v68, v58, v59
	v_add_f32_e32 v69, v60, v61
	v_readlane_b32 s2, v253, 59
	v_lshlrev_b64 v[78:79], 19, v[78:79]
	s_movk_i32 s1, 0x33c0
	v_add_f32_e32 v68, v68, v69
	v_mul_f32_e32 v69, v59, v59
	v_readlane_b32 s3, v253, 60
	v_and_or_b32 v0, v0, s1, v196
	s_nop 0
	s_nop 1
	v_bfe_u32 v91, v227, 4, 2
	v_sub_u32_e32 v90, 0, v91
	v_lshlrev_b32_e32 v90, 4, v90
	v_ashrrev_i32_e32 v91, 31, v90
	v_lshl_add_u64 v[90:91], v[76:77], 0, v[90:91]
	v_permlane16_swap_b32_e32 v62, v58
	v_permlane16_swap_b32_e32 v63, v59
	v_permlane16_swap_b32_e32 v64, v60
	v_permlane16_swap_b32_e32 v65, v61
	v_permlane32_swap_b32_e32 v62, v58
	v_permlane32_swap_b32_e32 v63, v59
	v_permlane32_swap_b32_e32 v64, v60
	v_permlane32_swap_b32_e32 v65, v61
	global_store_dwordx4 v[90:91], v[62:65], off
	global_store_dwordx4 v[90:91], v[58:61], off offset:64
	s_nop 1
	v_permlane32_swap_b32_e32 v62, v58
	v_permlane32_swap_b32_e32 v63, v59
	v_permlane32_swap_b32_e32 v64, v60
	v_permlane32_swap_b32_e32 v65, v61
	v_permlane16_swap_b32_e32 v62, v58
	v_permlane16_swap_b32_e32 v63, v59
	v_permlane16_swap_b32_e32 v64, v60
	v_permlane16_swap_b32_e32 v65, v61
	v_fmac_f32_e32 v69, v58, v58
	v_cvt_pk_bf16_f32 v62, v62, v63
	v_cvt_pk_bf16_f32 v63, v64, v65
	v_cvt_pk_bf16_f32 v64, v58, v59
	v_lshl_add_u64 v[58:59], s[2:3], 0, v[78:79]
	v_mul_f32_e32 v114, v61, v61
	v_lshl_add_u64 v[78:79], v[58:59], 0, s[24:25]
	v_lshlrev_b32_e32 v0, 1, v0
	v_fmac_f32_e32 v114, v60, v60
	v_cvt_pk_bf16_f32 v65, v60, v61
	v_lshl_add_u64 v[60:61], v[78:79], 0, v[0:1]
	global_store_dwordx4 v[60:61], v[62:65], off
	s_waitcnt vmcnt(3)
	v_permlane32_swap_b32_e32 v98, v92
	v_permlane32_swap_b32_e32 v99, v93
	v_permlane32_swap_b32_e32 v100, v94
	v_permlane32_swap_b32_e32 v101, v95
	v_permlane16_swap_b32_e32 v98, v92
	v_permlane16_swap_b32_e32 v99, v93
	v_permlane16_swap_b32_e32 v100, v94
	v_permlane16_swap_b32_e32 v101, v95
	v_sub_f32_e32 v61, v101, v163
	v_sub_f32_e32 v60, v100, v163
	v_sub_f32_e32 v63, v99, v163
	v_sub_f32_e32 v62, v98, v163
	v_pk_mul_f32 v[62:63], v[162:163], v[62:63] op_sel_hi:[0,1]
	v_pk_mul_f32 v[60:61], v[162:163], v[60:61] op_sel_hi:[0,1]
	v_pk_fma_f32 v[60:61], v[108:109], v[60:61], v[160:161]
	v_pk_fma_f32 v[62:63], v[106:107], v[62:63], v[158:159]
	v_pk_mul_f32 v[60:61], v[60:61], s[16:17] op_sel_hi:[1,0]
	v_pk_mul_f32 v[62:63], v[62:63], s[16:17] op_sel_hi:[1,0]
	v_pk_fma_f32 v[56:57], v[56:57], 0.5, v[60:61] op_sel_hi:[1,0,1]
	v_pk_fma_f32 v[54:55], v[54:55], 0.5, v[62:63] op_sel_hi:[1,0,1]
	v_add_f32_e32 v61, v56, v57
	v_add_f32_e32 v60, v54, v55
	v_add_f32_e32 v68, v118, v68
	v_add_f32_e32 v60, v60, v61
	v_add_f32_e32 v64, v68, v60
	v_mul_f32_e32 v60, v55, v55
	v_mul_f32_e32 v61, v57, v57
	v_add_f32_e32 v69, v69, v114
	v_fmac_f32_e32 v60, v54, v54
	v_fmac_f32_e32 v61, v56, v56
	v_add_f32_e32 v69, v119, v69
	v_add_f32_e32 v60, v60, v61
	v_add_f32_e32 v65, v69, v60
	v_sub_f32_e32 v61, v95, v163
	v_sub_f32_e32 v60, v94, v163
	v_sub_f32_e32 v63, v93, v163
	v_sub_f32_e32 v62, v92, v163
	v_pk_mul_f32 v[62:63], v[162:163], v[62:63] op_sel_hi:[0,1]
	v_pk_mul_f32 v[60:61], v[162:163], v[60:61] op_sel_hi:[0,1]
	v_pk_fma_f32 v[60:61], v[104:105], v[60:61], v[112:113]
	v_pk_fma_f32 v[62:63], v[102:103], v[62:63], v[110:111]
	v_pk_mul_f32 v[60:61], v[60:61], s[16:17] op_sel_hi:[1,0]
	v_pk_mul_f32 v[62:63], v[62:63], s[16:17] op_sel_hi:[1,0]
	v_pk_fma_f32 v[52:53], v[52:53], 0.5, v[60:61] op_sel_hi:[1,0,1]
	v_pk_fma_f32 v[50:51], v[50:51], 0.5, v[62:63] op_sel_hi:[1,0,1]
	v_add_f32_e32 v61, v52, v53
	v_add_f32_e32 v60, v50, v51
	v_add_f32_e32 v60, v60, v61
	v_mul_f32_e32 v61, v51, v51
	v_mul_f32_e32 v62, v53, v53
	s_nop 0
	s_nop 1
	v_bfe_u32 v69, v227, 4, 2
	v_sub_u32_e32 v68, 0, v69
	v_lshlrev_b32_e32 v68, 4, v68
	v_ashrrev_i32_e32 v69, 31, v68
	v_lshl_add_u64 v[68:69], v[76:77], 0, v[68:69]
	v_permlane16_swap_b32_e32 v54, v50
	v_permlane16_swap_b32_e32 v55, v51
	v_permlane16_swap_b32_e32 v56, v52
	v_permlane16_swap_b32_e32 v57, v53
	v_permlane32_swap_b32_e32 v54, v50
	v_permlane32_swap_b32_e32 v55, v51
	v_permlane32_swap_b32_e32 v56, v52
	v_permlane32_swap_b32_e32 v57, v53
	global_store_dwordx4 v[68:69], v[54:57], off offset:512
	global_store_dwordx4 v[68:69], v[50:53], off offset:576
	s_nop 1
	v_permlane32_swap_b32_e32 v54, v50
	v_permlane32_swap_b32_e32 v55, v51
	v_permlane32_swap_b32_e32 v56, v52
; __device__ __forceinline__ float xsum16(float v) { const auto r = __builtin_amdgcn_permlane16_swap(__float_as_uint(v), __float_as_uint(v), false, false); return __uint_as_float(r[0]) + __uint_as_float(r[1]); }
; __device__ __forceinline__ float xsum32(float v) { const auto r = __builtin_amdgcn_permlane32_swap(__float_as_uint(v), __float_as_uint(v), false, false); return __uint_as_float(r[0]) + __uint_as_float(r[1]); }
; __device__ __forceinline__ size_t blk_off(int r, int c, int K) { return (size_t)(r >> 8) * 256 * K + (size_t)(c >> 6) * (256 * 64) + (size_t)((r & 255) * 64 + (c & 63)); }
; __device__ __forceinline__ void row_stats4(const float* st, int rowb, int fq, float (&mu)[4], float (&rs)[4]) {
;     ...
;     for (int m = 0; m < 4; ++m) { float s1 = (a[m][0] + a[m][2]) + (b[m][0] + b[m][2]), s2 = (a[m][1] + a[m][3]) + (b[m][1] + b[m][3]);
;         s1 = xsum32(xsum16(s1)); s2 = xsum32(xsum16(s2));
;         const float mm = s1 * (1.0f / 1024.0f); mu[m] = mm; rs[m] = rsqrtf(fmaxf(s2 * (1.0f / 1024.0f) - mm * mm, 0.f) + LN_EPS_); }
;     __device__ __forceinline__ void operator()(const f32x4 (&acc)[2][2][4][2], const pg8::Unit& u, int wr, int wc, int fr, int fq) const {
;     ...
;             for (int m = 0; m < 4; ++m) { const int row = row0 + ai * 128 + m * 16; const float mu = mu4[m], rs = rs4[m];
;                 f32x4 yv[2][2], gq[2][2], bq_[2][2];
; #pragma unroll
;                 for (int bj = 0; bj < 2; ++bj)
; #pragma unroll
;                     for (int n = 0; n < 2; ++n) { yv[bj][n] = *(const f32x4*)(Yin + (size_t)row * D_ + col0 + bj * 128 + 4 * n); gq[bj][n] = *(const f32x4*)(g + col0 + bj * 128 + 4 * n); bq_[bj][n] = *(const f32x4*)(b + col0 + bj * 128 + 4 * n); }
;                 asm volatile("" ::: "memory");
;                 float s1 = 0.f, s2 = 0.f;
; #pragma unroll
;                 for (int bj = 0; bj < 2; ++bj) { float* yp = Y + (size_t)row * D_ + col0 + bj * 128; f32x4 v[2];
; #pragma unroll
;                     for (int n = 0; n < 2; ++n) { v[n] = (((yv[bj][n] - mu) * rs) * gq[bj][n] + bq_[bj][n]) * ALPHA_ + acc[ai][bj][m][n] * sc;
;                         *(f32x4*)(yp + 4 * n) = v[n]; s1 += (v[n][0] + v[n][1]) + (v[n][2] + v[n][3]); s2 += (v[n][0] * v[n][0] + v[n][1] * v[n][1]) + (v[n][2] * v[n][2] + v[n][3] * v[n][3]); }
;                     *(u32x4*)(Yb + blk_off(row, col0 + bj * 128, D_)) = pack8(v[0], v[1]); }
	v_permlane32_swap_b32_e32 v57, v53
	v_permlane16_swap_b32_e32 v54, v50
	v_permlane16_swap_b32_e32 v55, v51
	v_permlane16_swap_b32_e32 v56, v52
	v_permlane16_swap_b32_e32 v57, v53
	v_add_f32_e32 v60, v64, v60
	v_fmac_f32_e32 v61, v50, v50
	v_fmac_f32_e32 v62, v52, v52
	v_lshl_add_u64 v[76:77], v[58:59], 0, s[44:45]
	v_add_f32_e32 v61, v61, v62
	v_cvt_pk_bf16_f32 v54, v54, v55
	v_cvt_pk_bf16_f32 v55, v56, v57
	v_cvt_pk_bf16_f32 v56, v50, v51
	v_lshl_add_u64 v[50:51], v[76:77], 0, v[0:1]
	v_mov_b32_e32 v0, v60
	v_pk_add_f32 v[70:71], v[70:71], v[70:71] op_sel:[0,1] op_sel_hi:[1,0]
	v_pk_add_f32 v[72:73], v[72:73], v[72:73] op_sel:[0,1] op_sel_hi:[1,0]
	v_pk_add_f32 v[84:85], v[84:85], v[84:85] op_sel:[0,1] op_sel_hi:[1,0]
	v_add_f32_e32 v61, v65, v61
	v_cvt_pk_bf16_f32 v57, v52, v53
	v_permlane16_swap_b32_e32 v60, v0
	v_mov_b32_e32 v71, v70
	v_mov_b32_e32 v73, v72
	v_mov_b32_e32 v85, v84
	global_store_dwordx4 v[50:51], v[54:57], off
	v_add_f32_e32 v50, v60, v0
	v_mov_b32_e32 v0, v61
	v_permlane16_swap_b32_e32 v70, v71
	v_permlane16_swap_b32_e32 v72, v73
	v_permlane16_swap_b32_e32 v84, v85
	v_permlane16_swap_b32_e32 v61, v0
	v_add_f32_e32 v71, v70, v71
	v_add_f32_e32 v70, v72, v73
	v_add_f32_e32 v89, v84, v85
	v_add_f32_e32 v51, v61, v0
	v_mov_b32_e32 v73, v71
	v_mov_b32_e32 v72, v70
	v_mov_b32_e32 v91, v89
	v_mov_b32_e32 v90, v88
	v_mov_b32_e32 v85, v83
	v_mov_b32_e32 v84, v82
	v_mov_b32_e32 v52, v50
	v_mov_b32_e32 v53, v51
	v_permlane32_swap_b32_e32 v71, v73
	v_permlane32_swap_b32_e32 v70, v72
	v_permlane32_swap_b32_e32 v89, v91
	v_permlane32_swap_b32_e32 v88, v90
	v_permlane32_swap_b32_e32 v83, v85
	v_permlane32_swap_b32_e32 v82, v84
	v_permlane32_swap_b32_e32 v50, v52
	v_permlane32_swap_b32_e32 v51, v53
	s_and_saveexec_b64 s[24:25], s[40:41]
	s_cbranch_execz .LBB0_1713
	v_pk_add_f32 v[50:51], v[50:51], v[52:53]
	v_lshl_add_u64 v[52:53], s[8:9], 0, v[66:67]
	v_lshl_add_u64 v[52:53], s[38:39], 2, v[52:53]
	global_store_dwordx2 v[52:53], v[50:51], off
.LBB0_1713:
	s_or_b64 exec, exec, s[24:25]
	v_pk_add_f32 v[50:51], v[70:71], v[72:73]
	s_mov_b32 s2, 0x3a800000
	v_pk_mul_f32 v[92:93], v[50:51], s[2:3] op_sel_hi:[1,0]
	s_mov_b32 s1, 0x800000
	v_fma_f32 v0, -v93, v93, v92
	v_max_f32_e32 v0, 0, v0
	v_add_f32_e32 v0, 0x3727c5ac, v0
	v_cmp_gt_f32_e32 vcc, s1, v0
	v_mul_f32_e32 v50, 0x4b800000, v0
	s_load_dwordx16 s[60:75], s[34:35], 0x38
	v_cndmask_b32_e32 v0, v0, v50, vcc
	v_rsq_f32_e32 v0, v0
	s_mov_b32 s2, 0x3fd744fd
	s_movk_i32 s1, 0x37c0
	v_mul_f32_e32 v50, 0x45800000, v0
	v_cndmask_b32_e32 v92, v0, v50, vcc
	v_lshlrev_b64 v[50:51], 12, v[96:97]
	s_waitcnt lgkmcnt(0)
	v_lshl_add_u64 v[50:51], s[74:75], 0, v[50:51]
	v_lshl_add_u64 v[94:95], v[152:153], 2, v[50:51]
	s_nop 1
	v_bfe_u32 v53, v227, 4, 2
	v_sub_u32_e32 v52, 0, v53
	v_lshlrev_b32_e32 v52, 4, v52
	v_ashrrev_i32_e32 v53, 31, v52
	v_lshl_add_u64 v[52:53], v[94:95], 0, v[52:53]
	global_load_dwordx4 v[98:101], v[52:53], off offset:64
	global_load_dwordx4 v[102:105], v[52:53], off
	s_nop 1
	v_lshrrev_b32_e32 v0, 4, v227
	v_lshlrev_b32_e32 v0, 7, v0
	v_add_u32_e32 v0, 0x20100, v0
	ds_read_b128 v[106:109], v0 offset:16
	ds_read_b128 v[110:113], v0 offset:0
	ds_read_b128 v[114:117], v0 offset:80
	ds_read_b128 v[118:121], v0 offset:64
	s_nop 1
	v_bfe_u32 v55, v227, 4, 2
	v_sub_u32_e32 v54, 0, v55
	v_lshlrev_b32_e32 v54, 4, v54
	v_ashrrev_i32_e32 v55, 31, v54
	v_lshl_add_u64 v[54:55], v[94:95], 0, v[54:55]
	global_load_dwordx4 v[50:53], v[54:55], off offset:576
	global_load_dwordx4 v[70:73], v[54:55], off offset:512
	ds_read_b128 v[54:57], v0 offset:48
	ds_read_b128 v[62:65], v0 offset:32
	ds_read_b128 v[58:61], v0 offset:112
	ds_read_b128 v[66:69], v0 offset:96
	v_lshlrev_b32_e32 v0, 6, v96
	v_and_or_b32 v0, v0, s1, v196
	v_lshlrev_b32_e32 v0, 1, v0
	s_waitcnt vmcnt(2)
	v_permlane32_swap_b32_e32 v102, v98
	v_permlane32_swap_b32_e32 v103, v99
	v_permlane32_swap_b32_e32 v104, v100
	v_permlane32_swap_b32_e32 v105, v101
	v_permlane16_swap_b32_e32 v102, v98
	v_permlane16_swap_b32_e32 v103, v99
	v_permlane16_swap_b32_e32 v104, v100
	v_permlane16_swap_b32_e32 v105, v101
	v_sub_f32_e32 v97, v105, v93
	v_sub_f32_e32 v96, v104, v93
	v_sub_f32_e32 v103, v103, v93
	v_sub_f32_e32 v102, v102, v93
	v_pk_mul_f32 v[102:103], v[92:93], v[102:103] op_sel_hi:[0,1]
	v_pk_mul_f32 v[96:97], v[92:93], v[96:97] op_sel_hi:[0,1]
	s_waitcnt lgkmcnt(0)
; __device__ __forceinline__ float xsum16(float v) { const auto r = __builtin_amdgcn_permlane16_swap(__float_as_uint(v), __float_as_uint(v), false, false); return __uint_as_float(r[0]) + __uint_as_float(r[1]); }
; __device__ __forceinline__ float xsum32(float v) { const auto r = __builtin_amdgcn_permlane32_swap(__float_as_uint(v), __float_as_uint(v), false, false); return __uint_as_float(r[0]) + __uint_as_float(r[1]); }
; __device__ __forceinline__ size_t blk_off(int r, int c, int K) { return (size_t)(r >> 8) * 256 * K + (size_t)(c >> 6) * (256 * 64) + (size_t)((r & 255) * 64 + (c & 63)); }
; __device__ __forceinline__ u32x4 pack8(const f32x4 a, const f32x4 b) { u32x4 w; w.x = cvt_pk_bf16(a[0], a[1]); w.y = cvt_pk_bf16(a[2], a[3]); w.z = cvt_pk_bf16(b[0], b[1]); w.w = cvt_pk_bf16(b[2], b[3]); return w; }
;     __device__ __forceinline__ void operator()(const f32x4 (&acc)[2][2][4][2], const pg8::Unit& u, int wr, int wc, int fr, int fq) const {
;     ...
;                     for (int n = 0; n < 2; ++n) { yv[bj][n] = *(const f32x4*)(Yin + (size_t)row * D_ + col0 + bj * 128 + 4 * n); gq[bj][n] = *(const f32x4*)(g + col0 + bj * 128 + 4 * n); bq_[bj][n] = *(const f32x4*)(b + col0 + bj * 128 + 4 * n); }
;                 asm volatile("" ::: "memory");
;                 float s1 = 0.f, s2 = 0.f;
; #pragma unroll
;                 for (int bj = 0; bj < 2; ++bj) { float* yp = Y + (size_t)row * D_ + col0 + bj * 128; f32x4 v[2];
; #pragma unroll
;                     for (int n = 0; n < 2; ++n) { v[n] = (((yv[bj][n] - mu) * rs) * gq[bj][n] + bq_[bj][n]) * ALPHA_ + acc[ai][bj][m][n] * sc;
;                         *(f32x4*)(yp + 4 * n) = v[n]; s1 += (v[n][0] + v[n][1]) + (v[n][2] + v[n][3]); s2 += (v[n][0] * v[n][0] + v[n][1] * v[n][1]) + (v[n][2] * v[n][2] + v[n][3] * v[n][3]); }
;                     *(u32x4*)(Yb + blk_off(row, col0 + bj * 128, D_)) = pack8(v[0], v[1]); }
;                 s1 = xsum32(xsum16(s1)); s2 = xsum32(xsum16(s2));
;                 if (fq == 0) *(f32x2*)(stn + (size_t)row * 32 + (u.pn * 4 + wc) * 2) = (f32x2){s1, s2}; asm volatile("" ::: "memory"); } }
	v_pk_fma_f32 v[96:97], v[112:113], v[96:97], v[120:121]
	v_pk_fma_f32 v[102:103], v[110:111], v[102:103], v[118:119]
	v_pk_mul_f32 v[96:97], v[96:97], s[2:3] op_sel_hi:[1,0]
	v_pk_mul_f32 v[102:103], v[102:103], s[2:3] op_sel_hi:[1,0]
	v_pk_fma_f32 v[104:105], v[48:49], 0.5, v[96:97] op_sel_hi:[1,0,1]
	v_pk_fma_f32 v[102:103], v[46:47], 0.5, v[102:103] op_sel_hi:[1,0,1]
	v_add_f32_e32 v47, v104, v105
	v_add_f32_e32 v46, v102, v103
	v_add_f32_e32 v46, v46, v47
	v_add_f32_e32 v110, 0, v46
	v_mul_f32_e32 v46, v103, v103
	v_mul_f32_e32 v47, v105, v105
	v_fmac_f32_e32 v46, v102, v102
	v_fmac_f32_e32 v47, v104, v104
	v_add_f32_e32 v111, v46, v47
	v_sub_f32_e32 v47, v101, v93
	v_sub_f32_e32 v46, v100, v93
	v_sub_f32_e32 v49, v99, v93
	v_sub_f32_e32 v48, v98, v93
	v_pk_mul_f32 v[48:49], v[92:93], v[48:49] op_sel_hi:[0,1]
	v_pk_mul_f32 v[46:47], v[92:93], v[46:47] op_sel_hi:[0,1]
	v_pk_fma_f32 v[46:47], v[108:109], v[46:47], v[116:117]
	v_pk_fma_f32 v[48:49], v[106:107], v[48:49], v[114:115]
	v_pk_mul_f32 v[46:47], v[46:47], s[2:3] op_sel_hi:[1,0]
	v_pk_mul_f32 v[48:49], v[48:49], s[2:3] op_sel_hi:[1,0]
	v_pk_fma_f32 v[98:99], v[44:45], 0.5, v[46:47] op_sel_hi:[1,0,1]
	v_pk_fma_f32 v[96:97], v[42:43], 0.5, v[48:49] op_sel_hi:[1,0,1]
	v_add_f32_e32 v43, v98, v99
	v_add_f32_e32 v42, v96, v97
	v_add_f32_e32 v42, v42, v43
	v_add_f32_e32 v47, v110, v42
	v_mul_f32_e32 v42, v97, v97
	v_mul_f32_e32 v43, v99, v99
	v_fmac_f32_e32 v42, v96, v96
	v_fmac_f32_e32 v43, v98, v98
	v_add_f32_e32 v42, v42, v43
	v_add_f32_e32 v46, v111, v42
	v_cvt_pk_bf16_f32 v42, v102, v103
	v_cvt_pk_bf16_f32 v43, v104, v105
	v_cvt_pk_bf16_f32 v44, v96, v97
	v_cvt_pk_bf16_f32 v45, v98, v99
	v_lshl_add_u64 v[48:49], v[78:79], 0, v[0:1]
	s_nop 0
	s_nop 1
	v_bfe_u32 v101, v227, 4, 2
	v_sub_u32_e32 v100, 0, v101
	v_lshlrev_b32_e32 v100, 4, v100
	v_ashrrev_i32_e32 v101, 31, v100
	v_lshl_add_u64 v[100:101], v[94:95], 0, v[100:101]
	v_permlane16_swap_b32_e32 v102, v96
	v_permlane16_swap_b32_e32 v103, v97
	v_permlane16_swap_b32_e32 v104, v98
	v_permlane16_swap_b32_e32 v105, v99
	v_permlane32_swap_b32_e32 v102, v96
	v_permlane32_swap_b32_e32 v103, v97
	v_permlane32_swap_b32_e32 v104, v98
	v_permlane32_swap_b32_e32 v105, v99
	global_store_dwordx4 v[100:101], v[102:105], off
	global_store_dwordx4 v[100:101], v[96:99], off offset:64
	s_nop 1
	v_permlane32_swap_b32_e32 v102, v96
	v_permlane32_swap_b32_e32 v103, v97
	v_permlane32_swap_b32_e32 v104, v98
	v_permlane32_swap_b32_e32 v105, v99
	v_permlane16_swap_b32_e32 v102, v96
	v_permlane16_swap_b32_e32 v103, v97
	v_permlane16_swap_b32_e32 v104, v98
	v_permlane16_swap_b32_e32 v105, v99
	global_store_dwordx4 v[48:49], v[42:45], off
	s_nop 0
	s_waitcnt vmcnt(3)
	v_permlane32_swap_b32_e32 v70, v50
	v_permlane32_swap_b32_e32 v71, v51
	v_permlane32_swap_b32_e32 v72, v52
	v_permlane32_swap_b32_e32 v73, v53
	v_permlane16_swap_b32_e32 v70, v50
	v_permlane16_swap_b32_e32 v71, v51
	v_permlane16_swap_b32_e32 v72, v52
	v_permlane16_swap_b32_e32 v73, v53
	v_sub_f32_e32 v43, v73, v93
	v_sub_f32_e32 v42, v72, v93
	v_sub_f32_e32 v45, v71, v93
	v_sub_f32_e32 v44, v70, v93
	v_pk_mul_f32 v[44:45], v[92:93], v[44:45] op_sel_hi:[0,1]
	v_pk_mul_f32 v[42:43], v[92:93], v[42:43] op_sel_hi:[0,1]
	v_pk_fma_f32 v[42:43], v[64:65], v[42:43], v[68:69]
	v_pk_fma_f32 v[44:45], v[62:63], v[44:45], v[66:67]
	v_pk_mul_f32 v[42:43], v[42:43], s[2:3] op_sel_hi:[1,0]
	v_pk_mul_f32 v[44:45], v[44:45], s[2:3] op_sel_hi:[1,0]
	v_pk_fma_f32 v[40:41], v[40:41], 0.5, v[42:43] op_sel_hi:[1,0,1]
	v_pk_fma_f32 v[38:39], v[38:39], 0.5, v[44:45] op_sel_hi:[1,0,1]
	v_add_f32_e32 v43, v40, v41
	v_add_f32_e32 v42, v38, v39
	v_add_f32_e32 v42, v42, v43
	v_add_f32_e32 v47, v47, v42
	v_mul_f32_e32 v42, v39, v39
	v_mul_f32_e32 v43, v41, v41
	v_fmac_f32_e32 v42, v38, v38
	v_fmac_f32_e32 v43, v40, v40
	v_add_f32_e32 v42, v42, v43
	v_add_f32_e32 v46, v46, v42
	v_sub_f32_e32 v43, v53, v93
	v_sub_f32_e32 v42, v52, v93
	v_sub_f32_e32 v45, v51, v93
	v_sub_f32_e32 v44, v50, v93
	v_pk_mul_f32 v[44:45], v[92:93], v[44:45] op_sel_hi:[0,1]
	v_pk_mul_f32 v[42:43], v[92:93], v[42:43] op_sel_hi:[0,1]
	v_pk_fma_f32 v[42:43], v[56:57], v[42:43], v[60:61]
	v_pk_fma_f32 v[44:45], v[54:55], v[44:45], v[58:59]
	v_pk_mul_f32 v[42:43], v[42:43], s[2:3] op_sel_hi:[1,0]
	v_pk_mul_f32 v[44:45], v[44:45], s[2:3] op_sel_hi:[1,0]
	v_pk_fma_f32 v[36:37], v[36:37], 0.5, v[42:43] op_sel_hi:[1,0,1]
	v_pk_fma_f32 v[34:35], v[34:35], 0.5, v[44:45] op_sel_hi:[1,0,1]
	v_add_f32_e32 v43, v36, v37
	v_add_f32_e32 v42, v34, v35
	v_add_f32_e32 v42, v42, v43
	v_mul_f32_e32 v43, v35, v35
	v_mul_f32_e32 v44, v37, v37
	v_add_f32_e32 v42, v47, v42
	v_fmac_f32_e32 v43, v34, v34
	v_fmac_f32_e32 v44, v36, v36
	s_nop 0
	s_nop 1
	v_bfe_u32 v49, v227, 4, 2
	v_sub_u32_e32 v48, 0, v49
	v_lshlrev_b32_e32 v48, 4, v48
	v_ashrrev_i32_e32 v49, 31, v48
	v_lshl_add_u64 v[48:49], v[94:95], 0, v[48:49]
	v_permlane16_swap_b32_e32 v38, v34
	v_permlane16_swap_b32_e32 v39, v35
	v_permlane16_swap_b32_e32 v40, v36
	v_permlane16_swap_b32_e32 v41, v37
	v_permlane32_swap_b32_e32 v38, v34
	v_permlane32_swap_b32_e32 v39, v35
	v_permlane32_swap_b32_e32 v40, v36
	v_permlane32_swap_b32_e32 v41, v37
	global_store_dwordx4 v[48:49], v[38:41], off offset:512
	global_store_dwordx4 v[48:49], v[34:37], off offset:576
	s_nop 1
	v_permlane32_swap_b32_e32 v38, v34
	v_permlane32_swap_b32_e32 v39, v35
	v_permlane32_swap_b32_e32 v40, v36
	v_permlane32_swap_b32_e32 v41, v37
	v_permlane16_swap_b32_e32 v38, v34
	v_permlane16_swap_b32_e32 v39, v35
	v_permlane16_swap_b32_e32 v40, v36
	v_permlane16_swap_b32_e32 v41, v37
	v_add_f32_e32 v43, v43, v44
	v_cvt_pk_bf16_f32 v38, v38, v39
	v_cvt_pk_bf16_f32 v39, v40, v41
	v_cvt_pk_bf16_f32 v40, v34, v35
	v_lshl_add_u64 v[34:35], v[76:77], 0, v[0:1]
	v_mov_b32_e32 v0, v42
	v_add_f32_e32 v43, v46, v43
	v_cvt_pk_bf16_f32 v41, v36, v37
	v_permlane16_swap_b32_e32 v42, v0
	global_store_dwordx4 v[34:35], v[38:41], off
	v_add_f32_e32 v34, v42, v0
	v_mov_b32_e32 v0, v43
	s_nop 1
	v_permlane16_swap_b32_e32 v43, v0
	v_add_f32_e32 v35, v43, v0
	v_mov_b32_e32 v36, v34
	v_mov_b32_e32 v37, v35
	s_nop 0
	v_permlane32_swap_b32_e32 v34, v36
	v_permlane32_swap_b32_e32 v35, v37
	s_and_saveexec_b64 s[24:25], s[40:41]
	s_cbranch_execz .LBB0_1715
	v_pk_add_f32 v[34:35], v[34:35], v[36:37]
	v_lshl_add_u64 v[36:37], s[8:9], 0, v[86:87]
	v_lshl_add_u64 v[36:37], s[38:39], 2, v[36:37]
	global_store_dwordx2 v[36:37], v[34:35], off
; __device__ __forceinline__ float xsum16(float v) { const auto r = __builtin_amdgcn_permlane16_swap(__float_as_uint(v), __float_as_uint(v), false, false); return __uint_as_float(r[0]) + __uint_as_float(r[1]); }
; __device__ __forceinline__ float xsum32(float v) { const auto r = __builtin_amdgcn_permlane32_swap(__float_as_uint(v), __float_as_uint(v), false, false); return __uint_as_float(r[0]) + __uint_as_float(r[1]); }
; __device__ __forceinline__ size_t blk_off(int r, int c, int K) { return (size_t)(r >> 8) * 256 * K + (size_t)(c >> 6) * (256 * 64) + (size_t)((r & 255) * 64 + (c & 63)); }
; __device__ __forceinline__ void row_stats4(const float* st, int rowb, int fq, float (&mu)[4], float (&rs)[4]) {
;     ...
;     for (int m = 0; m < 4; ++m) { float s1 = (a[m][0] + a[m][2]) + (b[m][0] + b[m][2]), s2 = (a[m][1] + a[m][3]) + (b[m][1] + b[m][3]);
;         s1 = xsum32(xsum16(s1)); s2 = xsum32(xsum16(s2));
;         const float mm = s1 * (1.0f / 1024.0f); mu[m] = mm; rs[m] = rsqrtf(fmaxf(s2 * (1.0f / 1024.0f) - mm * mm, 0.f) + LN_EPS_); }
;     __device__ __forceinline__ void operator()(const f32x4 (&acc)[2][2][4][2], const pg8::Unit& u, int wr, int wc, int fr, int fq) const {
;     ...
;             for (int m = 0; m < 4; ++m) { const int row = row0 + ai * 128 + m * 16; const float mu = mu4[m], rs = rs4[m];
;                 f32x4 yv[2][2], gq[2][2], bq_[2][2];
; #pragma unroll
;                 for (int bj = 0; bj < 2; ++bj)
; #pragma unroll
;                     for (int n = 0; n < 2; ++n) { yv[bj][n] = *(const f32x4*)(Yin + (size_t)row * D_ + col0 + bj * 128 + 4 * n); gq[bj][n] = *(const f32x4*)(g + col0 + bj * 128 + 4 * n); bq_[bj][n] = *(const f32x4*)(b + col0 + bj * 128 + 4 * n); }
;                 asm volatile("" ::: "memory");
;                 float s1 = 0.f, s2 = 0.f;
; #pragma unroll
;                 for (int bj = 0; bj < 2; ++bj) { float* yp = Y + (size_t)row * D_ + col0 + bj * 128; f32x4 v[2];
; #pragma unroll
;                     for (int n = 0; n < 2; ++n) { v[n] = (((yv[bj][n] - mu) * rs) * gq[bj][n] + bq_[bj][n]) * ALPHA_ + acc[ai][bj][m][n] * sc;
;                         *(f32x4*)(yp + 4 * n) = v[n]; s1 += (v[n][0] + v[n][1]) + (v[n][2] + v[n][3]); s2 += (v[n][0] * v[n][0] + v[n][1] * v[n][1]) + (v[n][2] * v[n][2] + v[n][3] * v[n][3]); }
;                     *(u32x4*)(Yb + blk_off(row, col0 + bj * 128, D_)) = pack8(v[0], v[1]); }
.LBB0_1715:
	s_or_b64 exec, exec, s[24:25]
	v_pk_add_f32 v[34:35], v[88:89], v[90:91]
	s_mov_b32 s2, 0x3a800000
	v_pk_mul_f32 v[58:59], v[34:35], s[2:3] op_sel_hi:[1,0]
	s_mov_b32 s1, 0x800000
	v_fma_f32 v0, -v59, v59, v58
	v_max_f32_e32 v0, 0, v0
	v_add_f32_e32 v0, 0x3727c5ac, v0
	v_cmp_gt_f32_e32 vcc, s1, v0
	v_mul_f32_e32 v34, 0x4b800000, v0
	s_load_dwordx16 s[60:75], s[34:35], 0x38
	v_cndmask_b32_e32 v0, v0, v34, vcc
	v_rsq_f32_e32 v0, v0
	s_mov_b32 s2, 0x3fd744fd
	s_movk_i32 s1, 0x3bc0
	v_mul_f32_e32 v34, 0x45800000, v0
	v_cndmask_b32_e32 v58, v0, v34, vcc
	v_lshlrev_b64 v[34:35], 12, v[80:81]
	s_waitcnt lgkmcnt(0)
	v_lshl_add_u64 v[34:35], s[74:75], 0, v[34:35]
	v_lshl_add_u64 v[60:61], v[152:153], 2, v[34:35]
	s_nop 1
	v_bfe_u32 v37, v227, 4, 2
	v_sub_u32_e32 v36, 0, v37
	v_lshlrev_b32_e32 v36, 4, v36
	v_ashrrev_i32_e32 v37, 31, v36
	v_lshl_add_u64 v[36:37], v[60:61], 0, v[36:37]
	global_load_dwordx4 v[62:65], v[36:37], off offset:64
	global_load_dwordx4 v[66:69], v[36:37], off
	s_nop 1
	v_lshrrev_b32_e32 v0, 4, v227
	v_lshlrev_b32_e32 v0, 7, v0
	v_add_u32_e32 v0, 0x20100, v0
	ds_read_b128 v[70:73], v0 offset:16
	ds_read_b128 v[86:89], v0 offset:0
	ds_read_b128 v[90:93], v0 offset:80
	ds_read_b128 v[94:97], v0 offset:64
	s_nop 1
	v_bfe_u32 v39, v227, 4, 2
	v_sub_u32_e32 v38, 0, v39
	v_lshlrev_b32_e32 v38, 4, v38
	v_ashrrev_i32_e32 v39, 31, v38
	v_lshl_add_u64 v[38:39], v[60:61], 0, v[38:39]
	global_load_dwordx4 v[34:37], v[38:39], off offset:576
	global_load_dwordx4 v[54:57], v[38:39], off offset:512
	ds_read_b128 v[38:41], v0 offset:48
	ds_read_b128 v[46:49], v0 offset:32
	ds_read_b128 v[42:45], v0 offset:112
	ds_read_b128 v[50:53], v0 offset:96
	v_lshlrev_b32_e32 v0, 6, v80
	v_and_or_b32 v0, v0, s1, v196
	v_lshlrev_b32_e32 v0, 1, v0
	s_waitcnt vmcnt(2)
	v_permlane32_swap_b32_e32 v66, v62
	v_permlane32_swap_b32_e32 v67, v63
	v_permlane32_swap_b32_e32 v68, v64
	v_permlane32_swap_b32_e32 v69, v65
	v_permlane16_swap_b32_e32 v66, v62
	v_permlane16_swap_b32_e32 v67, v63
	v_permlane16_swap_b32_e32 v68, v64
	v_permlane16_swap_b32_e32 v69, v65
	v_sub_f32_e32 v69, v69, v59
	v_sub_f32_e32 v68, v68, v59
	v_sub_f32_e32 v67, v67, v59
	v_sub_f32_e32 v66, v66, v59
	v_pk_mul_f32 v[66:67], v[58:59], v[66:67] op_sel_hi:[0,1]
	v_pk_mul_f32 v[68:69], v[58:59], v[68:69] op_sel_hi:[0,1]
	s_waitcnt lgkmcnt(0)
	v_pk_fma_f32 v[68:69], v[88:89], v[68:69], v[96:97]
	v_pk_fma_f32 v[66:67], v[86:87], v[66:67], v[94:95]
	v_pk_mul_f32 v[68:69], v[68:69], s[2:3] op_sel_hi:[1,0]
	v_pk_mul_f32 v[66:67], v[66:67], s[2:3] op_sel_hi:[1,0]
	v_pk_fma_f32 v[68:69], v[32:33], 0.5, v[68:69] op_sel_hi:[1,0,1]
	v_pk_fma_f32 v[66:67], v[30:31], 0.5, v[66:67] op_sel_hi:[1,0,1]
	v_add_f32_e32 v31, v68, v69
	v_add_f32_e32 v30, v66, v67
	v_add_f32_e32 v30, v30, v31
	v_add_f32_e32 v86, 0, v30
	v_mul_f32_e32 v30, v67, v67
	v_mul_f32_e32 v31, v69, v69
	v_fmac_f32_e32 v30, v66, v66
	v_fmac_f32_e32 v31, v68, v68
	v_add_f32_e32 v87, v30, v31
	v_sub_f32_e32 v31, v65, v59
	v_sub_f32_e32 v30, v64, v59
	v_sub_f32_e32 v33, v63, v59
	v_sub_f32_e32 v32, v62, v59
	v_pk_mul_f32 v[32:33], v[58:59], v[32:33] op_sel_hi:[0,1]
	v_pk_mul_f32 v[30:31], v[58:59], v[30:31] op_sel_hi:[0,1]
	v_pk_fma_f32 v[30:31], v[72:73], v[30:31], v[92:93]
	v_pk_fma_f32 v[32:33], v[70:71], v[32:33], v[90:91]
	v_pk_mul_f32 v[30:31], v[30:31], s[2:3] op_sel_hi:[1,0]
	v_pk_mul_f32 v[32:33], v[32:33], s[2:3] op_sel_hi:[1,0]
	v_pk_fma_f32 v[64:65], v[28:29], 0.5, v[30:31] op_sel_hi:[1,0,1]
	v_pk_fma_f32 v[62:63], v[26:27], 0.5, v[32:33] op_sel_hi:[1,0,1]
	v_add_f32_e32 v27, v64, v65
	v_add_f32_e32 v26, v62, v63
	v_add_f32_e32 v26, v26, v27
	v_add_f32_e32 v31, v86, v26
	v_mul_f32_e32 v26, v63, v63
	v_mul_f32_e32 v27, v65, v65
	v_fmac_f32_e32 v26, v62, v62
	v_fmac_f32_e32 v27, v64, v64
	v_add_f32_e32 v26, v26, v27
	v_add_f32_e32 v30, v87, v26
	v_cvt_pk_bf16_f32 v26, v66, v67
	v_cvt_pk_bf16_f32 v27, v68, v69
	v_cvt_pk_bf16_f32 v28, v62, v63
	v_cvt_pk_bf16_f32 v29, v64, v65
	v_lshl_add_u64 v[32:33], v[78:79], 0, v[0:1]
	s_nop 0
	s_nop 1
	v_bfe_u32 v71, v227, 4, 2
	v_sub_u32_e32 v70, 0, v71
	v_lshlrev_b32_e32 v70, 4, v70
	v_ashrrev_i32_e32 v71, 31, v70
	v_lshl_add_u64 v[70:71], v[60:61], 0, v[70:71]
	v_permlane16_swap_b32_e32 v66, v62
	v_permlane16_swap_b32_e32 v67, v63
	v_permlane16_swap_b32_e32 v68, v64
	v_permlane16_swap_b32_e32 v69, v65
	v_permlane32_swap_b32_e32 v66, v62
	v_permlane32_swap_b32_e32 v67, v63
	v_permlane32_swap_b32_e32 v68, v64
	v_permlane32_swap_b32_e32 v69, v65
	global_store_dwordx4 v[70:71], v[66:69], off
	global_store_dwordx4 v[70:71], v[62:65], off offset:64
	s_nop 1
	v_permlane32_swap_b32_e32 v66, v62
	v_permlane32_swap_b32_e32 v67, v63
	v_permlane32_swap_b32_e32 v68, v64
	v_permlane32_swap_b32_e32 v69, v65
	v_permlane16_swap_b32_e32 v66, v62
	v_permlane16_swap_b32_e32 v67, v63
	v_permlane16_swap_b32_e32 v68, v64
	v_permlane16_swap_b32_e32 v69, v65
	global_store_dwordx4 v[32:33], v[26:29], off
	s_nop 0
	s_waitcnt vmcnt(3)
; __device__ __forceinline__ float xsum16(float v) { const auto r = __builtin_amdgcn_permlane16_swap(__float_as_uint(v), __float_as_uint(v), false, false); return __uint_as_float(r[0]) + __uint_as_float(r[1]); }
; __device__ __forceinline__ float xsum32(float v) { const auto r = __builtin_amdgcn_permlane32_swap(__float_as_uint(v), __float_as_uint(v), false, false); return __uint_as_float(r[0]) + __uint_as_float(r[1]); }
; __device__ __forceinline__ size_t blk_off(int r, int c, int K) { return (size_t)(r >> 8) * 256 * K + (size_t)(c >> 6) * (256 * 64) + (size_t)((r & 255) * 64 + (c & 63)); }
; __device__ __forceinline__ u32x4 pack8(const f32x4 a, const f32x4 b) { u32x4 w; w.x = cvt_pk_bf16(a[0], a[1]); w.y = cvt_pk_bf16(a[2], a[3]); w.z = cvt_pk_bf16(b[0], b[1]); w.w = cvt_pk_bf16(b[2], b[3]); return w; }
;     __device__ __forceinline__ void operator()(const f32x4 (&acc)[2][2][4][2], const pg8::Unit& u, int wr, int wc, int fr, int fq) const {
;     ...
;             for (int m = 0; m < 4; ++m) { const int row = row0 + ai * 128 + m * 16; const float mu = mu4[m], rs = rs4[m];
;                 f32x4 yv[2][2], gq[2][2], bq_[2][2];
; #pragma unroll
;                 for (int bj = 0; bj < 2; ++bj)
; #pragma unroll
;                     for (int n = 0; n < 2; ++n) { yv[bj][n] = *(const f32x4*)(Yin + (size_t)row * D_ + col0 + bj * 128 + 4 * n); gq[bj][n] = *(const f32x4*)(g + col0 + bj * 128 + 4 * n); bq_[bj][n] = *(const f32x4*)(b + col0 + bj * 128 + 4 * n); }
;                 asm volatile("" ::: "memory");
;                 float s1 = 0.f, s2 = 0.f;
; #pragma unroll
;                 for (int bj = 0; bj < 2; ++bj) { float* yp = Y + (size_t)row * D_ + col0 + bj * 128; f32x4 v[2];
; #pragma unroll
;                     for (int n = 0; n < 2; ++n) { v[n] = (((yv[bj][n] - mu) * rs) * gq[bj][n] + bq_[bj][n]) * ALPHA_ + acc[ai][bj][m][n] * sc;
;                         *(f32x4*)(yp + 4 * n) = v[n]; s1 += (v[n][0] + v[n][1]) + (v[n][2] + v[n][3]); s2 += (v[n][0] * v[n][0] + v[n][1] * v[n][1]) + (v[n][2] * v[n][2] + v[n][3] * v[n][3]); }
;                     *(u32x4*)(Yb + blk_off(row, col0 + bj * 128, D_)) = pack8(v[0], v[1]); }
;                 s1 = xsum32(xsum16(s1)); s2 = xsum32(xsum16(s2));
;                 if (fq == 0) *(f32x2*)(stn + (size_t)row * 32 + (u.pn * 4 + wc) * 2) = (f32x2){s1, s2}; asm volatile("" ::: "memory"); } }
	v_permlane32_swap_b32_e32 v54, v34
	v_permlane32_swap_b32_e32 v55, v35
	v_permlane32_swap_b32_e32 v56, v36
	v_permlane32_swap_b32_e32 v57, v37
	v_permlane16_swap_b32_e32 v54, v34
	v_permlane16_swap_b32_e32 v55, v35
	v_permlane16_swap_b32_e32 v56, v36
	v_permlane16_swap_b32_e32 v57, v37
	v_sub_f32_e32 v27, v57, v59
	v_sub_f32_e32 v26, v56, v59
	v_sub_f32_e32 v29, v55, v59
	v_sub_f32_e32 v28, v54, v59
	v_pk_mul_f32 v[28:29], v[58:59], v[28:29] op_sel_hi:[0,1]
	v_pk_mul_f32 v[26:27], v[58:59], v[26:27] op_sel_hi:[0,1]
	v_pk_fma_f32 v[26:27], v[48:49], v[26:27], v[52:53]
	v_pk_fma_f32 v[28:29], v[46:47], v[28:29], v[50:51]
	v_pk_mul_f32 v[26:27], v[26:27], s[2:3] op_sel_hi:[1,0]
	v_pk_mul_f32 v[28:29], v[28:29], s[2:3] op_sel_hi:[1,0]
	v_pk_fma_f32 v[24:25], v[24:25], 0.5, v[26:27] op_sel_hi:[1,0,1]
	v_pk_fma_f32 v[22:23], v[22:23], 0.5, v[28:29] op_sel_hi:[1,0,1]
	v_add_f32_e32 v27, v24, v25
	v_add_f32_e32 v26, v22, v23
	v_add_f32_e32 v26, v26, v27
	v_add_f32_e32 v31, v31, v26
	v_mul_f32_e32 v26, v23, v23
	v_mul_f32_e32 v27, v25, v25
	v_fmac_f32_e32 v26, v22, v22
	v_fmac_f32_e32 v27, v24, v24
	v_add_f32_e32 v26, v26, v27
	v_add_f32_e32 v30, v30, v26
	v_sub_f32_e32 v27, v37, v59
	v_sub_f32_e32 v26, v36, v59
	v_sub_f32_e32 v29, v35, v59
	v_sub_f32_e32 v28, v34, v59
	v_pk_mul_f32 v[28:29], v[58:59], v[28:29] op_sel_hi:[0,1]
	v_pk_mul_f32 v[26:27], v[58:59], v[26:27] op_sel_hi:[0,1]
	v_pk_fma_f32 v[26:27], v[40:41], v[26:27], v[44:45]
	v_pk_fma_f32 v[28:29], v[38:39], v[28:29], v[42:43]
	v_pk_mul_f32 v[26:27], v[26:27], s[2:3] op_sel_hi:[1,0]
	v_pk_mul_f32 v[28:29], v[28:29], s[2:3] op_sel_hi:[1,0]
	v_pk_fma_f32 v[20:21], v[20:21], 0.5, v[26:27] op_sel_hi:[1,0,1]
	v_pk_fma_f32 v[18:19], v[18:19], 0.5, v[28:29] op_sel_hi:[1,0,1]
	v_add_f32_e32 v27, v20, v21
	v_add_f32_e32 v26, v18, v19
	v_add_f32_e32 v26, v26, v27
	v_mul_f32_e32 v27, v19, v19
	v_mul_f32_e32 v28, v21, v21
	v_add_f32_e32 v26, v31, v26
	v_fmac_f32_e32 v27, v18, v18
	v_fmac_f32_e32 v28, v20, v20
	s_nop 0
	s_nop 1
	v_bfe_u32 v33, v227, 4, 2
	v_sub_u32_e32 v32, 0, v33
	v_lshlrev_b32_e32 v32, 4, v32
	v_ashrrev_i32_e32 v33, 31, v32
	v_lshl_add_u64 v[32:33], v[60:61], 0, v[32:33]
	v_permlane16_swap_b32_e32 v22, v18
	v_permlane16_swap_b32_e32 v23, v19
	v_permlane16_swap_b32_e32 v24, v20
	v_permlane16_swap_b32_e32 v25, v21
	v_permlane32_swap_b32_e32 v22, v18
	v_permlane32_swap_b32_e32 v23, v19
	v_permlane32_swap_b32_e32 v24, v20
	v_permlane32_swap_b32_e32 v25, v21
	global_store_dwordx4 v[32:33], v[22:25], off offset:512
	global_store_dwordx4 v[32:33], v[18:21], off offset:576
	s_nop 1
	v_permlane32_swap_b32_e32 v22, v18
	v_permlane32_swap_b32_e32 v23, v19
	v_permlane32_swap_b32_e32 v24, v20
	v_permlane32_swap_b32_e32 v25, v21
	v_permlane16_swap_b32_e32 v22, v18
	v_permlane16_swap_b32_e32 v23, v19
	v_permlane16_swap_b32_e32 v24, v20
	v_permlane16_swap_b32_e32 v25, v21
	v_add_f32_e32 v27, v27, v28
	v_cvt_pk_bf16_f32 v22, v22, v23
	v_cvt_pk_bf16_f32 v23, v24, v25
	v_cvt_pk_bf16_f32 v24, v18, v19
	v_lshl_add_u64 v[18:19], v[76:77], 0, v[0:1]
	v_mov_b32_e32 v0, v26
	v_add_f32_e32 v27, v30, v27
	v_cvt_pk_bf16_f32 v25, v20, v21
	v_permlane16_swap_b32_e32 v26, v0
	global_store_dwordx4 v[18:19], v[22:25], off
	v_add_f32_e32 v18, v26, v0
	v_mov_b32_e32 v0, v27
	s_nop 1
	v_permlane16_swap_b32_e32 v27, v0
	v_add_f32_e32 v19, v27, v0
	v_mov_b32_e32 v20, v18
	v_mov_b32_e32 v21, v19
	s_nop 0
	v_permlane32_swap_b32_e32 v18, v20
	v_permlane32_swap_b32_e32 v19, v21
	s_and_saveexec_b64 s[24:25], s[40:41]
	s_cbranch_execz .LBB0_1717
	v_pk_add_f32 v[18:19], v[18:19], v[20:21]
	v_lshlrev_b64 v[20:21], 7, v[80:81]
	v_lshl_add_u64 v[20:21], s[8:9], 0, v[20:21]
	v_lshl_add_u64 v[20:21], s[38:39], 2, v[20:21]
	global_store_dwordx2 v[20:21], v[18:19], off
.LBB0_1717:
	s_or_b64 exec, exec, s[24:25]
	v_pk_add_f32 v[18:19], v[82:83], v[84:85]
	s_mov_b32 s2, 0x3a800000
	v_pk_mul_f32 v[42:43], v[18:19], s[2:3] op_sel_hi:[1,0]
	s_mov_b32 s1, 0x800000
	v_fma_f32 v0, -v43, v43, v42
	v_max_f32_e32 v0, 0, v0
	v_add_f32_e32 v0, 0x3727c5ac, v0
	v_cmp_gt_f32_e32 vcc, s1, v0
	v_mul_f32_e32 v18, 0x4b800000, v0
	s_load_dwordx16 s[60:75], s[34:35], 0x38
	v_cndmask_b32_e32 v0, v0, v18, vcc
	v_rsq_f32_e32 v0, v0
	s_mov_b32 s2, 0x3fd744fd
	s_movk_i32 s1, 0x3fc0
	v_mul_f32_e32 v18, 0x45800000, v0
	v_cndmask_b32_e32 v42, v0, v18, vcc
	v_lshlrev_b64 v[18:19], 12, v[74:75]
	s_waitcnt lgkmcnt(0)
	v_lshl_add_u64 v[18:19], s[74:75], 0, v[18:19]
	v_lshl_add_u64 v[44:45], v[152:153], 2, v[18:19]
	s_nop 1
	v_bfe_u32 v21, v227, 4, 2
	v_sub_u32_e32 v20, 0, v21
	v_lshlrev_b32_e32 v20, 4, v20
	v_ashrrev_i32_e32 v21, 31, v20
	v_lshl_add_u64 v[20:21], v[44:45], 0, v[20:21]
	global_load_dwordx4 v[46:49], v[20:21], off offset:64
	global_load_dwordx4 v[50:53], v[20:21], off
	s_nop 1
	v_lshrrev_b32_e32 v0, 4, v227
	v_lshlrev_b32_e32 v0, 7, v0
	v_add_u32_e32 v0, 0x20100, v0
	ds_read_b128 v[54:57], v0 offset:16
	ds_read_b128 v[58:61], v0 offset:0
	ds_read_b128 v[62:65], v0 offset:80
	ds_read_b128 v[66:69], v0 offset:64
	s_nop 1
	v_bfe_u32 v23, v227, 4, 2
	v_sub_u32_e32 v22, 0, v23
	v_lshlrev_b32_e32 v22, 4, v22
	v_ashrrev_i32_e32 v23, 31, v22
	v_lshl_add_u64 v[22:23], v[44:45], 0, v[22:23]
	global_load_dwordx4 v[18:21], v[22:23], off offset:576
	global_load_dwordx4 v[38:41], v[22:23], off offset:512
	ds_read_b128 v[22:25], v0 offset:48
	ds_read_b128 v[30:33], v0 offset:32
	ds_read_b128 v[26:29], v0 offset:112
	ds_read_b128 v[34:37], v0 offset:96
	v_lshlrev_b32_e32 v0, 6, v74
	v_and_or_b32 v0, v0, s1, v196
	v_lshlrev_b32_e32 v0, 1, v0
	s_waitcnt vmcnt(2)
; __device__ __forceinline__ float xsum16(float v) { const auto r = __builtin_amdgcn_permlane16_swap(__float_as_uint(v), __float_as_uint(v), false, false); return __uint_as_float(r[0]) + __uint_as_float(r[1]); }
; __device__ __forceinline__ float xsum32(float v) { const auto r = __builtin_amdgcn_permlane32_swap(__float_as_uint(v), __float_as_uint(v), false, false); return __uint_as_float(r[0]) + __uint_as_float(r[1]); }
; __device__ __forceinline__ size_t blk_off(int r, int c, int K) { return (size_t)(r >> 8) * 256 * K + (size_t)(c >> 6) * (256 * 64) + (size_t)((r & 255) * 64 + (c & 63)); }
; __device__ __forceinline__ u32x4 pack8(const f32x4 a, const f32x4 b) { u32x4 w; w.x = cvt_pk_bf16(a[0], a[1]); w.y = cvt_pk_bf16(a[2], a[3]); w.z = cvt_pk_bf16(b[0], b[1]); w.w = cvt_pk_bf16(b[2], b[3]); return w; }
;     __device__ __forceinline__ void operator()(const f32x4 (&acc)[2][2][4][2], const pg8::Unit& u, int wr, int wc, int fr, int fq) const {
;     ...
;                     for (int n = 0; n < 2; ++n) { yv[bj][n] = *(const f32x4*)(Yin + (size_t)row * D_ + col0 + bj * 128 + 4 * n); gq[bj][n] = *(const f32x4*)(g + col0 + bj * 128 + 4 * n); bq_[bj][n] = *(const f32x4*)(b + col0 + bj * 128 + 4 * n); }
;                 asm volatile("" ::: "memory");
;                 float s1 = 0.f, s2 = 0.f;
; #pragma unroll
;                 for (int bj = 0; bj < 2; ++bj) { float* yp = Y + (size_t)row * D_ + col0 + bj * 128; f32x4 v[2];
; #pragma unroll
;                     for (int n = 0; n < 2; ++n) { v[n] = (((yv[bj][n] - mu) * rs) * gq[bj][n] + bq_[bj][n]) * ALPHA_ + acc[ai][bj][m][n] * sc;
;                         *(f32x4*)(yp + 4 * n) = v[n]; s1 += (v[n][0] + v[n][1]) + (v[n][2] + v[n][3]); s2 += (v[n][0] * v[n][0] + v[n][1] * v[n][1]) + (v[n][2] * v[n][2] + v[n][3] * v[n][3]); }
;                     *(u32x4*)(Yb + blk_off(row, col0 + bj * 128, D_)) = pack8(v[0], v[1]); }
;                 s1 = xsum32(xsum16(s1)); s2 = xsum32(xsum16(s2));
;                 if (fq == 0) *(f32x2*)(stn + (size_t)row * 32 + (u.pn * 4 + wc) * 2) = (f32x2){s1, s2}; asm volatile("" ::: "memory"); } }
	v_permlane32_swap_b32_e32 v50, v46
	v_permlane32_swap_b32_e32 v51, v47
	v_permlane32_swap_b32_e32 v52, v48
	v_permlane32_swap_b32_e32 v53, v49
	v_permlane16_swap_b32_e32 v50, v46
	v_permlane16_swap_b32_e32 v51, v47
	v_permlane16_swap_b32_e32 v52, v48
	v_permlane16_swap_b32_e32 v53, v49
	v_sub_f32_e32 v53, v53, v43
	v_sub_f32_e32 v52, v52, v43
	v_sub_f32_e32 v51, v51, v43
	v_sub_f32_e32 v50, v50, v43
	v_pk_mul_f32 v[50:51], v[42:43], v[50:51] op_sel_hi:[0,1]
	v_pk_mul_f32 v[52:53], v[42:43], v[52:53] op_sel_hi:[0,1]
	s_waitcnt lgkmcnt(0)
	v_pk_fma_f32 v[52:53], v[60:61], v[52:53], v[68:69]
	v_pk_fma_f32 v[50:51], v[58:59], v[50:51], v[66:67]
	v_pk_mul_f32 v[52:53], v[52:53], s[2:3] op_sel_hi:[1,0]
	v_pk_mul_f32 v[50:51], v[50:51], s[2:3] op_sel_hi:[1,0]
	v_pk_fma_f32 v[52:53], v[16:17], 0.5, v[52:53] op_sel_hi:[1,0,1]
	v_pk_fma_f32 v[50:51], v[14:15], 0.5, v[50:51] op_sel_hi:[1,0,1]
	v_add_f32_e32 v15, v52, v53
	v_add_f32_e32 v14, v50, v51
	v_add_f32_e32 v14, v14, v15
	v_add_f32_e32 v58, 0, v14
	v_mul_f32_e32 v14, v51, v51
	v_mul_f32_e32 v15, v53, v53
	v_fmac_f32_e32 v14, v50, v50
	v_fmac_f32_e32 v15, v52, v52
	v_add_f32_e32 v59, v14, v15
	v_sub_f32_e32 v15, v49, v43
	v_sub_f32_e32 v14, v48, v43
	v_sub_f32_e32 v17, v47, v43
	v_sub_f32_e32 v16, v46, v43
	v_pk_mul_f32 v[16:17], v[42:43], v[16:17] op_sel_hi:[0,1]
	v_pk_mul_f32 v[14:15], v[42:43], v[14:15] op_sel_hi:[0,1]
	v_pk_fma_f32 v[14:15], v[56:57], v[14:15], v[64:65]
	v_pk_fma_f32 v[16:17], v[54:55], v[16:17], v[62:63]
	v_pk_mul_f32 v[14:15], v[14:15], s[2:3] op_sel_hi:[1,0]
	v_pk_mul_f32 v[16:17], v[16:17], s[2:3] op_sel_hi:[1,0]
	v_pk_fma_f32 v[48:49], v[12:13], 0.5, v[14:15] op_sel_hi:[1,0,1]
	v_pk_fma_f32 v[46:47], v[10:11], 0.5, v[16:17] op_sel_hi:[1,0,1]
	v_add_f32_e32 v11, v48, v49
	v_add_f32_e32 v10, v46, v47
	v_add_f32_e32 v10, v10, v11
	v_add_f32_e32 v15, v58, v10
	v_mul_f32_e32 v10, v47, v47
	v_mul_f32_e32 v11, v49, v49
	v_fmac_f32_e32 v10, v46, v46
	v_fmac_f32_e32 v11, v48, v48
	v_add_f32_e32 v10, v10, v11
	v_add_f32_e32 v14, v59, v10
	v_cvt_pk_bf16_f32 v10, v50, v51
	v_cvt_pk_bf16_f32 v11, v52, v53
	v_cvt_pk_bf16_f32 v12, v46, v47
	v_cvt_pk_bf16_f32 v13, v48, v49
	v_lshl_add_u64 v[16:17], v[78:79], 0, v[0:1]
	s_nop 0
	s_nop 1
	v_bfe_u32 v55, v227, 4, 2
	v_sub_u32_e32 v54, 0, v55
	v_lshlrev_b32_e32 v54, 4, v54
	v_ashrrev_i32_e32 v55, 31, v54
	v_lshl_add_u64 v[54:55], v[44:45], 0, v[54:55]
	v_permlane16_swap_b32_e32 v50, v46
	v_permlane16_swap_b32_e32 v51, v47
	v_permlane16_swap_b32_e32 v52, v48
	v_permlane16_swap_b32_e32 v53, v49
	v_permlane32_swap_b32_e32 v50, v46
	v_permlane32_swap_b32_e32 v51, v47
	v_permlane32_swap_b32_e32 v52, v48
	v_permlane32_swap_b32_e32 v53, v49
	global_store_dwordx4 v[54:55], v[50:53], off
	global_store_dwordx4 v[54:55], v[46:49], off offset:64
	s_nop 1
	v_permlane32_swap_b32_e32 v50, v46
	v_permlane32_swap_b32_e32 v51, v47
	v_permlane32_swap_b32_e32 v52, v48
	v_permlane32_swap_b32_e32 v53, v49
	v_permlane16_swap_b32_e32 v50, v46
	v_permlane16_swap_b32_e32 v51, v47
	v_permlane16_swap_b32_e32 v52, v48
	v_permlane16_swap_b32_e32 v53, v49
	global_store_dwordx4 v[16:17], v[10:13], off
	s_nop 0
	s_waitcnt vmcnt(3)
	v_permlane32_swap_b32_e32 v38, v18
	v_permlane32_swap_b32_e32 v39, v19
	v_permlane32_swap_b32_e32 v40, v20
	v_permlane32_swap_b32_e32 v41, v21
	v_permlane16_swap_b32_e32 v38, v18
	v_permlane16_swap_b32_e32 v39, v19
	v_permlane16_swap_b32_e32 v40, v20
	v_permlane16_swap_b32_e32 v41, v21
	v_sub_f32_e32 v11, v41, v43
	v_sub_f32_e32 v10, v40, v43
	v_sub_f32_e32 v13, v39, v43
	v_sub_f32_e32 v12, v38, v43
	v_pk_mul_f32 v[12:13], v[42:43], v[12:13] op_sel_hi:[0,1]
	v_pk_mul_f32 v[10:11], v[42:43], v[10:11] op_sel_hi:[0,1]
	v_pk_fma_f32 v[10:11], v[32:33], v[10:11], v[36:37]
	v_pk_fma_f32 v[12:13], v[30:31], v[12:13], v[34:35]
	v_pk_mul_f32 v[10:11], v[10:11], s[2:3] op_sel_hi:[1,0]
	v_pk_mul_f32 v[12:13], v[12:13], s[2:3] op_sel_hi:[1,0]
	v_pk_fma_f32 v[8:9], v[8:9], 0.5, v[10:11] op_sel_hi:[1,0,1]
	v_pk_fma_f32 v[6:7], v[6:7], 0.5, v[12:13] op_sel_hi:[1,0,1]
	v_add_f32_e32 v11, v8, v9
	v_add_f32_e32 v10, v6, v7
	v_add_f32_e32 v10, v10, v11
	v_add_f32_e32 v15, v15, v10
	v_mul_f32_e32 v10, v7, v7
	v_mul_f32_e32 v11, v9, v9
	v_fmac_f32_e32 v10, v6, v6
	v_fmac_f32_e32 v11, v8, v8
	v_add_f32_e32 v10, v10, v11
	v_add_f32_e32 v14, v14, v10
	v_sub_f32_e32 v11, v21, v43
	v_sub_f32_e32 v10, v20, v43
	v_sub_f32_e32 v13, v19, v43
	v_sub_f32_e32 v12, v18, v43
	v_pk_mul_f32 v[12:13], v[42:43], v[12:13] op_sel_hi:[0,1]
	v_pk_mul_f32 v[10:11], v[42:43], v[10:11] op_sel_hi:[0,1]
	v_pk_fma_f32 v[10:11], v[24:25], v[10:11], v[28:29]
	v_pk_fma_f32 v[12:13], v[22:23], v[12:13], v[26:27]
	v_pk_mul_f32 v[10:11], v[10:11], s[2:3] op_sel_hi:[1,0]
	v_pk_mul_f32 v[12:13], v[12:13], s[2:3] op_sel_hi:[1,0]
	v_pk_fma_f32 v[4:5], v[4:5], 0.5, v[10:11] op_sel_hi:[1,0,1]
	v_pk_fma_f32 v[2:3], v[2:3], 0.5, v[12:13] op_sel_hi:[1,0,1]
	v_add_f32_e32 v11, v4, v5
	v_add_f32_e32 v10, v2, v3
	v_add_f32_e32 v10, v10, v11
	v_mul_f32_e32 v11, v3, v3
	v_mul_f32_e32 v12, v5, v5
	v_add_f32_e32 v10, v15, v10
	v_fmac_f32_e32 v11, v2, v2
	v_fmac_f32_e32 v12, v4, v4
	s_nop 0
	s_nop 1
	v_bfe_u32 v17, v227, 4, 2
	v_sub_u32_e32 v16, 0, v17
	v_lshlrev_b32_e32 v16, 4, v16
	v_ashrrev_i32_e32 v17, 31, v16
	v_lshl_add_u64 v[16:17], v[44:45], 0, v[16:17]
	v_permlane16_swap_b32_e32 v6, v2
	v_permlane16_swap_b32_e32 v7, v3
	v_permlane16_swap_b32_e32 v8, v4
	v_permlane16_swap_b32_e32 v9, v5
	v_permlane32_swap_b32_e32 v6, v2
	v_permlane32_swap_b32_e32 v7, v3
	v_permlane32_swap_b32_e32 v8, v4
	v_permlane32_swap_b32_e32 v9, v5
	global_store_dwordx4 v[16:17], v[6:9], off offset:512
	global_store_dwordx4 v[16:17], v[2:5], off offset:576
	s_nop 1
	v_permlane32_swap_b32_e32 v6, v2
	v_permlane32_swap_b32_e32 v7, v3
	v_permlane32_swap_b32_e32 v8, v4
	v_permlane32_swap_b32_e32 v9, v5
	v_permlane16_swap_b32_e32 v6, v2
	v_permlane16_swap_b32_e32 v7, v3
	v_permlane16_swap_b32_e32 v8, v4
	v_permlane16_swap_b32_e32 v9, v5
	v_add_f32_e32 v11, v11, v12
	v_cvt_pk_bf16_f32 v6, v6, v7
	v_cvt_pk_bf16_f32 v7, v8, v9
	v_cvt_pk_bf16_f32 v8, v2, v3
	v_lshl_add_u64 v[2:3], v[76:77], 0, v[0:1]
	v_mov_b32_e32 v0, v10
	v_add_f32_e32 v11, v14, v11
	v_cvt_pk_bf16_f32 v9, v4, v5
	v_permlane16_swap_b32_e32 v10, v0
	global_store_dwordx4 v[2:3], v[6:9], off
	v_add_f32_e32 v2, v10, v0
	v_mov_b32_e32 v0, v11
	s_nop 1
	v_permlane16_swap_b32_e32 v11, v0
	v_add_f32_e32 v3, v11, v0
	v_mov_b32_e32 v4, v2
	v_mov_b32_e32 v5, v3
	s_nop 0
	v_permlane32_swap_b32_e32 v2, v4
	v_permlane32_swap_b32_e32 v3, v5
	s_and_saveexec_b64 s[24:25], s[40:41]
	s_cbranch_execz .LBB0_1719
	v_pk_add_f32 v[2:3], v[2:3], v[4:5]
	v_lshlrev_b64 v[4:5], 7, v[74:75]
	v_lshl_add_u64 v[4:5], s[8:9], 0, v[4:5]
	v_lshl_add_u64 v[4:5], s[38:39], 2, v[4:5]
	global_store_dwordx2 v[4:5], v[2:3], off

; #define LAS __attribute__((address_space(3)))
; __global__ void __launch_bounds__(NWAVES * 64, 2) mega(Args a) {
;     extern __shared__ __attribute__((aligned(16))) unsigned char lds_raw[];
;     LAS unsigned char* lds = (LAS unsigned char*)lds_raw;
	.amdhsa_kernel _Z4mega4Args
		.amdhsa_group_segment_fixed_size 4096
		.amdhsa_private_segment_fixed_size 0
		.amdhsa_kernarg_size 392
		.amdhsa_user_sgpr_count 2
		.amdhsa_user_sgpr_dispatch_ptr 0
		.amdhsa_user_sgpr_queue_ptr 0
		.amdhsa_user_sgpr_kernarg_segment_ptr 1
		.amdhsa_user_sgpr_dispatch_id 0
		.amdhsa_user_sgpr_kernarg_preload_length 0
		.amdhsa_user_sgpr_kernarg_preload_offset 0
		.amdhsa_user_sgpr_private_segment_size 0
		.amdhsa_uses_dynamic_stack 0
		.amdhsa_enable_private_segment 0
		.amdhsa_system_sgpr_workgroup_id_x 1
		.amdhsa_system_sgpr_workgroup_id_y 0
		.amdhsa_system_sgpr_workgroup_id_z 0
		.amdhsa_system_sgpr_workgroup_info 0
		.amdhsa_system_vgpr_workitem_id 2
		.amdhsa_next_free_vgpr 256
		.amdhsa_next_free_sgpr 100
		.amdhsa_accum_offset 256
		.amdhsa_reserve_vcc 1
		.amdhsa_float_round_mode_32 0
		.amdhsa_float_round_mode_16_64 0
		.amdhsa_float_denorm_mode_32 3
		.amdhsa_float_denorm_mode_16_64 3
		.amdhsa_dx10_clamp 1
		.amdhsa_ieee_mode 1
		.amdhsa_fp16_overflow 0
		.amdhsa_tg_split 0
		.amdhsa_exception_fp_ieee_invalid_op 0
		.amdhsa_exception_fp_denorm_src 0
		.amdhsa_exception_fp_ieee_div_zero 0
		.amdhsa_exception_fp_ieee_overflow 0
		.amdhsa_exception_fp_ieee_underflow 0
		.amdhsa_exception_fp_ieee_inexact 0
		.amdhsa_exception_int_div_zero 0
	.end_amdhsa_kernel

; #define LAS __attribute__((address_space(3)))
;     __device__ __forceinline__ void operator()(const f32x4 (&acc)[2][2][4][2], const pg8::Unit& u, int wr, int wc, int fr, int fq) const {
;         const int row0 = u.pm * 256 + wr * 64 + fr, col0 = u.pn * 256 + wc * 32 + fq * 8;
; #pragma unroll
;         for (int ai = 0; ai < 2; ++ai) { float mu4[4], rs4[4]; row_stats4(stp, row0 + ai * 128, fq, mu4, rs4);
; #pragma unroll
;             for (int m = 0; m < 4; ++m) { const int row = row0 + ai * 128 + m * 16; const float mu = mu4[m], rs = rs4[m];
;                 f32x4 yv[2][2], gq[2][2], bq_[2][2];
; #pragma unroll
;                 for (int bj = 0; bj < 2; ++bj)
; #pragma unroll
;                     for (int n = 0; n < 2; ++n) { yv[bj][n] = *(const f32x4*)(Yin + (size_t)row * D_ + col0 + bj * 128 + 4 * n); gq[bj][n] = *(const f32x4*)(g + col0 + bj * 128 + 4 * n); bq_[bj][n] = *(const f32x4*)(b + col0 + bj * 128 + 4 * n); }
; __global__ void __launch_bounds__(NWAVES * 64, 2) mega(Args a) {
;     extern __shared__ __attribute__((aligned(16))) unsigned char lds_raw[];
;     LAS unsigned char* lds = (LAS unsigned char*)lds_raw;
amdhsa.kernels:
  - .agpr_count:     0
    .args:
      - .offset:         0
        .size:           136
        .value_kind:     by_value
      - .offset:         136
        .size:           4
        .value_kind:     hidden_block_count_x
      - .offset:         140
        .size:           4
        .value_kind:     hidden_block_count_y
      - .offset:         144
        .size:           4
        .value_kind:     hidden_block_count_z
      - .offset:         148
        .size:           2
        .value_kind:     hidden_group_size_x
      - .offset:         150
        .size:           2
        .value_kind:     hidden_group_size_y
      - .offset:         152
        .size:           2
        .value_kind:     hidden_group_size_z
      - .offset:         154
        .size:           2
        .value_kind:     hidden_remainder_x
      - .offset:         156
        .size:           2
        .value_kind:     hidden_remainder_y
      - .offset:         158
        .size:           2
        .value_kind:     hidden_remainder_z
      - .offset:         176
        .size:           8
        .value_kind:     hidden_global_offset_x
      - .offset:         184
        .size:           8
        .value_kind:     hidden_global_offset_y
      - .offset:         192
        .size:           8
        .value_kind:     hidden_global_offset_z
      - .offset:         200
        .size:           2
        .value_kind:     hidden_grid_dims
      - .offset:         224
        .size:           8
        .value_kind:     hidden_multigrid_sync_arg
      - .offset:         256
        .size:           4
        .value_kind:     hidden_dynamic_lds_size
    .group_segment_fixed_size: 4096
    .kernarg_segment_align: 8
    .kernarg_segment_size: 392
    .language:       OpenCL C
    .language_version:
      - 2
      - 0
    .max_flat_workgroup_size: 512
    .name:           _Z4mega4Args
    .private_segment_fixed_size: 0
    .sgpr_count:     106
    .sgpr_spill_count: 380
    .symbol:         _Z4mega4Args.kd
    .uniform_work_group_size: 1
    .uses_dynamic_stack: false
    .vgpr_count:     256
    .vgpr_spill_count: 0
    .wavefront_size: 64
